# P1/FF1 epilogues read the prefetch pool registers directly (no v_mov copies); relu^2 squares as packed multiplies
# speedup vs baseline: 1.0247x; 1.0047x over previous
; #define PG8_STAGE(bufoff, gbase, voff) do { _Pragma("unroll") for (int _i = 0; _i < 2; ++_i) \
;         __builtin_amdgcn_global_load_lds((const unsigned*)((const char*)(gbase) + (voff)[_i]), (LAS unsigned*)(lds + (bufoff) + ldsw + _i * 8192), 16, 0, 0); } while (0)
; #define PG8_LDA(dst, b, h) do { _Pragma("unroll") for (int m = 0; m < 4; ++m) _Pragma("unroll") for (int k = 0; k < 2; ++k) dst[m][k] = *(const LAS bf16x8*)(lds + PG8_SA(b, h) + aoff + m * 2048 + k * 1024); } while (0)
; #define PG8_LDB(dst, b, h) do { _Pragma("unroll") for (int n = 0; n < 2; ++n) _Pragma("unroll") for (int k = 0; k < 2; ++k) dst[n][k] = *(const LAS bf16x8*)(lds + PG8_SB(b, h) + boff + n * 2048 + k * 1024); } while (0)
; #define PG8_MMA(ai, bj, At, Bt) do { __builtin_amdgcn_s_setprio(1); _Pragma("unroll") for (int m = 0; m < 4; ++m) _Pragma("unroll") for (int n = 0; n < 2; ++n) _Pragma("unroll") for (int k = 0; k < 2; ++k) \
;         acc[ai][bj][m][n] = __builtin_amdgcn_mfma_f32_16x16x32_bf16(Bt[n][k], At[m][k], acc[ai][bj][m][n], 0, 0, 0); __builtin_amdgcn_s_setprio(0); } while (0)
; #define PG8_WAIT_L(n) asm volatile("s_waitcnt lgkmcnt(" #n ")" ::: "memory")
; #define PG8_BAR __builtin_amdgcn_s_barrier()
; #define PG8_SCHED __builtin_amdgcn_sched_barrier(0)
;     ...
;             PG8_LDB(B0, 0, 0); PG8_SCHED; PG8_LDA(At, 0, 0); PG8_STAGE(PG8_SA(1, 1), a1 + hA, voffA);
;             PG8_WAIT_L(8); PG8_BAR; PG8_WAIT_L(0); PG8_MMA(0, 0, At, B0); PG8_BAR; PG8_SCHED;
;             PG8_LDB(B1, 0, 1); PG8_STAGE(PG8_SB(0, 0), b2, voffB);
;             PG8_BAR; PG8_WAIT_L(0); PG8_MMA(0, 1, At, B1); PG8_BAR;
;             PG8_LDA(At, 0, 1); PG8_STAGE(PG8_SA(0, 0), a2, voffA);
;             PG8_BAR; PG8_WAIT_L(0); PG8_MMA(1, 0, At, B0); PG8_BAR; PG8_SCHED;
.LBB0_125:
	ds_read_b128 v[146:149], v155
	ds_read_b128 v[160:163], v155 offset:1024
	ds_read_b128 v[170:173], v155 offset:2048
	ds_read_b128 v[174:177], v155 offset:3072
	s_add_u32 s34, s30, 0xfffc0080
	s_addc_u32 s35, s31, -1
	s_cmp_eq_u32 s44, 12
	s_cselect_b32 s37, s7, s35
	s_cselect_b32 s36, s23, s34
	s_cselect_b32 s35, s21, s43
	s_cselect_b32 s34, s33, s42
	v_lshl_add_u64 v[150:151], s[30:31], 0, v[138:139]
	s_add_i32 m0, s29, 0xc000
	ds_read_b128 v[178:181], v156
	ds_read_b128 v[182:185], v156 offset:1024
	ds_read_b128 v[186:189], v156 offset:2048
	ds_read_b128 v[190:193], v156 offset:3072
	ds_read_b128 v[194:197], v156 offset:4096
	ds_read_b128 v[198:201], v156 offset:5120
	ds_read_b128 v[202:205], v156 offset:6144
	ds_read_b128 v[206:209], v156 offset:7168
	global_load_lds_dwordx4 v[150:151], off
	v_lshl_add_u64 v[150:151], s[30:31], 0, v[136:137]
	s_add_i32 m0, s29, 0xe000
	s_nop 0
	global_load_lds_dwordx4 v[150:151], off
	s_waitcnt lgkmcnt(8)
	s_barrier
	s_waitcnt lgkmcnt(0)
	s_setprio 1
	s_waitcnt lgkmcnt(0)
	v_mfma_f32_16x16x32_bf16 v[124:127], v[146:149], v[178:181], v[124:127]
	v_mfma_f32_16x16x32_bf16 v[120:123], v[170:173], v[178:181], v[120:123]
	v_mfma_f32_16x16x32_bf16 v[108:111], v[146:149], v[186:189], v[108:111]
	v_mfma_f32_16x16x32_bf16 v[104:107], v[170:173], v[186:189], v[104:107]
	v_mfma_f32_16x16x32_bf16 v[92:95], v[146:149], v[194:197], v[92:95]
	v_mfma_f32_16x16x32_bf16 v[88:91], v[170:173], v[194:197], v[88:91]
	v_mfma_f32_16x16x32_bf16 v[76:79], v[146:149], v[202:205], v[76:79]
	v_mfma_f32_16x16x32_bf16 v[72:75], v[170:173], v[202:205], v[72:75]
	v_mfma_f32_16x16x32_bf16 v[124:127], v[160:163], v[182:185], v[124:127]
	v_mfma_f32_16x16x32_bf16 v[120:123], v[174:177], v[182:185], v[120:123]
	v_mfma_f32_16x16x32_bf16 v[108:111], v[160:163], v[190:193], v[108:111]
	v_mfma_f32_16x16x32_bf16 v[104:107], v[174:177], v[190:193], v[104:107]
	v_mfma_f32_16x16x32_bf16 v[92:95], v[160:163], v[198:201], v[92:95]
	v_mfma_f32_16x16x32_bf16 v[88:91], v[174:177], v[198:201], v[88:91]
	v_mfma_f32_16x16x32_bf16 v[76:79], v[160:163], v[206:209], v[76:79]
	v_mfma_f32_16x16x32_bf16 v[72:75], v[174:177], v[206:209], v[72:75]
	s_setprio 0
	s_barrier
	s_add_i32 s45, s59, s51
	v_lshl_add_u64 v[150:151], s[34:35], 0, v[130:131]
	s_mov_b32 m0, s45
	ds_read_b128 v[210:213], v157
	ds_read_b128 v[214:217], v157 offset:1024
	ds_read_b128 v[218:221], v157 offset:2048
	ds_read_b128 v[222:225], v157 offset:3072
	global_load_lds_dwordx4 v[150:151], off
	v_lshl_add_u64 v[164:165], s[34:35], 0, v[134:135]
	s_add_i32 m0, s45, 0x2000
	s_nop 0
	global_load_lds_dwordx4 v[164:165], off
	s_barrier
	s_waitcnt lgkmcnt(0)
	s_setprio 1
	s_waitcnt lgkmcnt(0)
	v_mfma_f32_16x16x32_bf16 v[116:119], v[210:213], v[178:181], v[116:119]
	v_mfma_f32_16x16x32_bf16 v[112:115], v[218:221], v[178:181], v[112:115]
	v_mfma_f32_16x16x32_bf16 v[100:103], v[210:213], v[186:189], v[100:103]
	v_mfma_f32_16x16x32_bf16 v[96:99], v[218:221], v[186:189], v[96:99]
	v_mfma_f32_16x16x32_bf16 v[84:87], v[210:213], v[194:197], v[84:87]
	v_mfma_f32_16x16x32_bf16 v[80:83], v[218:221], v[194:197], v[80:83]
	v_mfma_f32_16x16x32_bf16 v[68:71], v[210:213], v[202:205], v[68:71]
	v_mfma_f32_16x16x32_bf16 v[64:67], v[218:221], v[202:205], v[64:67]
	v_mfma_f32_16x16x32_bf16 v[116:119], v[214:217], v[182:185], v[116:119]
	v_mfma_f32_16x16x32_bf16 v[112:115], v[222:225], v[182:185], v[112:115]
	v_mfma_f32_16x16x32_bf16 v[100:103], v[214:217], v[190:193], v[100:103]
	v_mfma_f32_16x16x32_bf16 v[96:99], v[222:225], v[190:193], v[96:99]
	v_mfma_f32_16x16x32_bf16 v[84:87], v[214:217], v[198:201], v[84:87]
	v_mfma_f32_16x16x32_bf16 v[80:83], v[222:225], v[198:201], v[80:83]
	v_mfma_f32_16x16x32_bf16 v[68:71], v[214:217], v[206:209], v[68:71]
	v_mfma_f32_16x16x32_bf16 v[64:67], v[222:225], v[206:209], v[64:67]
	s_setprio 0
	s_mov_b32 m0, s29
	v_lshl_add_u64 v[226:227], s[36:37], 0, v[128:129]
	s_barrier
	ds_read_b128 v[178:181], v156 offset:16384
	ds_read_b128 v[182:185], v156 offset:17408
	ds_read_b128 v[186:189], v156 offset:18432
	ds_read_b128 v[190:193], v156 offset:19456
	ds_read_b128 v[194:197], v156 offset:20480
	ds_read_b128 v[198:201], v156 offset:21504
	ds_read_b128 v[202:205], v156 offset:22528
	ds_read_b128 v[206:209], v156 offset:23552
	global_load_lds_dwordx4 v[226:227], off
	v_lshl_add_u64 v[228:229], s[36:37], 0, v[132:133]
	s_mov_b32 m0, s52
	s_nop 0
	global_load_lds_dwordx4 v[228:229], off
	s_barrier
	s_waitcnt lgkmcnt(0)
	s_setprio 1
	s_waitcnt lgkmcnt(0)
	v_mfma_f32_16x16x32_bf16 v[60:63], v[146:149], v[178:181], v[60:63]
	v_mfma_f32_16x16x32_bf16 v[56:59], v[170:173], v[178:181], v[56:59]
	v_mfma_f32_16x16x32_bf16 v[44:47], v[146:149], v[186:189], v[44:47]
	v_mfma_f32_16x16x32_bf16 v[40:43], v[170:173], v[186:189], v[40:43]
	v_mfma_f32_16x16x32_bf16 v[28:31], v[146:149], v[194:197], v[28:31]
	v_mfma_f32_16x16x32_bf16 v[24:27], v[170:173], v[194:197], v[24:27]
	v_mfma_f32_16x16x32_bf16 v[12:15], v[146:149], v[202:205], v[12:15]
	v_mfma_f32_16x16x32_bf16 v[8:11], v[170:173], v[202:205], v[8:11]
	v_mfma_f32_16x16x32_bf16 v[60:63], v[160:163], v[182:185], v[60:63]
	v_mfma_f32_16x16x32_bf16 v[56:59], v[174:177], v[182:185], v[56:59]
	v_mfma_f32_16x16x32_bf16 v[44:47], v[160:163], v[190:193], v[44:47]
	v_mfma_f32_16x16x32_bf16 v[40:43], v[174:177], v[190:193], v[40:43]
	v_mfma_f32_16x16x32_bf16 v[28:31], v[160:163], v[198:201], v[28:31]
	v_mfma_f32_16x16x32_bf16 v[24:27], v[174:177], v[198:201], v[24:27]
	v_mfma_f32_16x16x32_bf16 v[12:15], v[160:163], v[206:209], v[12:15]
	v_mfma_f32_16x16x32_bf16 v[8:11], v[174:177], v[206:209], v[8:11]
	s_setprio 0
	s_barrier
; #define PG8_STAGE(bufoff, gbase, voff) do { _Pragma("unroll") for (int _i = 0; _i < 2; ++_i) \
;         __builtin_amdgcn_global_load_lds((const unsigned*)((const char*)(gbase) + (voff)[_i]), (LAS unsigned*)(lds + (bufoff) + ldsw + _i * 8192), 16, 0, 0); } while (0)
; #define PG8_LDA(dst, b, h) do { _Pragma("unroll") for (int m = 0; m < 4; ++m) _Pragma("unroll") for (int k = 0; k < 2; ++k) dst[m][k] = *(const LAS bf16x8*)(lds + PG8_SA(b, h) + aoff + m * 2048 + k * 1024); } while (0)
; #define PG8_LDB(dst, b, h) do { _Pragma("unroll") for (int n = 0; n < 2; ++n) _Pragma("unroll") for (int k = 0; k < 2; ++k) dst[n][k] = *(const LAS bf16x8*)(lds + PG8_SB(b, h) + boff + n * 2048 + k * 1024); } while (0)
; #define PG8_MMA(ai, bj, At, Bt) do { __builtin_amdgcn_s_setprio(1); _Pragma("unroll") for (int m = 0; m < 4; ++m) _Pragma("unroll") for (int n = 0; n < 2; ++n) _Pragma("unroll") for (int k = 0; k < 2; ++k) \
;         acc[ai][bj][m][n] = __builtin_amdgcn_mfma_f32_16x16x32_bf16(Bt[n][k], At[m][k], acc[ai][bj][m][n], 0, 0, 0); __builtin_amdgcn_s_setprio(0); } while (0)
; #define PG8_WAIT_V(n) asm volatile("s_waitcnt vmcnt(" #n ")" ::: "memory")
; #define PG8_WAIT_L(n) asm volatile("s_waitcnt lgkmcnt(" #n ")" ::: "memory")
; #define PG8_BAR __builtin_amdgcn_s_barrier()
; #define PG8_SCHED __builtin_amdgcn_sched_barrier(0)
;     ...
;             PG8_STAGE(PG8_SB(0, 1), b2 + hB, voffB);
;             PG8_WAIT_V(6); PG8_BAR; PG8_MMA(1, 1, At, B1); PG8_BAR;
;             PG8_LDB(B0, 1, 0); PG8_SCHED; PG8_LDA(At, 1, 0); PG8_STAGE(PG8_SA(0, 1), a2 + hA, voffA);
;             PG8_WAIT_L(8); PG8_BAR; PG8_WAIT_L(0); PG8_MMA(0, 0, At, B0); PG8_BAR; PG8_SCHED;
;             PG8_LDB(B1, 1, 1); PG8_STAGE(PG8_SB(1, 0), b3, voffB);
;             PG8_BAR; PG8_WAIT_L(0); PG8_MMA(0, 1, At, B1); PG8_BAR;
;             PG8_LDA(At, 1, 1); PG8_STAGE(PG8_SA(1, 0), a3, voffA);
	s_add_u32 s64, s34, 0x40000
	s_addc_u32 s65, s35, 0
	s_add_i32 s45, s60, s51
	v_lshl_add_u64 v[146:147], s[64:65], 0, v[130:131]
	s_mov_b32 m0, s45
	s_nop 0
	global_load_lds_dwordx4 v[146:147], off
	v_lshl_add_u64 v[146:147], s[64:65], 0, v[134:135]
	s_add_i32 m0, s45, 0x2000
	s_nop 0
	global_load_lds_dwordx4 v[146:147], off
	s_waitcnt vmcnt(6)
	s_barrier
	s_setprio 1
	v_mfma_f32_16x16x32_bf16 v[52:55], v[210:213], v[178:181], v[52:55]
	v_mfma_f32_16x16x32_bf16 v[48:51], v[218:221], v[178:181], v[48:51]
	v_mfma_f32_16x16x32_bf16 v[36:39], v[210:213], v[186:189], v[36:39]
	v_mfma_f32_16x16x32_bf16 v[32:35], v[218:221], v[186:189], v[32:35]
	v_mfma_f32_16x16x32_bf16 v[20:23], v[210:213], v[194:197], v[20:23]
	v_mfma_f32_16x16x32_bf16 v[16:19], v[218:221], v[194:197], v[16:19]
	v_mfma_f32_16x16x32_bf16 v[4:7], v[210:213], v[202:205], v[4:7]
	v_mfma_f32_16x16x32_bf16 v[0:3], v[218:221], v[202:205], v[0:3]
	v_mfma_f32_16x16x32_bf16 v[52:55], v[214:217], v[182:185], v[52:55]
	v_mfma_f32_16x16x32_bf16 v[48:51], v[222:225], v[182:185], v[48:51]
	v_mfma_f32_16x16x32_bf16 v[36:39], v[214:217], v[190:193], v[36:39]
	v_mfma_f32_16x16x32_bf16 v[32:35], v[222:225], v[190:193], v[32:35]
	v_mfma_f32_16x16x32_bf16 v[20:23], v[214:217], v[198:201], v[20:23]
	v_mfma_f32_16x16x32_bf16 v[16:19], v[222:225], v[198:201], v[16:19]
	v_mfma_f32_16x16x32_bf16 v[4:7], v[214:217], v[206:209], v[4:7]
	v_mfma_f32_16x16x32_bf16 v[0:3], v[222:225], v[206:209], v[0:3]
	s_setprio 0
	s_add_i32 s45, 0, 0x18000
	v_add_u32_e32 v159, s45, v153
	s_barrier
	ds_read_b128 v[146:149], v159
	ds_read_b128 v[160:163], v159 offset:1024
	ds_read_b128 v[170:173], v159 offset:2048
	ds_read_b128 v[174:177], v159 offset:3072
	s_add_u32 s36, s36, 0x40000
	s_addc_u32 s37, s37, 0
	s_mov_b32 m0, s53
	v_lshl_add_u64 v[210:211], s[36:37], 0, v[128:129]
	ds_read_b128 v[178:181], v156 offset:32768
	ds_read_b128 v[182:185], v156 offset:33792
	ds_read_b128 v[186:189], v156 offset:34816
	ds_read_b128 v[190:193], v156 offset:35840
	ds_read_b128 v[194:197], v156 offset:36864
	ds_read_b128 v[198:201], v156 offset:37888
	ds_read_b128 v[202:205], v156 offset:38912
	ds_read_b128 v[206:209], v156 offset:39936
	global_load_lds_dwordx4 v[210:211], off
	v_lshl_add_u64 v[210:211], s[36:37], 0, v[132:133]
	s_mov_b32 m0, s54
	s_nop 0
	global_load_lds_dwordx4 v[210:211], off
	s_waitcnt lgkmcnt(8)
	s_barrier
	s_waitcnt lgkmcnt(0)
	s_setprio 1
	s_waitcnt lgkmcnt(0)
	v_mfma_f32_16x16x32_bf16 v[124:127], v[146:149], v[178:181], v[124:127]
	v_mfma_f32_16x16x32_bf16 v[120:123], v[170:173], v[178:181], v[120:123]
	v_mfma_f32_16x16x32_bf16 v[108:111], v[146:149], v[186:189], v[108:111]
	v_mfma_f32_16x16x32_bf16 v[104:107], v[170:173], v[186:189], v[104:107]
	v_mfma_f32_16x16x32_bf16 v[92:95], v[146:149], v[194:197], v[92:95]
	v_mfma_f32_16x16x32_bf16 v[88:91], v[170:173], v[194:197], v[88:91]
	v_mfma_f32_16x16x32_bf16 v[76:79], v[146:149], v[202:205], v[76:79]
	v_mfma_f32_16x16x32_bf16 v[72:75], v[170:173], v[202:205], v[72:75]
	v_mfma_f32_16x16x32_bf16 v[124:127], v[160:163], v[182:185], v[124:127]
	v_mfma_f32_16x16x32_bf16 v[120:123], v[174:177], v[182:185], v[120:123]
	v_mfma_f32_16x16x32_bf16 v[108:111], v[160:163], v[190:193], v[108:111]
	v_mfma_f32_16x16x32_bf16 v[104:107], v[174:177], v[190:193], v[104:107]
	v_mfma_f32_16x16x32_bf16 v[92:95], v[160:163], v[198:201], v[92:95]
	v_mfma_f32_16x16x32_bf16 v[88:91], v[174:177], v[198:201], v[88:91]
	v_mfma_f32_16x16x32_bf16 v[76:79], v[160:163], v[206:209], v[76:79]
	v_mfma_f32_16x16x32_bf16 v[72:75], v[174:177], v[206:209], v[72:75]
	s_setprio 0
	s_barrier
	s_add_i32 s36, 0, 0x1c000
	s_add_i32 s37, s45, s51
	v_add_u32_e32 v159, s36, v153
	v_lshl_add_u64 v[150:151], v[150:151], 0, s[18:19]
	s_mov_b32 m0, s37
	ds_read_b128 v[210:213], v159
	ds_read_b128 v[214:217], v159 offset:1024
	ds_read_b128 v[218:221], v159 offset:2048
	ds_read_b128 v[222:225], v159 offset:3072
	global_load_lds_dwordx4 v[150:151], off
	v_lshl_add_u64 v[150:151], v[164:165], 0, s[18:19]
	s_add_i32 m0, s37, 0x2000
	s_nop 0
	global_load_lds_dwordx4 v[150:151], off
	s_barrier
	s_waitcnt lgkmcnt(0)
	s_setprio 1
	s_waitcnt lgkmcnt(0)
	v_mfma_f32_16x16x32_bf16 v[116:119], v[210:213], v[178:181], v[116:119]
	v_mfma_f32_16x16x32_bf16 v[112:115], v[218:221], v[178:181], v[112:115]
	v_mfma_f32_16x16x32_bf16 v[100:103], v[210:213], v[186:189], v[100:103]
	v_mfma_f32_16x16x32_bf16 v[96:99], v[218:221], v[186:189], v[96:99]
	v_mfma_f32_16x16x32_bf16 v[84:87], v[210:213], v[194:197], v[84:87]
	v_mfma_f32_16x16x32_bf16 v[80:83], v[218:221], v[194:197], v[80:83]
	v_mfma_f32_16x16x32_bf16 v[68:71], v[210:213], v[202:205], v[68:71]
	v_mfma_f32_16x16x32_bf16 v[64:67], v[218:221], v[202:205], v[64:67]
	v_mfma_f32_16x16x32_bf16 v[116:119], v[214:217], v[182:185], v[116:119]
	v_mfma_f32_16x16x32_bf16 v[112:115], v[222:225], v[182:185], v[112:115]
	v_mfma_f32_16x16x32_bf16 v[100:103], v[214:217], v[190:193], v[100:103]
	v_mfma_f32_16x16x32_bf16 v[96:99], v[222:225], v[190:193], v[96:99]
	v_mfma_f32_16x16x32_bf16 v[84:87], v[214:217], v[198:201], v[84:87]
	v_mfma_f32_16x16x32_bf16 v[80:83], v[222:225], v[198:201], v[80:83]
	v_mfma_f32_16x16x32_bf16 v[68:71], v[214:217], v[206:209], v[68:71]
	v_mfma_f32_16x16x32_bf16 v[64:67], v[222:225], v[206:209], v[64:67]
	s_setprio 0
	s_mov_b32 m0, s56
	v_lshl_add_u64 v[150:151], v[226:227], 0, s[18:19]
	s_barrier
	ds_read_b128 v[178:181], v156 offset:49152
	ds_read_b128 v[182:185], v156 offset:50176
	ds_read_b128 v[186:189], v156 offset:51200
	ds_read_b128 v[190:193], v156 offset:52224
	ds_read_b128 v[194:197], v156 offset:53248
	ds_read_b128 v[198:201], v156 offset:54272
	ds_read_b128 v[202:205], v156 offset:55296
	ds_read_b128 v[206:209], v156 offset:56320
	global_load_lds_dwordx4 v[150:151], off
	v_lshl_add_u64 v[150:151], v[228:229], 0, s[18:19]
	s_mov_b32 m0, s57
	s_nop 0
	global_load_lds_dwordx4 v[150:151], off
	s_barrier
; #define PG8_STAGE(bufoff, gbase, voff) do { _Pragma("unroll") for (int _i = 0; _i < 2; ++_i) \
;         __builtin_amdgcn_global_load_lds((const unsigned*)((const char*)(gbase) + (voff)[_i]), (LAS unsigned*)(lds + (bufoff) + ldsw + _i * 8192), 16, 0, 0); } while (0)
; #define PG8_MMA(ai, bj, At, Bt) do { __builtin_amdgcn_s_setprio(1); _Pragma("unroll") for (int m = 0; m < 4; ++m) _Pragma("unroll") for (int n = 0; n < 2; ++n) _Pragma("unroll") for (int k = 0; k < 2; ++k) \
;         acc[ai][bj][m][n] = __builtin_amdgcn_mfma_f32_16x16x32_bf16(Bt[n][k], At[m][k], acc[ai][bj][m][n], 0, 0, 0); __builtin_amdgcn_s_setprio(0); } while (0)
; #define PG8_WAIT_V(n) asm volatile("s_waitcnt vmcnt(" #n ")" ::: "memory")
; #define PG8_WAIT_L(n) asm volatile("s_waitcnt lgkmcnt(" #n ")" ::: "memory")
; #define PG8_BAR __builtin_amdgcn_s_barrier()
; #define PG8_SCHED __builtin_amdgcn_sched_barrier(0)
;     ...
;             PG8_BAR; PG8_WAIT_L(0); PG8_MMA(1, 0, At, B0); PG8_BAR; PG8_SCHED;
;             PG8_STAGE(PG8_SB(1, 1), b3 + hB, voffB);
;             PG8_WAIT_V(6); PG8_BAR; PG8_MMA(1, 1, At, B1); PG8_BAR;
;         }
;     __device__ __forceinline__ void operator()(const f32x4 (&acc)[2][2][4][2], const Unit& u, int wr, int wc, int fr, int fq) const {
;         const int row0 = u.pm * 256 + wr * 64 + fr, col0 = u.pn * 256 + wc * 32 + 8 * fq;
; #pragma unroll
;         for (int ai = 0; ai < 2; ++ai)
; #pragma unroll
;             for (int m = 0; m < 4; ++m) {
;                 const int row = row0 + ai * 128 + m * 16; const float rs = row_rstd(ssq, row);
	s_waitcnt lgkmcnt(0)
	s_setprio 1
	s_waitcnt lgkmcnt(0)
	v_mfma_f32_16x16x32_bf16 v[60:63], v[146:149], v[178:181], v[60:63]
	v_mfma_f32_16x16x32_bf16 v[56:59], v[170:173], v[178:181], v[56:59]
	v_mfma_f32_16x16x32_bf16 v[44:47], v[146:149], v[186:189], v[44:47]
	v_mfma_f32_16x16x32_bf16 v[40:43], v[170:173], v[186:189], v[40:43]
	v_mfma_f32_16x16x32_bf16 v[28:31], v[146:149], v[194:197], v[28:31]
	v_mfma_f32_16x16x32_bf16 v[24:27], v[170:173], v[194:197], v[24:27]
	v_mfma_f32_16x16x32_bf16 v[12:15], v[146:149], v[202:205], v[12:15]
	v_mfma_f32_16x16x32_bf16 v[8:11], v[170:173], v[202:205], v[8:11]
	v_mfma_f32_16x16x32_bf16 v[60:63], v[160:163], v[182:185], v[60:63]
	v_mfma_f32_16x16x32_bf16 v[56:59], v[174:177], v[182:185], v[56:59]
	v_mfma_f32_16x16x32_bf16 v[44:47], v[160:163], v[190:193], v[44:47]
	v_mfma_f32_16x16x32_bf16 v[40:43], v[174:177], v[190:193], v[40:43]
	v_mfma_f32_16x16x32_bf16 v[28:31], v[160:163], v[198:201], v[28:31]
	v_mfma_f32_16x16x32_bf16 v[24:27], v[174:177], v[198:201], v[24:27]
	v_mfma_f32_16x16x32_bf16 v[12:15], v[160:163], v[206:209], v[12:15]
	v_mfma_f32_16x16x32_bf16 v[8:11], v[174:177], v[206:209], v[8:11]
	s_setprio 0
	s_barrier
	s_add_u32 s34, s34, 0x40080
	s_addc_u32 s35, s35, 0
	s_add_i32 s36, s36, s51
	v_lshl_add_u64 v[146:147], s[34:35], 0, v[130:131]
	s_mov_b32 m0, s36
	s_nop 0
	global_load_lds_dwordx4 v[146:147], off
	v_lshl_add_u64 v[146:147], s[34:35], 0, v[134:135]
	s_add_i32 m0, s36, 0x2000
	s_nop 0
	global_load_lds_dwordx4 v[146:147], off
	s_waitcnt vmcnt(6)
	s_barrier
	s_setprio 1
	v_mfma_f32_16x16x32_bf16 v[52:55], v[210:213], v[178:181], v[52:55]
	v_mfma_f32_16x16x32_bf16 v[48:51], v[218:221], v[178:181], v[48:51]
	v_mfma_f32_16x16x32_bf16 v[36:39], v[210:213], v[186:189], v[36:39]
	v_mfma_f32_16x16x32_bf16 v[32:35], v[218:221], v[186:189], v[32:35]
	v_mfma_f32_16x16x32_bf16 v[20:23], v[210:213], v[194:197], v[20:23]
	v_mfma_f32_16x16x32_bf16 v[16:19], v[218:221], v[194:197], v[16:19]
	v_mfma_f32_16x16x32_bf16 v[4:7], v[210:213], v[202:205], v[4:7]
	v_mfma_f32_16x16x32_bf16 v[0:3], v[218:221], v[202:205], v[0:3]
	v_mfma_f32_16x16x32_bf16 v[52:55], v[214:217], v[182:185], v[52:55]
	v_mfma_f32_16x16x32_bf16 v[48:51], v[222:225], v[182:185], v[48:51]
	v_mfma_f32_16x16x32_bf16 v[36:39], v[214:217], v[190:193], v[36:39]
	v_mfma_f32_16x16x32_bf16 v[32:35], v[222:225], v[190:193], v[32:35]
	v_mfma_f32_16x16x32_bf16 v[20:23], v[214:217], v[198:201], v[20:23]
	v_mfma_f32_16x16x32_bf16 v[16:19], v[222:225], v[198:201], v[16:19]
	v_mfma_f32_16x16x32_bf16 v[4:7], v[214:217], v[206:209], v[4:7]
	v_mfma_f32_16x16x32_bf16 v[0:3], v[222:225], v[206:209], v[0:3]
	s_setprio 0
	s_add_i32 s44, s44, 2
	s_add_u32 s42, s42, 0x100
	s_addc_u32 s43, s43, 0
	s_add_u32 s30, s30, 0x100
	s_addc_u32 s31, s31, 0
	s_cmp_gt_u32 s44, 13
	s_barrier
	s_cbranch_scc0 .LBB0_125
	v_lshl_add_u32 v150, s28, 8, v152
	v_ashrrev_i32_e32 v151, 31, v150
	v_lshlrev_b64 v[146:147], 6, v[150:151]
	v_lshl_add_u64 v[146:147], s[16:17], 0, v[146:147]
	v_subrev_u32_e32 v186, s16, v146
	v_add_u32_e32 v187, 0x0, v186
	global_load_dwordx4 v[188:191], v187, s[16:17]
	v_add_u32_e32 v187, 0x20, v186
	global_load_dwordx4 v[192:195], v187, s[16:17]
	v_add_u32_e32 v187, 0x10, v186
	global_load_dwordx4 v[196:199], v187, s[16:17]
	v_add_u32_e32 v187, 0x30, v186
	global_load_dwordx4 v[200:203], v187, s[16:17]
	v_add_u32_e32 v187, 0x400, v186
	global_load_dwordx4 v[204:207], v187, s[16:17]
	v_add_u32_e32 v187, 0x410, v186
	global_load_dwordx4 v[208:211], v187, s[16:17]
	v_add_u32_e32 v187, 0x420, v186
	global_load_dwordx4 v[212:215], v187, s[16:17]
	v_add_u32_e32 v187, 0x430, v186
	global_load_dwordx4 v[216:219], v187, s[16:17]
	v_add_u32_e32 v187, 0x800, v186
	global_load_dwordx4 v[220:223], v187, s[16:17]
	v_add_u32_e32 v187, 0x810, v186
	global_load_dwordx4 v[232:235], v187, s[16:17]
	v_add_u32_e32 v187, 0x820, v186
	global_load_dwordx4 v[236:239], v187, s[16:17]
	v_add_u32_e32 v187, 0x830, v186
	global_load_dwordx4 v[240:243], v187, s[16:17]
	v_lshl_or_b32 v148, s6, 8, v154
	v_mov_b64_e32 v[146:147], s[14:15]
	v_ashrrev_i32_e32 v149, 31, v148
	v_mad_i64_i32 v[164:165], s[6:7], v150, s62, v[146:147]
	v_or_b32_e32 v182, 16, v150
	v_lshlrev_b64 v[148:149], 1, v[148:149]
	v_ashrrev_i32_e32 v183, 31, v182
	s_mov_b64 s[34:35], s[24:25]
	s_mov_b32 s28, s22
	s_mov_b64 s[30:31], s[26:27]
	s_waitcnt vmcnt(8)
; __device__ __forceinline__ float bflo(unsigned w) { return __uint_as_float(w << 16); }
; __device__ __forceinline__ float bfhi(unsigned w) { return __uint_as_float(w & 0xffff0000u); }
; __device__ __forceinline__ unsigned pk2(float lo, float hi) { unsigned r; asm volatile("v_cvt_pk_bf16_f32 %0, %1, %2" : "=v"(r) : "v"(lo), "v"(hi)); return r; }
; __device__ __forceinline__ float row_rstd(const float* ssq, int row) {
;     const f32x4* p = (const f32x4*)(ssq + (size_t)row * 16);
;     const f32x4 a = p[0], b = p[1], c = p[2], d = p[3];
;     const float s = ((a[0] + a[1]) + (a[2] + a[3])) + ((b[0] + b[1]) + (b[2] + b[3])) + ((c[0] + c[1]) + (c[2] + c[3])) + ((d[0] + d[1]) + (d[2] + d[3]));
;     return rsqrtf(s * (1.0f / 1024.0f) + 1e-6f);
; }
; __device__ __forceinline__ u32x4 pack8(const f32x4 v0, const f32x4 v1) { u32x4 w; w.x = pk2(v0[0], v0[1]); w.y = pk2(v0[2], v0[3]); w.z = pk2(v1[0], v1[1]); w.w = pk2(v1[2], v1[3]); return w; }
; __device__ __forceinline__ void unpack8(const u32x4 w, f32x4& v0, f32x4& v1) { v0 = (f32x4){bflo(w.x), bfhi(w.x), bflo(w.y), bfhi(w.y)}; v1 = (f32x4){bflo(w.z), bfhi(w.z), bflo(w.w), bfhi(w.w)}; }
;     __device__ __forceinline__ void operator()(const f32x4 (&acc)[2][2][4][2], const Unit& u, int wr, int wc, int fr, int fq) const {
;         const int row0 = u.pm * 256 + wr * 64 + fr, col0 = u.pn * 256 + wc * 32 + 8 * fq;
; #pragma unroll
;         for (int ai = 0; ai < 2; ++ai)
; #pragma unroll
;             for (int m = 0; m < 4; ++m) {
;                 const int row = row0 + ai * 128 + m * 16; const float rs = row_rstd(ssq, row);
;                 bf16_t* rowp = O + (size_t)row * ldc + col0;
; #pragma unroll
;                 for (int bj = 0; bj < 2; ++bj) { f32x4 v0 = acc[ai][bj][m][0] * rs, v1 = acc[ai][bj][m][1] * rs;
;                     if (ACT == 1) {
; #pragma unroll
;                         for (int j = 0; j < 4; ++j) { const float a = fmaxf(v0[j], 0.f), b = fmaxf(v1[j], 0.f); v0[j] = a * a; v1[j] = b * b; } }
;                     *(u32x4*)(rowp + bj * 128) = pack8(v0, v1); }
	v_mov_b32_e32 v184, v189
	v_mov_b32_e32 v185, v190
	v_mov_b32_e32 v161, v191
	v_add_f32_e32 v162, v192, v193
	v_add_f32_e32 v170, v194, v195
	v_mov_b32_e32 v172, v197
	v_mov_b32_e32 v173, v198
	v_mov_b32_e32 v175, v199
	v_mov_b32_e32 v163, v202
	v_mov_b32_e32 v171, v203
	v_mov_b32_e32 v160, v188
	v_pk_add_f32 v[160:161], v[184:185], v[160:161]
	v_mov_b32_e32 v174, v196
	v_pk_add_f32 v[172:173], v[172:173], v[174:175]
	v_pk_add_f32 v[162:163], v[162:163], v[170:171]
	v_pk_add_f32 v[160:161], v[160:161], v[160:161] op_sel:[0,1] op_sel_hi:[1,0]
	v_pk_add_f32 v[170:171], v[172:173], v[172:173] op_sel:[0,1] op_sel_hi:[1,0]
	v_mov_b32_e32 v161, v200
	v_mov_b32_e32 v171, v201
	v_pk_add_f32 v[160:161], v[160:161], v[170:171]
	s_nop 0
	v_pk_add_f32 v[160:161], v[160:161], v[162:163]
	v_lshlrev_b64 v[162:163], 6, v[182:183]
	v_add_f32_e32 v151, v160, v161
	v_fmamk_f32 v151, v151, 0x3a800000, v158
	v_mul_f32_e32 v159, 0x4b800000, v151
	v_cmp_gt_f32_e32 vcc, s61, v151
	v_lshl_add_u64 v[160:161], v[164:165], 0, v[148:149]
	v_lshl_add_u64 v[162:163], s[16:17], 0, v[162:163]
	v_cndmask_b32_e32 v151, v151, v159, vcc
	v_rsq_f32_e32 v151, v151
	s_nop 0
	v_mul_f32_e32 v159, 0x45800000, v151
	v_cndmask_b32_e32 v164, v151, v159, vcc
	v_pk_mul_f32 v[126:127], v[126:127], v[164:165] op_sel_hi:[1,0]
	v_pk_mul_f32 v[124:125], v[124:125], v[164:165] op_sel_hi:[1,0]
	v_pk_mul_f32 v[122:123], v[122:123], v[164:165] op_sel_hi:[1,0]
	v_pk_mul_f32 v[120:121], v[120:121], v[164:165] op_sel_hi:[1,0]
	v_pk_mul_f32 v[118:119], v[118:119], v[164:165] op_sel_hi:[1,0]
	v_pk_mul_f32 v[116:117], v[116:117], v[164:165] op_sel_hi:[1,0]
	v_pk_mul_f32 v[170:171], v[114:115], v[164:165] op_sel_hi:[1,0]
	v_pk_mul_f32 v[164:165], v[112:113], v[164:165] op_sel_hi:[1,0]
	v_cvt_pk_bf16_f32 v112, v124, v125
	v_cvt_pk_bf16_f32 v113, v126, v127
	v_cvt_pk_bf16_f32 v114, v120, v121
	v_cvt_pk_bf16_f32 v115, v122, v123
	global_store_dwordx4 v[160:161], v[112:115], off sc1
	s_nop 1
	v_cvt_pk_bf16_f32 v112, v116, v117
	v_cvt_pk_bf16_f32 v113, v118, v119
	v_cvt_pk_bf16_f32 v114, v164, v165
	v_cvt_pk_bf16_f32 v115, v170, v171
	global_store_dwordx4 v[160:161], v[112:115], off offset:256 sc1
	s_nop 0
	v_or_b32_e32 v160, 32, v150
	v_mad_i64_i32 v[162:163], s[6:7], v182, s62, v[146:147]
	v_ashrrev_i32_e32 v161, 31, v160
	v_add_u32_e32 v187, 0xc00, v186
	global_load_dwordx4 v[188:191], v187, s[16:17]
	v_add_u32_e32 v187, 0xc10, v186
	global_load_dwordx4 v[192:195], v187, s[16:17]
	v_add_u32_e32 v187, 0xc20, v186
	global_load_dwordx4 v[196:199], v187, s[16:17]
	v_add_u32_e32 v187, 0xc30, v186
	global_load_dwordx4 v[200:203], v187, s[16:17]
	s_waitcnt vmcnt(10)
	v_mov_b32_e32 v164, v205
	v_mov_b32_e32 v165, v206
	v_mov_b32_e32 v113, v207
	v_mov_b32_e32 v114, v209
	v_mov_b32_e32 v115, v210
	v_mov_b32_e32 v117, v211
	v_mov_b32_e32 v112, v204
	v_pk_add_f32 v[112:113], v[164:165], v[112:113]
	v_mov_b32_e32 v116, v208
	v_pk_add_f32 v[114:115], v[114:115], v[116:117]
	v_pk_add_f32 v[112:113], v[112:113], v[112:113] op_sel:[0,1] op_sel_hi:[1,0]
	v_pk_add_f32 v[114:115], v[114:115], v[114:115] op_sel:[0,1] op_sel_hi:[1,0]
	v_add_f32_e32 v118, v212, v213
	v_add_f32_e32 v120, v214, v215
	v_mov_b32_e32 v119, v218
	v_mov_b32_e32 v121, v219
	v_mov_b32_e32 v113, v216
	v_mov_b32_e32 v115, v217
	v_pk_add_f32 v[116:117], v[118:119], v[120:121]
	v_pk_add_f32 v[112:113], v[112:113], v[114:115]
	v_lshlrev_b64 v[114:115], 6, v[160:161]
	v_pk_add_f32 v[112:113], v[112:113], v[116:117]
	v_lshl_add_u64 v[114:115], s[16:17], 0, v[114:115]
	v_add_f32_e32 v112, v112, v113
	v_fmamk_f32 v112, v112, 0x3a800000, v158
	v_mul_f32_e32 v113, 0x4b800000, v112
	v_cmp_gt_f32_e32 vcc, s61, v112
	s_nop 1
	v_cndmask_b32_e32 v112, v112, v113, vcc
	v_rsq_f32_e32 v116, v112
	v_lshl_add_u64 v[112:113], v[162:163], 0, v[148:149]
	v_mul_f32_e32 v117, 0x45800000, v116
	v_cndmask_b32_e32 v116, v116, v117, vcc
	v_pk_mul_f32 v[110:111], v[110:111], v[116:117] op_sel_hi:[1,0]
	v_pk_mul_f32 v[108:109], v[108:109], v[116:117] op_sel_hi:[1,0]
	v_pk_mul_f32 v[106:107], v[106:107], v[116:117] op_sel_hi:[1,0]
	v_pk_mul_f32 v[104:105], v[104:105], v[116:117] op_sel_hi:[1,0]
	v_pk_mul_f32 v[102:103], v[102:103], v[116:117] op_sel_hi:[1,0]
	v_pk_mul_f32 v[100:101], v[100:101], v[116:117] op_sel_hi:[1,0]
	v_pk_mul_f32 v[118:119], v[98:99], v[116:117] op_sel_hi:[1,0]
	v_pk_mul_f32 v[116:117], v[96:97], v[116:117] op_sel_hi:[1,0]
	v_cvt_pk_bf16_f32 v96, v108, v109
	v_cvt_pk_bf16_f32 v97, v110, v111
	v_cvt_pk_bf16_f32 v98, v104, v105
	v_cvt_pk_bf16_f32 v99, v106, v107
	global_store_dwordx4 v[112:113], v[96:99], off sc1
	s_nop 1
	v_cvt_pk_bf16_f32 v96, v100, v101
	v_cvt_pk_bf16_f32 v97, v102, v103
	v_cvt_pk_bf16_f32 v98, v116, v117
	v_cvt_pk_bf16_f32 v99, v118, v119
	global_store_dwordx4 v[112:113], v[96:99], off offset:256 sc1
	s_nop 0
	v_or_b32_e32 v112, 48, v150
	v_mad_i64_i32 v[114:115], s[6:7], v160, s62, v[146:147]
	v_ashrrev_i32_e32 v113, 31, v112
	v_add_u32_e32 v187, 0x2000, v186
	global_load_dwordx4 v[204:207], v187, s[16:17]
	v_add_u32_e32 v187, 0x2010, v186
	global_load_dwordx4 v[208:211], v187, s[16:17]
	v_add_u32_e32 v187, 0x2020, v186
	global_load_dwordx4 v[212:215], v187, s[16:17]
	v_add_u32_e32 v187, 0x2030, v186
	global_load_dwordx4 v[216:219], v187, s[16:17]
	s_waitcnt vmcnt(12)
; __device__ __forceinline__ float bflo(unsigned w) { return __uint_as_float(w << 16); }
; __device__ __forceinline__ float bfhi(unsigned w) { return __uint_as_float(w & 0xffff0000u); }
; __device__ __forceinline__ unsigned pk2(float lo, float hi) { unsigned r; asm volatile("v_cvt_pk_bf16_f32 %0, %1, %2" : "=v"(r) : "v"(lo), "v"(hi)); return r; }
; __device__ __forceinline__ float row_rstd(const float* ssq, int row) {
;     const f32x4* p = (const f32x4*)(ssq + (size_t)row * 16);
;     const f32x4 a = p[0], b = p[1], c = p[2], d = p[3];
;     const float s = ((a[0] + a[1]) + (a[2] + a[3])) + ((b[0] + b[1]) + (b[2] + b[3])) + ((c[0] + c[1]) + (c[2] + c[3])) + ((d[0] + d[1]) + (d[2] + d[3]));
;     return rsqrtf(s * (1.0f / 1024.0f) + 1e-6f);
; }
; __device__ __forceinline__ u32x4 pack8(const f32x4 v0, const f32x4 v1) { u32x4 w; w.x = pk2(v0[0], v0[1]); w.y = pk2(v0[2], v0[3]); w.z = pk2(v1[0], v1[1]); w.w = pk2(v1[2], v1[3]); return w; }
; __device__ __forceinline__ void unpack8(const u32x4 w, f32x4& v0, f32x4& v1) { v0 = (f32x4){bflo(w.x), bfhi(w.x), bflo(w.y), bfhi(w.y)}; v1 = (f32x4){bflo(w.z), bfhi(w.z), bflo(w.w), bfhi(w.w)}; }
;     __device__ __forceinline__ void operator()(const f32x4 (&acc)[2][2][4][2], const Unit& u, int wr, int wc, int fr, int fq) const {
;         const int row0 = u.pm * 256 + wr * 64 + fr, col0 = u.pn * 256 + wc * 32 + 8 * fq;
; #pragma unroll
;         for (int ai = 0; ai < 2; ++ai)
; #pragma unroll
;             for (int m = 0; m < 4; ++m) {
;                 const int row = row0 + ai * 128 + m * 16; const float rs = row_rstd(ssq, row);
;                 bf16_t* rowp = O + (size_t)row * ldc + col0;
; #pragma unroll
;                 for (int bj = 0; bj < 2; ++bj) { f32x4 v0 = acc[ai][bj][m][0] * rs, v1 = acc[ai][bj][m][1] * rs;
;                     if (ACT == 1) {
; #pragma unroll
;                         for (int j = 0; j < 4; ++j) { const float a = fmaxf(v0[j], 0.f), b = fmaxf(v1[j], 0.f); v0[j] = a * a; v1[j] = b * b; } }
;                     *(u32x4*)(rowp + bj * 128) = pack8(v0, v1); }
	v_mov_b32_e32 v116, v221
	v_mov_b32_e32 v117, v222
	v_mov_b32_e32 v97, v223
	v_mov_b32_e32 v98, v233
	v_mov_b32_e32 v99, v234
	v_mov_b32_e32 v101, v235
	v_mov_b32_e32 v96, v220
	v_pk_add_f32 v[96:97], v[116:117], v[96:97]
	v_mov_b32_e32 v100, v232
	v_pk_add_f32 v[98:99], v[98:99], v[100:101]
	v_pk_add_f32 v[96:97], v[96:97], v[96:97] op_sel:[0,1] op_sel_hi:[1,0]
	v_pk_add_f32 v[98:99], v[98:99], v[98:99] op_sel:[0,1] op_sel_hi:[1,0]
	v_add_f32_e32 v102, v236, v237
	v_add_f32_e32 v104, v238, v239
	v_mov_b32_e32 v103, v242
	v_mov_b32_e32 v105, v243
	v_mov_b32_e32 v97, v240
	v_mov_b32_e32 v99, v241
	v_pk_add_f32 v[100:101], v[102:103], v[104:105]
	v_pk_add_f32 v[96:97], v[96:97], v[98:99]
	v_lshlrev_b64 v[98:99], 6, v[112:113]
	v_pk_add_f32 v[96:97], v[96:97], v[100:101]
	v_lshl_add_u64 v[98:99], s[16:17], 0, v[98:99]
	v_add_f32_e32 v96, v96, v97
	v_fmamk_f32 v96, v96, 0x3a800000, v158
	v_mul_f32_e32 v97, 0x4b800000, v96
	v_cmp_gt_f32_e32 vcc, s61, v96
	s_nop 1
	v_cndmask_b32_e32 v96, v96, v97, vcc
	v_rsq_f32_e32 v100, v96
	v_lshl_add_u64 v[96:97], v[114:115], 0, v[148:149]
	v_mul_f32_e32 v101, 0x45800000, v100
	v_cndmask_b32_e32 v100, v100, v101, vcc
	v_pk_mul_f32 v[94:95], v[94:95], v[100:101] op_sel_hi:[1,0]
	v_pk_mul_f32 v[92:93], v[92:93], v[100:101] op_sel_hi:[1,0]
	v_pk_mul_f32 v[90:91], v[90:91], v[100:101] op_sel_hi:[1,0]
	v_pk_mul_f32 v[88:89], v[88:89], v[100:101] op_sel_hi:[1,0]
	v_pk_mul_f32 v[86:87], v[86:87], v[100:101] op_sel_hi:[1,0]
	v_pk_mul_f32 v[84:85], v[84:85], v[100:101] op_sel_hi:[1,0]
	v_pk_mul_f32 v[102:103], v[82:83], v[100:101] op_sel_hi:[1,0]
	v_pk_mul_f32 v[100:101], v[80:81], v[100:101] op_sel_hi:[1,0]
	v_cvt_pk_bf16_f32 v80, v92, v93
	v_cvt_pk_bf16_f32 v81, v94, v95
	v_cvt_pk_bf16_f32 v82, v88, v89
	v_cvt_pk_bf16_f32 v83, v90, v91
	global_store_dwordx4 v[96:97], v[80:83], off sc1
	s_nop 1
	v_cvt_pk_bf16_f32 v80, v84, v85
	v_cvt_pk_bf16_f32 v81, v86, v87
	v_cvt_pk_bf16_f32 v82, v100, v101
	v_cvt_pk_bf16_f32 v83, v102, v103
	global_store_dwordx4 v[96:97], v[80:83], off offset:256 sc1
	s_nop 0
	v_add_u32_e32 v96, 0x80, v150
	v_mad_i64_i32 v[98:99], s[6:7], v112, s62, v[146:147]
	v_ashrrev_i32_e32 v97, 31, v96
	v_add_u32_e32 v187, 0x2400, v186
	global_load_dwordx4 v[220:223], v187, s[16:17]
	v_add_u32_e32 v187, 0x2410, v186
	global_load_dwordx4 v[232:235], v187, s[16:17]
	v_add_u32_e32 v187, 0x2420, v186
	global_load_dwordx4 v[236:239], v187, s[16:17]
	v_add_u32_e32 v187, 0x2430, v186
	global_load_dwordx4 v[240:243], v187, s[16:17]
	s_waitcnt vmcnt(12)
	v_mov_b32_e32 v100, v189
	v_mov_b32_e32 v101, v190
	v_mov_b32_e32 v81, v191
	v_mov_b32_e32 v82, v193
	v_mov_b32_e32 v83, v194
	v_mov_b32_e32 v85, v195
	v_mov_b32_e32 v80, v188
	v_pk_add_f32 v[80:81], v[100:101], v[80:81]
	v_mov_b32_e32 v84, v192
	v_pk_add_f32 v[82:83], v[82:83], v[84:85]
	v_pk_add_f32 v[80:81], v[80:81], v[80:81] op_sel:[0,1] op_sel_hi:[1,0]
	v_pk_add_f32 v[82:83], v[82:83], v[82:83] op_sel:[0,1] op_sel_hi:[1,0]
	v_add_f32_e32 v86, v196, v197
	v_add_f32_e32 v88, v198, v199
	v_mov_b32_e32 v87, v202
	v_mov_b32_e32 v89, v203
	v_mov_b32_e32 v81, v200
	v_mov_b32_e32 v83, v201
	v_pk_add_f32 v[84:85], v[86:87], v[88:89]
	v_pk_add_f32 v[80:81], v[80:81], v[82:83]
	v_lshlrev_b64 v[82:83], 6, v[96:97]
	v_pk_add_f32 v[80:81], v[80:81], v[84:85]
	v_lshl_add_u64 v[82:83], s[16:17], 0, v[82:83]
	v_add_f32_e32 v80, v80, v81
	v_fmamk_f32 v80, v80, 0x3a800000, v158
	v_mul_f32_e32 v81, 0x4b800000, v80
	v_cmp_gt_f32_e32 vcc, s61, v80
	s_nop 1
	v_cndmask_b32_e32 v80, v80, v81, vcc
	v_rsq_f32_e32 v84, v80
	v_lshl_add_u64 v[80:81], v[98:99], 0, v[148:149]
	v_mul_f32_e32 v85, 0x45800000, v84
	v_cndmask_b32_e32 v84, v84, v85, vcc
	v_pk_mul_f32 v[78:79], v[78:79], v[84:85] op_sel_hi:[1,0]
	v_pk_mul_f32 v[76:77], v[76:77], v[84:85] op_sel_hi:[1,0]
	v_pk_mul_f32 v[74:75], v[74:75], v[84:85] op_sel_hi:[1,0]
	v_pk_mul_f32 v[72:73], v[72:73], v[84:85] op_sel_hi:[1,0]
	v_pk_mul_f32 v[70:71], v[70:71], v[84:85] op_sel_hi:[1,0]
	v_pk_mul_f32 v[68:69], v[68:69], v[84:85] op_sel_hi:[1,0]
	v_pk_mul_f32 v[86:87], v[66:67], v[84:85] op_sel_hi:[1,0]
	v_pk_mul_f32 v[84:85], v[64:65], v[84:85] op_sel_hi:[1,0]
	v_cvt_pk_bf16_f32 v64, v76, v77
	v_cvt_pk_bf16_f32 v65, v78, v79
	v_cvt_pk_bf16_f32 v66, v72, v73
	v_cvt_pk_bf16_f32 v67, v74, v75
	global_store_dwordx4 v[80:81], v[64:67], off sc1
	s_nop 1
	v_cvt_pk_bf16_f32 v64, v68, v69
	v_cvt_pk_bf16_f32 v65, v70, v71
	v_cvt_pk_bf16_f32 v66, v84, v85
	v_cvt_pk_bf16_f32 v67, v86, v87
	global_store_dwordx4 v[80:81], v[64:67], off offset:256 sc1
	s_nop 0
	v_add_u32_e32 v80, 0x90, v150
	v_mad_i64_i32 v[82:83], s[6:7], v96, s62, v[146:147]
	v_ashrrev_i32_e32 v81, 31, v80
	v_add_u32_e32 v187, 0x2800, v186
	global_load_dwordx4 v[188:191], v187, s[16:17]
	v_add_u32_e32 v187, 0x2810, v186
	global_load_dwordx4 v[192:195], v187, s[16:17]
	v_add_u32_e32 v187, 0x2820, v186
	global_load_dwordx4 v[196:199], v187, s[16:17]
	v_add_u32_e32 v187, 0x2830, v186
	global_load_dwordx4 v[200:203], v187, s[16:17]
	s_waitcnt vmcnt(12)
; __device__ __forceinline__ float bflo(unsigned w) { return __uint_as_float(w << 16); }
; __device__ __forceinline__ float bfhi(unsigned w) { return __uint_as_float(w & 0xffff0000u); }
; __device__ __forceinline__ unsigned pk2(float lo, float hi) { unsigned r; asm volatile("v_cvt_pk_bf16_f32 %0, %1, %2" : "=v"(r) : "v"(lo), "v"(hi)); return r; }
; __device__ __forceinline__ float row_rstd(const float* ssq, int row) {
;     const f32x4* p = (const f32x4*)(ssq + (size_t)row * 16);
;     const f32x4 a = p[0], b = p[1], c = p[2], d = p[3];
;     const float s = ((a[0] + a[1]) + (a[2] + a[3])) + ((b[0] + b[1]) + (b[2] + b[3])) + ((c[0] + c[1]) + (c[2] + c[3])) + ((d[0] + d[1]) + (d[2] + d[3]));
;     return rsqrtf(s * (1.0f / 1024.0f) + 1e-6f);
; }
; __device__ __forceinline__ u32x4 pack8(const f32x4 v0, const f32x4 v1) { u32x4 w; w.x = pk2(v0[0], v0[1]); w.y = pk2(v0[2], v0[3]); w.z = pk2(v1[0], v1[1]); w.w = pk2(v1[2], v1[3]); return w; }
; __device__ __forceinline__ void unpack8(const u32x4 w, f32x4& v0, f32x4& v1) { v0 = (f32x4){bflo(w.x), bfhi(w.x), bflo(w.y), bfhi(w.y)}; v1 = (f32x4){bflo(w.z), bfhi(w.z), bflo(w.w), bfhi(w.w)}; }
;     __device__ __forceinline__ void operator()(const f32x4 (&acc)[2][2][4][2], const Unit& u, int wr, int wc, int fr, int fq) const {
;         const int row0 = u.pm * 256 + wr * 64 + fr, col0 = u.pn * 256 + wc * 32 + 8 * fq;
; #pragma unroll
;         for (int ai = 0; ai < 2; ++ai)
; #pragma unroll
;             for (int m = 0; m < 4; ++m) {
;                 const int row = row0 + ai * 128 + m * 16; const float rs = row_rstd(ssq, row);
;                 bf16_t* rowp = O + (size_t)row * ldc + col0;
; #pragma unroll
;                 for (int bj = 0; bj < 2; ++bj) { f32x4 v0 = acc[ai][bj][m][0] * rs, v1 = acc[ai][bj][m][1] * rs;
;                     if (ACT == 1) {
; #pragma unroll
;                         for (int j = 0; j < 4; ++j) { const float a = fmaxf(v0[j], 0.f), b = fmaxf(v1[j], 0.f); v0[j] = a * a; v1[j] = b * b; } }
;                     *(u32x4*)(rowp + bj * 128) = pack8(v0, v1); }
	v_mov_b32_e32 v84, v205
	v_mov_b32_e32 v85, v206
	v_mov_b32_e32 v65, v207
	v_mov_b32_e32 v66, v209
	v_mov_b32_e32 v67, v210
	v_mov_b32_e32 v69, v211
	v_mov_b32_e32 v64, v204
	v_pk_add_f32 v[64:65], v[84:85], v[64:65]
	v_mov_b32_e32 v68, v208
	v_pk_add_f32 v[66:67], v[66:67], v[68:69]
	v_pk_add_f32 v[64:65], v[64:65], v[64:65] op_sel:[0,1] op_sel_hi:[1,0]
	v_pk_add_f32 v[66:67], v[66:67], v[66:67] op_sel:[0,1] op_sel_hi:[1,0]
	v_add_f32_e32 v70, v212, v213
	v_add_f32_e32 v72, v214, v215
	v_mov_b32_e32 v71, v218
	v_mov_b32_e32 v73, v219
	v_mov_b32_e32 v65, v216
	v_mov_b32_e32 v67, v217
	v_pk_add_f32 v[68:69], v[70:71], v[72:73]
	v_pk_add_f32 v[64:65], v[64:65], v[66:67]
	v_lshlrev_b64 v[66:67], 6, v[80:81]
	v_pk_add_f32 v[64:65], v[64:65], v[68:69]
	v_lshl_add_u64 v[66:67], s[16:17], 0, v[66:67]
	v_add_f32_e32 v64, v64, v65
	v_fmamk_f32 v64, v64, 0x3a800000, v158
	v_mul_f32_e32 v65, 0x4b800000, v64
	v_cmp_gt_f32_e32 vcc, s61, v64
	s_nop 1
	v_cndmask_b32_e32 v64, v64, v65, vcc
	v_rsq_f32_e32 v68, v64
	v_lshl_add_u64 v[64:65], v[82:83], 0, v[148:149]
	v_mul_f32_e32 v69, 0x45800000, v68
	v_cndmask_b32_e32 v68, v68, v69, vcc
	v_pk_mul_f32 v[62:63], v[62:63], v[68:69] op_sel_hi:[1,0]
	v_pk_mul_f32 v[60:61], v[60:61], v[68:69] op_sel_hi:[1,0]
	v_pk_mul_f32 v[58:59], v[58:59], v[68:69] op_sel_hi:[1,0]
	v_pk_mul_f32 v[56:57], v[56:57], v[68:69] op_sel_hi:[1,0]
	v_pk_mul_f32 v[54:55], v[54:55], v[68:69] op_sel_hi:[1,0]
	v_pk_mul_f32 v[52:53], v[52:53], v[68:69] op_sel_hi:[1,0]
	v_pk_mul_f32 v[70:71], v[50:51], v[68:69] op_sel_hi:[1,0]
	v_pk_mul_f32 v[68:69], v[48:49], v[68:69] op_sel_hi:[1,0]
	v_cvt_pk_bf16_f32 v48, v60, v61
	v_cvt_pk_bf16_f32 v49, v62, v63
	v_cvt_pk_bf16_f32 v50, v56, v57
	v_cvt_pk_bf16_f32 v51, v58, v59
	global_store_dwordx4 v[64:65], v[48:51], off sc1
	s_nop 1
	v_cvt_pk_bf16_f32 v48, v52, v53
	v_cvt_pk_bf16_f32 v49, v54, v55
	v_cvt_pk_bf16_f32 v50, v68, v69
	v_cvt_pk_bf16_f32 v51, v70, v71
	global_store_dwordx4 v[64:65], v[48:51], off offset:256 sc1
	s_nop 0
	v_add_u32_e32 v64, 0xa0, v150
	v_mad_i64_i32 v[66:67], s[6:7], v80, s62, v[146:147]
	v_ashrrev_i32_e32 v65, 31, v64
	v_add_u32_e32 v187, 0x2c00, v186
	global_load_dwordx4 v[204:207], v187, s[16:17]
	v_add_u32_e32 v187, 0x2c10, v186
	global_load_dwordx4 v[208:211], v187, s[16:17]
	v_add_u32_e32 v187, 0x2c20, v186
	global_load_dwordx4 v[212:215], v187, s[16:17]
	v_add_u32_e32 v187, 0x2c30, v186
	global_load_dwordx4 v[216:219], v187, s[16:17]
	s_waitcnt vmcnt(12)
	v_mov_b32_e32 v68, v221
	v_mov_b32_e32 v69, v222
	v_mov_b32_e32 v49, v223
	v_mov_b32_e32 v50, v233
	v_mov_b32_e32 v51, v234
	v_mov_b32_e32 v53, v235
	v_mov_b32_e32 v48, v220
	v_pk_add_f32 v[48:49], v[68:69], v[48:49]
	v_mov_b32_e32 v52, v232
	v_pk_add_f32 v[50:51], v[50:51], v[52:53]
	v_pk_add_f32 v[48:49], v[48:49], v[48:49] op_sel:[0,1] op_sel_hi:[1,0]
	v_pk_add_f32 v[50:51], v[50:51], v[50:51] op_sel:[0,1] op_sel_hi:[1,0]
	v_add_f32_e32 v54, v236, v237
	v_add_f32_e32 v56, v238, v239
	v_mov_b32_e32 v55, v242
	v_mov_b32_e32 v57, v243
	v_mov_b32_e32 v49, v240
	v_mov_b32_e32 v51, v241
	v_pk_add_f32 v[52:53], v[54:55], v[56:57]
	v_pk_add_f32 v[48:49], v[48:49], v[50:51]
	v_lshlrev_b64 v[50:51], 6, v[64:65]
	v_pk_add_f32 v[48:49], v[48:49], v[52:53]
	v_lshl_add_u64 v[50:51], s[16:17], 0, v[50:51]
	v_add_f32_e32 v48, v48, v49
	v_fmamk_f32 v48, v48, 0x3a800000, v158
	v_mul_f32_e32 v49, 0x4b800000, v48
	v_cmp_gt_f32_e32 vcc, s61, v48
	s_nop 1
	v_cndmask_b32_e32 v48, v48, v49, vcc
	v_rsq_f32_e32 v52, v48
	v_lshl_add_u64 v[48:49], v[66:67], 0, v[148:149]
	v_mul_f32_e32 v53, 0x45800000, v52
	v_cndmask_b32_e32 v52, v52, v53, vcc
	v_pk_mul_f32 v[46:47], v[46:47], v[52:53] op_sel_hi:[1,0]
	v_pk_mul_f32 v[44:45], v[44:45], v[52:53] op_sel_hi:[1,0]
	v_pk_mul_f32 v[42:43], v[42:43], v[52:53] op_sel_hi:[1,0]
	v_pk_mul_f32 v[40:41], v[40:41], v[52:53] op_sel_hi:[1,0]
	v_pk_mul_f32 v[38:39], v[38:39], v[52:53] op_sel_hi:[1,0]
	v_pk_mul_f32 v[36:37], v[36:37], v[52:53] op_sel_hi:[1,0]
	v_pk_mul_f32 v[54:55], v[34:35], v[52:53] op_sel_hi:[1,0]
	v_pk_mul_f32 v[52:53], v[32:33], v[52:53] op_sel_hi:[1,0]
	v_cvt_pk_bf16_f32 v32, v44, v45
	v_cvt_pk_bf16_f32 v33, v46, v47
	v_cvt_pk_bf16_f32 v34, v40, v41
	v_cvt_pk_bf16_f32 v35, v42, v43
	global_store_dwordx4 v[48:49], v[32:35], off sc1
	s_nop 1
	v_cvt_pk_bf16_f32 v32, v36, v37
	v_cvt_pk_bf16_f32 v33, v38, v39
	v_cvt_pk_bf16_f32 v34, v52, v53
	v_cvt_pk_bf16_f32 v35, v54, v55
	global_store_dwordx4 v[48:49], v[32:35], off offset:256 sc1
	s_nop 0
	v_add_u32_e32 v48, 0xb0, v150
	v_mad_i64_i32 v[50:51], s[6:7], v64, s62, v[146:147]
	v_ashrrev_i32_e32 v49, 31, v48
	s_mov_b32 s6, s20
	s_waitcnt vmcnt(8)
; __device__ __forceinline__ float bflo(unsigned w) { return __uint_as_float(w << 16); }
; __device__ __forceinline__ float bfhi(unsigned w) { return __uint_as_float(w & 0xffff0000u); }
; __device__ __forceinline__ unsigned pk2(float lo, float hi) { unsigned r; asm volatile("v_cvt_pk_bf16_f32 %0, %1, %2" : "=v"(r) : "v"(lo), "v"(hi)); return r; }
; __device__ __forceinline__ float row_rstd(const float* ssq, int row) {
;     const f32x4* p = (const f32x4*)(ssq + (size_t)row * 16);
;     const f32x4 a = p[0], b = p[1], c = p[2], d = p[3];
;     const float s = ((a[0] + a[1]) + (a[2] + a[3])) + ((b[0] + b[1]) + (b[2] + b[3])) + ((c[0] + c[1]) + (c[2] + c[3])) + ((d[0] + d[1]) + (d[2] + d[3]));
;     return rsqrtf(s * (1.0f / 1024.0f) + 1e-6f);
; }
; __device__ __forceinline__ u32x4 pack8(const f32x4 v0, const f32x4 v1) { u32x4 w; w.x = pk2(v0[0], v0[1]); w.y = pk2(v0[2], v0[3]); w.z = pk2(v1[0], v1[1]); w.w = pk2(v1[2], v1[3]); return w; }
; __device__ __forceinline__ void unpack8(const u32x4 w, f32x4& v0, f32x4& v1) { v0 = (f32x4){bflo(w.x), bfhi(w.x), bflo(w.y), bfhi(w.y)}; v1 = (f32x4){bflo(w.z), bfhi(w.z), bflo(w.w), bfhi(w.w)}; }
;     __device__ __forceinline__ void operator()(const f32x4 (&acc)[2][2][4][2], const Unit& u, int wr, int wc, int fr, int fq) const {
;         const int row0 = u.pm * 256 + wr * 64 + fr, col0 = u.pn * 256 + wc * 32 + 8 * fq;
; #pragma unroll
;         for (int ai = 0; ai < 2; ++ai)
; #pragma unroll
;             for (int m = 0; m < 4; ++m) {
;                 const int row = row0 + ai * 128 + m * 16; const float rs = row_rstd(ssq, row);
;                 bf16_t* rowp = O + (size_t)row * ldc + col0;
; #pragma unroll
;                 for (int bj = 0; bj < 2; ++bj) { f32x4 v0 = acc[ai][bj][m][0] * rs, v1 = acc[ai][bj][m][1] * rs;
;                     if (ACT == 1) {
; #pragma unroll
;                         for (int j = 0; j < 4; ++j) { const float a = fmaxf(v0[j], 0.f), b = fmaxf(v1[j], 0.f); v0[j] = a * a; v1[j] = b * b; } }
;                     *(u32x4*)(rowp + bj * 128) = pack8(v0, v1); }
	v_mov_b32_e32 v52, v189
	v_mov_b32_e32 v53, v190
	v_mov_b32_e32 v33, v191
	v_mov_b32_e32 v34, v193
	v_mov_b32_e32 v35, v194
	v_mov_b32_e32 v37, v195
	v_mov_b32_e32 v32, v188
	v_pk_add_f32 v[32:33], v[52:53], v[32:33]
	v_mov_b32_e32 v36, v192
	v_pk_add_f32 v[34:35], v[34:35], v[36:37]
	v_pk_add_f32 v[32:33], v[32:33], v[32:33] op_sel:[0,1] op_sel_hi:[1,0]
	v_pk_add_f32 v[34:35], v[34:35], v[34:35] op_sel:[0,1] op_sel_hi:[1,0]
	v_add_f32_e32 v38, v196, v197
	v_add_f32_e32 v40, v198, v199
	v_mov_b32_e32 v39, v202
	v_mov_b32_e32 v41, v203
	v_mov_b32_e32 v33, v200
	v_mov_b32_e32 v35, v201
	v_pk_add_f32 v[36:37], v[38:39], v[40:41]
	v_pk_add_f32 v[32:33], v[32:33], v[34:35]
	v_lshlrev_b64 v[34:35], 6, v[48:49]
	v_pk_add_f32 v[32:33], v[32:33], v[36:37]
	v_lshl_add_u64 v[34:35], s[16:17], 0, v[34:35]
	v_add_f32_e32 v32, v32, v33
	v_fmamk_f32 v32, v32, 0x3a800000, v158
	v_mul_f32_e32 v33, 0x4b800000, v32
	v_cmp_gt_f32_e32 vcc, s61, v32
	s_nop 1
	v_cndmask_b32_e32 v32, v32, v33, vcc
	v_rsq_f32_e32 v36, v32
	v_lshl_add_u64 v[32:33], v[50:51], 0, v[148:149]
	v_mul_f32_e32 v37, 0x45800000, v36
	v_cndmask_b32_e32 v36, v36, v37, vcc
	v_pk_mul_f32 v[30:31], v[30:31], v[36:37] op_sel_hi:[1,0]
	v_pk_mul_f32 v[28:29], v[28:29], v[36:37] op_sel_hi:[1,0]
	v_pk_mul_f32 v[26:27], v[26:27], v[36:37] op_sel_hi:[1,0]
	v_pk_mul_f32 v[24:25], v[24:25], v[36:37] op_sel_hi:[1,0]
	v_pk_mul_f32 v[22:23], v[22:23], v[36:37] op_sel_hi:[1,0]
	v_pk_mul_f32 v[20:21], v[20:21], v[36:37] op_sel_hi:[1,0]
	v_pk_mul_f32 v[38:39], v[18:19], v[36:37] op_sel_hi:[1,0]
	v_pk_mul_f32 v[36:37], v[16:17], v[36:37] op_sel_hi:[1,0]
	v_cvt_pk_bf16_f32 v16, v28, v29
	v_cvt_pk_bf16_f32 v17, v30, v31
	v_cvt_pk_bf16_f32 v18, v24, v25
	v_cvt_pk_bf16_f32 v19, v26, v27
	global_store_dwordx4 v[32:33], v[16:19], off sc1
	s_and_b64 vcc, exec, s[8:9]
	s_nop 0
	v_cvt_pk_bf16_f32 v16, v20, v21
	v_cvt_pk_bf16_f32 v17, v22, v23
	v_cvt_pk_bf16_f32 v18, v36, v37
	v_cvt_pk_bf16_f32 v19, v38, v39
	global_store_dwordx4 v[32:33], v[16:19], off offset:256 sc1
	s_nop 0
	s_waitcnt vmcnt(4)
	v_mov_b32_e32 v32, v205
	v_mov_b32_e32 v33, v206
	v_mov_b32_e32 v17, v207
	v_mov_b32_e32 v18, v209
	v_mov_b32_e32 v19, v210
	v_mov_b32_e32 v21, v211
	v_mov_b32_e32 v16, v204
	v_pk_add_f32 v[16:17], v[32:33], v[16:17]
	v_mov_b32_e32 v20, v208
	v_pk_add_f32 v[18:19], v[18:19], v[20:21]
	v_pk_add_f32 v[16:17], v[16:17], v[16:17] op_sel:[0,1] op_sel_hi:[1,0]
	v_pk_add_f32 v[18:19], v[18:19], v[18:19] op_sel:[0,1] op_sel_hi:[1,0]
	v_add_f32_e32 v22, v212, v213
	v_add_f32_e32 v24, v214, v215
	v_mov_b32_e32 v23, v218
	v_mov_b32_e32 v25, v219
	v_mov_b32_e32 v17, v216
	v_mov_b32_e32 v19, v217
	v_pk_add_f32 v[20:21], v[22:23], v[24:25]
	v_pk_add_f32 v[16:17], v[16:17], v[18:19]
	s_nop 0
	v_pk_add_f32 v[16:17], v[16:17], v[20:21]
	s_nop 0
	v_add_f32_e32 v16, v16, v17
	v_fmamk_f32 v16, v16, 0x3a800000, v158
	v_mul_f32_e32 v17, 0x4b800000, v16
	v_cmp_gt_f32_e64 s[8:9], s61, v16
	s_nop 1
	v_cndmask_b32_e64 v16, v16, v17, s[8:9]
	v_rsq_f32_e32 v18, v16
	v_mad_i64_i32 v[16:17], s[24:25], v48, s62, v[146:147]
	v_lshl_add_u64 v[16:17], v[16:17], 0, v[148:149]
	v_mul_f32_e32 v19, 0x45800000, v18
	v_cndmask_b32_e64 v18, v18, v19, s[8:9]
	v_pk_mul_f32 v[14:15], v[14:15], v[18:19] op_sel_hi:[1,0]
	v_pk_mul_f32 v[12:13], v[12:13], v[18:19] op_sel_hi:[1,0]
	v_pk_mul_f32 v[10:11], v[10:11], v[18:19] op_sel_hi:[1,0]
	v_pk_mul_f32 v[8:9], v[8:9], v[18:19] op_sel_hi:[1,0]
	v_pk_mul_f32 v[6:7], v[6:7], v[18:19] op_sel_hi:[1,0]
	v_pk_mul_f32 v[4:5], v[4:5], v[18:19] op_sel_hi:[1,0]
	v_pk_mul_f32 v[20:21], v[2:3], v[18:19] op_sel_hi:[1,0]
	v_pk_mul_f32 v[18:19], v[0:1], v[18:19] op_sel_hi:[1,0]
	v_cvt_pk_bf16_f32 v0, v12, v13
	v_cvt_pk_bf16_f32 v1, v14, v15
	v_cvt_pk_bf16_f32 v2, v8, v9
	v_cvt_pk_bf16_f32 v3, v10, v11
	global_store_dwordx4 v[16:17], v[0:3], off sc1
	s_nop 1
	v_cvt_pk_bf16_f32 v0, v4, v5
	v_cvt_pk_bf16_f32 v1, v6, v7
	v_cvt_pk_bf16_f32 v2, v18, v19
	v_cvt_pk_bf16_f32 v3, v20, v21
	global_store_dwordx4 v[16:17], v[0:3], off offset:256 sc1
	s_cbranch_vccz .LBB0_118
	s_waitcnt vmcnt(0)
	s_cmpk_gt_u32 s40, 0xff
	s_cbranch_scc1 .LBB0_129
	s_barrier

; #define PG8_STAGE(bufoff, gbase, voff) do { _Pragma("unroll") for (int _i = 0; _i < 2; ++_i) \
;         __builtin_amdgcn_global_load_lds((const unsigned*)((const char*)(gbase) + (voff)[_i]), (LAS unsigned*)(lds + (bufoff) + ldsw + _i * 8192), 16, 0, 0); } while (0)
; #define PG8_LDA(dst, b, h) do { _Pragma("unroll") for (int m = 0; m < 4; ++m) _Pragma("unroll") for (int k = 0; k < 2; ++k) dst[m][k] = *(const LAS bf16x8*)(lds + PG8_SA(b, h) + aoff + m * 2048 + k * 1024); } while (0)
; #define PG8_LDB(dst, b, h) do { _Pragma("unroll") for (int n = 0; n < 2; ++n) _Pragma("unroll") for (int k = 0; k < 2; ++k) dst[n][k] = *(const LAS bf16x8*)(lds + PG8_SB(b, h) + boff + n * 2048 + k * 1024); } while (0)
; #define PG8_MMA(ai, bj, At, Bt) do { __builtin_amdgcn_s_setprio(1); _Pragma("unroll") for (int m = 0; m < 4; ++m) _Pragma("unroll") for (int n = 0; n < 2; ++n) _Pragma("unroll") for (int k = 0; k < 2; ++k) \
;         acc[ai][bj][m][n] = __builtin_amdgcn_mfma_f32_16x16x32_bf16(Bt[n][k], At[m][k], acc[ai][bj][m][n], 0, 0, 0); __builtin_amdgcn_s_setprio(0); } while (0)
; #define PG8_WAIT_L(n) asm volatile("s_waitcnt lgkmcnt(" #n ")" ::: "memory")
; #define PG8_BAR __builtin_amdgcn_s_barrier()
; #define PG8_SCHED __builtin_amdgcn_sched_barrier(0)
;     ...
;             PG8_LDB(B0, 0, 0); PG8_SCHED; PG8_LDA(At, 0, 0); PG8_STAGE(PG8_SA(1, 1), a1 + hA, voffA);
;             PG8_WAIT_L(8); PG8_BAR; PG8_WAIT_L(0); PG8_MMA(0, 0, At, B0); PG8_BAR; PG8_SCHED;
;             PG8_LDB(B1, 0, 1); PG8_STAGE(PG8_SB(0, 0), b2, voffB);
;             PG8_BAR; PG8_WAIT_L(0); PG8_MMA(0, 1, At, B1); PG8_BAR;
;             PG8_LDA(At, 0, 1); PG8_STAGE(PG8_SA(0, 0), a2, voffA);
;             PG8_BAR; PG8_WAIT_L(0); PG8_MMA(1, 0, At, B0); PG8_BAR; PG8_SCHED;
.LBB0_958:
	ds_read_b128 v[156:159], v151
	ds_read_b128 v[160:163], v151 offset:1024
	ds_read_b128 v[170:173], v151 offset:2048
	ds_read_b128 v[174:177], v151 offset:3072
	s_add_u32 s43, s40, 0xfffc0080
	s_addc_u32 s44, s41, -1
	s_cmp_eq_u32 s42, 12
	s_cselect_b32 s57, s7, s44
	s_cselect_b32 s56, s8, s43
	s_cselect_b32 s55, s9, s39
	s_cselect_b32 s54, s29, s33
	v_lshl_add_u64 v[146:147], s[40:41], 0, v[138:139]
	s_add_i32 m0, s61, 0xc000
	ds_read_b128 v[178:181], v152
	ds_read_b128 v[182:185], v152 offset:1024
	ds_read_b128 v[186:189], v152 offset:2048
	ds_read_b128 v[190:193], v152 offset:3072
	ds_read_b128 v[194:197], v152 offset:4096
	ds_read_b128 v[198:201], v152 offset:5120
	ds_read_b128 v[202:205], v152 offset:6144
	ds_read_b128 v[206:209], v152 offset:7168
	global_load_lds_dwordx4 v[146:147], off
	v_lshl_add_u64 v[146:147], s[40:41], 0, v[136:137]
	s_add_i32 m0, s61, 0xe000
	s_nop 0
	global_load_lds_dwordx4 v[146:147], off
	s_waitcnt lgkmcnt(8)
	s_barrier
	s_waitcnt lgkmcnt(0)
	s_setprio 1
	s_waitcnt lgkmcnt(0)
	v_mfma_f32_16x16x32_bf16 v[124:127], v[156:159], v[178:181], v[124:127]
	v_mfma_f32_16x16x32_bf16 v[120:123], v[170:173], v[178:181], v[120:123]
	v_mfma_f32_16x16x32_bf16 v[108:111], v[156:159], v[186:189], v[108:111]
	v_mfma_f32_16x16x32_bf16 v[104:107], v[170:173], v[186:189], v[104:107]
	v_mfma_f32_16x16x32_bf16 v[92:95], v[156:159], v[194:197], v[92:95]
	v_mfma_f32_16x16x32_bf16 v[88:91], v[170:173], v[194:197], v[88:91]
	v_mfma_f32_16x16x32_bf16 v[76:79], v[156:159], v[202:205], v[76:79]
	v_mfma_f32_16x16x32_bf16 v[72:75], v[170:173], v[202:205], v[72:75]
	v_mfma_f32_16x16x32_bf16 v[124:127], v[160:163], v[182:185], v[124:127]
	v_mfma_f32_16x16x32_bf16 v[120:123], v[174:177], v[182:185], v[120:123]
	v_mfma_f32_16x16x32_bf16 v[108:111], v[160:163], v[190:193], v[108:111]
	v_mfma_f32_16x16x32_bf16 v[104:107], v[174:177], v[190:193], v[104:107]
	v_mfma_f32_16x16x32_bf16 v[92:95], v[160:163], v[198:201], v[92:95]
	v_mfma_f32_16x16x32_bf16 v[88:91], v[174:177], v[198:201], v[88:91]
	v_mfma_f32_16x16x32_bf16 v[76:79], v[160:163], v[206:209], v[76:79]
	v_mfma_f32_16x16x32_bf16 v[72:75], v[174:177], v[206:209], v[72:75]
	s_setprio 0
	s_barrier
	s_add_i32 s43, s69, s60
	v_lshl_add_u64 v[146:147], s[54:55], 0, v[130:131]
	s_mov_b32 m0, s43
	ds_read_b128 v[210:213], v153
	ds_read_b128 v[214:217], v153 offset:1024
	ds_read_b128 v[218:221], v153 offset:2048
	ds_read_b128 v[222:225], v153 offset:3072
	global_load_lds_dwordx4 v[146:147], off
	v_lshl_add_u64 v[164:165], s[54:55], 0, v[134:135]
	s_add_i32 m0, s43, 0x2000
	s_nop 0
	global_load_lds_dwordx4 v[164:165], off
	s_barrier
	s_waitcnt lgkmcnt(0)
	s_setprio 1
	s_waitcnt lgkmcnt(0)
	v_mfma_f32_16x16x32_bf16 v[116:119], v[210:213], v[178:181], v[116:119]
	v_mfma_f32_16x16x32_bf16 v[112:115], v[218:221], v[178:181], v[112:115]
	v_mfma_f32_16x16x32_bf16 v[100:103], v[210:213], v[186:189], v[100:103]
	v_mfma_f32_16x16x32_bf16 v[96:99], v[218:221], v[186:189], v[96:99]
	v_mfma_f32_16x16x32_bf16 v[84:87], v[210:213], v[194:197], v[84:87]
	v_mfma_f32_16x16x32_bf16 v[80:83], v[218:221], v[194:197], v[80:83]
	v_mfma_f32_16x16x32_bf16 v[68:71], v[210:213], v[202:205], v[68:71]
	v_mfma_f32_16x16x32_bf16 v[64:67], v[218:221], v[202:205], v[64:67]
	v_mfma_f32_16x16x32_bf16 v[116:119], v[214:217], v[182:185], v[116:119]
	v_mfma_f32_16x16x32_bf16 v[112:115], v[222:225], v[182:185], v[112:115]
	v_mfma_f32_16x16x32_bf16 v[100:103], v[214:217], v[190:193], v[100:103]
	v_mfma_f32_16x16x32_bf16 v[96:99], v[222:225], v[190:193], v[96:99]
	v_mfma_f32_16x16x32_bf16 v[84:87], v[214:217], v[198:201], v[84:87]
	v_mfma_f32_16x16x32_bf16 v[80:83], v[222:225], v[198:201], v[80:83]
	v_mfma_f32_16x16x32_bf16 v[68:71], v[214:217], v[206:209], v[68:71]
	v_mfma_f32_16x16x32_bf16 v[64:67], v[222:225], v[206:209], v[64:67]
	s_setprio 0
	s_mov_b32 m0, s61
	v_lshl_add_u64 v[226:227], s[56:57], 0, v[128:129]
	s_barrier
	ds_read_b128 v[178:181], v152 offset:16384
	ds_read_b128 v[182:185], v152 offset:17408
	ds_read_b128 v[186:189], v152 offset:18432
	ds_read_b128 v[190:193], v152 offset:19456
	ds_read_b128 v[194:197], v152 offset:20480
	ds_read_b128 v[198:201], v152 offset:21504
	ds_read_b128 v[202:205], v152 offset:22528
	ds_read_b128 v[206:209], v152 offset:23552
	global_load_lds_dwordx4 v[226:227], off
	v_lshl_add_u64 v[228:229], s[56:57], 0, v[132:133]
	s_mov_b32 m0, s62
	s_nop 0
	global_load_lds_dwordx4 v[228:229], off
	s_barrier
	s_waitcnt lgkmcnt(0)
	s_setprio 1
	s_waitcnt lgkmcnt(0)
	v_mfma_f32_16x16x32_bf16 v[60:63], v[156:159], v[178:181], v[60:63]
	v_mfma_f32_16x16x32_bf16 v[56:59], v[170:173], v[178:181], v[56:59]
	v_mfma_f32_16x16x32_bf16 v[44:47], v[156:159], v[186:189], v[44:47]
	v_mfma_f32_16x16x32_bf16 v[40:43], v[170:173], v[186:189], v[40:43]
	v_mfma_f32_16x16x32_bf16 v[28:31], v[156:159], v[194:197], v[28:31]
	v_mfma_f32_16x16x32_bf16 v[24:27], v[170:173], v[194:197], v[24:27]
	v_mfma_f32_16x16x32_bf16 v[12:15], v[156:159], v[202:205], v[12:15]
	v_mfma_f32_16x16x32_bf16 v[8:11], v[170:173], v[202:205], v[8:11]
	v_mfma_f32_16x16x32_bf16 v[60:63], v[160:163], v[182:185], v[60:63]
	v_mfma_f32_16x16x32_bf16 v[56:59], v[174:177], v[182:185], v[56:59]
	v_mfma_f32_16x16x32_bf16 v[44:47], v[160:163], v[190:193], v[44:47]
	v_mfma_f32_16x16x32_bf16 v[40:43], v[174:177], v[190:193], v[40:43]
	v_mfma_f32_16x16x32_bf16 v[28:31], v[160:163], v[198:201], v[28:31]
	v_mfma_f32_16x16x32_bf16 v[24:27], v[174:177], v[198:201], v[24:27]
	v_mfma_f32_16x16x32_bf16 v[12:15], v[160:163], v[206:209], v[12:15]
	v_mfma_f32_16x16x32_bf16 v[8:11], v[174:177], v[206:209], v[8:11]
	s_setprio 0
	s_barrier
; #define PG8_STAGE(bufoff, gbase, voff) do { _Pragma("unroll") for (int _i = 0; _i < 2; ++_i) \
;         __builtin_amdgcn_global_load_lds((const unsigned*)((const char*)(gbase) + (voff)[_i]), (LAS unsigned*)(lds + (bufoff) + ldsw + _i * 8192), 16, 0, 0); } while (0)
; #define PG8_LDA(dst, b, h) do { _Pragma("unroll") for (int m = 0; m < 4; ++m) _Pragma("unroll") for (int k = 0; k < 2; ++k) dst[m][k] = *(const LAS bf16x8*)(lds + PG8_SA(b, h) + aoff + m * 2048 + k * 1024); } while (0)
; #define PG8_LDB(dst, b, h) do { _Pragma("unroll") for (int n = 0; n < 2; ++n) _Pragma("unroll") for (int k = 0; k < 2; ++k) dst[n][k] = *(const LAS bf16x8*)(lds + PG8_SB(b, h) + boff + n * 2048 + k * 1024); } while (0)
; #define PG8_MMA(ai, bj, At, Bt) do { __builtin_amdgcn_s_setprio(1); _Pragma("unroll") for (int m = 0; m < 4; ++m) _Pragma("unroll") for (int n = 0; n < 2; ++n) _Pragma("unroll") for (int k = 0; k < 2; ++k) \
;         acc[ai][bj][m][n] = __builtin_amdgcn_mfma_f32_16x16x32_bf16(Bt[n][k], At[m][k], acc[ai][bj][m][n], 0, 0, 0); __builtin_amdgcn_s_setprio(0); } while (0)
; #define PG8_WAIT_V(n) asm volatile("s_waitcnt vmcnt(" #n ")" ::: "memory")
; #define PG8_WAIT_L(n) asm volatile("s_waitcnt lgkmcnt(" #n ")" ::: "memory")
; #define PG8_BAR __builtin_amdgcn_s_barrier()
; #define PG8_SCHED __builtin_amdgcn_sched_barrier(0)
;     ...
;             PG8_STAGE(PG8_SB(0, 1), b2 + hB, voffB);
;             PG8_WAIT_V(6); PG8_BAR; PG8_MMA(1, 1, At, B1); PG8_BAR;
;             PG8_LDB(B0, 1, 0); PG8_SCHED; PG8_LDA(At, 1, 0); PG8_STAGE(PG8_SA(0, 1), a2 + hA, voffA);
;             PG8_WAIT_L(8); PG8_BAR; PG8_WAIT_L(0); PG8_MMA(0, 0, At, B0); PG8_BAR; PG8_SCHED;
;             PG8_LDB(B1, 1, 1); PG8_STAGE(PG8_SB(1, 0), b3, voffB);
;             PG8_BAR; PG8_WAIT_L(0); PG8_MMA(0, 1, At, B1); PG8_BAR;
;             PG8_LDA(At, 1, 1); PG8_STAGE(PG8_SA(1, 0), a3, voffA);
	s_add_u32 s44, s54, 0x40000
	s_addc_u32 s45, s55, 0
	s_add_i32 s43, s70, s60
	v_lshl_add_u64 v[156:157], s[44:45], 0, v[130:131]
	s_mov_b32 m0, s43
	s_nop 0
	global_load_lds_dwordx4 v[156:157], off
	v_lshl_add_u64 v[156:157], s[44:45], 0, v[134:135]
	s_add_i32 m0, s43, 0x2000
	s_nop 0
	global_load_lds_dwordx4 v[156:157], off
	s_waitcnt vmcnt(6)
	s_barrier
	s_setprio 1
	v_mfma_f32_16x16x32_bf16 v[52:55], v[210:213], v[178:181], v[52:55]
	v_mfma_f32_16x16x32_bf16 v[48:51], v[218:221], v[178:181], v[48:51]
	v_mfma_f32_16x16x32_bf16 v[36:39], v[210:213], v[186:189], v[36:39]
	v_mfma_f32_16x16x32_bf16 v[32:35], v[218:221], v[186:189], v[32:35]
	v_mfma_f32_16x16x32_bf16 v[20:23], v[210:213], v[194:197], v[20:23]
	v_mfma_f32_16x16x32_bf16 v[16:19], v[218:221], v[194:197], v[16:19]
	v_mfma_f32_16x16x32_bf16 v[4:7], v[210:213], v[202:205], v[4:7]
	v_mfma_f32_16x16x32_bf16 v[0:3], v[218:221], v[202:205], v[0:3]
	v_mfma_f32_16x16x32_bf16 v[52:55], v[214:217], v[182:185], v[52:55]
	v_mfma_f32_16x16x32_bf16 v[48:51], v[222:225], v[182:185], v[48:51]
	v_mfma_f32_16x16x32_bf16 v[36:39], v[214:217], v[190:193], v[36:39]
	v_mfma_f32_16x16x32_bf16 v[32:35], v[222:225], v[190:193], v[32:35]
	v_mfma_f32_16x16x32_bf16 v[20:23], v[214:217], v[198:201], v[20:23]
	v_mfma_f32_16x16x32_bf16 v[16:19], v[222:225], v[198:201], v[16:19]
	v_mfma_f32_16x16x32_bf16 v[4:7], v[214:217], v[206:209], v[4:7]
	v_mfma_f32_16x16x32_bf16 v[0:3], v[222:225], v[206:209], v[0:3]
	s_setprio 0
	s_add_i32 s43, 0, 0x18000
	v_add_u32_e32 v155, s43, v149
	s_barrier
	ds_read_b128 v[156:159], v155
	ds_read_b128 v[160:163], v155 offset:1024
	ds_read_b128 v[170:173], v155 offset:2048
	ds_read_b128 v[174:177], v155 offset:3072
	s_add_u32 s44, s56, 0x40000
	s_addc_u32 s45, s57, 0
	s_mov_b32 m0, s63
	v_lshl_add_u64 v[210:211], s[44:45], 0, v[128:129]
	ds_read_b128 v[178:181], v152 offset:32768
	ds_read_b128 v[182:185], v152 offset:33792
	ds_read_b128 v[186:189], v152 offset:34816
	ds_read_b128 v[190:193], v152 offset:35840
	ds_read_b128 v[194:197], v152 offset:36864
	ds_read_b128 v[198:201], v152 offset:37888
	ds_read_b128 v[202:205], v152 offset:38912
	ds_read_b128 v[206:209], v152 offset:39936
	global_load_lds_dwordx4 v[210:211], off
	v_lshl_add_u64 v[210:211], s[44:45], 0, v[132:133]
	s_mov_b32 m0, s64
	s_nop 0
	global_load_lds_dwordx4 v[210:211], off
	s_waitcnt lgkmcnt(8)
	s_barrier
	s_waitcnt lgkmcnt(0)
	s_setprio 1
	s_waitcnt lgkmcnt(0)
	v_mfma_f32_16x16x32_bf16 v[124:127], v[156:159], v[178:181], v[124:127]
	v_mfma_f32_16x16x32_bf16 v[120:123], v[170:173], v[178:181], v[120:123]
	v_mfma_f32_16x16x32_bf16 v[108:111], v[156:159], v[186:189], v[108:111]
	v_mfma_f32_16x16x32_bf16 v[104:107], v[170:173], v[186:189], v[104:107]
	v_mfma_f32_16x16x32_bf16 v[92:95], v[156:159], v[194:197], v[92:95]
	v_mfma_f32_16x16x32_bf16 v[88:91], v[170:173], v[194:197], v[88:91]
	v_mfma_f32_16x16x32_bf16 v[76:79], v[156:159], v[202:205], v[76:79]
	v_mfma_f32_16x16x32_bf16 v[72:75], v[170:173], v[202:205], v[72:75]
	v_mfma_f32_16x16x32_bf16 v[124:127], v[160:163], v[182:185], v[124:127]
	v_mfma_f32_16x16x32_bf16 v[120:123], v[174:177], v[182:185], v[120:123]
	v_mfma_f32_16x16x32_bf16 v[108:111], v[160:163], v[190:193], v[108:111]
	v_mfma_f32_16x16x32_bf16 v[104:107], v[174:177], v[190:193], v[104:107]
	v_mfma_f32_16x16x32_bf16 v[92:95], v[160:163], v[198:201], v[92:95]
	v_mfma_f32_16x16x32_bf16 v[88:91], v[174:177], v[198:201], v[88:91]
	v_mfma_f32_16x16x32_bf16 v[76:79], v[160:163], v[206:209], v[76:79]
	v_mfma_f32_16x16x32_bf16 v[72:75], v[174:177], v[206:209], v[72:75]
	s_setprio 0
	s_barrier
	s_add_i32 s56, 0, 0x1c000
	s_add_i32 s43, s43, s60
	v_add_u32_e32 v155, s56, v149
	v_lshl_add_u64 v[146:147], v[146:147], 0, s[30:31]
	s_mov_b32 m0, s43
	ds_read_b128 v[210:213], v155
	ds_read_b128 v[214:217], v155 offset:1024
	ds_read_b128 v[218:221], v155 offset:2048
	ds_read_b128 v[222:225], v155 offset:3072
	global_load_lds_dwordx4 v[146:147], off
	v_lshl_add_u64 v[146:147], v[164:165], 0, s[30:31]
	s_add_i32 m0, s43, 0x2000
	s_nop 0
	global_load_lds_dwordx4 v[146:147], off
	s_barrier
	s_waitcnt lgkmcnt(0)
	s_setprio 1
	s_waitcnt lgkmcnt(0)
	v_mfma_f32_16x16x32_bf16 v[116:119], v[210:213], v[178:181], v[116:119]
	v_mfma_f32_16x16x32_bf16 v[112:115], v[218:221], v[178:181], v[112:115]
	v_mfma_f32_16x16x32_bf16 v[100:103], v[210:213], v[186:189], v[100:103]
	v_mfma_f32_16x16x32_bf16 v[96:99], v[218:221], v[186:189], v[96:99]
	v_mfma_f32_16x16x32_bf16 v[84:87], v[210:213], v[194:197], v[84:87]
	v_mfma_f32_16x16x32_bf16 v[80:83], v[218:221], v[194:197], v[80:83]
	v_mfma_f32_16x16x32_bf16 v[68:71], v[210:213], v[202:205], v[68:71]
	v_mfma_f32_16x16x32_bf16 v[64:67], v[218:221], v[202:205], v[64:67]
	v_mfma_f32_16x16x32_bf16 v[116:119], v[214:217], v[182:185], v[116:119]
	v_mfma_f32_16x16x32_bf16 v[112:115], v[222:225], v[182:185], v[112:115]
	v_mfma_f32_16x16x32_bf16 v[100:103], v[214:217], v[190:193], v[100:103]
	v_mfma_f32_16x16x32_bf16 v[96:99], v[222:225], v[190:193], v[96:99]
	v_mfma_f32_16x16x32_bf16 v[84:87], v[214:217], v[198:201], v[84:87]
	v_mfma_f32_16x16x32_bf16 v[80:83], v[222:225], v[198:201], v[80:83]
	v_mfma_f32_16x16x32_bf16 v[68:71], v[214:217], v[206:209], v[68:71]
	v_mfma_f32_16x16x32_bf16 v[64:67], v[222:225], v[206:209], v[64:67]
	s_setprio 0
	s_mov_b32 m0, s66
	v_lshl_add_u64 v[146:147], v[226:227], 0, s[30:31]
	s_barrier
	ds_read_b128 v[178:181], v152 offset:49152
	ds_read_b128 v[182:185], v152 offset:50176
	ds_read_b128 v[186:189], v152 offset:51200
	ds_read_b128 v[190:193], v152 offset:52224
	ds_read_b128 v[194:197], v152 offset:53248
	ds_read_b128 v[198:201], v152 offset:54272
	ds_read_b128 v[202:205], v152 offset:55296
	ds_read_b128 v[206:209], v152 offset:56320
	global_load_lds_dwordx4 v[146:147], off
	v_lshl_add_u64 v[146:147], v[228:229], 0, s[30:31]
	s_mov_b32 m0, s67
	s_nop 0
	global_load_lds_dwordx4 v[146:147], off
	s_barrier
; #define PG8_STAGE(bufoff, gbase, voff) do { _Pragma("unroll") for (int _i = 0; _i < 2; ++_i) \
;         __builtin_amdgcn_global_load_lds((const unsigned*)((const char*)(gbase) + (voff)[_i]), (LAS unsigned*)(lds + (bufoff) + ldsw + _i * 8192), 16, 0, 0); } while (0)
; #define PG8_MMA(ai, bj, At, Bt) do { __builtin_amdgcn_s_setprio(1); _Pragma("unroll") for (int m = 0; m < 4; ++m) _Pragma("unroll") for (int n = 0; n < 2; ++n) _Pragma("unroll") for (int k = 0; k < 2; ++k) \
;         acc[ai][bj][m][n] = __builtin_amdgcn_mfma_f32_16x16x32_bf16(Bt[n][k], At[m][k], acc[ai][bj][m][n], 0, 0, 0); __builtin_amdgcn_s_setprio(0); } while (0)
; #define PG8_WAIT_V(n) asm volatile("s_waitcnt vmcnt(" #n ")" ::: "memory")
; #define PG8_WAIT_L(n) asm volatile("s_waitcnt lgkmcnt(" #n ")" ::: "memory")
; #define PG8_BAR __builtin_amdgcn_s_barrier()
; #define PG8_SCHED __builtin_amdgcn_sched_barrier(0)
;     ...
;             PG8_BAR; PG8_WAIT_L(0); PG8_MMA(1, 0, At, B0); PG8_BAR; PG8_SCHED;
;             PG8_STAGE(PG8_SB(1, 1), b3 + hB, voffB);
;             PG8_WAIT_V(6); PG8_BAR; PG8_MMA(1, 1, At, B1); PG8_BAR;
;         }
;     __device__ __forceinline__ void operator()(const f32x4 (&acc)[2][2][4][2], const Unit& u, int wr, int wc, int fr, int fq) const {
;         const int row0 = u.pm * 256 + wr * 64 + fr, col0 = u.pn * 256 + wc * 32 + 8 * fq;
; #pragma unroll
;         for (int ai = 0; ai < 2; ++ai)
; #pragma unroll
;             for (int m = 0; m < 4; ++m) {
;                 const int row = row0 + ai * 128 + m * 16; const float rs = row_rstd(ssq, row);
	s_waitcnt lgkmcnt(0)
	s_setprio 1
	s_waitcnt lgkmcnt(0)
	v_mfma_f32_16x16x32_bf16 v[60:63], v[156:159], v[178:181], v[60:63]
	v_mfma_f32_16x16x32_bf16 v[56:59], v[170:173], v[178:181], v[56:59]
	v_mfma_f32_16x16x32_bf16 v[44:47], v[156:159], v[186:189], v[44:47]
	v_mfma_f32_16x16x32_bf16 v[40:43], v[170:173], v[186:189], v[40:43]
	v_mfma_f32_16x16x32_bf16 v[28:31], v[156:159], v[194:197], v[28:31]
	v_mfma_f32_16x16x32_bf16 v[24:27], v[170:173], v[194:197], v[24:27]
	v_mfma_f32_16x16x32_bf16 v[12:15], v[156:159], v[202:205], v[12:15]
	v_mfma_f32_16x16x32_bf16 v[8:11], v[170:173], v[202:205], v[8:11]
	v_mfma_f32_16x16x32_bf16 v[60:63], v[160:163], v[182:185], v[60:63]
	v_mfma_f32_16x16x32_bf16 v[56:59], v[174:177], v[182:185], v[56:59]
	v_mfma_f32_16x16x32_bf16 v[44:47], v[160:163], v[190:193], v[44:47]
	v_mfma_f32_16x16x32_bf16 v[40:43], v[174:177], v[190:193], v[40:43]
	v_mfma_f32_16x16x32_bf16 v[28:31], v[160:163], v[198:201], v[28:31]
	v_mfma_f32_16x16x32_bf16 v[24:27], v[174:177], v[198:201], v[24:27]
	v_mfma_f32_16x16x32_bf16 v[12:15], v[160:163], v[206:209], v[12:15]
	v_mfma_f32_16x16x32_bf16 v[8:11], v[174:177], v[206:209], v[8:11]
	s_setprio 0
	s_barrier
	s_add_u32 s44, s54, 0x40080
	s_addc_u32 s45, s55, 0
	s_add_i32 s43, s56, s60
	v_lshl_add_u64 v[146:147], s[44:45], 0, v[130:131]
	s_mov_b32 m0, s43
	s_nop 0
	global_load_lds_dwordx4 v[146:147], off
	v_lshl_add_u64 v[146:147], s[44:45], 0, v[134:135]
	s_add_i32 m0, s43, 0x2000
	s_nop 0
	global_load_lds_dwordx4 v[146:147], off
	s_waitcnt vmcnt(6)
	s_barrier
	s_setprio 1
	v_mfma_f32_16x16x32_bf16 v[52:55], v[210:213], v[178:181], v[52:55]
	v_mfma_f32_16x16x32_bf16 v[48:51], v[218:221], v[178:181], v[48:51]
	v_mfma_f32_16x16x32_bf16 v[36:39], v[210:213], v[186:189], v[36:39]
	v_mfma_f32_16x16x32_bf16 v[32:35], v[218:221], v[186:189], v[32:35]
	v_mfma_f32_16x16x32_bf16 v[20:23], v[210:213], v[194:197], v[20:23]
	v_mfma_f32_16x16x32_bf16 v[16:19], v[218:221], v[194:197], v[16:19]
	v_mfma_f32_16x16x32_bf16 v[4:7], v[210:213], v[202:205], v[4:7]
	v_mfma_f32_16x16x32_bf16 v[0:3], v[218:221], v[202:205], v[0:3]
	v_mfma_f32_16x16x32_bf16 v[52:55], v[214:217], v[182:185], v[52:55]
	v_mfma_f32_16x16x32_bf16 v[48:51], v[222:225], v[182:185], v[48:51]
	v_mfma_f32_16x16x32_bf16 v[36:39], v[214:217], v[190:193], v[36:39]
	v_mfma_f32_16x16x32_bf16 v[32:35], v[222:225], v[190:193], v[32:35]
	v_mfma_f32_16x16x32_bf16 v[20:23], v[214:217], v[198:201], v[20:23]
	v_mfma_f32_16x16x32_bf16 v[16:19], v[222:225], v[198:201], v[16:19]
	v_mfma_f32_16x16x32_bf16 v[4:7], v[214:217], v[206:209], v[4:7]
	v_mfma_f32_16x16x32_bf16 v[0:3], v[222:225], v[206:209], v[0:3]
	s_setprio 0
	s_add_i32 s42, s42, 2
	s_add_u32 s33, s33, 0x100
	s_addc_u32 s39, s39, 0
	s_add_u32 s40, s40, 0x100
	s_addc_u32 s41, s41, 0
	s_cmp_gt_u32 s42, 13
	s_barrier
	s_cbranch_scc0 .LBB0_958
	v_lshl_add_u32 v146, s75, 8, v148
	v_ashrrev_i32_e32 v147, 31, v146
	v_lshlrev_b64 v[156:157], 6, v[146:147]
	v_lshl_add_u64 v[164:165], s[26:27], 0, v[156:157]
	v_subrev_u32_e32 v180, s26, v164
	v_add_u32_e32 v181, 0x0, v180
	global_load_dwordx4 v[182:185], v181, s[26:27]
	v_add_u32_e32 v181, 0x10, v180
	global_load_dwordx4 v[186:189], v181, s[26:27]
	v_add_u32_e32 v181, 0x20, v180
	global_load_dwordx4 v[190:193], v181, s[26:27]
	v_add_u32_e32 v181, 0x30, v180
	global_load_dwordx4 v[194:197], v181, s[26:27]
	v_add_u32_e32 v181, 0x400, v180
	global_load_dwordx4 v[198:201], v181, s[26:27]
	v_add_u32_e32 v181, 0x410, v180
	global_load_dwordx4 v[202:205], v181, s[26:27]
	v_add_u32_e32 v181, 0x420, v180
	global_load_dwordx4 v[206:209], v181, s[26:27]
	v_add_u32_e32 v181, 0x430, v180
	global_load_dwordx4 v[210:213], v181, s[26:27]
	v_add_u32_e32 v181, 0x800, v180
	global_load_dwordx4 v[214:217], v181, s[26:27]
	v_add_u32_e32 v181, 0x810, v180
	global_load_dwordx4 v[218:221], v181, s[26:27]
	v_add_u32_e32 v181, 0x820, v180
	global_load_dwordx4 v[222:225], v181, s[26:27]
	v_add_u32_e32 v181, 0x830, v180
	global_load_dwordx4 v[232:235], v181, s[26:27]
	v_add_u32_e32 v181, 0xc00, v180
	global_load_dwordx4 v[236:239], v181, s[26:27]
	v_add_u32_e32 v181, 0xc10, v180
	global_load_dwordx4 v[240:243], v181, s[26:27]
	v_add_u32_e32 v181, 0xc20, v180
	global_load_dwordx4 v[244:247], v181, s[26:27]
	v_add_u32_e32 v181, 0xc30, v180
	global_load_dwordx4 v[248:251], v181, s[26:27]
	v_or_b32_e32 v164, 16, v146
	v_lshl_or_b32 v147, s6, 9, v150
	v_ashrrev_i32_e32 v165, 31, v164
	v_lshl_add_u32 v155, v146, 13, v147
	s_waitcnt vmcnt(12)
; __device__ __forceinline__ u32x4 pack8(const f32x4 v0, const f32x4 v1) { u32x4 w; w.x = pk2(v0[0], v0[1]); w.y = pk2(v0[2], v0[3]); w.z = pk2(v1[0], v1[1]); w.w = pk2(v1[2], v1[3]); return w; }
; __device__ __forceinline__ float row_rstd(const float* ssq, int row) {
;     const f32x4* p = (const f32x4*)(ssq + (size_t)row * 16);
;     const f32x4 a = p[0], b = p[1], c = p[2], d = p[3];
;     const float s = ((a[0] + a[1]) + (a[2] + a[3])) + ((b[0] + b[1]) + (b[2] + b[3])) + ((c[0] + c[1]) + (c[2] + c[3])) + ((d[0] + d[1]) + (d[2] + d[3]));
;     return rsqrtf(s * (1.0f / 1024.0f) + 1e-6f);
;     __device__ __forceinline__ void operator()(const f32x4 (&acc)[2][2][4][2], const Unit& u, int wr, int wc, int fr, int fq) const {
;     ...
;         const int row0 = row_off + u.pm * 256 + wr * 64 + fr, col0 = u.pn * 256 + wc * 32 + 8 * fq;
; #pragma unroll
;         for (int ai = 0; ai < 2; ++ai)
; #pragma unroll
;             for (int m = 0; m < 4; ++m) {
;                 const int row = row0 + ai * 128 + m * 16; const float rs = row_rstd(ssq, row);
; #pragma unroll
;                 for (int bj = 0; bj < 2; ++bj) { f32x4 v0 = acc[ai][bj][m][0] * rs, v1 = acc[ai][bj][m][1] * rs;
; #pragma unroll
;                     for (int j = 0; j < 4; ++j) { const float a = fmaxf(v0[j], 0.f), b = fmaxf(v1[j], 0.f); v0[j] = a * a; v1[j] = b * b; }
;                     __builtin_amdgcn_raw_buffer_store_b128(pack8(v0, v1), rsrc, (unsigned)(((size_t)row * DFF + col0 + bj * 128) * 2), 0, 16  ); }
	v_mov_b32_e32 v178, v183
	v_mov_b32_e32 v179, v184
	v_mov_b32_e32 v157, v185
	v_mov_b32_e32 v158, v187
	v_mov_b32_e32 v159, v188
	v_mov_b32_e32 v161, v189
	v_mov_b32_e32 v156, v182
	v_pk_add_f32 v[156:157], v[178:179], v[156:157]
	v_mov_b32_e32 v160, v186
	v_pk_add_f32 v[158:159], v[158:159], v[160:161]
	v_pk_add_f32 v[156:157], v[156:157], v[156:157] op_sel:[0,1] op_sel_hi:[1,0]
	v_pk_add_f32 v[158:159], v[158:159], v[158:159] op_sel:[0,1] op_sel_hi:[1,0]
	v_add_f32_e32 v162, v190, v191
	v_add_f32_e32 v170, v192, v193
	v_mov_b32_e32 v163, v196
	v_mov_b32_e32 v171, v197
	v_mov_b32_e32 v157, v194
	v_mov_b32_e32 v159, v195
	v_pk_add_f32 v[160:161], v[162:163], v[170:171]
	v_pk_add_f32 v[156:157], v[156:157], v[158:159]
	s_nop 0
	v_pk_add_f32 v[156:157], v[156:157], v[160:161]
	s_nop 0
	v_add_f32_e32 v156, v156, v157
	v_fmamk_f32 v156, v156, 0x3a800000, v154
	v_mul_f32_e32 v157, 0x4b800000, v156
	v_cmp_gt_f32_e32 vcc, s71, v156
	s_nop 1
	v_cndmask_b32_e32 v156, v156, v157, vcc
	v_rsq_f32_e32 v158, v156
	v_lshlrev_b64 v[156:157], 6, v[164:165]
	v_lshl_add_u64 v[156:157], s[26:27], 0, v[156:157]
	v_mul_f32_e32 v159, 0x45800000, v158
	v_cndmask_b32_e32 v158, v158, v159, vcc
	v_pk_mul_f32 v[126:127], v[126:127], v[158:159] op_sel_hi:[1,0]
	v_pk_mul_f32 v[124:125], v[124:125], v[158:159] op_sel_hi:[1,0]
	v_pk_mul_f32 v[122:123], v[122:123], v[158:159] op_sel_hi:[1,0]
	v_pk_mul_f32 v[120:121], v[120:121], v[158:159] op_sel_hi:[1,0]
	v_pk_mul_f32 v[114:115], v[114:115], v[158:159] op_sel_hi:[1,0]
	v_pk_mul_f32 v[112:113], v[112:113], v[158:159] op_sel_hi:[1,0]
	v_pk_mul_f32 v[118:119], v[118:119], v[158:159] op_sel_hi:[1,0]
	v_pk_mul_f32 v[116:117], v[116:117], v[158:159] op_sel_hi:[1,0]
	v_max_f32_e32 v124, 0, v124
	v_max_f32_e32 v120, 0, v120
	v_max_f32_e32 v125, 0, v125
	v_max_f32_e32 v121, 0, v121
	v_max_f32_e32 v126, 0, v126
	v_max_f32_e32 v122, 0, v122
	v_max_f32_e32 v127, 0, v127
	v_max_f32_e32 v123, 0, v123
	v_max_f32_e32 v112, 0, v112
	v_max_f32_e32 v113, 0, v113
	v_max_f32_e32 v114, 0, v114
	v_max_f32_e32 v115, 0, v115
	v_max_f32_e32 v116, 0, v116
	v_max_f32_e32 v117, 0, v117
	v_max_f32_e32 v118, 0, v118
	v_max_f32_e32 v119, 0, v119
	v_pk_mul_f32 v[124:125], v[124:125], v[124:125]
	v_pk_mul_f32 v[120:121], v[120:121], v[120:121]
	v_pk_mul_f32 v[126:127], v[126:127], v[126:127]
	v_pk_mul_f32 v[122:123], v[122:123], v[122:123]
	v_pk_mul_f32 v[158:159], v[112:113], v[112:113]
	v_pk_mul_f32 v[160:161], v[114:115], v[114:115]
	v_cvt_pk_bf16_f32 v112, v124, v125
	v_cvt_pk_bf16_f32 v113, v126, v127
	v_cvt_pk_bf16_f32 v114, v120, v121
	v_cvt_pk_bf16_f32 v115, v122, v123
	v_pk_mul_f32 v[116:117], v[116:117], v[116:117]
	v_pk_mul_f32 v[118:119], v[118:119], v[118:119]
	buffer_store_dwordx4 v[112:115], v155, s[16:19], 0 offen sc1
	s_nop 1
	v_cvt_pk_bf16_f32 v112, v116, v117
	v_cvt_pk_bf16_f32 v113, v118, v119
	v_cvt_pk_bf16_f32 v114, v158, v159
	v_cvt_pk_bf16_f32 v115, v160, v161
	buffer_store_dwordx4 v[112:115], v155, s[16:19], 0 offen offset:256 sc1
	s_nop 0
	v_or_b32_e32 v156, 32, v146
	v_ashrrev_i32_e32 v157, 31, v156
	v_lshl_add_u32 v155, v164, 13, v147
	v_add_u32_e32 v181, 0x2000, v180
	global_load_dwordx4 v[182:185], v181, s[26:27]
	v_add_u32_e32 v181, 0x2010, v180
	global_load_dwordx4 v[186:189], v181, s[26:27]
	v_add_u32_e32 v181, 0x2020, v180
	global_load_dwordx4 v[190:193], v181, s[26:27]
	v_add_u32_e32 v181, 0x2030, v180
	global_load_dwordx4 v[194:197], v181, s[26:27]
	s_waitcnt vmcnt(14)
	v_mov_b32_e32 v158, v199
	v_mov_b32_e32 v159, v200
	v_mov_b32_e32 v113, v201
	v_mov_b32_e32 v114, v203
	v_mov_b32_e32 v115, v204
	v_mov_b32_e32 v117, v205
	v_mov_b32_e32 v112, v198
	v_pk_add_f32 v[112:113], v[158:159], v[112:113]
	v_mov_b32_e32 v116, v202
	v_pk_add_f32 v[114:115], v[114:115], v[116:117]
	v_pk_add_f32 v[112:113], v[112:113], v[112:113] op_sel:[0,1] op_sel_hi:[1,0]
	v_pk_add_f32 v[114:115], v[114:115], v[114:115] op_sel:[0,1] op_sel_hi:[1,0]
	v_add_f32_e32 v118, v206, v207
	v_add_f32_e32 v120, v208, v209
	v_mov_b32_e32 v119, v212
	v_mov_b32_e32 v121, v213
	v_mov_b32_e32 v113, v210
	v_mov_b32_e32 v115, v211
	v_pk_add_f32 v[116:117], v[118:119], v[120:121]
	v_pk_add_f32 v[112:113], v[112:113], v[114:115]
	s_nop 0
	v_pk_add_f32 v[112:113], v[112:113], v[116:117]
	s_nop 0
	v_add_f32_e32 v112, v112, v113
	v_fmamk_f32 v112, v112, 0x3a800000, v154
	v_mul_f32_e32 v113, 0x4b800000, v112
	v_cmp_gt_f32_e32 vcc, s71, v112
	s_nop 1
	v_cndmask_b32_e32 v112, v112, v113, vcc
	v_rsq_f32_e32 v114, v112
	v_lshlrev_b64 v[112:113], 6, v[156:157]
	v_lshl_add_u64 v[112:113], s[26:27], 0, v[112:113]
	v_mul_f32_e32 v115, 0x45800000, v114
	v_cndmask_b32_e32 v114, v114, v115, vcc
	v_pk_mul_f32 v[110:111], v[110:111], v[114:115] op_sel_hi:[1,0]
	v_pk_mul_f32 v[108:109], v[108:109], v[114:115] op_sel_hi:[1,0]
	v_pk_mul_f32 v[106:107], v[106:107], v[114:115] op_sel_hi:[1,0]
	v_pk_mul_f32 v[104:105], v[104:105], v[114:115] op_sel_hi:[1,0]
	v_pk_mul_f32 v[98:99], v[98:99], v[114:115] op_sel_hi:[1,0]
	v_pk_mul_f32 v[96:97], v[96:97], v[114:115] op_sel_hi:[1,0]
	v_pk_mul_f32 v[102:103], v[102:103], v[114:115] op_sel_hi:[1,0]
	v_pk_mul_f32 v[100:101], v[100:101], v[114:115] op_sel_hi:[1,0]
	v_max_f32_e32 v108, 0, v108
	v_max_f32_e32 v104, 0, v104
	v_max_f32_e32 v109, 0, v109
	v_max_f32_e32 v105, 0, v105
	v_max_f32_e32 v110, 0, v110
	v_max_f32_e32 v106, 0, v106
	v_max_f32_e32 v111, 0, v111
	v_max_f32_e32 v107, 0, v107
	v_max_f32_e32 v96, 0, v96
	v_max_f32_e32 v97, 0, v97
	v_max_f32_e32 v98, 0, v98
	v_max_f32_e32 v99, 0, v99
	v_max_f32_e32 v100, 0, v100
	v_max_f32_e32 v101, 0, v101
	v_max_f32_e32 v102, 0, v102
	v_max_f32_e32 v103, 0, v103
	v_pk_mul_f32 v[108:109], v[108:109], v[108:109]
	v_pk_mul_f32 v[104:105], v[104:105], v[104:105]
	v_pk_mul_f32 v[110:111], v[110:111], v[110:111]
	v_pk_mul_f32 v[106:107], v[106:107], v[106:107]
	v_pk_mul_f32 v[114:115], v[96:97], v[96:97]
	v_pk_mul_f32 v[116:117], v[98:99], v[98:99]
	v_cvt_pk_bf16_f32 v96, v108, v109
	v_cvt_pk_bf16_f32 v97, v110, v111
	v_cvt_pk_bf16_f32 v98, v104, v105
	v_cvt_pk_bf16_f32 v99, v106, v107
	v_pk_mul_f32 v[100:101], v[100:101], v[100:101]
	v_pk_mul_f32 v[102:103], v[102:103], v[102:103]
	buffer_store_dwordx4 v[96:99], v155, s[16:19], 0 offen sc1
	s_nop 1
	v_cvt_pk_bf16_f32 v96, v100, v101
	v_cvt_pk_bf16_f32 v97, v102, v103
	v_cvt_pk_bf16_f32 v98, v114, v115
	v_cvt_pk_bf16_f32 v99, v116, v117
	buffer_store_dwordx4 v[96:99], v155, s[16:19], 0 offen offset:256 sc1
	s_nop 0
	v_or_b32_e32 v112, 48, v146
	v_ashrrev_i32_e32 v113, 31, v112
	v_lshl_add_u32 v116, v156, 13, v147
	v_add_u32_e32 v181, 0x2400, v180
	global_load_dwordx4 v[198:201], v181, s[26:27]
	v_add_u32_e32 v181, 0x2410, v180
	global_load_dwordx4 v[202:205], v181, s[26:27]
	v_add_u32_e32 v181, 0x2420, v180
	global_load_dwordx4 v[206:209], v181, s[26:27]
	v_add_u32_e32 v181, 0x2430, v180
	global_load_dwordx4 v[210:213], v181, s[26:27]
	s_waitcnt vmcnt(16)
; __device__ __forceinline__ u32x4 pack8(const f32x4 v0, const f32x4 v1) { u32x4 w; w.x = pk2(v0[0], v0[1]); w.y = pk2(v0[2], v0[3]); w.z = pk2(v1[0], v1[1]); w.w = pk2(v1[2], v1[3]); return w; }
; __device__ __forceinline__ float row_rstd(const float* ssq, int row) {
;     const f32x4* p = (const f32x4*)(ssq + (size_t)row * 16);
;     const f32x4 a = p[0], b = p[1], c = p[2], d = p[3];
;     const float s = ((a[0] + a[1]) + (a[2] + a[3])) + ((b[0] + b[1]) + (b[2] + b[3])) + ((c[0] + c[1]) + (c[2] + c[3])) + ((d[0] + d[1]) + (d[2] + d[3]));
;     return rsqrtf(s * (1.0f / 1024.0f) + 1e-6f);
; }
;     __device__ __forceinline__ void operator()(const f32x4 (&acc)[2][2][4][2], const Unit& u, int wr, int wc, int fr, int fq) const {
;         const __amdgpu_buffer_rsrc_t rsrc = __builtin_amdgcn_make_buffer_rsrc((void*)O, 0, T_ALL * DFF * 2, 0x00020000);
;         const int row0 = row_off + u.pm * 256 + wr * 64 + fr, col0 = u.pn * 256 + wc * 32 + 8 * fq;
; #pragma unroll
;         for (int ai = 0; ai < 2; ++ai)
; #pragma unroll
;             for (int m = 0; m < 4; ++m) {
;                 const int row = row0 + ai * 128 + m * 16; const float rs = row_rstd(ssq, row);
; #pragma unroll
;                 for (int bj = 0; bj < 2; ++bj) { f32x4 v0 = acc[ai][bj][m][0] * rs, v1 = acc[ai][bj][m][1] * rs;
; #pragma unroll
;                     for (int j = 0; j < 4; ++j) { const float a = fmaxf(v0[j], 0.f), b = fmaxf(v1[j], 0.f); v0[j] = a * a; v1[j] = b * b; }
;                     __builtin_amdgcn_raw_buffer_store_b128(pack8(v0, v1), rsrc, (unsigned)(((size_t)row * DFF + col0 + bj * 128) * 2), 0, 16  ); }
	v_mov_b32_e32 v114, v215
	v_mov_b32_e32 v115, v216
	v_mov_b32_e32 v97, v217
	v_mov_b32_e32 v98, v219
	v_mov_b32_e32 v99, v220
	v_mov_b32_e32 v101, v221
	v_mov_b32_e32 v96, v214
	v_pk_add_f32 v[96:97], v[114:115], v[96:97]
	v_mov_b32_e32 v100, v218
	v_pk_add_f32 v[98:99], v[98:99], v[100:101]
	v_pk_add_f32 v[96:97], v[96:97], v[96:97] op_sel:[0,1] op_sel_hi:[1,0]
	v_pk_add_f32 v[98:99], v[98:99], v[98:99] op_sel:[0,1] op_sel_hi:[1,0]
	v_add_f32_e32 v102, v222, v223
	v_add_f32_e32 v104, v224, v225
	v_mov_b32_e32 v103, v234
	v_mov_b32_e32 v105, v235
	v_mov_b32_e32 v97, v232
	v_mov_b32_e32 v99, v233
	v_pk_add_f32 v[100:101], v[102:103], v[104:105]
	v_pk_add_f32 v[96:97], v[96:97], v[98:99]
	s_nop 0
	v_pk_add_f32 v[96:97], v[96:97], v[100:101]
	s_nop 0
	v_add_f32_e32 v96, v96, v97
	v_fmamk_f32 v96, v96, 0x3a800000, v154
	v_mul_f32_e32 v97, 0x4b800000, v96
	v_cmp_gt_f32_e32 vcc, s71, v96
	s_nop 1
	v_cndmask_b32_e32 v96, v96, v97, vcc
	v_rsq_f32_e32 v98, v96
	v_lshlrev_b64 v[96:97], 6, v[112:113]
	v_lshl_add_u64 v[96:97], s[26:27], 0, v[96:97]
	v_mul_f32_e32 v99, 0x45800000, v98
	v_cndmask_b32_e32 v98, v98, v99, vcc
	v_pk_mul_f32 v[94:95], v[94:95], v[98:99] op_sel_hi:[1,0]
	v_pk_mul_f32 v[92:93], v[92:93], v[98:99] op_sel_hi:[1,0]
	v_pk_mul_f32 v[90:91], v[90:91], v[98:99] op_sel_hi:[1,0]
	v_pk_mul_f32 v[88:89], v[88:89], v[98:99] op_sel_hi:[1,0]
	v_pk_mul_f32 v[82:83], v[82:83], v[98:99] op_sel_hi:[1,0]
	v_pk_mul_f32 v[80:81], v[80:81], v[98:99] op_sel_hi:[1,0]
	v_pk_mul_f32 v[86:87], v[86:87], v[98:99] op_sel_hi:[1,0]
	v_pk_mul_f32 v[84:85], v[84:85], v[98:99] op_sel_hi:[1,0]
	v_max_f32_e32 v92, 0, v92
	v_max_f32_e32 v88, 0, v88
	v_max_f32_e32 v93, 0, v93
	v_max_f32_e32 v89, 0, v89
	v_max_f32_e32 v94, 0, v94
	v_max_f32_e32 v90, 0, v90
	v_max_f32_e32 v95, 0, v95
	v_max_f32_e32 v91, 0, v91
	v_max_f32_e32 v80, 0, v80
	v_max_f32_e32 v81, 0, v81
	v_max_f32_e32 v82, 0, v82
	v_max_f32_e32 v83, 0, v83
	v_max_f32_e32 v84, 0, v84
	v_max_f32_e32 v85, 0, v85
	v_max_f32_e32 v86, 0, v86
	v_max_f32_e32 v87, 0, v87
	v_pk_mul_f32 v[92:93], v[92:93], v[92:93]
	v_pk_mul_f32 v[88:89], v[88:89], v[88:89]
	v_pk_mul_f32 v[94:95], v[94:95], v[94:95]
	v_pk_mul_f32 v[90:91], v[90:91], v[90:91]
	v_pk_mul_f32 v[98:99], v[80:81], v[80:81]
	v_pk_mul_f32 v[100:101], v[82:83], v[82:83]
	v_cvt_pk_bf16_f32 v80, v92, v93
	v_cvt_pk_bf16_f32 v81, v94, v95
	v_cvt_pk_bf16_f32 v82, v88, v89
	v_cvt_pk_bf16_f32 v83, v90, v91
	v_pk_mul_f32 v[84:85], v[84:85], v[84:85]
	v_pk_mul_f32 v[86:87], v[86:87], v[86:87]
	buffer_store_dwordx4 v[80:83], v116, s[16:19], 0 offen sc1
	s_nop 1
	v_cvt_pk_bf16_f32 v80, v84, v85
	v_cvt_pk_bf16_f32 v81, v86, v87
	v_cvt_pk_bf16_f32 v82, v98, v99
	v_cvt_pk_bf16_f32 v83, v100, v101
	buffer_store_dwordx4 v[80:83], v116, s[16:19], 0 offen offset:256 sc1
	s_nop 0
	v_add_u32_e32 v96, 0x80, v146
	v_ashrrev_i32_e32 v97, 31, v96
	v_lshl_add_u32 v100, v112, 13, v147
	v_add_u32_e32 v181, 0x2800, v180
	global_load_dwordx4 v[214:217], v181, s[26:27]
	v_add_u32_e32 v181, 0x2810, v180
	global_load_dwordx4 v[218:221], v181, s[26:27]
	v_add_u32_e32 v181, 0x2820, v180
	global_load_dwordx4 v[222:225], v181, s[26:27]
	v_add_u32_e32 v181, 0x2830, v180
	global_load_dwordx4 v[232:235], v181, s[26:27]
	s_waitcnt vmcnt(18)
	v_mov_b32_e32 v98, v237
	v_mov_b32_e32 v99, v238
	v_mov_b32_e32 v81, v239
	v_mov_b32_e32 v82, v241
	v_mov_b32_e32 v83, v242
	v_mov_b32_e32 v85, v243
	v_mov_b32_e32 v80, v236
	v_pk_add_f32 v[80:81], v[98:99], v[80:81]
	v_mov_b32_e32 v84, v240
	v_pk_add_f32 v[82:83], v[82:83], v[84:85]
	v_pk_add_f32 v[80:81], v[80:81], v[80:81] op_sel:[0,1] op_sel_hi:[1,0]
	v_pk_add_f32 v[82:83], v[82:83], v[82:83] op_sel:[0,1] op_sel_hi:[1,0]
	v_add_f32_e32 v86, v244, v245
	v_add_f32_e32 v88, v246, v247
	v_mov_b32_e32 v87, v250
	v_mov_b32_e32 v89, v251
	v_mov_b32_e32 v81, v248
	v_mov_b32_e32 v83, v249
	v_pk_add_f32 v[84:85], v[86:87], v[88:89]
	v_pk_add_f32 v[80:81], v[80:81], v[82:83]
	s_nop 0
	v_pk_add_f32 v[80:81], v[80:81], v[84:85]
	s_nop 0
	v_add_f32_e32 v80, v80, v81
	v_fmamk_f32 v80, v80, 0x3a800000, v154
	v_mul_f32_e32 v81, 0x4b800000, v80
	v_cmp_gt_f32_e32 vcc, s71, v80
	s_nop 1
	v_cndmask_b32_e32 v80, v80, v81, vcc
	v_rsq_f32_e32 v82, v80
	v_lshlrev_b64 v[80:81], 6, v[96:97]
	v_lshl_add_u64 v[80:81], s[26:27], 0, v[80:81]
	v_mul_f32_e32 v83, 0x45800000, v82
	v_cndmask_b32_e32 v82, v82, v83, vcc
	v_pk_mul_f32 v[78:79], v[78:79], v[82:83] op_sel_hi:[1,0]
	v_pk_mul_f32 v[76:77], v[76:77], v[82:83] op_sel_hi:[1,0]
	v_pk_mul_f32 v[74:75], v[74:75], v[82:83] op_sel_hi:[1,0]
	v_pk_mul_f32 v[72:73], v[72:73], v[82:83] op_sel_hi:[1,0]
	v_pk_mul_f32 v[66:67], v[66:67], v[82:83] op_sel_hi:[1,0]
	v_pk_mul_f32 v[64:65], v[64:65], v[82:83] op_sel_hi:[1,0]
	v_pk_mul_f32 v[70:71], v[70:71], v[82:83] op_sel_hi:[1,0]
	v_pk_mul_f32 v[68:69], v[68:69], v[82:83] op_sel_hi:[1,0]
	v_max_f32_e32 v76, 0, v76
	v_max_f32_e32 v72, 0, v72
	v_max_f32_e32 v77, 0, v77
	v_max_f32_e32 v73, 0, v73
	v_max_f32_e32 v78, 0, v78
	v_max_f32_e32 v74, 0, v74
	v_max_f32_e32 v79, 0, v79
	v_max_f32_e32 v75, 0, v75
	v_max_f32_e32 v64, 0, v64
	v_max_f32_e32 v65, 0, v65
	v_max_f32_e32 v66, 0, v66
	v_max_f32_e32 v67, 0, v67
	v_max_f32_e32 v68, 0, v68
	v_max_f32_e32 v69, 0, v69
	v_max_f32_e32 v70, 0, v70
	v_max_f32_e32 v71, 0, v71
	v_pk_mul_f32 v[76:77], v[76:77], v[76:77]
	v_pk_mul_f32 v[72:73], v[72:73], v[72:73]
	v_pk_mul_f32 v[78:79], v[78:79], v[78:79]
	v_pk_mul_f32 v[74:75], v[74:75], v[74:75]
	v_pk_mul_f32 v[82:83], v[64:65], v[64:65]
	v_pk_mul_f32 v[84:85], v[66:67], v[66:67]
	v_cvt_pk_bf16_f32 v64, v76, v77
	v_cvt_pk_bf16_f32 v65, v78, v79
	v_cvt_pk_bf16_f32 v66, v72, v73
	v_cvt_pk_bf16_f32 v67, v74, v75
	v_pk_mul_f32 v[68:69], v[68:69], v[68:69]
	v_pk_mul_f32 v[70:71], v[70:71], v[70:71]
	buffer_store_dwordx4 v[64:67], v100, s[16:19], 0 offen sc1
	s_nop 1
	v_cvt_pk_bf16_f32 v64, v68, v69
	v_cvt_pk_bf16_f32 v65, v70, v71
	v_cvt_pk_bf16_f32 v66, v82, v83
	v_cvt_pk_bf16_f32 v67, v84, v85
	buffer_store_dwordx4 v[64:67], v100, s[16:19], 0 offen offset:256 sc1
	s_nop 0
	v_add_u32_e32 v80, 0x90, v146
	v_ashrrev_i32_e32 v81, 31, v80
	v_lshl_add_u32 v84, v96, 13, v147
	v_add_u32_e32 v181, 0x2c00, v180
	global_load_dwordx4 v[236:239], v181, s[26:27]
	v_add_u32_e32 v181, 0x2c10, v180
	global_load_dwordx4 v[240:243], v181, s[26:27]
	v_add_u32_e32 v181, 0x2c20, v180
	global_load_dwordx4 v[244:247], v181, s[26:27]
	v_add_u32_e32 v181, 0x2c30, v180
	global_load_dwordx4 v[248:251], v181, s[26:27]
	s_waitcnt vmcnt(18)
; __device__ __forceinline__ u32x4 pack8(const f32x4 v0, const f32x4 v1) { u32x4 w; w.x = pk2(v0[0], v0[1]); w.y = pk2(v0[2], v0[3]); w.z = pk2(v1[0], v1[1]); w.w = pk2(v1[2], v1[3]); return w; }
; __device__ __forceinline__ float row_rstd(const float* ssq, int row) {
;     const f32x4* p = (const f32x4*)(ssq + (size_t)row * 16);
;     const f32x4 a = p[0], b = p[1], c = p[2], d = p[3];
;     const float s = ((a[0] + a[1]) + (a[2] + a[3])) + ((b[0] + b[1]) + (b[2] + b[3])) + ((c[0] + c[1]) + (c[2] + c[3])) + ((d[0] + d[1]) + (d[2] + d[3]));
;     return rsqrtf(s * (1.0f / 1024.0f) + 1e-6f);
; }
;     __device__ __forceinline__ void operator()(const f32x4 (&acc)[2][2][4][2], const Unit& u, int wr, int wc, int fr, int fq) const {
;         const __amdgpu_buffer_rsrc_t rsrc = __builtin_amdgcn_make_buffer_rsrc((void*)O, 0, T_ALL * DFF * 2, 0x00020000);
;         const int row0 = row_off + u.pm * 256 + wr * 64 + fr, col0 = u.pn * 256 + wc * 32 + 8 * fq;
; #pragma unroll
;         for (int ai = 0; ai < 2; ++ai)
; #pragma unroll
;             for (int m = 0; m < 4; ++m) {
;                 const int row = row0 + ai * 128 + m * 16; const float rs = row_rstd(ssq, row);
; #pragma unroll
;                 for (int bj = 0; bj < 2; ++bj) { f32x4 v0 = acc[ai][bj][m][0] * rs, v1 = acc[ai][bj][m][1] * rs;
; #pragma unroll
;                     for (int j = 0; j < 4; ++j) { const float a = fmaxf(v0[j], 0.f), b = fmaxf(v1[j], 0.f); v0[j] = a * a; v1[j] = b * b; }
;                     __builtin_amdgcn_raw_buffer_store_b128(pack8(v0, v1), rsrc, (unsigned)(((size_t)row * DFF + col0 + bj * 128) * 2), 0, 16  ); }
	v_mov_b32_e32 v82, v183
	v_mov_b32_e32 v83, v184
	v_mov_b32_e32 v65, v185
	v_mov_b32_e32 v66, v187
	v_mov_b32_e32 v67, v188
	v_mov_b32_e32 v69, v189
	v_mov_b32_e32 v64, v182
	v_pk_add_f32 v[64:65], v[82:83], v[64:65]
	v_mov_b32_e32 v68, v186
	v_pk_add_f32 v[66:67], v[66:67], v[68:69]
	v_pk_add_f32 v[64:65], v[64:65], v[64:65] op_sel:[0,1] op_sel_hi:[1,0]
	v_pk_add_f32 v[66:67], v[66:67], v[66:67] op_sel:[0,1] op_sel_hi:[1,0]
	v_add_f32_e32 v70, v190, v191
	v_add_f32_e32 v72, v192, v193
	v_mov_b32_e32 v71, v196
	v_mov_b32_e32 v73, v197
	v_mov_b32_e32 v65, v194
	v_mov_b32_e32 v67, v195
	v_pk_add_f32 v[68:69], v[70:71], v[72:73]
	v_pk_add_f32 v[64:65], v[64:65], v[66:67]
	s_nop 0
	v_pk_add_f32 v[64:65], v[64:65], v[68:69]
	s_nop 0
	v_add_f32_e32 v64, v64, v65
	v_fmamk_f32 v64, v64, 0x3a800000, v154
	v_mul_f32_e32 v65, 0x4b800000, v64
	v_cmp_gt_f32_e32 vcc, s71, v64
	s_nop 1
	v_cndmask_b32_e32 v64, v64, v65, vcc
	v_rsq_f32_e32 v66, v64
	v_lshlrev_b64 v[64:65], 6, v[80:81]
	v_lshl_add_u64 v[64:65], s[26:27], 0, v[64:65]
	v_mul_f32_e32 v67, 0x45800000, v66
	v_cndmask_b32_e32 v66, v66, v67, vcc
	v_pk_mul_f32 v[62:63], v[62:63], v[66:67] op_sel_hi:[1,0]
	v_pk_mul_f32 v[60:61], v[60:61], v[66:67] op_sel_hi:[1,0]
	v_pk_mul_f32 v[58:59], v[58:59], v[66:67] op_sel_hi:[1,0]
	v_pk_mul_f32 v[56:57], v[56:57], v[66:67] op_sel_hi:[1,0]
	v_pk_mul_f32 v[50:51], v[50:51], v[66:67] op_sel_hi:[1,0]
	v_pk_mul_f32 v[48:49], v[48:49], v[66:67] op_sel_hi:[1,0]
	v_pk_mul_f32 v[54:55], v[54:55], v[66:67] op_sel_hi:[1,0]
	v_pk_mul_f32 v[52:53], v[52:53], v[66:67] op_sel_hi:[1,0]
	v_max_f32_e32 v60, 0, v60
	v_max_f32_e32 v56, 0, v56
	v_max_f32_e32 v61, 0, v61
	v_max_f32_e32 v57, 0, v57
	v_max_f32_e32 v62, 0, v62
	v_max_f32_e32 v58, 0, v58
	v_max_f32_e32 v63, 0, v63
	v_max_f32_e32 v59, 0, v59
	v_max_f32_e32 v48, 0, v48
	v_max_f32_e32 v49, 0, v49
	v_max_f32_e32 v50, 0, v50
	v_max_f32_e32 v51, 0, v51
	v_max_f32_e32 v52, 0, v52
	v_max_f32_e32 v53, 0, v53
	v_max_f32_e32 v54, 0, v54
	v_max_f32_e32 v55, 0, v55
	v_pk_mul_f32 v[60:61], v[60:61], v[60:61]
	v_pk_mul_f32 v[56:57], v[56:57], v[56:57]
	v_pk_mul_f32 v[62:63], v[62:63], v[62:63]
	v_pk_mul_f32 v[58:59], v[58:59], v[58:59]
	v_pk_mul_f32 v[66:67], v[48:49], v[48:49]
	v_pk_mul_f32 v[68:69], v[50:51], v[50:51]
	v_cvt_pk_bf16_f32 v48, v60, v61
	v_cvt_pk_bf16_f32 v49, v62, v63
	v_cvt_pk_bf16_f32 v50, v56, v57
	v_cvt_pk_bf16_f32 v51, v58, v59
	v_pk_mul_f32 v[52:53], v[52:53], v[52:53]
	v_pk_mul_f32 v[54:55], v[54:55], v[54:55]
	buffer_store_dwordx4 v[48:51], v84, s[16:19], 0 offen sc1
	s_nop 1
	v_cvt_pk_bf16_f32 v48, v52, v53
	v_cvt_pk_bf16_f32 v49, v54, v55
	v_cvt_pk_bf16_f32 v50, v66, v67
	v_cvt_pk_bf16_f32 v51, v68, v69
	buffer_store_dwordx4 v[48:51], v84, s[16:19], 0 offen offset:256 sc1
	s_nop 0
	v_add_u32_e32 v64, 0xa0, v146
	v_ashrrev_i32_e32 v65, 31, v64
	v_lshl_add_u32 v68, v80, 13, v147
	s_waitcnt vmcnt(14)
	v_mov_b32_e32 v66, v199
	v_mov_b32_e32 v67, v200
	v_mov_b32_e32 v49, v201
	v_mov_b32_e32 v50, v203
	v_mov_b32_e32 v51, v204
	v_mov_b32_e32 v53, v205
	v_mov_b32_e32 v48, v198
	v_pk_add_f32 v[48:49], v[66:67], v[48:49]
	v_mov_b32_e32 v52, v202
	v_pk_add_f32 v[50:51], v[50:51], v[52:53]
	v_pk_add_f32 v[48:49], v[48:49], v[48:49] op_sel:[0,1] op_sel_hi:[1,0]
	v_pk_add_f32 v[50:51], v[50:51], v[50:51] op_sel:[0,1] op_sel_hi:[1,0]
	v_add_f32_e32 v54, v206, v207
	v_add_f32_e32 v56, v208, v209
	v_mov_b32_e32 v55, v212
	v_mov_b32_e32 v57, v213
	v_mov_b32_e32 v49, v210
	v_mov_b32_e32 v51, v211
	v_pk_add_f32 v[52:53], v[54:55], v[56:57]
	v_pk_add_f32 v[48:49], v[48:49], v[50:51]
	s_nop 0
	v_pk_add_f32 v[48:49], v[48:49], v[52:53]
	s_nop 0
	v_add_f32_e32 v48, v48, v49
	v_fmamk_f32 v48, v48, 0x3a800000, v154
	v_mul_f32_e32 v49, 0x4b800000, v48
	v_cmp_gt_f32_e32 vcc, s71, v48
	s_nop 1
	v_cndmask_b32_e32 v48, v48, v49, vcc
	v_rsq_f32_e32 v50, v48
	v_lshlrev_b64 v[48:49], 6, v[64:65]
	v_lshl_add_u64 v[48:49], s[26:27], 0, v[48:49]
	v_mul_f32_e32 v51, 0x45800000, v50
	v_cndmask_b32_e32 v50, v50, v51, vcc
	v_pk_mul_f32 v[46:47], v[46:47], v[50:51] op_sel_hi:[1,0]
	v_pk_mul_f32 v[44:45], v[44:45], v[50:51] op_sel_hi:[1,0]
	v_pk_mul_f32 v[42:43], v[42:43], v[50:51] op_sel_hi:[1,0]
	v_pk_mul_f32 v[40:41], v[40:41], v[50:51] op_sel_hi:[1,0]
	v_pk_mul_f32 v[34:35], v[34:35], v[50:51] op_sel_hi:[1,0]
	v_pk_mul_f32 v[32:33], v[32:33], v[50:51] op_sel_hi:[1,0]
	v_pk_mul_f32 v[38:39], v[38:39], v[50:51] op_sel_hi:[1,0]
	v_pk_mul_f32 v[36:37], v[36:37], v[50:51] op_sel_hi:[1,0]
	v_max_f32_e32 v44, 0, v44
	v_max_f32_e32 v40, 0, v40
	v_max_f32_e32 v45, 0, v45
	v_max_f32_e32 v41, 0, v41
	v_max_f32_e32 v46, 0, v46
	v_max_f32_e32 v42, 0, v42
	v_max_f32_e32 v47, 0, v47
	v_max_f32_e32 v43, 0, v43
	v_max_f32_e32 v32, 0, v32
	v_max_f32_e32 v33, 0, v33
	v_max_f32_e32 v34, 0, v34
	v_max_f32_e32 v35, 0, v35
	v_max_f32_e32 v36, 0, v36
	v_max_f32_e32 v37, 0, v37
	v_max_f32_e32 v38, 0, v38
	v_max_f32_e32 v39, 0, v39
	v_pk_mul_f32 v[44:45], v[44:45], v[44:45]
	v_pk_mul_f32 v[40:41], v[40:41], v[40:41]
	v_pk_mul_f32 v[46:47], v[46:47], v[46:47]
	v_pk_mul_f32 v[42:43], v[42:43], v[42:43]
	v_pk_mul_f32 v[50:51], v[32:33], v[32:33]
	v_pk_mul_f32 v[52:53], v[34:35], v[34:35]
	v_cvt_pk_bf16_f32 v32, v44, v45
	v_cvt_pk_bf16_f32 v33, v46, v47
	v_cvt_pk_bf16_f32 v34, v40, v41
	v_cvt_pk_bf16_f32 v35, v42, v43
	v_pk_mul_f32 v[36:37], v[36:37], v[36:37]
	v_pk_mul_f32 v[38:39], v[38:39], v[38:39]
	buffer_store_dwordx4 v[32:35], v68, s[16:19], 0 offen sc1
	s_nop 1
	v_cvt_pk_bf16_f32 v32, v36, v37
	v_cvt_pk_bf16_f32 v33, v38, v39
	v_cvt_pk_bf16_f32 v34, v50, v51
	v_cvt_pk_bf16_f32 v35, v52, v53
	buffer_store_dwordx4 v[32:35], v68, s[16:19], 0 offen offset:256 sc1
	s_nop 0
	v_add_u32_e32 v48, 0xb0, v146
	v_ashrrev_i32_e32 v49, 31, v48
	v_lshl_add_u32 v52, v64, 13, v147
	s_waitcnt vmcnt(10)
; __device__ __forceinline__ u32x4 pack8(const f32x4 v0, const f32x4 v1) { u32x4 w; w.x = pk2(v0[0], v0[1]); w.y = pk2(v0[2], v0[3]); w.z = pk2(v1[0], v1[1]); w.w = pk2(v1[2], v1[3]); return w; }
; __device__ __forceinline__ float row_rstd(const float* ssq, int row) {
;     const f32x4* p = (const f32x4*)(ssq + (size_t)row * 16);
;     const f32x4 a = p[0], b = p[1], c = p[2], d = p[3];
;     const float s = ((a[0] + a[1]) + (a[2] + a[3])) + ((b[0] + b[1]) + (b[2] + b[3])) + ((c[0] + c[1]) + (c[2] + c[3])) + ((d[0] + d[1]) + (d[2] + d[3]));
;     return rsqrtf(s * (1.0f / 1024.0f) + 1e-6f);
; }
;     __device__ __forceinline__ void operator()(const f32x4 (&acc)[2][2][4][2], const Unit& u, int wr, int wc, int fr, int fq) const {
;         const __amdgpu_buffer_rsrc_t rsrc = __builtin_amdgcn_make_buffer_rsrc((void*)O, 0, T_ALL * DFF * 2, 0x00020000);
;         const int row0 = row_off + u.pm * 256 + wr * 64 + fr, col0 = u.pn * 256 + wc * 32 + 8 * fq;
; #pragma unroll
;         for (int ai = 0; ai < 2; ++ai)
; #pragma unroll
;             for (int m = 0; m < 4; ++m) {
;                 const int row = row0 + ai * 128 + m * 16; const float rs = row_rstd(ssq, row);
; #pragma unroll
;                 for (int bj = 0; bj < 2; ++bj) { f32x4 v0 = acc[ai][bj][m][0] * rs, v1 = acc[ai][bj][m][1] * rs;
; #pragma unroll
;                     for (int j = 0; j < 4; ++j) { const float a = fmaxf(v0[j], 0.f), b = fmaxf(v1[j], 0.f); v0[j] = a * a; v1[j] = b * b; }
;                     __builtin_amdgcn_raw_buffer_store_b128(pack8(v0, v1), rsrc, (unsigned)(((size_t)row * DFF + col0 + bj * 128) * 2), 0, 16  ); }
;             }
;         asm volatile("s_waitcnt vmcnt(0)" ::: "memory");
;         if (fr == 0 && fq == 0) (void)__hip_atomic_fetch_add(ready + 64 * (pm_off + u.pm), 1u, __ATOMIC_RELAXED, __HIP_MEMORY_SCOPE_AGENT);
;     }
	v_mov_b32_e32 v50, v215
	v_mov_b32_e32 v51, v216
	v_mov_b32_e32 v33, v217
	v_mov_b32_e32 v34, v219
	v_mov_b32_e32 v35, v220
	v_mov_b32_e32 v37, v221
	v_mov_b32_e32 v32, v214
	v_pk_add_f32 v[32:33], v[50:51], v[32:33]
	v_mov_b32_e32 v36, v218
	v_pk_add_f32 v[34:35], v[34:35], v[36:37]
	v_pk_add_f32 v[32:33], v[32:33], v[32:33] op_sel:[0,1] op_sel_hi:[1,0]
	v_pk_add_f32 v[34:35], v[34:35], v[34:35] op_sel:[0,1] op_sel_hi:[1,0]
	v_add_f32_e32 v38, v222, v223
	v_add_f32_e32 v40, v224, v225
	v_mov_b32_e32 v39, v234
	v_mov_b32_e32 v41, v235
	v_mov_b32_e32 v33, v232
	v_mov_b32_e32 v35, v233
	v_pk_add_f32 v[36:37], v[38:39], v[40:41]
	v_pk_add_f32 v[32:33], v[32:33], v[34:35]
	s_nop 0
	v_pk_add_f32 v[32:33], v[32:33], v[36:37]
	s_nop 0
	v_add_f32_e32 v32, v32, v33
	v_fmamk_f32 v32, v32, 0x3a800000, v154
	v_mul_f32_e32 v33, 0x4b800000, v32
	v_cmp_gt_f32_e32 vcc, s71, v32
	s_nop 1
	v_cndmask_b32_e32 v32, v32, v33, vcc
	v_rsq_f32_e32 v34, v32
	v_lshlrev_b64 v[32:33], 6, v[48:49]
	v_lshl_add_u64 v[32:33], s[26:27], 0, v[32:33]
	v_mul_f32_e32 v35, 0x45800000, v34
	v_cndmask_b32_e32 v34, v34, v35, vcc
	v_pk_mul_f32 v[30:31], v[30:31], v[34:35] op_sel_hi:[1,0]
	v_pk_mul_f32 v[28:29], v[28:29], v[34:35] op_sel_hi:[1,0]
	v_pk_mul_f32 v[26:27], v[26:27], v[34:35] op_sel_hi:[1,0]
	v_pk_mul_f32 v[24:25], v[24:25], v[34:35] op_sel_hi:[1,0]
	v_pk_mul_f32 v[18:19], v[18:19], v[34:35] op_sel_hi:[1,0]
	v_pk_mul_f32 v[16:17], v[16:17], v[34:35] op_sel_hi:[1,0]
	v_pk_mul_f32 v[22:23], v[22:23], v[34:35] op_sel_hi:[1,0]
	v_pk_mul_f32 v[20:21], v[20:21], v[34:35] op_sel_hi:[1,0]
	v_max_f32_e32 v28, 0, v28
	v_max_f32_e32 v24, 0, v24
	v_max_f32_e32 v29, 0, v29
	v_max_f32_e32 v25, 0, v25
	v_max_f32_e32 v30, 0, v30
	v_max_f32_e32 v26, 0, v26
	v_max_f32_e32 v31, 0, v31
	v_max_f32_e32 v27, 0, v27
	v_max_f32_e32 v16, 0, v16
	v_max_f32_e32 v17, 0, v17
	v_max_f32_e32 v18, 0, v18
	v_max_f32_e32 v19, 0, v19
	v_max_f32_e32 v20, 0, v20
	v_max_f32_e32 v21, 0, v21
	v_max_f32_e32 v22, 0, v22
	v_max_f32_e32 v23, 0, v23
	v_pk_mul_f32 v[28:29], v[28:29], v[28:29]
	v_pk_mul_f32 v[24:25], v[24:25], v[24:25]
	v_pk_mul_f32 v[30:31], v[30:31], v[30:31]
	v_pk_mul_f32 v[26:27], v[26:27], v[26:27]
	v_pk_mul_f32 v[34:35], v[16:17], v[16:17]
	v_pk_mul_f32 v[36:37], v[18:19], v[18:19]
	v_cvt_pk_bf16_f32 v16, v28, v29
	v_cvt_pk_bf16_f32 v17, v30, v31
	v_cvt_pk_bf16_f32 v18, v24, v25
	v_cvt_pk_bf16_f32 v19, v26, v27
	v_pk_mul_f32 v[20:21], v[20:21], v[20:21]
	v_pk_mul_f32 v[22:23], v[22:23], v[22:23]
	buffer_store_dwordx4 v[16:19], v52, s[16:19], 0 offen sc1
	s_nop 1
	v_cvt_pk_bf16_f32 v16, v20, v21
	v_cvt_pk_bf16_f32 v17, v22, v23
	v_cvt_pk_bf16_f32 v18, v34, v35
	v_cvt_pk_bf16_f32 v19, v36, v37
	buffer_store_dwordx4 v[16:19], v52, s[16:19], 0 offen offset:256 sc1
	s_nop 0
	s_waitcnt vmcnt(6)
	v_mov_b32_e32 v32, v237
	v_mov_b32_e32 v33, v238
	v_mov_b32_e32 v17, v239
	v_mov_b32_e32 v18, v241
	v_mov_b32_e32 v19, v242
	v_mov_b32_e32 v21, v243
	v_mov_b32_e32 v16, v236
	v_pk_add_f32 v[16:17], v[32:33], v[16:17]
	v_mov_b32_e32 v20, v240
	v_pk_add_f32 v[18:19], v[18:19], v[20:21]
	v_pk_add_f32 v[16:17], v[16:17], v[16:17] op_sel:[0,1] op_sel_hi:[1,0]
	v_pk_add_f32 v[18:19], v[18:19], v[18:19] op_sel:[0,1] op_sel_hi:[1,0]
	v_add_f32_e32 v22, v244, v245
	v_add_f32_e32 v24, v246, v247
	v_mov_b32_e32 v23, v250
	v_mov_b32_e32 v25, v251
	v_mov_b32_e32 v17, v248
	v_mov_b32_e32 v19, v249
	v_pk_add_f32 v[20:21], v[22:23], v[24:25]
	v_pk_add_f32 v[16:17], v[16:17], v[18:19]
	s_nop 0
	v_pk_add_f32 v[16:17], v[16:17], v[20:21]
	s_nop 0
	v_add_f32_e32 v16, v16, v17
	v_fmamk_f32 v16, v16, 0x3a800000, v154
	v_mul_f32_e32 v17, 0x4b800000, v16
	v_cmp_gt_f32_e32 vcc, s71, v16
	s_nop 1
	v_cndmask_b32_e32 v16, v16, v17, vcc
	v_rsq_f32_e32 v16, v16
	v_lshl_add_u32 v17, v48, 13, v147
	v_mul_f32_e32 v18, 0x45800000, v16
	v_cndmask_b32_e32 v16, v16, v18, vcc
	v_pk_mul_f32 v[14:15], v[14:15], v[16:17] op_sel_hi:[1,0]
	v_pk_mul_f32 v[12:13], v[12:13], v[16:17] op_sel_hi:[1,0]
	v_pk_mul_f32 v[10:11], v[10:11], v[16:17] op_sel_hi:[1,0]
	v_pk_mul_f32 v[8:9], v[8:9], v[16:17] op_sel_hi:[1,0]
	v_pk_mul_f32 v[2:3], v[2:3], v[16:17] op_sel_hi:[1,0]
	v_pk_mul_f32 v[0:1], v[0:1], v[16:17] op_sel_hi:[1,0]
	v_pk_mul_f32 v[6:7], v[6:7], v[16:17] op_sel_hi:[1,0]
	v_pk_mul_f32 v[4:5], v[4:5], v[16:17] op_sel_hi:[1,0]
	v_max_f32_e32 v12, 0, v12
	v_max_f32_e32 v8, 0, v8
	v_max_f32_e32 v13, 0, v13
	v_max_f32_e32 v9, 0, v9
	v_max_f32_e32 v14, 0, v14
	v_max_f32_e32 v10, 0, v10
	v_max_f32_e32 v15, 0, v15
	v_max_f32_e32 v11, 0, v11
	v_max_f32_e32 v0, 0, v0
	v_max_f32_e32 v1, 0, v1
	v_max_f32_e32 v2, 0, v2
	v_max_f32_e32 v3, 0, v3
	v_max_f32_e32 v4, 0, v4
	v_max_f32_e32 v5, 0, v5
	v_max_f32_e32 v6, 0, v6
	v_max_f32_e32 v7, 0, v7
	v_pk_mul_f32 v[12:13], v[12:13], v[12:13]
	v_pk_mul_f32 v[8:9], v[8:9], v[8:9]
	v_pk_mul_f32 v[14:15], v[14:15], v[14:15]
	v_pk_mul_f32 v[10:11], v[10:11], v[10:11]
	v_mul_f32_e32 v16, v0, v0
	v_mul_f32_e32 v18, v1, v1
	v_mul_f32_e32 v19, v2, v2
	v_mul_f32_e32 v20, v3, v3
	v_cvt_pk_bf16_f32 v0, v12, v13
	v_cvt_pk_bf16_f32 v1, v14, v15
	v_cvt_pk_bf16_f32 v2, v8, v9
	v_cvt_pk_bf16_f32 v3, v10, v11
	v_pk_mul_f32 v[4:5], v[4:5], v[4:5]
	v_pk_mul_f32 v[6:7], v[6:7], v[6:7]
	buffer_store_dwordx4 v[0:3], v17, s[16:19], 0 offen sc1
	s_nop 1
	v_cvt_pk_bf16_f32 v0, v4, v5
	v_cvt_pk_bf16_f32 v1, v6, v7
	v_cvt_pk_bf16_f32 v2, v16, v18
	v_cvt_pk_bf16_f32 v3, v19, v20
	buffer_store_dwordx4 v[0:3], v17, s[16:19], 0 offen offset:256 sc1
	s_waitcnt vmcnt(0)
	s_and_saveexec_b64 s[40:41], s[10:11]
	s_cbranch_execz .LBB0_950
	s_mov_b64 s[54:55], exec
	v_mbcnt_lo_u32_b32 v0, s54, 0
	v_mbcnt_hi_u32_b32 v0, s55, v0
	v_cmp_eq_u32_e32 vcc, 0, v0
	s_and_b64 s[6:7], exec, vcc
	s_mov_b64 exec, s[6:7]
	s_cbranch_execz .LBB0_950
	s_lshl_b32 s6, s75, 6
	s_ashr_i32 s7, s6, 31
	s_lshl_b64 s[6:7], s[6:7], 2
	s_add_u32 s6, s73, s6
	s_addc_u32 s7, s74, s7
	s_bcnt1_i32_b64 s8, s[54:55]
	v_mov_b32_e32 v0, s8
	global_atomic_add v131, v0, s[6:7]
	s_branch .LBB0_950

; #define PG8_STAGE(bufoff, gbase, voff) do { _Pragma("unroll") for (int _i = 0; _i < 2; ++_i) \
;         __builtin_amdgcn_global_load_lds((const unsigned*)((const char*)(gbase) + (voff)[_i]), (LAS unsigned*)(lds + (bufoff) + ldsw + _i * 8192), 16, 0, 0); } while (0)
; #define PG8_LDA(dst, b, h) do { _Pragma("unroll") for (int m = 0; m < 4; ++m) _Pragma("unroll") for (int k = 0; k < 2; ++k) dst[m][k] = *(const LAS bf16x8*)(lds + PG8_SA(b, h) + aoff + m * 2048 + k * 1024); } while (0)
; #define PG8_LDB(dst, b, h) do { _Pragma("unroll") for (int n = 0; n < 2; ++n) _Pragma("unroll") for (int k = 0; k < 2; ++k) dst[n][k] = *(const LAS bf16x8*)(lds + PG8_SB(b, h) + boff + n * 2048 + k * 1024); } while (0)
; #define PG8_MMA(ai, bj, At, Bt) do { __builtin_amdgcn_s_setprio(1); _Pragma("unroll") for (int m = 0; m < 4; ++m) _Pragma("unroll") for (int n = 0; n < 2; ++n) _Pragma("unroll") for (int k = 0; k < 2; ++k) \
;         acc[ai][bj][m][n] = __builtin_amdgcn_mfma_f32_16x16x32_bf16(Bt[n][k], At[m][k], acc[ai][bj][m][n], 0, 0, 0); __builtin_amdgcn_s_setprio(0); } while (0)
; #define PG8_WAIT_L(n) asm volatile("s_waitcnt lgkmcnt(" #n ")" ::: "memory")
; #define PG8_BAR __builtin_amdgcn_s_barrier()
; #define PG8_SCHED __builtin_amdgcn_sched_barrier(0)
;     ...
;         for (int t = 0; t < nt; t += 2) {
;             const bool last = (t == nt - 2);
;             const char* a1 = cA + (size_t)(t + 1) * kstep;
;             const char* a2 = last ? nA : cA + (size_t)(t + 2) * kstep; const char* b2 = last ? nB : cB + (size_t)(t + 2) * kstep;
;             const char* a3 = a2 + kstep; const char* b3 = b2 + kstep;
;             if (last && has_next) PG8_A_READY(nxt);
;             PG8_LDB(B0, 0, 0); PG8_SCHED; PG8_LDA(At, 0, 0); PG8_STAGE(PG8_SA(1, 1), a1 + hA, voffA);
;             PG8_WAIT_L(8); PG8_BAR; PG8_WAIT_L(0); PG8_MMA(0, 0, At, B0); PG8_BAR; PG8_SCHED;
;             PG8_LDB(B1, 0, 1); PG8_STAGE(PG8_SB(0, 0), b2, voffB);
;             PG8_BAR; PG8_WAIT_L(0); PG8_MMA(0, 1, At, B1); PG8_BAR;
;             PG8_LDA(At, 0, 1); PG8_STAGE(PG8_SA(0, 0), a2, voffA);
;             PG8_BAR; PG8_WAIT_L(0); PG8_MMA(1, 0, At, B0); PG8_BAR; PG8_SCHED;
;             PG8_STAGE(PG8_SB(0, 1), b2 + hB, voffB);
.LBB0_981:
	ds_read_b128 v[150:153], v143
	ds_read_b128 v[154:157], v143 offset:1024
	ds_read_b128 v[158:161], v143 offset:2048
	ds_read_b128 v[162:165], v143 offset:3072
	s_add_u32 s40, s38, 0xfffc0080
	s_addc_u32 s41, s39, -1
	s_cmp_eq_u32 s42, 12
	s_cselect_b32 s55, s7, s41
	s_cselect_b32 s54, s8, s40
	s_cselect_b32 s41, s9, s35
	s_cselect_b32 s40, s25, s33
	v_lshl_add_u64 v[202:203], s[38:39], 0, v[138:139]
	s_add_i32 m0, s61, 0xc000
	ds_read_b128 v[170:173], v146
	ds_read_b128 v[174:177], v146 offset:1024
	ds_read_b128 v[178:181], v146 offset:2048
	ds_read_b128 v[182:185], v146 offset:3072
	ds_read_b128 v[186:189], v146 offset:4096
	ds_read_b128 v[190:193], v146 offset:5120
	ds_read_b128 v[194:197], v146 offset:6144
	ds_read_b128 v[198:201], v146 offset:7168
	global_load_lds_dwordx4 v[202:203], off
	v_lshl_add_u64 v[202:203], s[38:39], 0, v[136:137]
	s_add_i32 m0, s61, 0xe000
	s_nop 0
	global_load_lds_dwordx4 v[202:203], off
	s_waitcnt lgkmcnt(8)
	s_barrier
	s_waitcnt lgkmcnt(0)
	s_setprio 1
	s_waitcnt lgkmcnt(0)
	v_mfma_f32_16x16x32_bf16 v[124:127], v[150:153], v[170:173], v[124:127]
	v_mfma_f32_16x16x32_bf16 v[120:123], v[158:161], v[170:173], v[120:123]
	v_mfma_f32_16x16x32_bf16 v[108:111], v[150:153], v[178:181], v[108:111]
	v_mfma_f32_16x16x32_bf16 v[104:107], v[158:161], v[178:181], v[104:107]
	v_mfma_f32_16x16x32_bf16 v[92:95], v[150:153], v[186:189], v[92:95]
	v_mfma_f32_16x16x32_bf16 v[88:91], v[158:161], v[186:189], v[88:91]
	v_mfma_f32_16x16x32_bf16 v[76:79], v[150:153], v[194:197], v[76:79]
	v_mfma_f32_16x16x32_bf16 v[72:75], v[158:161], v[194:197], v[72:75]
	v_mfma_f32_16x16x32_bf16 v[124:127], v[154:157], v[174:177], v[124:127]
	v_mfma_f32_16x16x32_bf16 v[120:123], v[162:165], v[174:177], v[120:123]
	v_mfma_f32_16x16x32_bf16 v[108:111], v[154:157], v[182:185], v[108:111]
	v_mfma_f32_16x16x32_bf16 v[104:107], v[162:165], v[182:185], v[104:107]
	v_mfma_f32_16x16x32_bf16 v[92:95], v[154:157], v[190:193], v[92:95]
	v_mfma_f32_16x16x32_bf16 v[88:91], v[162:165], v[190:193], v[88:91]
	v_mfma_f32_16x16x32_bf16 v[76:79], v[154:157], v[198:201], v[76:79]
	v_mfma_f32_16x16x32_bf16 v[72:75], v[162:165], v[198:201], v[72:75]
	s_setprio 0
	s_barrier
	s_add_i32 s43, s69, s60
	v_lshl_add_u64 v[218:219], s[40:41], 0, v[130:131]
	s_mov_b32 m0, s43
	ds_read_b128 v[202:205], v147
	ds_read_b128 v[206:209], v147 offset:1024
	ds_read_b128 v[210:213], v147 offset:2048
	ds_read_b128 v[214:217], v147 offset:3072
	global_load_lds_dwordx4 v[218:219], off
	v_lshl_add_u64 v[220:221], s[40:41], 0, v[134:135]
	s_add_i32 m0, s43, 0x2000
	s_nop 0
	global_load_lds_dwordx4 v[220:221], off
	s_barrier
	s_waitcnt lgkmcnt(0)
	s_setprio 1
	s_waitcnt lgkmcnt(0)
	v_mfma_f32_16x16x32_bf16 v[116:119], v[202:205], v[170:173], v[116:119]
	v_mfma_f32_16x16x32_bf16 v[112:115], v[210:213], v[170:173], v[112:115]
	v_mfma_f32_16x16x32_bf16 v[100:103], v[202:205], v[178:181], v[100:103]
	v_mfma_f32_16x16x32_bf16 v[96:99], v[210:213], v[178:181], v[96:99]
	v_mfma_f32_16x16x32_bf16 v[84:87], v[202:205], v[186:189], v[84:87]
	v_mfma_f32_16x16x32_bf16 v[80:83], v[210:213], v[186:189], v[80:83]
	v_mfma_f32_16x16x32_bf16 v[68:71], v[202:205], v[194:197], v[68:71]
	v_mfma_f32_16x16x32_bf16 v[64:67], v[210:213], v[194:197], v[64:67]
	v_mfma_f32_16x16x32_bf16 v[116:119], v[206:209], v[174:177], v[116:119]
	v_mfma_f32_16x16x32_bf16 v[112:115], v[214:217], v[174:177], v[112:115]
	v_mfma_f32_16x16x32_bf16 v[100:103], v[206:209], v[182:185], v[100:103]
	v_mfma_f32_16x16x32_bf16 v[96:99], v[214:217], v[182:185], v[96:99]
	v_mfma_f32_16x16x32_bf16 v[84:87], v[206:209], v[190:193], v[84:87]
	v_mfma_f32_16x16x32_bf16 v[80:83], v[214:217], v[190:193], v[80:83]
	v_mfma_f32_16x16x32_bf16 v[68:71], v[206:209], v[198:201], v[68:71]
	v_mfma_f32_16x16x32_bf16 v[64:67], v[214:217], v[198:201], v[64:67]
	s_setprio 0
	s_mov_b32 m0, s61
	v_lshl_add_u64 v[222:223], s[54:55], 0, v[128:129]
	s_barrier
	ds_read_b128 v[170:173], v146 offset:16384
	ds_read_b128 v[174:177], v146 offset:17408
	ds_read_b128 v[178:181], v146 offset:18432
	ds_read_b128 v[182:185], v146 offset:19456
	ds_read_b128 v[186:189], v146 offset:20480
	ds_read_b128 v[190:193], v146 offset:21504
	ds_read_b128 v[194:197], v146 offset:22528
	ds_read_b128 v[198:201], v146 offset:23552
	global_load_lds_dwordx4 v[222:223], off
	v_lshl_add_u64 v[224:225], s[54:55], 0, v[132:133]
	s_mov_b32 m0, s62
	s_nop 0
	global_load_lds_dwordx4 v[224:225], off
	s_barrier
	s_waitcnt lgkmcnt(0)
	s_setprio 1
	s_waitcnt lgkmcnt(0)
	v_mfma_f32_16x16x32_bf16 v[60:63], v[150:153], v[170:173], v[60:63]
	v_mfma_f32_16x16x32_bf16 v[56:59], v[158:161], v[170:173], v[56:59]
	v_mfma_f32_16x16x32_bf16 v[44:47], v[150:153], v[178:181], v[44:47]
	v_mfma_f32_16x16x32_bf16 v[40:43], v[158:161], v[178:181], v[40:43]
	v_mfma_f32_16x16x32_bf16 v[28:31], v[150:153], v[186:189], v[28:31]
	v_mfma_f32_16x16x32_bf16 v[24:27], v[158:161], v[186:189], v[24:27]
	v_mfma_f32_16x16x32_bf16 v[12:15], v[150:153], v[194:197], v[12:15]
	v_mfma_f32_16x16x32_bf16 v[8:11], v[158:161], v[194:197], v[8:11]
	v_mfma_f32_16x16x32_bf16 v[60:63], v[154:157], v[174:177], v[60:63]
	v_mfma_f32_16x16x32_bf16 v[56:59], v[162:165], v[174:177], v[56:59]
	v_mfma_f32_16x16x32_bf16 v[44:47], v[154:157], v[182:185], v[44:47]
	v_mfma_f32_16x16x32_bf16 v[40:43], v[162:165], v[182:185], v[40:43]
	v_mfma_f32_16x16x32_bf16 v[28:31], v[154:157], v[190:193], v[28:31]
	v_mfma_f32_16x16x32_bf16 v[24:27], v[162:165], v[190:193], v[24:27]
	v_mfma_f32_16x16x32_bf16 v[12:15], v[154:157], v[198:201], v[12:15]
	v_mfma_f32_16x16x32_bf16 v[8:11], v[162:165], v[198:201], v[8:11]
	s_setprio 0
	s_barrier
; #define PG8_STAGE(bufoff, gbase, voff) do { _Pragma("unroll") for (int _i = 0; _i < 2; ++_i) \
;         __builtin_amdgcn_global_load_lds((const unsigned*)((const char*)(gbase) + (voff)[_i]), (LAS unsigned*)(lds + (bufoff) + ldsw + _i * 8192), 16, 0, 0); } while (0)
; #define PG8_LDA(dst, b, h) do { _Pragma("unroll") for (int m = 0; m < 4; ++m) _Pragma("unroll") for (int k = 0; k < 2; ++k) dst[m][k] = *(const LAS bf16x8*)(lds + PG8_SA(b, h) + aoff + m * 2048 + k * 1024); } while (0)
; #define PG8_LDB(dst, b, h) do { _Pragma("unroll") for (int n = 0; n < 2; ++n) _Pragma("unroll") for (int k = 0; k < 2; ++k) dst[n][k] = *(const LAS bf16x8*)(lds + PG8_SB(b, h) + boff + n * 2048 + k * 1024); } while (0)
; #define PG8_MMA(ai, bj, At, Bt) do { __builtin_amdgcn_s_setprio(1); _Pragma("unroll") for (int m = 0; m < 4; ++m) _Pragma("unroll") for (int n = 0; n < 2; ++n) _Pragma("unroll") for (int k = 0; k < 2; ++k) \
;         acc[ai][bj][m][n] = __builtin_amdgcn_mfma_f32_16x16x32_bf16(Bt[n][k], At[m][k], acc[ai][bj][m][n], 0, 0, 0); __builtin_amdgcn_s_setprio(0); } while (0)
; #define PG8_WAIT_V(n) asm volatile("s_waitcnt vmcnt(" #n ")" ::: "memory")
; #define PG8_WAIT_L(n) asm volatile("s_waitcnt lgkmcnt(" #n ")" ::: "memory")
; #define PG8_BAR __builtin_amdgcn_s_barrier()
; #define PG8_SCHED __builtin_amdgcn_sched_barrier(0)
;     ...
;             PG8_STAGE(PG8_SB(0, 1), b2 + hB, voffB);
;             PG8_WAIT_V(6); PG8_BAR; PG8_MMA(1, 1, At, B1); PG8_BAR;
;             PG8_LDB(B0, 1, 0); PG8_SCHED; PG8_LDA(At, 1, 0); PG8_STAGE(PG8_SA(0, 1), a2 + hA, voffA);
;             PG8_WAIT_L(8); PG8_BAR; PG8_WAIT_L(0); PG8_MMA(0, 0, At, B0); PG8_BAR; PG8_SCHED;
;             PG8_LDB(B1, 1, 1); PG8_STAGE(PG8_SB(1, 0), b3, voffB);
;             PG8_BAR; PG8_WAIT_L(0); PG8_MMA(0, 1, At, B1); PG8_BAR;
;             PG8_LDA(At, 1, 1); PG8_STAGE(PG8_SA(1, 0), a3, voffA);
;             PG8_BAR; PG8_WAIT_L(0); PG8_MMA(1, 0, At, B0); PG8_BAR; PG8_SCHED;
	s_add_u32 s44, s40, 0x40000
	s_addc_u32 s45, s41, 0
	s_add_i32 s43, s70, s60
	v_lshl_add_u64 v[150:151], s[44:45], 0, v[130:131]
	s_mov_b32 m0, s43
	s_nop 0
	global_load_lds_dwordx4 v[150:151], off
	v_lshl_add_u64 v[150:151], s[44:45], 0, v[134:135]
	s_add_i32 m0, s43, 0x2000
	s_nop 0
	global_load_lds_dwordx4 v[150:151], off
	s_waitcnt vmcnt(6)
	s_barrier
	s_setprio 1
	v_mfma_f32_16x16x32_bf16 v[52:55], v[202:205], v[170:173], v[52:55]
	v_mfma_f32_16x16x32_bf16 v[48:51], v[210:213], v[170:173], v[48:51]
	v_mfma_f32_16x16x32_bf16 v[36:39], v[202:205], v[178:181], v[36:39]
	v_mfma_f32_16x16x32_bf16 v[32:35], v[210:213], v[178:181], v[32:35]
	v_mfma_f32_16x16x32_bf16 v[20:23], v[202:205], v[186:189], v[20:23]
	v_mfma_f32_16x16x32_bf16 v[16:19], v[210:213], v[186:189], v[16:19]
	v_mfma_f32_16x16x32_bf16 v[4:7], v[202:205], v[194:197], v[4:7]
	v_mfma_f32_16x16x32_bf16 v[0:3], v[210:213], v[194:197], v[0:3]
	v_mfma_f32_16x16x32_bf16 v[52:55], v[206:209], v[174:177], v[52:55]
	v_mfma_f32_16x16x32_bf16 v[48:51], v[214:217], v[174:177], v[48:51]
	v_mfma_f32_16x16x32_bf16 v[36:39], v[206:209], v[182:185], v[36:39]
	v_mfma_f32_16x16x32_bf16 v[32:35], v[214:217], v[182:185], v[32:35]
	v_mfma_f32_16x16x32_bf16 v[20:23], v[206:209], v[190:193], v[20:23]
	v_mfma_f32_16x16x32_bf16 v[16:19], v[214:217], v[190:193], v[16:19]
	v_mfma_f32_16x16x32_bf16 v[4:7], v[206:209], v[198:201], v[4:7]
	v_mfma_f32_16x16x32_bf16 v[0:3], v[214:217], v[198:201], v[0:3]
	s_setprio 0
	s_add_i32 s43, 0, 0x18000
	v_add_u32_e32 v149, s43, v141
	s_barrier
	ds_read_b128 v[150:153], v149
	ds_read_b128 v[154:157], v149 offset:1024
	ds_read_b128 v[158:161], v149 offset:2048
	ds_read_b128 v[162:165], v149 offset:3072
	s_add_u32 s44, s54, 0x40000
	s_addc_u32 s45, s55, 0
	s_mov_b32 m0, s63
	v_lshl_add_u64 v[202:203], s[44:45], 0, v[128:129]
	ds_read_b128 v[170:173], v146 offset:32768
	ds_read_b128 v[174:177], v146 offset:33792
	ds_read_b128 v[178:181], v146 offset:34816
	ds_read_b128 v[182:185], v146 offset:35840
	ds_read_b128 v[186:189], v146 offset:36864
	ds_read_b128 v[190:193], v146 offset:37888
	ds_read_b128 v[194:197], v146 offset:38912
	ds_read_b128 v[198:201], v146 offset:39936
	global_load_lds_dwordx4 v[202:203], off
	v_lshl_add_u64 v[202:203], s[44:45], 0, v[132:133]
	s_mov_b32 m0, s64
	s_nop 0
	global_load_lds_dwordx4 v[202:203], off
	s_waitcnt lgkmcnt(8)
	s_barrier
	s_waitcnt lgkmcnt(0)
	s_setprio 1
	s_waitcnt lgkmcnt(0)
	v_mfma_f32_16x16x32_bf16 v[124:127], v[150:153], v[170:173], v[124:127]
	v_mfma_f32_16x16x32_bf16 v[120:123], v[158:161], v[170:173], v[120:123]
	v_mfma_f32_16x16x32_bf16 v[108:111], v[150:153], v[178:181], v[108:111]
	v_mfma_f32_16x16x32_bf16 v[104:107], v[158:161], v[178:181], v[104:107]
	v_mfma_f32_16x16x32_bf16 v[92:95], v[150:153], v[186:189], v[92:95]
	v_mfma_f32_16x16x32_bf16 v[88:91], v[158:161], v[186:189], v[88:91]
	v_mfma_f32_16x16x32_bf16 v[76:79], v[150:153], v[194:197], v[76:79]
	v_mfma_f32_16x16x32_bf16 v[72:75], v[158:161], v[194:197], v[72:75]
	v_mfma_f32_16x16x32_bf16 v[124:127], v[154:157], v[174:177], v[124:127]
	v_mfma_f32_16x16x32_bf16 v[120:123], v[162:165], v[174:177], v[120:123]
	v_mfma_f32_16x16x32_bf16 v[108:111], v[154:157], v[182:185], v[108:111]
	v_mfma_f32_16x16x32_bf16 v[104:107], v[162:165], v[182:185], v[104:107]
	v_mfma_f32_16x16x32_bf16 v[92:95], v[154:157], v[190:193], v[92:95]
	v_mfma_f32_16x16x32_bf16 v[88:91], v[162:165], v[190:193], v[88:91]
	v_mfma_f32_16x16x32_bf16 v[76:79], v[154:157], v[198:201], v[76:79]
	v_mfma_f32_16x16x32_bf16 v[72:75], v[162:165], v[198:201], v[72:75]
	s_setprio 0
	s_barrier
	s_add_i32 s44, 0, 0x1c000
	s_add_i32 s43, s43, s60
	v_add_u32_e32 v149, s44, v141
	v_lshl_add_u64 v[218:219], v[218:219], 0, s[26:27]
	s_mov_b32 m0, s43
	ds_read_b128 v[202:205], v149
	ds_read_b128 v[206:209], v149 offset:1024
	ds_read_b128 v[210:213], v149 offset:2048
	ds_read_b128 v[214:217], v149 offset:3072
	global_load_lds_dwordx4 v[218:219], off
	v_lshl_add_u64 v[218:219], v[220:221], 0, s[26:27]
	s_add_i32 m0, s43, 0x2000
	s_nop 0
	global_load_lds_dwordx4 v[218:219], off
	s_barrier
	s_waitcnt lgkmcnt(0)
	s_setprio 1
	s_waitcnt lgkmcnt(0)
	v_mfma_f32_16x16x32_bf16 v[116:119], v[202:205], v[170:173], v[116:119]
	v_mfma_f32_16x16x32_bf16 v[112:115], v[210:213], v[170:173], v[112:115]
	v_mfma_f32_16x16x32_bf16 v[100:103], v[202:205], v[178:181], v[100:103]
	v_mfma_f32_16x16x32_bf16 v[96:99], v[210:213], v[178:181], v[96:99]
	v_mfma_f32_16x16x32_bf16 v[84:87], v[202:205], v[186:189], v[84:87]
	v_mfma_f32_16x16x32_bf16 v[80:83], v[210:213], v[186:189], v[80:83]
	v_mfma_f32_16x16x32_bf16 v[68:71], v[202:205], v[194:197], v[68:71]
	v_mfma_f32_16x16x32_bf16 v[64:67], v[210:213], v[194:197], v[64:67]
	v_mfma_f32_16x16x32_bf16 v[116:119], v[206:209], v[174:177], v[116:119]
	v_mfma_f32_16x16x32_bf16 v[112:115], v[214:217], v[174:177], v[112:115]
	v_mfma_f32_16x16x32_bf16 v[100:103], v[206:209], v[182:185], v[100:103]
	v_mfma_f32_16x16x32_bf16 v[96:99], v[214:217], v[182:185], v[96:99]
	v_mfma_f32_16x16x32_bf16 v[84:87], v[206:209], v[190:193], v[84:87]
	v_mfma_f32_16x16x32_bf16 v[80:83], v[214:217], v[190:193], v[80:83]
	v_mfma_f32_16x16x32_bf16 v[68:71], v[206:209], v[198:201], v[68:71]
	v_mfma_f32_16x16x32_bf16 v[64:67], v[214:217], v[198:201], v[64:67]
	s_setprio 0
	s_mov_b32 m0, s66
	v_lshl_add_u64 v[218:219], v[222:223], 0, s[26:27]
	s_barrier
	ds_read_b128 v[170:173], v146 offset:49152
	ds_read_b128 v[174:177], v146 offset:50176
	ds_read_b128 v[178:181], v146 offset:51200
	ds_read_b128 v[182:185], v146 offset:52224
	ds_read_b128 v[186:189], v146 offset:53248
	ds_read_b128 v[190:193], v146 offset:54272
	ds_read_b128 v[194:197], v146 offset:55296
	ds_read_b128 v[198:201], v146 offset:56320
	global_load_lds_dwordx4 v[218:219], off
	v_lshl_add_u64 v[218:219], v[224:225], 0, s[26:27]
	s_mov_b32 m0, s67
	s_nop 0
	global_load_lds_dwordx4 v[218:219], off
	s_barrier
; #define PG8_STAGE(bufoff, gbase, voff) do { _Pragma("unroll") for (int _i = 0; _i < 2; ++_i) \
;         __builtin_amdgcn_global_load_lds((const unsigned*)((const char*)(gbase) + (voff)[_i]), (LAS unsigned*)(lds + (bufoff) + ldsw + _i * 8192), 16, 0, 0); } while (0)
; #define PG8_MMA(ai, bj, At, Bt) do { __builtin_amdgcn_s_setprio(1); _Pragma("unroll") for (int m = 0; m < 4; ++m) _Pragma("unroll") for (int n = 0; n < 2; ++n) _Pragma("unroll") for (int k = 0; k < 2; ++k) \
;         acc[ai][bj][m][n] = __builtin_amdgcn_mfma_f32_16x16x32_bf16(Bt[n][k], At[m][k], acc[ai][bj][m][n], 0, 0, 0); __builtin_amdgcn_s_setprio(0); } while (0)
; #define PG8_WAIT_V(n) asm volatile("s_waitcnt vmcnt(" #n ")" ::: "memory")
; #define PG8_WAIT_L(n) asm volatile("s_waitcnt lgkmcnt(" #n ")" ::: "memory")
; #define PG8_BAR __builtin_amdgcn_s_barrier()
; #define PG8_SCHED __builtin_amdgcn_sched_barrier(0)
;     ...
;             PG8_BAR; PG8_WAIT_L(0); PG8_MMA(1, 0, At, B0); PG8_BAR; PG8_SCHED;
;             PG8_STAGE(PG8_SB(1, 1), b3 + hB, voffB);
;             PG8_WAIT_V(6); PG8_BAR; PG8_MMA(1, 1, At, B1); PG8_BAR;
;         }
; __device__ __forceinline__ float row_rstd(const float* ssq, int row) {
;     const f32x4* p = (const f32x4*)(ssq + (size_t)row * 16);
;     const f32x4 a = p[0], b = p[1], c = p[2], d = p[3];
;     __device__ __forceinline__ void operator()(const f32x4 (&acc)[2][2][4][2], const Unit& u, int wr, int wc, int fr, int fq) const {
;     ...
;                 const int row = row0 + ai * 128 + m * 16; const float rs = row_rstd(ssq, row);
	s_waitcnt lgkmcnt(0)
	s_setprio 1
	s_waitcnt lgkmcnt(0)
	v_mfma_f32_16x16x32_bf16 v[60:63], v[150:153], v[170:173], v[60:63]
	v_mfma_f32_16x16x32_bf16 v[56:59], v[158:161], v[170:173], v[56:59]
	v_mfma_f32_16x16x32_bf16 v[44:47], v[150:153], v[178:181], v[44:47]
	v_mfma_f32_16x16x32_bf16 v[40:43], v[158:161], v[178:181], v[40:43]
	v_mfma_f32_16x16x32_bf16 v[28:31], v[150:153], v[186:189], v[28:31]
	v_mfma_f32_16x16x32_bf16 v[24:27], v[158:161], v[186:189], v[24:27]
	v_mfma_f32_16x16x32_bf16 v[12:15], v[150:153], v[194:197], v[12:15]
	v_mfma_f32_16x16x32_bf16 v[8:11], v[158:161], v[194:197], v[8:11]
	v_mfma_f32_16x16x32_bf16 v[60:63], v[154:157], v[174:177], v[60:63]
	v_mfma_f32_16x16x32_bf16 v[56:59], v[162:165], v[174:177], v[56:59]
	v_mfma_f32_16x16x32_bf16 v[44:47], v[154:157], v[182:185], v[44:47]
	v_mfma_f32_16x16x32_bf16 v[40:43], v[162:165], v[182:185], v[40:43]
	v_mfma_f32_16x16x32_bf16 v[28:31], v[154:157], v[190:193], v[28:31]
	v_mfma_f32_16x16x32_bf16 v[24:27], v[162:165], v[190:193], v[24:27]
	v_mfma_f32_16x16x32_bf16 v[12:15], v[154:157], v[198:201], v[12:15]
	v_mfma_f32_16x16x32_bf16 v[8:11], v[162:165], v[198:201], v[8:11]
	s_setprio 0
	s_barrier
	s_add_u32 s40, s40, 0x40080
	s_addc_u32 s41, s41, 0
	s_add_i32 s43, s44, s60
	v_lshl_add_u64 v[150:151], s[40:41], 0, v[130:131]
	s_mov_b32 m0, s43
	s_nop 0
	global_load_lds_dwordx4 v[150:151], off
	v_lshl_add_u64 v[150:151], s[40:41], 0, v[134:135]
	s_add_i32 m0, s43, 0x2000
	s_nop 0
	global_load_lds_dwordx4 v[150:151], off
	s_waitcnt vmcnt(6)
	s_barrier
	s_setprio 1
	v_mfma_f32_16x16x32_bf16 v[52:55], v[202:205], v[170:173], v[52:55]
	v_mfma_f32_16x16x32_bf16 v[48:51], v[210:213], v[170:173], v[48:51]
	v_mfma_f32_16x16x32_bf16 v[36:39], v[202:205], v[178:181], v[36:39]
	v_mfma_f32_16x16x32_bf16 v[32:35], v[210:213], v[178:181], v[32:35]
	v_mfma_f32_16x16x32_bf16 v[20:23], v[202:205], v[186:189], v[20:23]
	v_mfma_f32_16x16x32_bf16 v[16:19], v[210:213], v[186:189], v[16:19]
	v_mfma_f32_16x16x32_bf16 v[4:7], v[202:205], v[194:197], v[4:7]
	v_mfma_f32_16x16x32_bf16 v[0:3], v[210:213], v[194:197], v[0:3]
	v_mfma_f32_16x16x32_bf16 v[52:55], v[206:209], v[174:177], v[52:55]
	v_mfma_f32_16x16x32_bf16 v[48:51], v[214:217], v[174:177], v[48:51]
	v_mfma_f32_16x16x32_bf16 v[36:39], v[206:209], v[182:185], v[36:39]
	v_mfma_f32_16x16x32_bf16 v[32:35], v[214:217], v[182:185], v[32:35]
	v_mfma_f32_16x16x32_bf16 v[20:23], v[206:209], v[190:193], v[20:23]
	v_mfma_f32_16x16x32_bf16 v[16:19], v[214:217], v[190:193], v[16:19]
	v_mfma_f32_16x16x32_bf16 v[4:7], v[206:209], v[198:201], v[4:7]
	v_mfma_f32_16x16x32_bf16 v[0:3], v[214:217], v[198:201], v[0:3]
	s_setprio 0
	s_add_i32 s42, s42, 2
	s_add_u32 s33, s33, 0x100
	s_addc_u32 s35, s35, 0
	s_add_u32 s38, s38, 0x100
	s_addc_u32 s39, s39, 0
	s_cmp_gt_u32 s42, 13
	s_barrier
	s_cbranch_scc0 .LBB0_981
	v_lshl_add_u32 v150, s75, 8, v140
	v_add_u32_e32 v164, 0x4000, v150
	v_ashrrev_i32_e32 v165, 31, v164
	v_lshlrev_b64 v[152:153], 6, v[164:165]
	v_lshl_add_u64 v[170:171], s[18:19], 0, v[152:153]
	v_subrev_u32_e32 v176, s18, v170
	v_add_u32_e32 v177, 0x0, v176
	global_load_dwordx4 v[178:181], v177, s[18:19]
	v_add_u32_e32 v177, 0x10, v176
	global_load_dwordx4 v[182:185], v177, s[18:19]
	v_add_u32_e32 v177, 0x20, v176
	global_load_dwordx4 v[186:189], v177, s[18:19]
	v_add_u32_e32 v177, 0x30, v176
	global_load_dwordx4 v[190:193], v177, s[18:19]
	v_add_u32_e32 v177, 0x400, v176
	global_load_dwordx4 v[194:197], v177, s[18:19]
	v_add_u32_e32 v177, 0x410, v176
	global_load_dwordx4 v[198:201], v177, s[18:19]
	v_add_u32_e32 v177, 0x420, v176
	global_load_dwordx4 v[202:205], v177, s[18:19]
	v_add_u32_e32 v177, 0x430, v176
	global_load_dwordx4 v[206:209], v177, s[18:19]
	v_add_u32_e32 v177, 0x800, v176
	global_load_dwordx4 v[210:213], v177, s[18:19]
	v_add_u32_e32 v177, 0x810, v176
	global_load_dwordx4 v[214:217], v177, s[18:19]
	v_add_u32_e32 v177, 0x820, v176
	global_load_dwordx4 v[232:235], v177, s[18:19]
	v_add_u32_e32 v177, 0x830, v176
	global_load_dwordx4 v[236:239], v177, s[18:19]
	v_add_u32_e32 v177, 0xc00, v176
	global_load_dwordx4 v[240:243], v177, s[18:19]
	v_add_u32_e32 v177, 0xc10, v176
	global_load_dwordx4 v[244:247], v177, s[18:19]
	v_add_u32_e32 v177, 0xc20, v176
	global_load_dwordx4 v[248:251], v177, s[18:19]
	v_add_u32_e32 v177, 0xc30, v176
	global_load_dwordx4 v[252:255], v177, s[18:19]
	s_nop 0
	v_lshl_or_b32 v149, s6, 9, v142
	v_lshl_add_u32 v151, v164, 13, v149
	v_add_u32_e32 v174, 0x4010, v150
	v_ashrrev_i32_e32 v175, 31, v174
	s_waitcnt vmcnt(12)
; __device__ __forceinline__ u32x4 pack8(const f32x4 v0, const f32x4 v1) { u32x4 w; w.x = pk2(v0[0], v0[1]); w.y = pk2(v0[2], v0[3]); w.z = pk2(v1[0], v1[1]); w.w = pk2(v1[2], v1[3]); return w; }
; __device__ __forceinline__ float row_rstd(const float* ssq, int row) {
;     const f32x4* p = (const f32x4*)(ssq + (size_t)row * 16);
;     const f32x4 a = p[0], b = p[1], c = p[2], d = p[3];
;     const float s = ((a[0] + a[1]) + (a[2] + a[3])) + ((b[0] + b[1]) + (b[2] + b[3])) + ((c[0] + c[1]) + (c[2] + c[3])) + ((d[0] + d[1]) + (d[2] + d[3]));
;     return rsqrtf(s * (1.0f / 1024.0f) + 1e-6f);
; }
;     __device__ __forceinline__ void operator()(const f32x4 (&acc)[2][2][4][2], const Unit& u, int wr, int wc, int fr, int fq) const {
;         const __amdgpu_buffer_rsrc_t rsrc = __builtin_amdgcn_make_buffer_rsrc((void*)O, 0, T_ALL * DFF * 2, 0x00020000);
;         const int row0 = row_off + u.pm * 256 + wr * 64 + fr, col0 = u.pn * 256 + wc * 32 + 8 * fq;
; #pragma unroll
;         for (int ai = 0; ai < 2; ++ai)
; #pragma unroll
;             for (int m = 0; m < 4; ++m) {
;                 const int row = row0 + ai * 128 + m * 16; const float rs = row_rstd(ssq, row);
; #pragma unroll
;                 for (int bj = 0; bj < 2; ++bj) { f32x4 v0 = acc[ai][bj][m][0] * rs, v1 = acc[ai][bj][m][1] * rs;
; #pragma unroll
;                     for (int j = 0; j < 4; ++j) { const float a = fmaxf(v0[j], 0.f), b = fmaxf(v1[j], 0.f); v0[j] = a * a; v1[j] = b * b; }
;                     __builtin_amdgcn_raw_buffer_store_b128(pack8(v0, v1), rsrc, (unsigned)(((size_t)row * DFF + col0 + bj * 128) * 2), 0, 16  ); }
	v_mov_b32_e32 v164, v179
	v_mov_b32_e32 v165, v180
	v_mov_b32_e32 v153, v181
	v_mov_b32_e32 v154, v183
	v_mov_b32_e32 v155, v184
	v_mov_b32_e32 v157, v185
	v_mov_b32_e32 v152, v178
	v_pk_add_f32 v[152:153], v[164:165], v[152:153]
	v_mov_b32_e32 v156, v182
	v_pk_add_f32 v[154:155], v[154:155], v[156:157]
	v_pk_add_f32 v[152:153], v[152:153], v[152:153] op_sel:[0,1] op_sel_hi:[1,0]
	v_pk_add_f32 v[154:155], v[154:155], v[154:155] op_sel:[0,1] op_sel_hi:[1,0]
	v_add_f32_e32 v158, v186, v187
	v_add_f32_e32 v160, v188, v189
	v_mov_b32_e32 v159, v192
	v_mov_b32_e32 v161, v193
	v_mov_b32_e32 v153, v190
	v_mov_b32_e32 v155, v191
	v_pk_add_f32 v[156:157], v[158:159], v[160:161]
	v_pk_add_f32 v[152:153], v[152:153], v[154:155]
	s_nop 0
	v_pk_add_f32 v[152:153], v[152:153], v[156:157]
	s_nop 0
	v_add_f32_e32 v152, v152, v153
	v_fmamk_f32 v152, v152, 0x3a800000, v148
	v_mul_f32_e32 v153, 0x4b800000, v152
	v_cmp_gt_f32_e32 vcc, s71, v152
	s_nop 1
	v_cndmask_b32_e32 v152, v152, v153, vcc
	v_rsq_f32_e32 v154, v152
	v_lshlrev_b64 v[152:153], 6, v[174:175]
	v_lshl_add_u64 v[152:153], s[18:19], 0, v[152:153]
	v_mul_f32_e32 v155, 0x45800000, v154
	v_cndmask_b32_e32 v154, v154, v155, vcc
	v_pk_mul_f32 v[126:127], v[126:127], v[154:155] op_sel_hi:[1,0]
	v_pk_mul_f32 v[124:125], v[124:125], v[154:155] op_sel_hi:[1,0]
	v_pk_mul_f32 v[122:123], v[122:123], v[154:155] op_sel_hi:[1,0]
	v_pk_mul_f32 v[120:121], v[120:121], v[154:155] op_sel_hi:[1,0]
	v_pk_mul_f32 v[114:115], v[114:115], v[154:155] op_sel_hi:[1,0]
	v_pk_mul_f32 v[112:113], v[112:113], v[154:155] op_sel_hi:[1,0]
	v_pk_mul_f32 v[118:119], v[118:119], v[154:155] op_sel_hi:[1,0]
	v_pk_mul_f32 v[116:117], v[116:117], v[154:155] op_sel_hi:[1,0]
	v_max_f32_e32 v124, 0, v124
	v_max_f32_e32 v120, 0, v120
	v_max_f32_e32 v125, 0, v125
	v_max_f32_e32 v121, 0, v121
	v_max_f32_e32 v126, 0, v126
	v_max_f32_e32 v122, 0, v122
	v_max_f32_e32 v127, 0, v127
	v_max_f32_e32 v123, 0, v123
	v_max_f32_e32 v112, 0, v112
	v_max_f32_e32 v113, 0, v113
	v_max_f32_e32 v114, 0, v114
	v_max_f32_e32 v115, 0, v115
	v_max_f32_e32 v116, 0, v116
	v_max_f32_e32 v117, 0, v117
	v_max_f32_e32 v118, 0, v118
	v_max_f32_e32 v119, 0, v119
	v_pk_mul_f32 v[124:125], v[124:125], v[124:125]
	v_pk_mul_f32 v[120:121], v[120:121], v[120:121]
	v_pk_mul_f32 v[126:127], v[126:127], v[126:127]
	v_pk_mul_f32 v[122:123], v[122:123], v[122:123]
	v_pk_mul_f32 v[154:155], v[112:113], v[112:113]
	v_pk_mul_f32 v[156:157], v[114:115], v[114:115]
	v_cvt_pk_bf16_f32 v112, v124, v125
	v_cvt_pk_bf16_f32 v113, v126, v127
	v_cvt_pk_bf16_f32 v114, v120, v121
	v_cvt_pk_bf16_f32 v115, v122, v123
	v_pk_mul_f32 v[116:117], v[116:117], v[116:117]
	v_pk_mul_f32 v[118:119], v[118:119], v[118:119]
	buffer_store_dwordx4 v[112:115], v151, s[12:15], 0 offen sc1
	s_nop 1
	v_cvt_pk_bf16_f32 v112, v116, v117
	v_cvt_pk_bf16_f32 v113, v118, v119
	v_cvt_pk_bf16_f32 v114, v154, v155
	v_cvt_pk_bf16_f32 v115, v156, v157
	buffer_store_dwordx4 v[112:115], v151, s[12:15], 0 offen offset:256 sc1
	s_nop 0
	v_add_u32_e32 v152, 0x4020, v150
	v_ashrrev_i32_e32 v153, 31, v152
	v_lshl_add_u32 v151, v174, 13, v149
	v_add_u32_e32 v177, 0x2000, v176
	global_load_dwordx4 v[178:181], v177, s[18:19]
	v_add_u32_e32 v177, 0x2010, v176
	global_load_dwordx4 v[182:185], v177, s[18:19]
	v_add_u32_e32 v177, 0x2020, v176
	global_load_dwordx4 v[186:189], v177, s[18:19]
	v_add_u32_e32 v177, 0x2030, v176
	global_load_dwordx4 v[190:193], v177, s[18:19]
	s_waitcnt vmcnt(14)
	v_mov_b32_e32 v154, v195
	v_mov_b32_e32 v155, v196
	v_mov_b32_e32 v113, v197
	v_mov_b32_e32 v114, v199
	v_mov_b32_e32 v115, v200
	v_mov_b32_e32 v117, v201
	v_mov_b32_e32 v112, v194
	v_pk_add_f32 v[112:113], v[154:155], v[112:113]
	v_mov_b32_e32 v116, v198
	v_pk_add_f32 v[114:115], v[114:115], v[116:117]
	v_pk_add_f32 v[112:113], v[112:113], v[112:113] op_sel:[0,1] op_sel_hi:[1,0]
	v_pk_add_f32 v[114:115], v[114:115], v[114:115] op_sel:[0,1] op_sel_hi:[1,0]
	v_add_f32_e32 v118, v202, v203
	v_add_f32_e32 v120, v204, v205
	v_mov_b32_e32 v119, v208
	v_mov_b32_e32 v121, v209
	v_mov_b32_e32 v113, v206
	v_mov_b32_e32 v115, v207
	v_pk_add_f32 v[116:117], v[118:119], v[120:121]
	v_pk_add_f32 v[112:113], v[112:113], v[114:115]
	s_nop 0
	v_pk_add_f32 v[112:113], v[112:113], v[116:117]
	s_nop 0
	v_add_f32_e32 v112, v112, v113
	v_fmamk_f32 v112, v112, 0x3a800000, v148
	v_mul_f32_e32 v113, 0x4b800000, v112
	v_cmp_gt_f32_e32 vcc, s71, v112
	s_nop 1
	v_cndmask_b32_e32 v112, v112, v113, vcc
	v_rsq_f32_e32 v114, v112
	v_lshlrev_b64 v[112:113], 6, v[152:153]
	v_lshl_add_u64 v[112:113], s[18:19], 0, v[112:113]
	v_mul_f32_e32 v115, 0x45800000, v114
	v_cndmask_b32_e32 v114, v114, v115, vcc
	v_pk_mul_f32 v[110:111], v[110:111], v[114:115] op_sel_hi:[1,0]
	v_pk_mul_f32 v[108:109], v[108:109], v[114:115] op_sel_hi:[1,0]
	v_pk_mul_f32 v[106:107], v[106:107], v[114:115] op_sel_hi:[1,0]
	v_pk_mul_f32 v[104:105], v[104:105], v[114:115] op_sel_hi:[1,0]
	v_pk_mul_f32 v[98:99], v[98:99], v[114:115] op_sel_hi:[1,0]
	v_pk_mul_f32 v[96:97], v[96:97], v[114:115] op_sel_hi:[1,0]
	v_pk_mul_f32 v[102:103], v[102:103], v[114:115] op_sel_hi:[1,0]
	v_pk_mul_f32 v[100:101], v[100:101], v[114:115] op_sel_hi:[1,0]
	v_max_f32_e32 v108, 0, v108
	v_max_f32_e32 v104, 0, v104
	v_max_f32_e32 v109, 0, v109
	v_max_f32_e32 v105, 0, v105
	v_max_f32_e32 v110, 0, v110
	v_max_f32_e32 v106, 0, v106
	v_max_f32_e32 v111, 0, v111
	v_max_f32_e32 v107, 0, v107
	v_max_f32_e32 v96, 0, v96
	v_max_f32_e32 v97, 0, v97
	v_max_f32_e32 v98, 0, v98
	v_max_f32_e32 v99, 0, v99
	v_max_f32_e32 v100, 0, v100
	v_max_f32_e32 v101, 0, v101
	v_max_f32_e32 v102, 0, v102
	v_max_f32_e32 v103, 0, v103
	v_pk_mul_f32 v[108:109], v[108:109], v[108:109]
	v_pk_mul_f32 v[104:105], v[104:105], v[104:105]
	v_pk_mul_f32 v[110:111], v[110:111], v[110:111]
	v_pk_mul_f32 v[106:107], v[106:107], v[106:107]
	v_pk_mul_f32 v[114:115], v[96:97], v[96:97]
	v_pk_mul_f32 v[116:117], v[98:99], v[98:99]
	v_cvt_pk_bf16_f32 v96, v108, v109
	v_cvt_pk_bf16_f32 v97, v110, v111
	v_cvt_pk_bf16_f32 v98, v104, v105
	v_cvt_pk_bf16_f32 v99, v106, v107
	v_pk_mul_f32 v[100:101], v[100:101], v[100:101]
	v_pk_mul_f32 v[102:103], v[102:103], v[102:103]
	buffer_store_dwordx4 v[96:99], v151, s[12:15], 0 offen sc1
	s_nop 1
	v_cvt_pk_bf16_f32 v96, v100, v101
	v_cvt_pk_bf16_f32 v97, v102, v103
	v_cvt_pk_bf16_f32 v98, v114, v115
	v_cvt_pk_bf16_f32 v99, v116, v117
	buffer_store_dwordx4 v[96:99], v151, s[12:15], 0 offen offset:256 sc1
	s_nop 0
	v_add_u32_e32 v112, 0x4030, v150
	v_ashrrev_i32_e32 v113, 31, v112
	v_lshl_add_u32 v116, v152, 13, v149
	v_add_u32_e32 v177, 0x2400, v176
	global_load_dwordx4 v[194:197], v177, s[18:19]
	v_add_u32_e32 v177, 0x2410, v176
	global_load_dwordx4 v[198:201], v177, s[18:19]
	v_add_u32_e32 v177, 0x2420, v176
	global_load_dwordx4 v[202:205], v177, s[18:19]
	v_add_u32_e32 v177, 0x2430, v176
	global_load_dwordx4 v[206:209], v177, s[18:19]
	s_waitcnt vmcnt(16)
; __device__ __forceinline__ u32x4 pack8(const f32x4 v0, const f32x4 v1) { u32x4 w; w.x = pk2(v0[0], v0[1]); w.y = pk2(v0[2], v0[3]); w.z = pk2(v1[0], v1[1]); w.w = pk2(v1[2], v1[3]); return w; }
; __device__ __forceinline__ float row_rstd(const float* ssq, int row) {
;     const f32x4* p = (const f32x4*)(ssq + (size_t)row * 16);
;     const f32x4 a = p[0], b = p[1], c = p[2], d = p[3];
;     const float s = ((a[0] + a[1]) + (a[2] + a[3])) + ((b[0] + b[1]) + (b[2] + b[3])) + ((c[0] + c[1]) + (c[2] + c[3])) + ((d[0] + d[1]) + (d[2] + d[3]));
;     return rsqrtf(s * (1.0f / 1024.0f) + 1e-6f);
; }
;     __device__ __forceinline__ void operator()(const f32x4 (&acc)[2][2][4][2], const Unit& u, int wr, int wc, int fr, int fq) const {
;         const __amdgpu_buffer_rsrc_t rsrc = __builtin_amdgcn_make_buffer_rsrc((void*)O, 0, T_ALL * DFF * 2, 0x00020000);
;         const int row0 = row_off + u.pm * 256 + wr * 64 + fr, col0 = u.pn * 256 + wc * 32 + 8 * fq;
; #pragma unroll
;         for (int ai = 0; ai < 2; ++ai)
; #pragma unroll
;             for (int m = 0; m < 4; ++m) {
;                 const int row = row0 + ai * 128 + m * 16; const float rs = row_rstd(ssq, row);
; #pragma unroll
;                 for (int bj = 0; bj < 2; ++bj) { f32x4 v0 = acc[ai][bj][m][0] * rs, v1 = acc[ai][bj][m][1] * rs;
; #pragma unroll
;                     for (int j = 0; j < 4; ++j) { const float a = fmaxf(v0[j], 0.f), b = fmaxf(v1[j], 0.f); v0[j] = a * a; v1[j] = b * b; }
;                     __builtin_amdgcn_raw_buffer_store_b128(pack8(v0, v1), rsrc, (unsigned)(((size_t)row * DFF + col0 + bj * 128) * 2), 0, 16  ); }
	v_mov_b32_e32 v114, v211
	v_mov_b32_e32 v115, v212
	v_mov_b32_e32 v97, v213
	v_mov_b32_e32 v98, v215
	v_mov_b32_e32 v99, v216
	v_mov_b32_e32 v101, v217
	v_mov_b32_e32 v96, v210
	v_pk_add_f32 v[96:97], v[114:115], v[96:97]
	v_mov_b32_e32 v100, v214
	v_pk_add_f32 v[98:99], v[98:99], v[100:101]
	v_pk_add_f32 v[96:97], v[96:97], v[96:97] op_sel:[0,1] op_sel_hi:[1,0]
	v_pk_add_f32 v[98:99], v[98:99], v[98:99] op_sel:[0,1] op_sel_hi:[1,0]
	v_add_f32_e32 v102, v232, v233
	v_add_f32_e32 v104, v234, v235
	v_mov_b32_e32 v103, v238
	v_mov_b32_e32 v105, v239
	v_mov_b32_e32 v97, v236
	v_mov_b32_e32 v99, v237
	v_pk_add_f32 v[100:101], v[102:103], v[104:105]
	v_pk_add_f32 v[96:97], v[96:97], v[98:99]
	s_nop 0
	v_pk_add_f32 v[96:97], v[96:97], v[100:101]
	s_nop 0
	v_add_f32_e32 v96, v96, v97
	v_fmamk_f32 v96, v96, 0x3a800000, v148
	v_mul_f32_e32 v97, 0x4b800000, v96
	v_cmp_gt_f32_e32 vcc, s71, v96
	s_nop 1
	v_cndmask_b32_e32 v96, v96, v97, vcc
	v_rsq_f32_e32 v98, v96
	v_lshlrev_b64 v[96:97], 6, v[112:113]
	v_lshl_add_u64 v[96:97], s[18:19], 0, v[96:97]
	v_mul_f32_e32 v99, 0x45800000, v98
	v_cndmask_b32_e32 v98, v98, v99, vcc
	v_pk_mul_f32 v[94:95], v[94:95], v[98:99] op_sel_hi:[1,0]
	v_pk_mul_f32 v[92:93], v[92:93], v[98:99] op_sel_hi:[1,0]
	v_pk_mul_f32 v[90:91], v[90:91], v[98:99] op_sel_hi:[1,0]
	v_pk_mul_f32 v[88:89], v[88:89], v[98:99] op_sel_hi:[1,0]
	v_pk_mul_f32 v[82:83], v[82:83], v[98:99] op_sel_hi:[1,0]
	v_pk_mul_f32 v[80:81], v[80:81], v[98:99] op_sel_hi:[1,0]
	v_pk_mul_f32 v[86:87], v[86:87], v[98:99] op_sel_hi:[1,0]
	v_pk_mul_f32 v[84:85], v[84:85], v[98:99] op_sel_hi:[1,0]
	v_max_f32_e32 v92, 0, v92
	v_max_f32_e32 v88, 0, v88
	v_max_f32_e32 v93, 0, v93
	v_max_f32_e32 v89, 0, v89
	v_max_f32_e32 v94, 0, v94
	v_max_f32_e32 v90, 0, v90
	v_max_f32_e32 v95, 0, v95
	v_max_f32_e32 v91, 0, v91
	v_max_f32_e32 v80, 0, v80
	v_max_f32_e32 v81, 0, v81
	v_max_f32_e32 v82, 0, v82
	v_max_f32_e32 v83, 0, v83
	v_max_f32_e32 v84, 0, v84
	v_max_f32_e32 v85, 0, v85
	v_max_f32_e32 v86, 0, v86
	v_max_f32_e32 v87, 0, v87
	v_pk_mul_f32 v[92:93], v[92:93], v[92:93]
	v_pk_mul_f32 v[88:89], v[88:89], v[88:89]
	v_pk_mul_f32 v[94:95], v[94:95], v[94:95]
	v_pk_mul_f32 v[90:91], v[90:91], v[90:91]
	v_pk_mul_f32 v[98:99], v[80:81], v[80:81]
	v_pk_mul_f32 v[100:101], v[82:83], v[82:83]
	v_cvt_pk_bf16_f32 v80, v92, v93
	v_cvt_pk_bf16_f32 v81, v94, v95
	v_cvt_pk_bf16_f32 v82, v88, v89
	v_cvt_pk_bf16_f32 v83, v90, v91
	v_pk_mul_f32 v[84:85], v[84:85], v[84:85]
	v_pk_mul_f32 v[86:87], v[86:87], v[86:87]
	buffer_store_dwordx4 v[80:83], v116, s[12:15], 0 offen sc1
	s_nop 1
	v_cvt_pk_bf16_f32 v80, v84, v85
	v_cvt_pk_bf16_f32 v81, v86, v87
	v_cvt_pk_bf16_f32 v82, v98, v99
	v_cvt_pk_bf16_f32 v83, v100, v101
	buffer_store_dwordx4 v[80:83], v116, s[12:15], 0 offen offset:256 sc1
	s_nop 0
	v_add_u32_e32 v96, 0x4080, v150
	v_ashrrev_i32_e32 v97, 31, v96
	v_lshl_add_u32 v100, v112, 13, v149
	v_add_u32_e32 v177, 0x2800, v176
	global_load_dwordx4 v[210:213], v177, s[18:19]
	v_add_u32_e32 v177, 0x2810, v176
	global_load_dwordx4 v[214:217], v177, s[18:19]
	v_add_u32_e32 v177, 0x2820, v176
	global_load_dwordx4 v[232:235], v177, s[18:19]
	v_add_u32_e32 v177, 0x2830, v176
	global_load_dwordx4 v[236:239], v177, s[18:19]
	s_waitcnt vmcnt(18)
	v_mov_b32_e32 v98, v241
	v_mov_b32_e32 v99, v242
	v_mov_b32_e32 v81, v243
	v_mov_b32_e32 v82, v245
	v_mov_b32_e32 v83, v246
	v_mov_b32_e32 v85, v247
	v_mov_b32_e32 v80, v240
	v_pk_add_f32 v[80:81], v[98:99], v[80:81]
	v_mov_b32_e32 v84, v244
	v_pk_add_f32 v[82:83], v[82:83], v[84:85]
	v_pk_add_f32 v[80:81], v[80:81], v[80:81] op_sel:[0,1] op_sel_hi:[1,0]
	v_pk_add_f32 v[82:83], v[82:83], v[82:83] op_sel:[0,1] op_sel_hi:[1,0]
	v_add_f32_e32 v86, v248, v249
	v_add_f32_e32 v88, v250, v251
	v_mov_b32_e32 v87, v254
	v_mov_b32_e32 v89, v255
	v_mov_b32_e32 v81, v252
	v_mov_b32_e32 v83, v253
	v_pk_add_f32 v[84:85], v[86:87], v[88:89]
	v_pk_add_f32 v[80:81], v[80:81], v[82:83]
	s_nop 0
	v_pk_add_f32 v[80:81], v[80:81], v[84:85]
	s_nop 0
	v_add_f32_e32 v80, v80, v81
	v_fmamk_f32 v80, v80, 0x3a800000, v148
	v_mul_f32_e32 v81, 0x4b800000, v80
	v_cmp_gt_f32_e32 vcc, s71, v80
	s_nop 1
	v_cndmask_b32_e32 v80, v80, v81, vcc
	v_rsq_f32_e32 v82, v80
	v_lshlrev_b64 v[80:81], 6, v[96:97]
	v_lshl_add_u64 v[80:81], s[18:19], 0, v[80:81]
	v_mul_f32_e32 v83, 0x45800000, v82
	v_cndmask_b32_e32 v82, v82, v83, vcc
	v_pk_mul_f32 v[78:79], v[78:79], v[82:83] op_sel_hi:[1,0]
	v_pk_mul_f32 v[76:77], v[76:77], v[82:83] op_sel_hi:[1,0]
	v_pk_mul_f32 v[74:75], v[74:75], v[82:83] op_sel_hi:[1,0]
	v_pk_mul_f32 v[72:73], v[72:73], v[82:83] op_sel_hi:[1,0]
	v_pk_mul_f32 v[66:67], v[66:67], v[82:83] op_sel_hi:[1,0]
	v_pk_mul_f32 v[64:65], v[64:65], v[82:83] op_sel_hi:[1,0]
	v_pk_mul_f32 v[70:71], v[70:71], v[82:83] op_sel_hi:[1,0]
	v_pk_mul_f32 v[68:69], v[68:69], v[82:83] op_sel_hi:[1,0]
	v_max_f32_e32 v76, 0, v76
	v_max_f32_e32 v72, 0, v72
	v_max_f32_e32 v77, 0, v77
	v_max_f32_e32 v73, 0, v73
	v_max_f32_e32 v78, 0, v78
	v_max_f32_e32 v74, 0, v74
	v_max_f32_e32 v79, 0, v79
	v_max_f32_e32 v75, 0, v75
	v_max_f32_e32 v64, 0, v64
	v_max_f32_e32 v65, 0, v65
	v_max_f32_e32 v66, 0, v66
	v_max_f32_e32 v67, 0, v67
	v_max_f32_e32 v68, 0, v68
	v_max_f32_e32 v69, 0, v69
	v_max_f32_e32 v70, 0, v70
	v_max_f32_e32 v71, 0, v71
	v_pk_mul_f32 v[76:77], v[76:77], v[76:77]
	v_pk_mul_f32 v[72:73], v[72:73], v[72:73]
	v_pk_mul_f32 v[78:79], v[78:79], v[78:79]
	v_pk_mul_f32 v[74:75], v[74:75], v[74:75]
	v_pk_mul_f32 v[82:83], v[64:65], v[64:65]
	v_pk_mul_f32 v[84:85], v[66:67], v[66:67]
	v_cvt_pk_bf16_f32 v64, v76, v77
	v_cvt_pk_bf16_f32 v65, v78, v79
	v_cvt_pk_bf16_f32 v66, v72, v73
	v_cvt_pk_bf16_f32 v67, v74, v75
	v_pk_mul_f32 v[68:69], v[68:69], v[68:69]
	v_pk_mul_f32 v[70:71], v[70:71], v[70:71]
	buffer_store_dwordx4 v[64:67], v100, s[12:15], 0 offen sc1
	s_nop 1
	v_cvt_pk_bf16_f32 v64, v68, v69
	v_cvt_pk_bf16_f32 v65, v70, v71
	v_cvt_pk_bf16_f32 v66, v82, v83
	v_cvt_pk_bf16_f32 v67, v84, v85
	buffer_store_dwordx4 v[64:67], v100, s[12:15], 0 offen offset:256 sc1
	s_nop 0
	v_add_u32_e32 v80, 0x4090, v150
	v_ashrrev_i32_e32 v81, 31, v80
	v_lshl_add_u32 v84, v96, 13, v149
	v_add_u32_e32 v177, 0x2c00, v176
	global_load_dwordx4 v[240:243], v177, s[18:19]
	v_add_u32_e32 v177, 0x2c10, v176
	global_load_dwordx4 v[244:247], v177, s[18:19]
	v_add_u32_e32 v177, 0x2c20, v176
	global_load_dwordx4 v[248:251], v177, s[18:19]
	v_add_u32_e32 v177, 0x2c30, v176
	global_load_dwordx4 v[252:255], v177, s[18:19]
	s_waitcnt vmcnt(18)
; __device__ __forceinline__ u32x4 pack8(const f32x4 v0, const f32x4 v1) { u32x4 w; w.x = pk2(v0[0], v0[1]); w.y = pk2(v0[2], v0[3]); w.z = pk2(v1[0], v1[1]); w.w = pk2(v1[2], v1[3]); return w; }
; __device__ __forceinline__ float row_rstd(const float* ssq, int row) {
;     const f32x4* p = (const f32x4*)(ssq + (size_t)row * 16);
;     const f32x4 a = p[0], b = p[1], c = p[2], d = p[3];
;     const float s = ((a[0] + a[1]) + (a[2] + a[3])) + ((b[0] + b[1]) + (b[2] + b[3])) + ((c[0] + c[1]) + (c[2] + c[3])) + ((d[0] + d[1]) + (d[2] + d[3]));
;     return rsqrtf(s * (1.0f / 1024.0f) + 1e-6f);
; }
;     __device__ __forceinline__ void operator()(const f32x4 (&acc)[2][2][4][2], const Unit& u, int wr, int wc, int fr, int fq) const {
;         const __amdgpu_buffer_rsrc_t rsrc = __builtin_amdgcn_make_buffer_rsrc((void*)O, 0, T_ALL * DFF * 2, 0x00020000);
;         const int row0 = row_off + u.pm * 256 + wr * 64 + fr, col0 = u.pn * 256 + wc * 32 + 8 * fq;
; #pragma unroll
;         for (int ai = 0; ai < 2; ++ai)
; #pragma unroll
;             for (int m = 0; m < 4; ++m) {
;                 const int row = row0 + ai * 128 + m * 16; const float rs = row_rstd(ssq, row);
; #pragma unroll
;                 for (int bj = 0; bj < 2; ++bj) { f32x4 v0 = acc[ai][bj][m][0] * rs, v1 = acc[ai][bj][m][1] * rs;
; #pragma unroll
;                     for (int j = 0; j < 4; ++j) { const float a = fmaxf(v0[j], 0.f), b = fmaxf(v1[j], 0.f); v0[j] = a * a; v1[j] = b * b; }
;                     __builtin_amdgcn_raw_buffer_store_b128(pack8(v0, v1), rsrc, (unsigned)(((size_t)row * DFF + col0 + bj * 128) * 2), 0, 16  ); }
	v_mov_b32_e32 v82, v179
	v_mov_b32_e32 v83, v180
	v_mov_b32_e32 v65, v181
	v_mov_b32_e32 v66, v183
	v_mov_b32_e32 v67, v184
	v_mov_b32_e32 v69, v185
	v_mov_b32_e32 v64, v178
	v_pk_add_f32 v[64:65], v[82:83], v[64:65]
	v_mov_b32_e32 v68, v182
	v_pk_add_f32 v[66:67], v[66:67], v[68:69]
	v_pk_add_f32 v[64:65], v[64:65], v[64:65] op_sel:[0,1] op_sel_hi:[1,0]
	v_pk_add_f32 v[66:67], v[66:67], v[66:67] op_sel:[0,1] op_sel_hi:[1,0]
	v_add_f32_e32 v70, v186, v187
	v_add_f32_e32 v72, v188, v189
	v_mov_b32_e32 v71, v192
	v_mov_b32_e32 v73, v193
	v_mov_b32_e32 v65, v190
	v_mov_b32_e32 v67, v191
	v_pk_add_f32 v[68:69], v[70:71], v[72:73]
	v_pk_add_f32 v[64:65], v[64:65], v[66:67]
	s_nop 0
	v_pk_add_f32 v[64:65], v[64:65], v[68:69]
	s_nop 0
	v_add_f32_e32 v64, v64, v65
	v_fmamk_f32 v64, v64, 0x3a800000, v148
	v_mul_f32_e32 v65, 0x4b800000, v64
	v_cmp_gt_f32_e32 vcc, s71, v64
	s_nop 1
	v_cndmask_b32_e32 v64, v64, v65, vcc
	v_rsq_f32_e32 v66, v64
	v_lshlrev_b64 v[64:65], 6, v[80:81]
	v_lshl_add_u64 v[64:65], s[18:19], 0, v[64:65]
	v_mul_f32_e32 v67, 0x45800000, v66
	v_cndmask_b32_e32 v66, v66, v67, vcc
	v_pk_mul_f32 v[62:63], v[62:63], v[66:67] op_sel_hi:[1,0]
	v_pk_mul_f32 v[60:61], v[60:61], v[66:67] op_sel_hi:[1,0]
	v_pk_mul_f32 v[58:59], v[58:59], v[66:67] op_sel_hi:[1,0]
	v_pk_mul_f32 v[56:57], v[56:57], v[66:67] op_sel_hi:[1,0]
	v_pk_mul_f32 v[50:51], v[50:51], v[66:67] op_sel_hi:[1,0]
	v_pk_mul_f32 v[48:49], v[48:49], v[66:67] op_sel_hi:[1,0]
	v_pk_mul_f32 v[54:55], v[54:55], v[66:67] op_sel_hi:[1,0]
	v_pk_mul_f32 v[52:53], v[52:53], v[66:67] op_sel_hi:[1,0]
	v_max_f32_e32 v60, 0, v60
	v_max_f32_e32 v56, 0, v56
	v_max_f32_e32 v61, 0, v61
	v_max_f32_e32 v57, 0, v57
	v_max_f32_e32 v62, 0, v62
	v_max_f32_e32 v58, 0, v58
	v_max_f32_e32 v63, 0, v63
	v_max_f32_e32 v59, 0, v59
	v_max_f32_e32 v48, 0, v48
	v_max_f32_e32 v49, 0, v49
	v_max_f32_e32 v50, 0, v50
	v_max_f32_e32 v51, 0, v51
	v_max_f32_e32 v52, 0, v52
	v_max_f32_e32 v53, 0, v53
	v_max_f32_e32 v54, 0, v54
	v_max_f32_e32 v55, 0, v55
	v_pk_mul_f32 v[60:61], v[60:61], v[60:61]
	v_pk_mul_f32 v[56:57], v[56:57], v[56:57]
	v_pk_mul_f32 v[62:63], v[62:63], v[62:63]
	v_pk_mul_f32 v[58:59], v[58:59], v[58:59]
	v_pk_mul_f32 v[66:67], v[48:49], v[48:49]
	v_pk_mul_f32 v[68:69], v[50:51], v[50:51]
	v_cvt_pk_bf16_f32 v48, v60, v61
	v_cvt_pk_bf16_f32 v49, v62, v63
	v_cvt_pk_bf16_f32 v50, v56, v57
	v_cvt_pk_bf16_f32 v51, v58, v59
	v_pk_mul_f32 v[52:53], v[52:53], v[52:53]
	v_pk_mul_f32 v[54:55], v[54:55], v[54:55]
	buffer_store_dwordx4 v[48:51], v84, s[12:15], 0 offen sc1
	s_nop 1
	v_cvt_pk_bf16_f32 v48, v52, v53
	v_cvt_pk_bf16_f32 v49, v54, v55
	v_cvt_pk_bf16_f32 v50, v66, v67
	v_cvt_pk_bf16_f32 v51, v68, v69
	buffer_store_dwordx4 v[48:51], v84, s[12:15], 0 offen offset:256 sc1
	s_nop 0
	v_add_u32_e32 v64, 0x40a0, v150
	v_ashrrev_i32_e32 v65, 31, v64
	v_lshl_add_u32 v68, v80, 13, v149
	s_waitcnt vmcnt(14)
	v_mov_b32_e32 v66, v195
	v_mov_b32_e32 v67, v196
	v_mov_b32_e32 v49, v197
	v_mov_b32_e32 v50, v199
	v_mov_b32_e32 v51, v200
	v_mov_b32_e32 v53, v201
	v_mov_b32_e32 v48, v194
	v_pk_add_f32 v[48:49], v[66:67], v[48:49]
	v_mov_b32_e32 v52, v198
	v_pk_add_f32 v[50:51], v[50:51], v[52:53]
	v_pk_add_f32 v[48:49], v[48:49], v[48:49] op_sel:[0,1] op_sel_hi:[1,0]
	v_pk_add_f32 v[50:51], v[50:51], v[50:51] op_sel:[0,1] op_sel_hi:[1,0]
	v_add_f32_e32 v54, v202, v203
	v_add_f32_e32 v56, v204, v205
	v_mov_b32_e32 v55, v208
	v_mov_b32_e32 v57, v209
	v_mov_b32_e32 v49, v206
	v_mov_b32_e32 v51, v207
	v_pk_add_f32 v[52:53], v[54:55], v[56:57]
	v_pk_add_f32 v[48:49], v[48:49], v[50:51]
	s_nop 0
	v_pk_add_f32 v[48:49], v[48:49], v[52:53]
	s_nop 0
	v_add_f32_e32 v48, v48, v49
	v_fmamk_f32 v48, v48, 0x3a800000, v148
	v_mul_f32_e32 v49, 0x4b800000, v48
	v_cmp_gt_f32_e32 vcc, s71, v48
	s_nop 1
	v_cndmask_b32_e32 v48, v48, v49, vcc
	v_rsq_f32_e32 v50, v48
	v_lshlrev_b64 v[48:49], 6, v[64:65]
	v_lshl_add_u64 v[48:49], s[18:19], 0, v[48:49]
	v_mul_f32_e32 v51, 0x45800000, v50
	v_cndmask_b32_e32 v50, v50, v51, vcc
	v_pk_mul_f32 v[46:47], v[46:47], v[50:51] op_sel_hi:[1,0]
	v_pk_mul_f32 v[44:45], v[44:45], v[50:51] op_sel_hi:[1,0]
	v_pk_mul_f32 v[42:43], v[42:43], v[50:51] op_sel_hi:[1,0]
	v_pk_mul_f32 v[40:41], v[40:41], v[50:51] op_sel_hi:[1,0]
	v_pk_mul_f32 v[34:35], v[34:35], v[50:51] op_sel_hi:[1,0]
	v_pk_mul_f32 v[32:33], v[32:33], v[50:51] op_sel_hi:[1,0]
	v_pk_mul_f32 v[38:39], v[38:39], v[50:51] op_sel_hi:[1,0]
	v_pk_mul_f32 v[36:37], v[36:37], v[50:51] op_sel_hi:[1,0]
	v_max_f32_e32 v44, 0, v44
	v_max_f32_e32 v40, 0, v40
	v_max_f32_e32 v45, 0, v45
	v_max_f32_e32 v41, 0, v41
	v_max_f32_e32 v46, 0, v46
	v_max_f32_e32 v42, 0, v42
	v_max_f32_e32 v47, 0, v47
	v_max_f32_e32 v43, 0, v43
	v_max_f32_e32 v32, 0, v32
	v_max_f32_e32 v33, 0, v33
	v_max_f32_e32 v34, 0, v34
	v_max_f32_e32 v35, 0, v35
	v_max_f32_e32 v36, 0, v36
	v_max_f32_e32 v37, 0, v37
	v_max_f32_e32 v38, 0, v38
	v_max_f32_e32 v39, 0, v39
	v_pk_mul_f32 v[44:45], v[44:45], v[44:45]
	v_pk_mul_f32 v[40:41], v[40:41], v[40:41]
	v_pk_mul_f32 v[46:47], v[46:47], v[46:47]
	v_pk_mul_f32 v[42:43], v[42:43], v[42:43]
	v_pk_mul_f32 v[50:51], v[32:33], v[32:33]
	v_pk_mul_f32 v[52:53], v[34:35], v[34:35]
	v_cvt_pk_bf16_f32 v32, v44, v45
	v_cvt_pk_bf16_f32 v33, v46, v47
	v_cvt_pk_bf16_f32 v34, v40, v41
	v_cvt_pk_bf16_f32 v35, v42, v43
	v_pk_mul_f32 v[36:37], v[36:37], v[36:37]
	v_pk_mul_f32 v[38:39], v[38:39], v[38:39]
	buffer_store_dwordx4 v[32:35], v68, s[12:15], 0 offen sc1
	s_nop 1
	v_cvt_pk_bf16_f32 v32, v36, v37
	v_cvt_pk_bf16_f32 v33, v38, v39
	v_cvt_pk_bf16_f32 v34, v50, v51
	v_cvt_pk_bf16_f32 v35, v52, v53
	buffer_store_dwordx4 v[32:35], v68, s[12:15], 0 offen offset:256 sc1
	s_nop 0
	v_add_u32_e32 v48, 0x40b0, v150
	v_ashrrev_i32_e32 v49, 31, v48
	v_lshl_add_u32 v52, v64, 13, v149
	s_waitcnt vmcnt(10)
; __device__ __forceinline__ u32x4 pack8(const f32x4 v0, const f32x4 v1) { u32x4 w; w.x = pk2(v0[0], v0[1]); w.y = pk2(v0[2], v0[3]); w.z = pk2(v1[0], v1[1]); w.w = pk2(v1[2], v1[3]); return w; }
; __device__ __forceinline__ float row_rstd(const float* ssq, int row) {
;     const f32x4* p = (const f32x4*)(ssq + (size_t)row * 16);
;     const f32x4 a = p[0], b = p[1], c = p[2], d = p[3];
;     const float s = ((a[0] + a[1]) + (a[2] + a[3])) + ((b[0] + b[1]) + (b[2] + b[3])) + ((c[0] + c[1]) + (c[2] + c[3])) + ((d[0] + d[1]) + (d[2] + d[3]));
;     return rsqrtf(s * (1.0f / 1024.0f) + 1e-6f);
; }
;     __device__ __forceinline__ void operator()(const f32x4 (&acc)[2][2][4][2], const Unit& u, int wr, int wc, int fr, int fq) const {
;         const __amdgpu_buffer_rsrc_t rsrc = __builtin_amdgcn_make_buffer_rsrc((void*)O, 0, T_ALL * DFF * 2, 0x00020000);
;         const int row0 = row_off + u.pm * 256 + wr * 64 + fr, col0 = u.pn * 256 + wc * 32 + 8 * fq;
; #pragma unroll
;         for (int ai = 0; ai < 2; ++ai)
; #pragma unroll
;             for (int m = 0; m < 4; ++m) {
;                 const int row = row0 + ai * 128 + m * 16; const float rs = row_rstd(ssq, row);
; #pragma unroll
;                 for (int bj = 0; bj < 2; ++bj) { f32x4 v0 = acc[ai][bj][m][0] * rs, v1 = acc[ai][bj][m][1] * rs;
; #pragma unroll
;                     for (int j = 0; j < 4; ++j) { const float a = fmaxf(v0[j], 0.f), b = fmaxf(v1[j], 0.f); v0[j] = a * a; v1[j] = b * b; }
;                     __builtin_amdgcn_raw_buffer_store_b128(pack8(v0, v1), rsrc, (unsigned)(((size_t)row * DFF + col0 + bj * 128) * 2), 0, 16  ); }
;             }
;         asm volatile("s_waitcnt vmcnt(0)" ::: "memory");
;         if (fr == 0 && fq == 0) (void)__hip_atomic_fetch_add(ready + 64 * (pm_off + u.pm), 1u, __ATOMIC_RELAXED, __HIP_MEMORY_SCOPE_AGENT);
;     }
	v_mov_b32_e32 v50, v211
	v_mov_b32_e32 v51, v212
	v_mov_b32_e32 v33, v213
	v_mov_b32_e32 v34, v215
	v_mov_b32_e32 v35, v216
	v_mov_b32_e32 v37, v217
	v_mov_b32_e32 v32, v210
	v_pk_add_f32 v[32:33], v[50:51], v[32:33]
	v_mov_b32_e32 v36, v214
	v_pk_add_f32 v[34:35], v[34:35], v[36:37]
	v_pk_add_f32 v[32:33], v[32:33], v[32:33] op_sel:[0,1] op_sel_hi:[1,0]
	v_pk_add_f32 v[34:35], v[34:35], v[34:35] op_sel:[0,1] op_sel_hi:[1,0]
	v_add_f32_e32 v38, v232, v233
	v_add_f32_e32 v40, v234, v235
	v_mov_b32_e32 v39, v238
	v_mov_b32_e32 v41, v239
	v_mov_b32_e32 v33, v236
	v_mov_b32_e32 v35, v237
	v_pk_add_f32 v[36:37], v[38:39], v[40:41]
	v_pk_add_f32 v[32:33], v[32:33], v[34:35]
	s_nop 0
	v_pk_add_f32 v[32:33], v[32:33], v[36:37]
	s_nop 0
	v_add_f32_e32 v32, v32, v33
	v_fmamk_f32 v32, v32, 0x3a800000, v148
	v_mul_f32_e32 v33, 0x4b800000, v32
	v_cmp_gt_f32_e32 vcc, s71, v32
	s_nop 1
	v_cndmask_b32_e32 v32, v32, v33, vcc
	v_rsq_f32_e32 v34, v32
	v_lshlrev_b64 v[32:33], 6, v[48:49]
	v_lshl_add_u64 v[32:33], s[18:19], 0, v[32:33]
	v_mul_f32_e32 v35, 0x45800000, v34
	v_cndmask_b32_e32 v34, v34, v35, vcc
	v_pk_mul_f32 v[30:31], v[30:31], v[34:35] op_sel_hi:[1,0]
	v_pk_mul_f32 v[28:29], v[28:29], v[34:35] op_sel_hi:[1,0]
	v_pk_mul_f32 v[26:27], v[26:27], v[34:35] op_sel_hi:[1,0]
	v_pk_mul_f32 v[24:25], v[24:25], v[34:35] op_sel_hi:[1,0]
	v_pk_mul_f32 v[18:19], v[18:19], v[34:35] op_sel_hi:[1,0]
	v_pk_mul_f32 v[16:17], v[16:17], v[34:35] op_sel_hi:[1,0]
	v_pk_mul_f32 v[22:23], v[22:23], v[34:35] op_sel_hi:[1,0]
	v_pk_mul_f32 v[20:21], v[20:21], v[34:35] op_sel_hi:[1,0]
	v_max_f32_e32 v28, 0, v28
	v_max_f32_e32 v24, 0, v24
	v_max_f32_e32 v29, 0, v29
	v_max_f32_e32 v25, 0, v25
	v_max_f32_e32 v30, 0, v30
	v_max_f32_e32 v26, 0, v26
	v_max_f32_e32 v31, 0, v31
	v_max_f32_e32 v27, 0, v27
	v_max_f32_e32 v16, 0, v16
	v_max_f32_e32 v17, 0, v17
	v_max_f32_e32 v18, 0, v18
	v_max_f32_e32 v19, 0, v19
	v_max_f32_e32 v20, 0, v20
	v_max_f32_e32 v21, 0, v21
	v_max_f32_e32 v22, 0, v22
	v_max_f32_e32 v23, 0, v23
	v_pk_mul_f32 v[28:29], v[28:29], v[28:29]
	v_pk_mul_f32 v[24:25], v[24:25], v[24:25]
	v_pk_mul_f32 v[30:31], v[30:31], v[30:31]
	v_pk_mul_f32 v[26:27], v[26:27], v[26:27]
	v_pk_mul_f32 v[34:35], v[16:17], v[16:17]
	v_pk_mul_f32 v[36:37], v[18:19], v[18:19]
	v_cvt_pk_bf16_f32 v16, v28, v29
	v_cvt_pk_bf16_f32 v17, v30, v31
	v_cvt_pk_bf16_f32 v18, v24, v25
	v_cvt_pk_bf16_f32 v19, v26, v27
	v_pk_mul_f32 v[20:21], v[20:21], v[20:21]
	v_pk_mul_f32 v[22:23], v[22:23], v[22:23]
	buffer_store_dwordx4 v[16:19], v52, s[12:15], 0 offen sc1
	s_nop 1
	v_cvt_pk_bf16_f32 v16, v20, v21
	v_cvt_pk_bf16_f32 v17, v22, v23
	v_cvt_pk_bf16_f32 v18, v34, v35
	v_cvt_pk_bf16_f32 v19, v36, v37
	buffer_store_dwordx4 v[16:19], v52, s[12:15], 0 offen offset:256 sc1
	s_nop 0
	s_waitcnt vmcnt(6)
	v_mov_b32_e32 v32, v241
	v_mov_b32_e32 v33, v242
	v_mov_b32_e32 v17, v243
	v_mov_b32_e32 v18, v245
	v_mov_b32_e32 v19, v246
	v_mov_b32_e32 v21, v247
	v_mov_b32_e32 v16, v240
	v_pk_add_f32 v[16:17], v[32:33], v[16:17]
	v_mov_b32_e32 v20, v244
	v_pk_add_f32 v[18:19], v[18:19], v[20:21]
	v_pk_add_f32 v[16:17], v[16:17], v[16:17] op_sel:[0,1] op_sel_hi:[1,0]
	v_pk_add_f32 v[18:19], v[18:19], v[18:19] op_sel:[0,1] op_sel_hi:[1,0]
	v_add_f32_e32 v22, v248, v249
	v_add_f32_e32 v24, v250, v251
	v_mov_b32_e32 v23, v254
	v_mov_b32_e32 v25, v255
	v_mov_b32_e32 v17, v252
	v_mov_b32_e32 v19, v253
	v_pk_add_f32 v[20:21], v[22:23], v[24:25]
	v_pk_add_f32 v[16:17], v[16:17], v[18:19]
	s_nop 0
	v_pk_add_f32 v[16:17], v[16:17], v[20:21]
	s_nop 0
	v_add_f32_e32 v16, v16, v17
	v_fmamk_f32 v16, v16, 0x3a800000, v148
	v_mul_f32_e32 v17, 0x4b800000, v16
	v_cmp_gt_f32_e32 vcc, s71, v16
	s_nop 1
	v_cndmask_b32_e32 v16, v16, v17, vcc
	v_rsq_f32_e32 v16, v16
	v_lshl_add_u32 v17, v48, 13, v149
	v_mul_f32_e32 v18, 0x45800000, v16
	v_cndmask_b32_e32 v16, v16, v18, vcc
	v_pk_mul_f32 v[14:15], v[14:15], v[16:17] op_sel_hi:[1,0]
	v_pk_mul_f32 v[12:13], v[12:13], v[16:17] op_sel_hi:[1,0]
	v_pk_mul_f32 v[10:11], v[10:11], v[16:17] op_sel_hi:[1,0]
	v_pk_mul_f32 v[8:9], v[8:9], v[16:17] op_sel_hi:[1,0]
	v_pk_mul_f32 v[2:3], v[2:3], v[16:17] op_sel_hi:[1,0]
	v_pk_mul_f32 v[0:1], v[0:1], v[16:17] op_sel_hi:[1,0]
	v_pk_mul_f32 v[6:7], v[6:7], v[16:17] op_sel_hi:[1,0]
	v_pk_mul_f32 v[4:5], v[4:5], v[16:17] op_sel_hi:[1,0]
	v_max_f32_e32 v12, 0, v12
	v_max_f32_e32 v8, 0, v8
	v_max_f32_e32 v13, 0, v13
	v_max_f32_e32 v9, 0, v9
	v_max_f32_e32 v14, 0, v14
	v_max_f32_e32 v10, 0, v10
	v_max_f32_e32 v15, 0, v15
	v_max_f32_e32 v11, 0, v11
	v_max_f32_e32 v0, 0, v0
	v_max_f32_e32 v1, 0, v1
	v_max_f32_e32 v2, 0, v2
	v_max_f32_e32 v3, 0, v3
	v_max_f32_e32 v4, 0, v4
	v_max_f32_e32 v5, 0, v5
	v_max_f32_e32 v6, 0, v6
	v_max_f32_e32 v7, 0, v7
	v_pk_mul_f32 v[12:13], v[12:13], v[12:13]
	v_pk_mul_f32 v[8:9], v[8:9], v[8:9]
	v_pk_mul_f32 v[14:15], v[14:15], v[14:15]
	v_pk_mul_f32 v[10:11], v[10:11], v[10:11]
	v_mul_f32_e32 v16, v0, v0
	v_mul_f32_e32 v18, v1, v1
	v_mul_f32_e32 v19, v2, v2
	v_mul_f32_e32 v20, v3, v3
	v_cvt_pk_bf16_f32 v0, v12, v13
	v_cvt_pk_bf16_f32 v1, v14, v15
	v_cvt_pk_bf16_f32 v2, v8, v9
	v_cvt_pk_bf16_f32 v3, v10, v11
	v_pk_mul_f32 v[4:5], v[4:5], v[4:5]
	v_pk_mul_f32 v[6:7], v[6:7], v[6:7]
	buffer_store_dwordx4 v[0:3], v17, s[12:15], 0 offen sc1
	s_nop 1
	v_cvt_pk_bf16_f32 v0, v4, v5
	v_cvt_pk_bf16_f32 v1, v6, v7
	v_cvt_pk_bf16_f32 v2, v16, v18
	v_cvt_pk_bf16_f32 v3, v19, v20
	buffer_store_dwordx4 v[0:3], v17, s[12:15], 0 offen offset:256 sc1
	s_waitcnt vmcnt(0)
	s_and_saveexec_b64 s[38:39], s[10:11]
	s_cbranch_execz .LBB0_973
	s_mov_b64 s[40:41], exec
	v_mbcnt_lo_u32_b32 v0, s40, 0
	v_mbcnt_hi_u32_b32 v0, s41, v0
	v_cmp_eq_u32_e32 vcc, 0, v0
	s_and_b64 s[6:7], exec, vcc
	s_mov_b64 exec, s[6:7]
	s_cbranch_execz .LBB0_973
	s_lshl_b32 s6, s75, 6
	s_addk_i32 s6, 0x1000
	s_ashr_i32 s7, s6, 31
	s_lshl_b64 s[6:7], s[6:7], 2
	s_add_u32 s6, s73, s6
	s_addc_u32 s7, s74, s7
	s_bcnt1_i32_b64 s8, s[40:41]
	v_mov_b32_e32 v0, s8
	global_atomic_add v131, v0, s[6:7]
	s_branch .LBB0_973

; #define PG8_STAGE(bufoff, gbase, voff) do { _Pragma("unroll") for (int _i = 0; _i < 2; ++_i) \
;         __builtin_amdgcn_global_load_lds((const unsigned*)((const char*)(gbase) + (voff)[_i]), (LAS unsigned*)(lds + (bufoff) + ldsw + _i * 8192), 16, 0, 0); } while (0)
; #define PG8_LDA(dst, b, h) do { _Pragma("unroll") for (int m = 0; m < 4; ++m) _Pragma("unroll") for (int k = 0; k < 2; ++k) dst[m][k] = *(const LAS bf16x8*)(lds + PG8_SA(b, h) + aoff + m * 2048 + k * 1024); } while (0)
; #define PG8_LDB(dst, b, h) do { _Pragma("unroll") for (int n = 0; n < 2; ++n) _Pragma("unroll") for (int k = 0; k < 2; ++k) dst[n][k] = *(const LAS bf16x8*)(lds + PG8_SB(b, h) + boff + n * 2048 + k * 1024); } while (0)
; #define PG8_MMA(ai, bj, At, Bt) do { __builtin_amdgcn_s_setprio(1); _Pragma("unroll") for (int m = 0; m < 4; ++m) _Pragma("unroll") for (int n = 0; n < 2; ++n) _Pragma("unroll") for (int k = 0; k < 2; ++k) \
;         acc[ai][bj][m][n] = __builtin_amdgcn_mfma_f32_16x16x32_bf16(Bt[n][k], At[m][k], acc[ai][bj][m][n], 0, 0, 0); __builtin_amdgcn_s_setprio(0); } while (0)
; #define PG8_WAIT_L(n) asm volatile("s_waitcnt lgkmcnt(" #n ")" ::: "memory")
; #define PG8_BAR __builtin_amdgcn_s_barrier()
; #define PG8_SCHED __builtin_amdgcn_sched_barrier(0)
;     ...
;         for (int t = 0; t < nt; t += 2) {
;             const bool last = (t == nt - 2);
;             const char* a1 = cA + (size_t)(t + 1) * kstep;
;             const char* a2 = last ? nA : cA + (size_t)(t + 2) * kstep; const char* b2 = last ? nB : cB + (size_t)(t + 2) * kstep;
;             const char* a3 = a2 + kstep; const char* b3 = b2 + kstep;
;             if (last && has_next) PG8_A_READY(nxt);
;             PG8_LDB(B0, 0, 0); PG8_SCHED; PG8_LDA(At, 0, 0); PG8_STAGE(PG8_SA(1, 1), a1 + hA, voffA);
;             PG8_WAIT_L(8); PG8_BAR; PG8_WAIT_L(0); PG8_MMA(0, 0, At, B0); PG8_BAR; PG8_SCHED;
;             PG8_LDB(B1, 0, 1); PG8_STAGE(PG8_SB(0, 0), b2, voffB);
;             PG8_BAR; PG8_WAIT_L(0); PG8_MMA(0, 1, At, B1); PG8_BAR;
;             PG8_LDA(At, 0, 1); PG8_STAGE(PG8_SA(0, 0), a2, voffA);
;             PG8_BAR; PG8_WAIT_L(0); PG8_MMA(1, 0, At, B0); PG8_BAR; PG8_SCHED;
;             PG8_STAGE(PG8_SB(0, 1), b2 + hB, voffB);
.LBB0_1288:
	ds_read_b128 v[146:149], v155
	ds_read_b128 v[160:163], v155 offset:1024
	ds_read_b128 v[170:173], v155 offset:2048
	ds_read_b128 v[174:177], v155 offset:3072
	s_add_u32 s36, s34, 0xfffc0080
	s_addc_u32 s37, s35, -1
	s_cmp_eq_u32 s42, 12
	s_cselect_b32 s39, s7, s37
	s_cselect_b32 s38, s8, s36
	s_cselect_b32 s37, s9, s33
	s_cselect_b32 s36, s23, s25
	v_lshl_add_u64 v[150:151], s[34:35], 0, v[138:139]
	s_add_i32 m0, s31, 0xc000
	ds_read_b128 v[178:181], v156
	ds_read_b128 v[182:185], v156 offset:1024
	ds_read_b128 v[186:189], v156 offset:2048
	ds_read_b128 v[190:193], v156 offset:3072
	ds_read_b128 v[194:197], v156 offset:4096
	ds_read_b128 v[198:201], v156 offset:5120
	ds_read_b128 v[202:205], v156 offset:6144
	ds_read_b128 v[206:209], v156 offset:7168
	global_load_lds_dwordx4 v[150:151], off
	v_lshl_add_u64 v[150:151], s[34:35], 0, v[136:137]
	s_add_i32 m0, s31, 0xe000
	s_nop 0
	global_load_lds_dwordx4 v[150:151], off
	s_waitcnt lgkmcnt(8)
	s_barrier
	s_waitcnt lgkmcnt(0)
	s_setprio 1
	s_waitcnt lgkmcnt(0)
	v_mfma_f32_16x16x32_bf16 v[124:127], v[146:149], v[178:181], v[124:127]
	v_mfma_f32_16x16x32_bf16 v[120:123], v[170:173], v[178:181], v[120:123]
	v_mfma_f32_16x16x32_bf16 v[108:111], v[146:149], v[186:189], v[108:111]
	v_mfma_f32_16x16x32_bf16 v[104:107], v[170:173], v[186:189], v[104:107]
	v_mfma_f32_16x16x32_bf16 v[92:95], v[146:149], v[194:197], v[92:95]
	v_mfma_f32_16x16x32_bf16 v[88:91], v[170:173], v[194:197], v[88:91]
	v_mfma_f32_16x16x32_bf16 v[76:79], v[146:149], v[202:205], v[76:79]
	v_mfma_f32_16x16x32_bf16 v[72:75], v[170:173], v[202:205], v[72:75]
	v_mfma_f32_16x16x32_bf16 v[124:127], v[160:163], v[182:185], v[124:127]
	v_mfma_f32_16x16x32_bf16 v[120:123], v[174:177], v[182:185], v[120:123]
	v_mfma_f32_16x16x32_bf16 v[108:111], v[160:163], v[190:193], v[108:111]
	v_mfma_f32_16x16x32_bf16 v[104:107], v[174:177], v[190:193], v[104:107]
	v_mfma_f32_16x16x32_bf16 v[92:95], v[160:163], v[198:201], v[92:95]
	v_mfma_f32_16x16x32_bf16 v[88:91], v[174:177], v[198:201], v[88:91]
	v_mfma_f32_16x16x32_bf16 v[76:79], v[160:163], v[206:209], v[76:79]
	v_mfma_f32_16x16x32_bf16 v[72:75], v[174:177], v[206:209], v[72:75]
	s_setprio 0
	s_barrier
	s_add_i32 s43, s63, s55
	v_lshl_add_u64 v[150:151], s[36:37], 0, v[130:131]
	s_mov_b32 m0, s43
	ds_read_b128 v[210:213], v157
	ds_read_b128 v[214:217], v157 offset:1024
	ds_read_b128 v[218:221], v157 offset:2048
	ds_read_b128 v[222:225], v157 offset:3072
	global_load_lds_dwordx4 v[150:151], off
	v_lshl_add_u64 v[164:165], s[36:37], 0, v[134:135]
	s_add_i32 m0, s43, 0x2000
	s_nop 0
	global_load_lds_dwordx4 v[164:165], off
	s_barrier
	s_waitcnt lgkmcnt(0)
	s_setprio 1
	s_waitcnt lgkmcnt(0)
	v_mfma_f32_16x16x32_bf16 v[116:119], v[210:213], v[178:181], v[116:119]
	v_mfma_f32_16x16x32_bf16 v[112:115], v[218:221], v[178:181], v[112:115]
	v_mfma_f32_16x16x32_bf16 v[100:103], v[210:213], v[186:189], v[100:103]
	v_mfma_f32_16x16x32_bf16 v[96:99], v[218:221], v[186:189], v[96:99]
	v_mfma_f32_16x16x32_bf16 v[84:87], v[210:213], v[194:197], v[84:87]
	v_mfma_f32_16x16x32_bf16 v[80:83], v[218:221], v[194:197], v[80:83]
	v_mfma_f32_16x16x32_bf16 v[68:71], v[210:213], v[202:205], v[68:71]
	v_mfma_f32_16x16x32_bf16 v[64:67], v[218:221], v[202:205], v[64:67]
	v_mfma_f32_16x16x32_bf16 v[116:119], v[214:217], v[182:185], v[116:119]
	v_mfma_f32_16x16x32_bf16 v[112:115], v[222:225], v[182:185], v[112:115]
	v_mfma_f32_16x16x32_bf16 v[100:103], v[214:217], v[190:193], v[100:103]
	v_mfma_f32_16x16x32_bf16 v[96:99], v[222:225], v[190:193], v[96:99]
	v_mfma_f32_16x16x32_bf16 v[84:87], v[214:217], v[198:201], v[84:87]
	v_mfma_f32_16x16x32_bf16 v[80:83], v[222:225], v[198:201], v[80:83]
	v_mfma_f32_16x16x32_bf16 v[68:71], v[214:217], v[206:209], v[68:71]
	v_mfma_f32_16x16x32_bf16 v[64:67], v[222:225], v[206:209], v[64:67]
	s_setprio 0
	s_mov_b32 m0, s31
	v_lshl_add_u64 v[226:227], s[38:39], 0, v[128:129]
	s_barrier
	ds_read_b128 v[178:181], v156 offset:16384
	ds_read_b128 v[182:185], v156 offset:17408
	ds_read_b128 v[186:189], v156 offset:18432
	ds_read_b128 v[190:193], v156 offset:19456
	ds_read_b128 v[194:197], v156 offset:20480
	ds_read_b128 v[198:201], v156 offset:21504
	ds_read_b128 v[202:205], v156 offset:22528
	ds_read_b128 v[206:209], v156 offset:23552
	global_load_lds_dwordx4 v[226:227], off
	v_lshl_add_u64 v[228:229], s[38:39], 0, v[132:133]
	s_mov_b32 m0, s56
	s_nop 0
	global_load_lds_dwordx4 v[228:229], off
	s_barrier
	s_waitcnt lgkmcnt(0)
	s_setprio 1
	s_waitcnt lgkmcnt(0)
	v_mfma_f32_16x16x32_bf16 v[60:63], v[146:149], v[178:181], v[60:63]
	v_mfma_f32_16x16x32_bf16 v[56:59], v[170:173], v[178:181], v[56:59]
	v_mfma_f32_16x16x32_bf16 v[44:47], v[146:149], v[186:189], v[44:47]
	v_mfma_f32_16x16x32_bf16 v[40:43], v[170:173], v[186:189], v[40:43]
	v_mfma_f32_16x16x32_bf16 v[28:31], v[146:149], v[194:197], v[28:31]
	v_mfma_f32_16x16x32_bf16 v[24:27], v[170:173], v[194:197], v[24:27]
	v_mfma_f32_16x16x32_bf16 v[12:15], v[146:149], v[202:205], v[12:15]
	v_mfma_f32_16x16x32_bf16 v[8:11], v[170:173], v[202:205], v[8:11]
	v_mfma_f32_16x16x32_bf16 v[60:63], v[160:163], v[182:185], v[60:63]
	v_mfma_f32_16x16x32_bf16 v[56:59], v[174:177], v[182:185], v[56:59]
	v_mfma_f32_16x16x32_bf16 v[44:47], v[160:163], v[190:193], v[44:47]
	v_mfma_f32_16x16x32_bf16 v[40:43], v[174:177], v[190:193], v[40:43]
	v_mfma_f32_16x16x32_bf16 v[28:31], v[160:163], v[198:201], v[28:31]
	v_mfma_f32_16x16x32_bf16 v[24:27], v[174:177], v[198:201], v[24:27]
	v_mfma_f32_16x16x32_bf16 v[12:15], v[160:163], v[206:209], v[12:15]
	v_mfma_f32_16x16x32_bf16 v[8:11], v[174:177], v[206:209], v[8:11]
	s_setprio 0
	s_barrier
; #define PG8_STAGE(bufoff, gbase, voff) do { _Pragma("unroll") for (int _i = 0; _i < 2; ++_i) \
;         __builtin_amdgcn_global_load_lds((const unsigned*)((const char*)(gbase) + (voff)[_i]), (LAS unsigned*)(lds + (bufoff) + ldsw + _i * 8192), 16, 0, 0); } while (0)
; #define PG8_LDA(dst, b, h) do { _Pragma("unroll") for (int m = 0; m < 4; ++m) _Pragma("unroll") for (int k = 0; k < 2; ++k) dst[m][k] = *(const LAS bf16x8*)(lds + PG8_SA(b, h) + aoff + m * 2048 + k * 1024); } while (0)
; #define PG8_LDB(dst, b, h) do { _Pragma("unroll") for (int n = 0; n < 2; ++n) _Pragma("unroll") for (int k = 0; k < 2; ++k) dst[n][k] = *(const LAS bf16x8*)(lds + PG8_SB(b, h) + boff + n * 2048 + k * 1024); } while (0)
; #define PG8_MMA(ai, bj, At, Bt) do { __builtin_amdgcn_s_setprio(1); _Pragma("unroll") for (int m = 0; m < 4; ++m) _Pragma("unroll") for (int n = 0; n < 2; ++n) _Pragma("unroll") for (int k = 0; k < 2; ++k) \
;         acc[ai][bj][m][n] = __builtin_amdgcn_mfma_f32_16x16x32_bf16(Bt[n][k], At[m][k], acc[ai][bj][m][n], 0, 0, 0); __builtin_amdgcn_s_setprio(0); } while (0)
; #define PG8_WAIT_V(n) asm volatile("s_waitcnt vmcnt(" #n ")" ::: "memory")
; #define PG8_WAIT_L(n) asm volatile("s_waitcnt lgkmcnt(" #n ")" ::: "memory")
; #define PG8_BAR __builtin_amdgcn_s_barrier()
; #define PG8_SCHED __builtin_amdgcn_sched_barrier(0)
;     ...
;             PG8_STAGE(PG8_SB(0, 1), b2 + hB, voffB);
;             PG8_WAIT_V(6); PG8_BAR; PG8_MMA(1, 1, At, B1); PG8_BAR;
;             PG8_LDB(B0, 1, 0); PG8_SCHED; PG8_LDA(At, 1, 0); PG8_STAGE(PG8_SA(0, 1), a2 + hA, voffA);
;             PG8_WAIT_L(8); PG8_BAR; PG8_WAIT_L(0); PG8_MMA(0, 0, At, B0); PG8_BAR; PG8_SCHED;
;             PG8_LDB(B1, 1, 1); PG8_STAGE(PG8_SB(1, 0), b3, voffB);
;             PG8_BAR; PG8_WAIT_L(0); PG8_MMA(0, 1, At, B1); PG8_BAR;
;             PG8_LDA(At, 1, 1); PG8_STAGE(PG8_SA(1, 0), a3, voffA);
;             PG8_BAR; PG8_WAIT_L(0); PG8_MMA(1, 0, At, B0); PG8_BAR; PG8_SCHED;
	s_add_u32 s44, s36, 0x40000
	s_addc_u32 s45, s37, 0
	s_add_i32 s43, s64, s55
	v_lshl_add_u64 v[146:147], s[44:45], 0, v[130:131]
	s_mov_b32 m0, s43
	s_nop 0
	global_load_lds_dwordx4 v[146:147], off
	v_lshl_add_u64 v[146:147], s[44:45], 0, v[134:135]
	s_add_i32 m0, s43, 0x2000
	s_nop 0
	global_load_lds_dwordx4 v[146:147], off
	s_waitcnt vmcnt(6)
	s_barrier
	s_setprio 1
	v_mfma_f32_16x16x32_bf16 v[52:55], v[210:213], v[178:181], v[52:55]
	v_mfma_f32_16x16x32_bf16 v[48:51], v[218:221], v[178:181], v[48:51]
	v_mfma_f32_16x16x32_bf16 v[36:39], v[210:213], v[186:189], v[36:39]
	v_mfma_f32_16x16x32_bf16 v[32:35], v[218:221], v[186:189], v[32:35]
	v_mfma_f32_16x16x32_bf16 v[20:23], v[210:213], v[194:197], v[20:23]
	v_mfma_f32_16x16x32_bf16 v[16:19], v[218:221], v[194:197], v[16:19]
	v_mfma_f32_16x16x32_bf16 v[4:7], v[210:213], v[202:205], v[4:7]
	v_mfma_f32_16x16x32_bf16 v[0:3], v[218:221], v[202:205], v[0:3]
	v_mfma_f32_16x16x32_bf16 v[52:55], v[214:217], v[182:185], v[52:55]
	v_mfma_f32_16x16x32_bf16 v[48:51], v[222:225], v[182:185], v[48:51]
	v_mfma_f32_16x16x32_bf16 v[36:39], v[214:217], v[190:193], v[36:39]
	v_mfma_f32_16x16x32_bf16 v[32:35], v[222:225], v[190:193], v[32:35]
	v_mfma_f32_16x16x32_bf16 v[20:23], v[214:217], v[198:201], v[20:23]
	v_mfma_f32_16x16x32_bf16 v[16:19], v[222:225], v[198:201], v[16:19]
	v_mfma_f32_16x16x32_bf16 v[4:7], v[214:217], v[206:209], v[4:7]
	v_mfma_f32_16x16x32_bf16 v[0:3], v[222:225], v[206:209], v[0:3]
	s_setprio 0
	s_add_i32 s43, 0, 0x18000
	v_add_u32_e32 v159, s43, v153
	s_barrier
	ds_read_b128 v[146:149], v159
	ds_read_b128 v[160:163], v159 offset:1024
	ds_read_b128 v[170:173], v159 offset:2048
	ds_read_b128 v[174:177], v159 offset:3072
	s_add_u32 s38, s38, 0x40000
	s_addc_u32 s39, s39, 0
	s_mov_b32 m0, s57
	v_lshl_add_u64 v[210:211], s[38:39], 0, v[128:129]
	ds_read_b128 v[178:181], v156 offset:32768
	ds_read_b128 v[182:185], v156 offset:33792
	ds_read_b128 v[186:189], v156 offset:34816
	ds_read_b128 v[190:193], v156 offset:35840
	ds_read_b128 v[194:197], v156 offset:36864
	ds_read_b128 v[198:201], v156 offset:37888
	ds_read_b128 v[202:205], v156 offset:38912
	ds_read_b128 v[206:209], v156 offset:39936
	global_load_lds_dwordx4 v[210:211], off
	v_lshl_add_u64 v[210:211], s[38:39], 0, v[132:133]
	s_mov_b32 m0, s58
	s_nop 0
	global_load_lds_dwordx4 v[210:211], off
	s_waitcnt lgkmcnt(8)
	s_barrier
	s_waitcnt lgkmcnt(0)
	s_setprio 1
	s_waitcnt lgkmcnt(0)
	v_mfma_f32_16x16x32_bf16 v[124:127], v[146:149], v[178:181], v[124:127]
	v_mfma_f32_16x16x32_bf16 v[120:123], v[170:173], v[178:181], v[120:123]
	v_mfma_f32_16x16x32_bf16 v[108:111], v[146:149], v[186:189], v[108:111]
	v_mfma_f32_16x16x32_bf16 v[104:107], v[170:173], v[186:189], v[104:107]
	v_mfma_f32_16x16x32_bf16 v[92:95], v[146:149], v[194:197], v[92:95]
	v_mfma_f32_16x16x32_bf16 v[88:91], v[170:173], v[194:197], v[88:91]
	v_mfma_f32_16x16x32_bf16 v[76:79], v[146:149], v[202:205], v[76:79]
	v_mfma_f32_16x16x32_bf16 v[72:75], v[170:173], v[202:205], v[72:75]
	v_mfma_f32_16x16x32_bf16 v[124:127], v[160:163], v[182:185], v[124:127]
	v_mfma_f32_16x16x32_bf16 v[120:123], v[174:177], v[182:185], v[120:123]
	v_mfma_f32_16x16x32_bf16 v[108:111], v[160:163], v[190:193], v[108:111]
	v_mfma_f32_16x16x32_bf16 v[104:107], v[174:177], v[190:193], v[104:107]
	v_mfma_f32_16x16x32_bf16 v[92:95], v[160:163], v[198:201], v[92:95]
	v_mfma_f32_16x16x32_bf16 v[88:91], v[174:177], v[198:201], v[88:91]
	v_mfma_f32_16x16x32_bf16 v[76:79], v[160:163], v[206:209], v[76:79]
	v_mfma_f32_16x16x32_bf16 v[72:75], v[174:177], v[206:209], v[72:75]
	s_setprio 0
	s_barrier
	s_add_i32 s38, 0, 0x1c000
	s_add_i32 s39, s43, s55
	v_add_u32_e32 v159, s38, v153
	v_lshl_add_u64 v[150:151], v[150:151], 0, s[20:21]
	s_mov_b32 m0, s39
	ds_read_b128 v[210:213], v159
	ds_read_b128 v[214:217], v159 offset:1024
	ds_read_b128 v[218:221], v159 offset:2048
	ds_read_b128 v[222:225], v159 offset:3072
	global_load_lds_dwordx4 v[150:151], off
	v_lshl_add_u64 v[150:151], v[164:165], 0, s[20:21]
	s_add_i32 m0, s39, 0x2000
	s_nop 0
	global_load_lds_dwordx4 v[150:151], off
	s_barrier
	s_waitcnt lgkmcnt(0)
	s_setprio 1
	s_waitcnt lgkmcnt(0)
	v_mfma_f32_16x16x32_bf16 v[116:119], v[210:213], v[178:181], v[116:119]
	v_mfma_f32_16x16x32_bf16 v[112:115], v[218:221], v[178:181], v[112:115]
	v_mfma_f32_16x16x32_bf16 v[100:103], v[210:213], v[186:189], v[100:103]
	v_mfma_f32_16x16x32_bf16 v[96:99], v[218:221], v[186:189], v[96:99]
	v_mfma_f32_16x16x32_bf16 v[84:87], v[210:213], v[194:197], v[84:87]
	v_mfma_f32_16x16x32_bf16 v[80:83], v[218:221], v[194:197], v[80:83]
	v_mfma_f32_16x16x32_bf16 v[68:71], v[210:213], v[202:205], v[68:71]
	v_mfma_f32_16x16x32_bf16 v[64:67], v[218:221], v[202:205], v[64:67]
	v_mfma_f32_16x16x32_bf16 v[116:119], v[214:217], v[182:185], v[116:119]
	v_mfma_f32_16x16x32_bf16 v[112:115], v[222:225], v[182:185], v[112:115]
	v_mfma_f32_16x16x32_bf16 v[100:103], v[214:217], v[190:193], v[100:103]
	v_mfma_f32_16x16x32_bf16 v[96:99], v[222:225], v[190:193], v[96:99]
	v_mfma_f32_16x16x32_bf16 v[84:87], v[214:217], v[198:201], v[84:87]
	v_mfma_f32_16x16x32_bf16 v[80:83], v[222:225], v[198:201], v[80:83]
	v_mfma_f32_16x16x32_bf16 v[68:71], v[214:217], v[206:209], v[68:71]
	v_mfma_f32_16x16x32_bf16 v[64:67], v[222:225], v[206:209], v[64:67]
	s_setprio 0
	s_mov_b32 m0, s60
	v_lshl_add_u64 v[150:151], v[226:227], 0, s[20:21]
	s_barrier
	ds_read_b128 v[178:181], v156 offset:49152
	ds_read_b128 v[182:185], v156 offset:50176
	ds_read_b128 v[186:189], v156 offset:51200
	ds_read_b128 v[190:193], v156 offset:52224
	ds_read_b128 v[194:197], v156 offset:53248
	ds_read_b128 v[198:201], v156 offset:54272
	ds_read_b128 v[202:205], v156 offset:55296
	ds_read_b128 v[206:209], v156 offset:56320
	global_load_lds_dwordx4 v[150:151], off
	v_lshl_add_u64 v[150:151], v[228:229], 0, s[20:21]
	s_mov_b32 m0, s61
	s_nop 0
	global_load_lds_dwordx4 v[150:151], off
	s_barrier
; #define PG8_STAGE(bufoff, gbase, voff) do { _Pragma("unroll") for (int _i = 0; _i < 2; ++_i) \
;         __builtin_amdgcn_global_load_lds((const unsigned*)((const char*)(gbase) + (voff)[_i]), (LAS unsigned*)(lds + (bufoff) + ldsw + _i * 8192), 16, 0, 0); } while (0)
; #define PG8_MMA(ai, bj, At, Bt) do { __builtin_amdgcn_s_setprio(1); _Pragma("unroll") for (int m = 0; m < 4; ++m) _Pragma("unroll") for (int n = 0; n < 2; ++n) _Pragma("unroll") for (int k = 0; k < 2; ++k) \
;         acc[ai][bj][m][n] = __builtin_amdgcn_mfma_f32_16x16x32_bf16(Bt[n][k], At[m][k], acc[ai][bj][m][n], 0, 0, 0); __builtin_amdgcn_s_setprio(0); } while (0)
; #define PG8_WAIT_V(n) asm volatile("s_waitcnt vmcnt(" #n ")" ::: "memory")
; #define PG8_WAIT_L(n) asm volatile("s_waitcnt lgkmcnt(" #n ")" ::: "memory")
; #define PG8_BAR __builtin_amdgcn_s_barrier()
; #define PG8_SCHED __builtin_amdgcn_sched_barrier(0)
;     ...
;             PG8_BAR; PG8_WAIT_L(0); PG8_MMA(1, 0, At, B0); PG8_BAR; PG8_SCHED;
;             PG8_STAGE(PG8_SB(1, 1), b3 + hB, voffB);
;             PG8_WAIT_V(6); PG8_BAR; PG8_MMA(1, 1, At, B1); PG8_BAR;
;         }
; __device__ __forceinline__ float row_rstd(const float* ssq, int row) {
;     const f32x4* p = (const f32x4*)(ssq + (size_t)row * 16);
;     const f32x4 a = p[0], b = p[1], c = p[2], d = p[3];
;     __device__ __forceinline__ void operator()(const f32x4 (&acc)[2][2][4][2], const Unit& u, int wr, int wc, int fr, int fq) const {
;         const int row0 = u.pm * 256 + wr * 64 + fr, col0 = u.pn * 256 + wc * 32 + 8 * fq;
; #pragma unroll
;         for (int ai = 0; ai < 2; ++ai)
; #pragma unroll
;             for (int m = 0; m < 4; ++m) {
;                 const int row = row0 + ai * 128 + m * 16; const float rs = row_rstd(ssq, row);
;                 bf16_t* rowp = O + (size_t)row * ldc + col0;
	s_waitcnt lgkmcnt(0)
	s_setprio 1
	s_waitcnt lgkmcnt(0)
	v_mfma_f32_16x16x32_bf16 v[60:63], v[146:149], v[178:181], v[60:63]
	v_mfma_f32_16x16x32_bf16 v[56:59], v[170:173], v[178:181], v[56:59]
	v_mfma_f32_16x16x32_bf16 v[44:47], v[146:149], v[186:189], v[44:47]
	v_mfma_f32_16x16x32_bf16 v[40:43], v[170:173], v[186:189], v[40:43]
	v_mfma_f32_16x16x32_bf16 v[28:31], v[146:149], v[194:197], v[28:31]
	v_mfma_f32_16x16x32_bf16 v[24:27], v[170:173], v[194:197], v[24:27]
	v_mfma_f32_16x16x32_bf16 v[12:15], v[146:149], v[202:205], v[12:15]
	v_mfma_f32_16x16x32_bf16 v[8:11], v[170:173], v[202:205], v[8:11]
	v_mfma_f32_16x16x32_bf16 v[60:63], v[160:163], v[182:185], v[60:63]
	v_mfma_f32_16x16x32_bf16 v[56:59], v[174:177], v[182:185], v[56:59]
	v_mfma_f32_16x16x32_bf16 v[44:47], v[160:163], v[190:193], v[44:47]
	v_mfma_f32_16x16x32_bf16 v[40:43], v[174:177], v[190:193], v[40:43]
	v_mfma_f32_16x16x32_bf16 v[28:31], v[160:163], v[198:201], v[28:31]
	v_mfma_f32_16x16x32_bf16 v[24:27], v[174:177], v[198:201], v[24:27]
	v_mfma_f32_16x16x32_bf16 v[12:15], v[160:163], v[206:209], v[12:15]
	v_mfma_f32_16x16x32_bf16 v[8:11], v[174:177], v[206:209], v[8:11]
	s_setprio 0
	s_barrier
	s_add_u32 s36, s36, 0x40080
	s_addc_u32 s37, s37, 0
	s_add_i32 s38, s38, s55
	v_lshl_add_u64 v[146:147], s[36:37], 0, v[130:131]
	s_mov_b32 m0, s38
	s_nop 0
	global_load_lds_dwordx4 v[146:147], off
	v_lshl_add_u64 v[146:147], s[36:37], 0, v[134:135]
	s_add_i32 m0, s38, 0x2000
	s_nop 0
	global_load_lds_dwordx4 v[146:147], off
	s_waitcnt vmcnt(6)
	s_barrier
	s_setprio 1
	v_mfma_f32_16x16x32_bf16 v[52:55], v[210:213], v[178:181], v[52:55]
	v_mfma_f32_16x16x32_bf16 v[48:51], v[218:221], v[178:181], v[48:51]
	v_mfma_f32_16x16x32_bf16 v[36:39], v[210:213], v[186:189], v[36:39]
	v_mfma_f32_16x16x32_bf16 v[32:35], v[218:221], v[186:189], v[32:35]
	v_mfma_f32_16x16x32_bf16 v[20:23], v[210:213], v[194:197], v[20:23]
	v_mfma_f32_16x16x32_bf16 v[16:19], v[218:221], v[194:197], v[16:19]
	v_mfma_f32_16x16x32_bf16 v[4:7], v[210:213], v[202:205], v[4:7]
	v_mfma_f32_16x16x32_bf16 v[0:3], v[218:221], v[202:205], v[0:3]
	v_mfma_f32_16x16x32_bf16 v[52:55], v[214:217], v[182:185], v[52:55]
	v_mfma_f32_16x16x32_bf16 v[48:51], v[222:225], v[182:185], v[48:51]
	v_mfma_f32_16x16x32_bf16 v[36:39], v[214:217], v[190:193], v[36:39]
	v_mfma_f32_16x16x32_bf16 v[32:35], v[222:225], v[190:193], v[32:35]
	v_mfma_f32_16x16x32_bf16 v[20:23], v[214:217], v[198:201], v[20:23]
	v_mfma_f32_16x16x32_bf16 v[16:19], v[222:225], v[198:201], v[16:19]
	v_mfma_f32_16x16x32_bf16 v[4:7], v[214:217], v[206:209], v[4:7]
	v_mfma_f32_16x16x32_bf16 v[0:3], v[222:225], v[206:209], v[0:3]
	s_setprio 0
	s_add_i32 s42, s42, 2
	s_add_u32 s25, s25, 0x100
	s_addc_u32 s33, s33, 0
	s_add_u32 s34, s34, 0x100
	s_addc_u32 s35, s35, 0
	s_cmp_gt_u32 s42, 13
	s_barrier
	s_cbranch_scc0 .LBB0_1288
	v_lshl_add_u32 v150, s30, 8, v152
	v_ashrrev_i32_e32 v151, 31, v150
	v_lshlrev_b64 v[146:147], 6, v[150:151]
	v_lshl_add_u64 v[146:147], s[18:19], 0, v[146:147]
	v_subrev_u32_e32 v186, s18, v146
	v_add_u32_e32 v187, 0x0, v186
	global_load_dwordx4 v[188:191], v187, s[18:19]
	v_add_u32_e32 v187, 0x10, v186
	global_load_dwordx4 v[192:195], v187, s[18:19]
	v_add_u32_e32 v187, 0x20, v186
	global_load_dwordx4 v[196:199], v187, s[18:19]
	v_add_u32_e32 v187, 0x30, v186
	global_load_dwordx4 v[200:203], v187, s[18:19]
	v_add_u32_e32 v187, 0x400, v186
	global_load_dwordx4 v[204:207], v187, s[18:19]
	v_add_u32_e32 v187, 0x410, v186
	global_load_dwordx4 v[208:211], v187, s[18:19]
	v_add_u32_e32 v187, 0x420, v186
	global_load_dwordx4 v[212:215], v187, s[18:19]
	v_add_u32_e32 v187, 0x430, v186
	global_load_dwordx4 v[216:219], v187, s[18:19]
	v_add_u32_e32 v187, 0x800, v186
	global_load_dwordx4 v[220:223], v187, s[18:19]
	v_add_u32_e32 v187, 0x810, v186
	global_load_dwordx4 v[232:235], v187, s[18:19]
	v_add_u32_e32 v187, 0x820, v186
	global_load_dwordx4 v[236:239], v187, s[18:19]
	v_add_u32_e32 v187, 0x830, v186
	global_load_dwordx4 v[240:243], v187, s[18:19]
	v_lshl_or_b32 v148, s6, 8, v154
	v_mov_b64_e32 v[146:147], s[16:17]
	v_ashrrev_i32_e32 v149, 31, v148
	v_mad_i64_i32 v[164:165], s[6:7], v150, s66, v[146:147]
	v_or_b32_e32 v182, 16, v150
	v_lshlrev_b64 v[148:149], 1, v[148:149]
	v_ashrrev_i32_e32 v183, 31, v182
	s_mov_b32 s30, s24
	s_mov_b64 s[34:35], s[28:29]
	s_mov_b64 s[36:37], s[26:27]
	s_waitcnt vmcnt(8)
; __device__ __forceinline__ u32x4 pack8(const f32x4 v0, const f32x4 v1) { u32x4 w; w.x = pk2(v0[0], v0[1]); w.y = pk2(v0[2], v0[3]); w.z = pk2(v1[0], v1[1]); w.w = pk2(v1[2], v1[3]); return w; }
; __device__ __forceinline__ float row_rstd(const float* ssq, int row) {
;     const f32x4* p = (const f32x4*)(ssq + (size_t)row * 16);
;     const f32x4 a = p[0], b = p[1], c = p[2], d = p[3];
;     const float s = ((a[0] + a[1]) + (a[2] + a[3])) + ((b[0] + b[1]) + (b[2] + b[3])) + ((c[0] + c[1]) + (c[2] + c[3])) + ((d[0] + d[1]) + (d[2] + d[3]));
;     return rsqrtf(s * (1.0f / 1024.0f) + 1e-6f);
; }
;     __device__ __forceinline__ void operator()(const f32x4 (&acc)[2][2][4][2], const Unit& u, int wr, int wc, int fr, int fq) const {
;         const int row0 = u.pm * 256 + wr * 64 + fr, col0 = u.pn * 256 + wc * 32 + 8 * fq;
; #pragma unroll
;         for (int ai = 0; ai < 2; ++ai)
; #pragma unroll
;             for (int m = 0; m < 4; ++m) {
;                 const int row = row0 + ai * 128 + m * 16; const float rs = row_rstd(ssq, row);
;                 bf16_t* rowp = O + (size_t)row * ldc + col0;
; #pragma unroll
;                 for (int bj = 0; bj < 2; ++bj) { f32x4 v0 = acc[ai][bj][m][0] * rs, v1 = acc[ai][bj][m][1] * rs;
;                     if (ACT == 1) {
; #pragma unroll
;                         for (int j = 0; j < 4; ++j) { const float a = fmaxf(v0[j], 0.f), b = fmaxf(v1[j], 0.f); v0[j] = a * a; v1[j] = b * b; } }
;                     *(u32x4*)(rowp + bj * 128) = pack8(v0, v1); }
;             }
	v_mov_b32_e32 v184, v189
	v_mov_b32_e32 v185, v190
	v_mov_b32_e32 v161, v191
	v_mov_b32_e32 v162, v193
	v_mov_b32_e32 v163, v194
	v_mov_b32_e32 v171, v195
	v_mov_b32_e32 v160, v188
	v_pk_add_f32 v[160:161], v[184:185], v[160:161]
	v_mov_b32_e32 v170, v192
	v_pk_add_f32 v[162:163], v[162:163], v[170:171]
	v_pk_add_f32 v[160:161], v[160:161], v[160:161] op_sel:[0,1] op_sel_hi:[1,0]
	v_pk_add_f32 v[162:163], v[162:163], v[162:163] op_sel:[0,1] op_sel_hi:[1,0]
	v_add_f32_e32 v172, v196, v197
	v_add_f32_e32 v174, v198, v199
	v_mov_b32_e32 v173, v202
	v_mov_b32_e32 v175, v203
	v_mov_b32_e32 v161, v200
	v_mov_b32_e32 v163, v201
	v_pk_add_f32 v[170:171], v[172:173], v[174:175]
	v_pk_add_f32 v[160:161], v[160:161], v[162:163]
	v_lshlrev_b64 v[162:163], 6, v[182:183]
	v_pk_add_f32 v[160:161], v[160:161], v[170:171]
	v_lshl_add_u64 v[162:163], s[18:19], 0, v[162:163]
	v_add_f32_e32 v151, v160, v161
	v_fmamk_f32 v151, v151, 0x3a800000, v158
	v_mul_f32_e32 v159, 0x4b800000, v151
	v_cmp_gt_f32_e32 vcc, s65, v151
	v_lshl_add_u64 v[160:161], v[164:165], 0, v[148:149]
	s_nop 0
	v_cndmask_b32_e32 v151, v151, v159, vcc
	v_rsq_f32_e32 v151, v151
	s_nop 0
	v_mul_f32_e32 v159, 0x45800000, v151
	v_cndmask_b32_e32 v164, v151, v159, vcc
	v_pk_mul_f32 v[126:127], v[126:127], v[164:165] op_sel_hi:[1,0]
	v_pk_mul_f32 v[124:125], v[124:125], v[164:165] op_sel_hi:[1,0]
	v_pk_mul_f32 v[122:123], v[122:123], v[164:165] op_sel_hi:[1,0]
	v_pk_mul_f32 v[120:121], v[120:121], v[164:165] op_sel_hi:[1,0]
	v_pk_mul_f32 v[118:119], v[118:119], v[164:165] op_sel_hi:[1,0]
	v_pk_mul_f32 v[116:117], v[116:117], v[164:165] op_sel_hi:[1,0]
	v_pk_mul_f32 v[170:171], v[114:115], v[164:165] op_sel_hi:[1,0]
	v_pk_mul_f32 v[164:165], v[112:113], v[164:165] op_sel_hi:[1,0]
	v_cvt_pk_bf16_f32 v112, v124, v125
	v_cvt_pk_bf16_f32 v113, v126, v127
	v_cvt_pk_bf16_f32 v114, v120, v121
	v_cvt_pk_bf16_f32 v115, v122, v123
	global_store_dwordx4 v[160:161], v[112:115], off sc1
	s_nop 1
	v_cvt_pk_bf16_f32 v112, v116, v117
	v_cvt_pk_bf16_f32 v113, v118, v119
	v_cvt_pk_bf16_f32 v114, v164, v165
	v_cvt_pk_bf16_f32 v115, v170, v171
	global_store_dwordx4 v[160:161], v[112:115], off offset:256 sc1
	s_nop 0
	v_or_b32_e32 v160, 32, v150
	v_mad_i64_i32 v[162:163], s[6:7], v182, s66, v[146:147]
	v_ashrrev_i32_e32 v161, 31, v160
	v_add_u32_e32 v187, 0xc00, v186
	global_load_dwordx4 v[188:191], v187, s[18:19]
	v_add_u32_e32 v187, 0xc10, v186
	global_load_dwordx4 v[192:195], v187, s[18:19]
	v_add_u32_e32 v187, 0xc20, v186
	global_load_dwordx4 v[196:199], v187, s[18:19]
	v_add_u32_e32 v187, 0xc30, v186
	global_load_dwordx4 v[200:203], v187, s[18:19]
	s_waitcnt vmcnt(10)
	v_mov_b32_e32 v164, v205
	v_mov_b32_e32 v165, v206
	v_mov_b32_e32 v113, v207
	v_mov_b32_e32 v114, v209
	v_mov_b32_e32 v115, v210
	v_mov_b32_e32 v117, v211
	v_mov_b32_e32 v112, v204
	v_pk_add_f32 v[112:113], v[164:165], v[112:113]
	v_mov_b32_e32 v116, v208
	v_pk_add_f32 v[114:115], v[114:115], v[116:117]
	v_pk_add_f32 v[112:113], v[112:113], v[112:113] op_sel:[0,1] op_sel_hi:[1,0]
	v_pk_add_f32 v[114:115], v[114:115], v[114:115] op_sel:[0,1] op_sel_hi:[1,0]
	v_add_f32_e32 v118, v212, v213
	v_add_f32_e32 v120, v214, v215
	v_mov_b32_e32 v119, v218
	v_mov_b32_e32 v121, v219
	v_mov_b32_e32 v113, v216
	v_mov_b32_e32 v115, v217
	v_pk_add_f32 v[116:117], v[118:119], v[120:121]
	v_pk_add_f32 v[112:113], v[112:113], v[114:115]
	v_lshlrev_b64 v[114:115], 6, v[160:161]
	v_pk_add_f32 v[112:113], v[112:113], v[116:117]
	v_lshl_add_u64 v[114:115], s[18:19], 0, v[114:115]
	v_add_f32_e32 v112, v112, v113
	v_fmamk_f32 v112, v112, 0x3a800000, v158
	v_mul_f32_e32 v113, 0x4b800000, v112
	v_cmp_gt_f32_e32 vcc, s65, v112
	s_nop 1
	v_cndmask_b32_e32 v112, v112, v113, vcc
	v_rsq_f32_e32 v116, v112
	v_lshl_add_u64 v[112:113], v[162:163], 0, v[148:149]
	v_mul_f32_e32 v117, 0x45800000, v116
	v_cndmask_b32_e32 v116, v116, v117, vcc
	v_pk_mul_f32 v[110:111], v[110:111], v[116:117] op_sel_hi:[1,0]
	v_pk_mul_f32 v[108:109], v[108:109], v[116:117] op_sel_hi:[1,0]
	v_pk_mul_f32 v[106:107], v[106:107], v[116:117] op_sel_hi:[1,0]
	v_pk_mul_f32 v[104:105], v[104:105], v[116:117] op_sel_hi:[1,0]
	v_pk_mul_f32 v[102:103], v[102:103], v[116:117] op_sel_hi:[1,0]
	v_pk_mul_f32 v[100:101], v[100:101], v[116:117] op_sel_hi:[1,0]
	v_pk_mul_f32 v[118:119], v[98:99], v[116:117] op_sel_hi:[1,0]
	v_pk_mul_f32 v[116:117], v[96:97], v[116:117] op_sel_hi:[1,0]
	v_cvt_pk_bf16_f32 v96, v108, v109
	v_cvt_pk_bf16_f32 v97, v110, v111
	v_cvt_pk_bf16_f32 v98, v104, v105
	v_cvt_pk_bf16_f32 v99, v106, v107
	global_store_dwordx4 v[112:113], v[96:99], off sc1
	s_nop 1
	v_cvt_pk_bf16_f32 v96, v100, v101
	v_cvt_pk_bf16_f32 v97, v102, v103
	v_cvt_pk_bf16_f32 v98, v116, v117
	v_cvt_pk_bf16_f32 v99, v118, v119
	global_store_dwordx4 v[112:113], v[96:99], off offset:256 sc1
	s_nop 0
	v_or_b32_e32 v112, 48, v150
	v_mad_i64_i32 v[114:115], s[6:7], v160, s66, v[146:147]
	v_ashrrev_i32_e32 v113, 31, v112
	v_add_u32_e32 v187, 0x2000, v186
	global_load_dwordx4 v[204:207], v187, s[18:19]
	v_add_u32_e32 v187, 0x2010, v186
	global_load_dwordx4 v[208:211], v187, s[18:19]
	v_add_u32_e32 v187, 0x2020, v186
	global_load_dwordx4 v[212:215], v187, s[18:19]
	v_add_u32_e32 v187, 0x2030, v186
	global_load_dwordx4 v[216:219], v187, s[18:19]
	s_waitcnt vmcnt(12)
; __device__ __forceinline__ u32x4 pack8(const f32x4 v0, const f32x4 v1) { u32x4 w; w.x = pk2(v0[0], v0[1]); w.y = pk2(v0[2], v0[3]); w.z = pk2(v1[0], v1[1]); w.w = pk2(v1[2], v1[3]); return w; }
; __device__ __forceinline__ float row_rstd(const float* ssq, int row) {
;     const f32x4* p = (const f32x4*)(ssq + (size_t)row * 16);
;     const f32x4 a = p[0], b = p[1], c = p[2], d = p[3];
;     const float s = ((a[0] + a[1]) + (a[2] + a[3])) + ((b[0] + b[1]) + (b[2] + b[3])) + ((c[0] + c[1]) + (c[2] + c[3])) + ((d[0] + d[1]) + (d[2] + d[3]));
;     return rsqrtf(s * (1.0f / 1024.0f) + 1e-6f);
; }
;     __device__ __forceinline__ void operator()(const f32x4 (&acc)[2][2][4][2], const Unit& u, int wr, int wc, int fr, int fq) const {
;         const int row0 = u.pm * 256 + wr * 64 + fr, col0 = u.pn * 256 + wc * 32 + 8 * fq;
; #pragma unroll
;         for (int ai = 0; ai < 2; ++ai)
; #pragma unroll
;             for (int m = 0; m < 4; ++m) {
;                 const int row = row0 + ai * 128 + m * 16; const float rs = row_rstd(ssq, row);
;                 bf16_t* rowp = O + (size_t)row * ldc + col0;
; #pragma unroll
;                 for (int bj = 0; bj < 2; ++bj) { f32x4 v0 = acc[ai][bj][m][0] * rs, v1 = acc[ai][bj][m][1] * rs;
;                     if (ACT == 1) {
; #pragma unroll
;                         for (int j = 0; j < 4; ++j) { const float a = fmaxf(v0[j], 0.f), b = fmaxf(v1[j], 0.f); v0[j] = a * a; v1[j] = b * b; } }
;                     *(u32x4*)(rowp + bj * 128) = pack8(v0, v1); }
;             }
	v_mov_b32_e32 v116, v221
	v_mov_b32_e32 v117, v222
	v_mov_b32_e32 v97, v223
	v_mov_b32_e32 v98, v233
	v_mov_b32_e32 v99, v234
	v_mov_b32_e32 v101, v235
	v_mov_b32_e32 v96, v220
	v_pk_add_f32 v[96:97], v[116:117], v[96:97]
	v_mov_b32_e32 v100, v232
	v_pk_add_f32 v[98:99], v[98:99], v[100:101]
	v_pk_add_f32 v[96:97], v[96:97], v[96:97] op_sel:[0,1] op_sel_hi:[1,0]
	v_pk_add_f32 v[98:99], v[98:99], v[98:99] op_sel:[0,1] op_sel_hi:[1,0]
	v_add_f32_e32 v102, v236, v237
	v_add_f32_e32 v104, v238, v239
	v_mov_b32_e32 v103, v242
	v_mov_b32_e32 v105, v243
	v_mov_b32_e32 v97, v240
	v_mov_b32_e32 v99, v241
	v_pk_add_f32 v[100:101], v[102:103], v[104:105]
	v_pk_add_f32 v[96:97], v[96:97], v[98:99]
	v_lshlrev_b64 v[98:99], 6, v[112:113]
	v_pk_add_f32 v[96:97], v[96:97], v[100:101]
	v_lshl_add_u64 v[98:99], s[18:19], 0, v[98:99]
	v_add_f32_e32 v96, v96, v97
	v_fmamk_f32 v96, v96, 0x3a800000, v158
	v_mul_f32_e32 v97, 0x4b800000, v96
	v_cmp_gt_f32_e32 vcc, s65, v96
	s_nop 1
	v_cndmask_b32_e32 v96, v96, v97, vcc
	v_rsq_f32_e32 v100, v96
	v_lshl_add_u64 v[96:97], v[114:115], 0, v[148:149]
	v_mul_f32_e32 v101, 0x45800000, v100
	v_cndmask_b32_e32 v100, v100, v101, vcc
	v_pk_mul_f32 v[94:95], v[94:95], v[100:101] op_sel_hi:[1,0]
	v_pk_mul_f32 v[92:93], v[92:93], v[100:101] op_sel_hi:[1,0]
	v_pk_mul_f32 v[90:91], v[90:91], v[100:101] op_sel_hi:[1,0]
	v_pk_mul_f32 v[88:89], v[88:89], v[100:101] op_sel_hi:[1,0]
	v_pk_mul_f32 v[86:87], v[86:87], v[100:101] op_sel_hi:[1,0]
	v_pk_mul_f32 v[84:85], v[84:85], v[100:101] op_sel_hi:[1,0]
	v_pk_mul_f32 v[102:103], v[82:83], v[100:101] op_sel_hi:[1,0]
	v_pk_mul_f32 v[100:101], v[80:81], v[100:101] op_sel_hi:[1,0]
	v_cvt_pk_bf16_f32 v80, v92, v93
	v_cvt_pk_bf16_f32 v81, v94, v95
	v_cvt_pk_bf16_f32 v82, v88, v89
	v_cvt_pk_bf16_f32 v83, v90, v91
	global_store_dwordx4 v[96:97], v[80:83], off sc1
	s_nop 1
	v_cvt_pk_bf16_f32 v80, v84, v85
	v_cvt_pk_bf16_f32 v81, v86, v87
	v_cvt_pk_bf16_f32 v82, v100, v101
	v_cvt_pk_bf16_f32 v83, v102, v103
	global_store_dwordx4 v[96:97], v[80:83], off offset:256 sc1
	s_nop 0
	v_add_u32_e32 v96, 0x80, v150
	v_mad_i64_i32 v[98:99], s[6:7], v112, s66, v[146:147]
	v_ashrrev_i32_e32 v97, 31, v96
	v_add_u32_e32 v187, 0x2400, v186
	global_load_dwordx4 v[220:223], v187, s[18:19]
	v_add_u32_e32 v187, 0x2410, v186
	global_load_dwordx4 v[232:235], v187, s[18:19]
	v_add_u32_e32 v187, 0x2420, v186
	global_load_dwordx4 v[236:239], v187, s[18:19]
	v_add_u32_e32 v187, 0x2430, v186
	global_load_dwordx4 v[240:243], v187, s[18:19]
	s_waitcnt vmcnt(12)
	v_mov_b32_e32 v100, v189
	v_mov_b32_e32 v101, v190
	v_mov_b32_e32 v81, v191
	v_mov_b32_e32 v82, v193
	v_mov_b32_e32 v83, v194
	v_mov_b32_e32 v85, v195
	v_mov_b32_e32 v80, v188
	v_pk_add_f32 v[80:81], v[100:101], v[80:81]
	v_mov_b32_e32 v84, v192
	v_pk_add_f32 v[82:83], v[82:83], v[84:85]
	v_pk_add_f32 v[80:81], v[80:81], v[80:81] op_sel:[0,1] op_sel_hi:[1,0]
	v_pk_add_f32 v[82:83], v[82:83], v[82:83] op_sel:[0,1] op_sel_hi:[1,0]
	v_add_f32_e32 v86, v196, v197
	v_add_f32_e32 v88, v198, v199
	v_mov_b32_e32 v87, v202
	v_mov_b32_e32 v89, v203
	v_mov_b32_e32 v81, v200
	v_mov_b32_e32 v83, v201
	v_pk_add_f32 v[84:85], v[86:87], v[88:89]
	v_pk_add_f32 v[80:81], v[80:81], v[82:83]
	v_lshlrev_b64 v[82:83], 6, v[96:97]
	v_pk_add_f32 v[80:81], v[80:81], v[84:85]
	v_lshl_add_u64 v[82:83], s[18:19], 0, v[82:83]
	v_add_f32_e32 v80, v80, v81
	v_fmamk_f32 v80, v80, 0x3a800000, v158
	v_mul_f32_e32 v81, 0x4b800000, v80
	v_cmp_gt_f32_e32 vcc, s65, v80
	s_nop 1
	v_cndmask_b32_e32 v80, v80, v81, vcc
	v_rsq_f32_e32 v84, v80
	v_lshl_add_u64 v[80:81], v[98:99], 0, v[148:149]
	v_mul_f32_e32 v85, 0x45800000, v84
	v_cndmask_b32_e32 v84, v84, v85, vcc
	v_pk_mul_f32 v[78:79], v[78:79], v[84:85] op_sel_hi:[1,0]
	v_pk_mul_f32 v[76:77], v[76:77], v[84:85] op_sel_hi:[1,0]
	v_pk_mul_f32 v[74:75], v[74:75], v[84:85] op_sel_hi:[1,0]
	v_pk_mul_f32 v[72:73], v[72:73], v[84:85] op_sel_hi:[1,0]
	v_pk_mul_f32 v[70:71], v[70:71], v[84:85] op_sel_hi:[1,0]
	v_pk_mul_f32 v[68:69], v[68:69], v[84:85] op_sel_hi:[1,0]
	v_pk_mul_f32 v[86:87], v[66:67], v[84:85] op_sel_hi:[1,0]
	v_pk_mul_f32 v[84:85], v[64:65], v[84:85] op_sel_hi:[1,0]
	v_cvt_pk_bf16_f32 v64, v76, v77
	v_cvt_pk_bf16_f32 v65, v78, v79
	v_cvt_pk_bf16_f32 v66, v72, v73
	v_cvt_pk_bf16_f32 v67, v74, v75
	global_store_dwordx4 v[80:81], v[64:67], off sc1
	s_nop 1
	v_cvt_pk_bf16_f32 v64, v68, v69
	v_cvt_pk_bf16_f32 v65, v70, v71
	v_cvt_pk_bf16_f32 v66, v84, v85
	v_cvt_pk_bf16_f32 v67, v86, v87
	global_store_dwordx4 v[80:81], v[64:67], off offset:256 sc1
	s_nop 0
	v_add_u32_e32 v80, 0x90, v150
	v_mad_i64_i32 v[82:83], s[6:7], v96, s66, v[146:147]
	v_ashrrev_i32_e32 v81, 31, v80
	v_add_u32_e32 v187, 0x2800, v186
	global_load_dwordx4 v[188:191], v187, s[18:19]
	v_add_u32_e32 v187, 0x2810, v186
	global_load_dwordx4 v[192:195], v187, s[18:19]
	v_add_u32_e32 v187, 0x2820, v186
	global_load_dwordx4 v[196:199], v187, s[18:19]
	v_add_u32_e32 v187, 0x2830, v186
	global_load_dwordx4 v[200:203], v187, s[18:19]
	s_waitcnt vmcnt(12)
; __device__ __forceinline__ u32x4 pack8(const f32x4 v0, const f32x4 v1) { u32x4 w; w.x = pk2(v0[0], v0[1]); w.y = pk2(v0[2], v0[3]); w.z = pk2(v1[0], v1[1]); w.w = pk2(v1[2], v1[3]); return w; }
; __device__ __forceinline__ float row_rstd(const float* ssq, int row) {
;     const f32x4* p = (const f32x4*)(ssq + (size_t)row * 16);
;     const f32x4 a = p[0], b = p[1], c = p[2], d = p[3];
;     const float s = ((a[0] + a[1]) + (a[2] + a[3])) + ((b[0] + b[1]) + (b[2] + b[3])) + ((c[0] + c[1]) + (c[2] + c[3])) + ((d[0] + d[1]) + (d[2] + d[3]));
;     return rsqrtf(s * (1.0f / 1024.0f) + 1e-6f);
; }
;     __device__ __forceinline__ void operator()(const f32x4 (&acc)[2][2][4][2], const Unit& u, int wr, int wc, int fr, int fq) const {
;         const int row0 = u.pm * 256 + wr * 64 + fr, col0 = u.pn * 256 + wc * 32 + 8 * fq;
; #pragma unroll
;         for (int ai = 0; ai < 2; ++ai)
; #pragma unroll
;             for (int m = 0; m < 4; ++m) {
;                 const int row = row0 + ai * 128 + m * 16; const float rs = row_rstd(ssq, row);
;                 bf16_t* rowp = O + (size_t)row * ldc + col0;
; #pragma unroll
;                 for (int bj = 0; bj < 2; ++bj) { f32x4 v0 = acc[ai][bj][m][0] * rs, v1 = acc[ai][bj][m][1] * rs;
;                     if (ACT == 1) {
; #pragma unroll
;                         for (int j = 0; j < 4; ++j) { const float a = fmaxf(v0[j], 0.f), b = fmaxf(v1[j], 0.f); v0[j] = a * a; v1[j] = b * b; } }
;                     *(u32x4*)(rowp + bj * 128) = pack8(v0, v1); }
;             }
	v_mov_b32_e32 v84, v205
	v_mov_b32_e32 v85, v206
	v_mov_b32_e32 v65, v207
	v_mov_b32_e32 v66, v209
	v_mov_b32_e32 v67, v210
	v_mov_b32_e32 v69, v211
	v_mov_b32_e32 v64, v204
	v_pk_add_f32 v[64:65], v[84:85], v[64:65]
	v_mov_b32_e32 v68, v208
	v_pk_add_f32 v[66:67], v[66:67], v[68:69]
	v_pk_add_f32 v[64:65], v[64:65], v[64:65] op_sel:[0,1] op_sel_hi:[1,0]
	v_pk_add_f32 v[66:67], v[66:67], v[66:67] op_sel:[0,1] op_sel_hi:[1,0]
	v_add_f32_e32 v70, v212, v213
	v_add_f32_e32 v72, v214, v215
	v_mov_b32_e32 v71, v218
	v_mov_b32_e32 v73, v219
	v_mov_b32_e32 v65, v216
	v_mov_b32_e32 v67, v217
	v_pk_add_f32 v[68:69], v[70:71], v[72:73]
	v_pk_add_f32 v[64:65], v[64:65], v[66:67]
	v_lshlrev_b64 v[66:67], 6, v[80:81]
	v_pk_add_f32 v[64:65], v[64:65], v[68:69]
	v_lshl_add_u64 v[66:67], s[18:19], 0, v[66:67]
	v_add_f32_e32 v64, v64, v65
	v_fmamk_f32 v64, v64, 0x3a800000, v158
	v_mul_f32_e32 v65, 0x4b800000, v64
	v_cmp_gt_f32_e32 vcc, s65, v64
	s_nop 1
	v_cndmask_b32_e32 v64, v64, v65, vcc
	v_rsq_f32_e32 v68, v64
	v_lshl_add_u64 v[64:65], v[82:83], 0, v[148:149]
	v_mul_f32_e32 v69, 0x45800000, v68
	v_cndmask_b32_e32 v68, v68, v69, vcc
	v_pk_mul_f32 v[62:63], v[62:63], v[68:69] op_sel_hi:[1,0]
	v_pk_mul_f32 v[60:61], v[60:61], v[68:69] op_sel_hi:[1,0]
	v_pk_mul_f32 v[58:59], v[58:59], v[68:69] op_sel_hi:[1,0]
	v_pk_mul_f32 v[56:57], v[56:57], v[68:69] op_sel_hi:[1,0]
	v_pk_mul_f32 v[54:55], v[54:55], v[68:69] op_sel_hi:[1,0]
	v_pk_mul_f32 v[52:53], v[52:53], v[68:69] op_sel_hi:[1,0]
	v_pk_mul_f32 v[70:71], v[50:51], v[68:69] op_sel_hi:[1,0]
	v_pk_mul_f32 v[68:69], v[48:49], v[68:69] op_sel_hi:[1,0]
	v_cvt_pk_bf16_f32 v48, v60, v61
	v_cvt_pk_bf16_f32 v49, v62, v63
	v_cvt_pk_bf16_f32 v50, v56, v57
	v_cvt_pk_bf16_f32 v51, v58, v59
	global_store_dwordx4 v[64:65], v[48:51], off sc1
	s_nop 1
	v_cvt_pk_bf16_f32 v48, v52, v53
	v_cvt_pk_bf16_f32 v49, v54, v55
	v_cvt_pk_bf16_f32 v50, v68, v69
	v_cvt_pk_bf16_f32 v51, v70, v71
	global_store_dwordx4 v[64:65], v[48:51], off offset:256 sc1
	s_nop 0
	v_add_u32_e32 v64, 0xa0, v150
	v_mad_i64_i32 v[66:67], s[6:7], v80, s66, v[146:147]
	v_ashrrev_i32_e32 v65, 31, v64
	v_add_u32_e32 v187, 0x2c00, v186
	global_load_dwordx4 v[204:207], v187, s[18:19]
	v_add_u32_e32 v187, 0x2c10, v186
	global_load_dwordx4 v[208:211], v187, s[18:19]
	v_add_u32_e32 v187, 0x2c20, v186
	global_load_dwordx4 v[212:215], v187, s[18:19]
	v_add_u32_e32 v187, 0x2c30, v186
	global_load_dwordx4 v[216:219], v187, s[18:19]
	s_waitcnt vmcnt(12)
	v_mov_b32_e32 v68, v221
	v_mov_b32_e32 v69, v222
	v_mov_b32_e32 v49, v223
	v_mov_b32_e32 v50, v233
	v_mov_b32_e32 v51, v234
	v_mov_b32_e32 v53, v235
	v_mov_b32_e32 v48, v220
	v_pk_add_f32 v[48:49], v[68:69], v[48:49]
	v_mov_b32_e32 v52, v232
	v_pk_add_f32 v[50:51], v[50:51], v[52:53]
	v_pk_add_f32 v[48:49], v[48:49], v[48:49] op_sel:[0,1] op_sel_hi:[1,0]
	v_pk_add_f32 v[50:51], v[50:51], v[50:51] op_sel:[0,1] op_sel_hi:[1,0]
	v_add_f32_e32 v54, v236, v237
	v_add_f32_e32 v56, v238, v239
	v_mov_b32_e32 v55, v242
	v_mov_b32_e32 v57, v243
	v_mov_b32_e32 v49, v240
	v_mov_b32_e32 v51, v241
	v_pk_add_f32 v[52:53], v[54:55], v[56:57]
	v_pk_add_f32 v[48:49], v[48:49], v[50:51]
	v_lshlrev_b64 v[50:51], 6, v[64:65]
	v_pk_add_f32 v[48:49], v[48:49], v[52:53]
	v_lshl_add_u64 v[50:51], s[18:19], 0, v[50:51]
	v_add_f32_e32 v48, v48, v49
	v_fmamk_f32 v48, v48, 0x3a800000, v158
	v_mul_f32_e32 v49, 0x4b800000, v48
	v_cmp_gt_f32_e32 vcc, s65, v48
	s_nop 1
	v_cndmask_b32_e32 v48, v48, v49, vcc
	v_rsq_f32_e32 v52, v48
	v_lshl_add_u64 v[48:49], v[66:67], 0, v[148:149]
	v_mul_f32_e32 v53, 0x45800000, v52
	v_cndmask_b32_e32 v52, v52, v53, vcc
	v_pk_mul_f32 v[46:47], v[46:47], v[52:53] op_sel_hi:[1,0]
	v_pk_mul_f32 v[44:45], v[44:45], v[52:53] op_sel_hi:[1,0]
	v_pk_mul_f32 v[42:43], v[42:43], v[52:53] op_sel_hi:[1,0]
	v_pk_mul_f32 v[40:41], v[40:41], v[52:53] op_sel_hi:[1,0]
	v_pk_mul_f32 v[38:39], v[38:39], v[52:53] op_sel_hi:[1,0]
	v_pk_mul_f32 v[36:37], v[36:37], v[52:53] op_sel_hi:[1,0]
	v_pk_mul_f32 v[54:55], v[34:35], v[52:53] op_sel_hi:[1,0]
	v_pk_mul_f32 v[52:53], v[32:33], v[52:53] op_sel_hi:[1,0]
	v_cvt_pk_bf16_f32 v32, v44, v45
	v_cvt_pk_bf16_f32 v33, v46, v47
	v_cvt_pk_bf16_f32 v34, v40, v41
	v_cvt_pk_bf16_f32 v35, v42, v43
	global_store_dwordx4 v[48:49], v[32:35], off sc1
	s_nop 1
	v_cvt_pk_bf16_f32 v32, v36, v37
	v_cvt_pk_bf16_f32 v33, v38, v39
	v_cvt_pk_bf16_f32 v34, v52, v53
	v_cvt_pk_bf16_f32 v35, v54, v55
	global_store_dwordx4 v[48:49], v[32:35], off offset:256 sc1
	s_nop 0
	v_add_u32_e32 v48, 0xb0, v150
	v_mad_i64_i32 v[50:51], s[6:7], v64, s66, v[146:147]
	v_ashrrev_i32_e32 v49, 31, v48
	s_mov_b32 s6, s22
	s_waitcnt vmcnt(8)
; __device__ __forceinline__ u32x4 pack8(const f32x4 v0, const f32x4 v1) { u32x4 w; w.x = pk2(v0[0], v0[1]); w.y = pk2(v0[2], v0[3]); w.z = pk2(v1[0], v1[1]); w.w = pk2(v1[2], v1[3]); return w; }
;     ...
;         E(acc, cur, wr, wc, fr, fq);
;         if (!has_next) break;
; #pragma unroll
;         for (int a = 0; a < 2; ++a)
; #pragma unroll
;             for (int b = 0; b < 2; ++b)
; #pragma unroll
;                 for (int m = 0; m < 4; ++m)
; #pragma unroll
;                     for (int n = 0; n < 2; ++n) acc[a][b][m][n] = (f32x4){0.f, 0.f, 0.f, 0.f};
;         cur = nxt; cA = nA; cB = nB; ++ui;
;     }
;     __device__ __forceinline__ void operator()(const f32x4 (&acc)[2][2][4][2], const Unit& u, int wr, int wc, int fr, int fq) const {
;         const int row0 = u.pm * 256 + wr * 64 + fr, col0 = u.pn * 256 + wc * 32 + 8 * fq;
; #pragma unroll
;         for (int ai = 0; ai < 2; ++ai)
; #pragma unroll
;             for (int m = 0; m < 4; ++m) {
;                 const int row = row0 + ai * 128 + m * 16; const float rs = row_rstd(ssq, row);
;                 bf16_t* rowp = O + (size_t)row * ldc + col0;
; #pragma unroll
;                 for (int bj = 0; bj < 2; ++bj) { f32x4 v0 = acc[ai][bj][m][0] * rs, v1 = acc[ai][bj][m][1] * rs;
;                     if (ACT == 1) {
; #pragma unroll
;                         for (int j = 0; j < 4; ++j) { const float a = fmaxf(v0[j], 0.f), b = fmaxf(v1[j], 0.f); v0[j] = a * a; v1[j] = b * b; } }
;                     *(u32x4*)(rowp + bj * 128) = pack8(v0, v1); }
;             }
;     }
	v_mov_b32_e32 v52, v189
	v_mov_b32_e32 v53, v190
	v_mov_b32_e32 v33, v191
	v_mov_b32_e32 v34, v193
	v_mov_b32_e32 v35, v194
	v_mov_b32_e32 v37, v195
	v_mov_b32_e32 v32, v188
	v_pk_add_f32 v[32:33], v[52:53], v[32:33]
	v_mov_b32_e32 v36, v192
	v_pk_add_f32 v[34:35], v[34:35], v[36:37]
	v_pk_add_f32 v[32:33], v[32:33], v[32:33] op_sel:[0,1] op_sel_hi:[1,0]
	v_pk_add_f32 v[34:35], v[34:35], v[34:35] op_sel:[0,1] op_sel_hi:[1,0]
	v_add_f32_e32 v38, v196, v197
	v_add_f32_e32 v40, v198, v199
	v_mov_b32_e32 v39, v202
	v_mov_b32_e32 v41, v203
	v_mov_b32_e32 v33, v200
	v_mov_b32_e32 v35, v201
	v_pk_add_f32 v[36:37], v[38:39], v[40:41]
	v_pk_add_f32 v[32:33], v[32:33], v[34:35]
	v_lshlrev_b64 v[34:35], 6, v[48:49]
	v_pk_add_f32 v[32:33], v[32:33], v[36:37]
	v_lshl_add_u64 v[34:35], s[18:19], 0, v[34:35]
	v_add_f32_e32 v32, v32, v33
	v_fmamk_f32 v32, v32, 0x3a800000, v158
	v_mul_f32_e32 v33, 0x4b800000, v32
	v_cmp_gt_f32_e32 vcc, s65, v32
	s_nop 1
	v_cndmask_b32_e32 v32, v32, v33, vcc
	v_rsq_f32_e32 v36, v32
	v_lshl_add_u64 v[32:33], v[50:51], 0, v[148:149]
	v_mul_f32_e32 v37, 0x45800000, v36
	v_cndmask_b32_e32 v36, v36, v37, vcc
	v_pk_mul_f32 v[30:31], v[30:31], v[36:37] op_sel_hi:[1,0]
	v_pk_mul_f32 v[28:29], v[28:29], v[36:37] op_sel_hi:[1,0]
	v_pk_mul_f32 v[26:27], v[26:27], v[36:37] op_sel_hi:[1,0]
	v_pk_mul_f32 v[24:25], v[24:25], v[36:37] op_sel_hi:[1,0]
	v_pk_mul_f32 v[22:23], v[22:23], v[36:37] op_sel_hi:[1,0]
	v_pk_mul_f32 v[20:21], v[20:21], v[36:37] op_sel_hi:[1,0]
	v_pk_mul_f32 v[38:39], v[18:19], v[36:37] op_sel_hi:[1,0]
	v_pk_mul_f32 v[36:37], v[16:17], v[36:37] op_sel_hi:[1,0]
	v_cvt_pk_bf16_f32 v16, v28, v29
	v_cvt_pk_bf16_f32 v17, v30, v31
	v_cvt_pk_bf16_f32 v18, v24, v25
	v_cvt_pk_bf16_f32 v19, v26, v27
	global_store_dwordx4 v[32:33], v[16:19], off sc1
	s_and_b64 vcc, exec, s[10:11]
	s_nop 0
	v_cvt_pk_bf16_f32 v16, v20, v21
	v_cvt_pk_bf16_f32 v17, v22, v23
	v_cvt_pk_bf16_f32 v18, v36, v37
	v_cvt_pk_bf16_f32 v19, v38, v39
	global_store_dwordx4 v[32:33], v[16:19], off offset:256 sc1
	s_nop 0
	s_waitcnt vmcnt(4)
	v_mov_b32_e32 v32, v205
	v_mov_b32_e32 v33, v206
	v_mov_b32_e32 v17, v207
	v_mov_b32_e32 v18, v209
	v_mov_b32_e32 v19, v210
	v_mov_b32_e32 v21, v211
	v_mov_b32_e32 v16, v204
	v_pk_add_f32 v[16:17], v[32:33], v[16:17]
	v_mov_b32_e32 v20, v208
	v_pk_add_f32 v[18:19], v[18:19], v[20:21]
	v_pk_add_f32 v[16:17], v[16:17], v[16:17] op_sel:[0,1] op_sel_hi:[1,0]
	v_pk_add_f32 v[18:19], v[18:19], v[18:19] op_sel:[0,1] op_sel_hi:[1,0]
	v_add_f32_e32 v22, v212, v213
	v_add_f32_e32 v24, v214, v215
	v_mov_b32_e32 v23, v218
	v_mov_b32_e32 v25, v219
	v_mov_b32_e32 v17, v216
	v_mov_b32_e32 v19, v217
	v_pk_add_f32 v[20:21], v[22:23], v[24:25]
	v_pk_add_f32 v[16:17], v[16:17], v[18:19]
	s_nop 0
	v_pk_add_f32 v[16:17], v[16:17], v[20:21]
	s_nop 0
	v_add_f32_e32 v16, v16, v17
	v_fmamk_f32 v16, v16, 0x3a800000, v158
	v_mul_f32_e32 v17, 0x4b800000, v16
	v_cmp_gt_f32_e64 s[10:11], s65, v16
	s_nop 1
	v_cndmask_b32_e64 v16, v16, v17, s[10:11]
	v_rsq_f32_e32 v18, v16
	v_mad_i64_i32 v[16:17], s[8:9], v48, s66, v[146:147]
	v_lshl_add_u64 v[16:17], v[16:17], 0, v[148:149]
	v_mul_f32_e32 v19, 0x45800000, v18
	v_cndmask_b32_e64 v18, v18, v19, s[10:11]
	v_pk_mul_f32 v[14:15], v[14:15], v[18:19] op_sel_hi:[1,0]
	v_pk_mul_f32 v[12:13], v[12:13], v[18:19] op_sel_hi:[1,0]
	v_pk_mul_f32 v[10:11], v[10:11], v[18:19] op_sel_hi:[1,0]
	v_pk_mul_f32 v[8:9], v[8:9], v[18:19] op_sel_hi:[1,0]
	v_pk_mul_f32 v[6:7], v[6:7], v[18:19] op_sel_hi:[1,0]
	v_pk_mul_f32 v[4:5], v[4:5], v[18:19] op_sel_hi:[1,0]
	v_pk_mul_f32 v[20:21], v[2:3], v[18:19] op_sel_hi:[1,0]
	v_pk_mul_f32 v[18:19], v[0:1], v[18:19] op_sel_hi:[1,0]
	v_cvt_pk_bf16_f32 v0, v12, v13
	v_cvt_pk_bf16_f32 v1, v14, v15
	v_cvt_pk_bf16_f32 v2, v8, v9
	v_cvt_pk_bf16_f32 v3, v10, v11
	global_store_dwordx4 v[16:17], v[0:3], off sc1
	s_nop 1
	v_cvt_pk_bf16_f32 v0, v4, v5
	v_cvt_pk_bf16_f32 v1, v6, v7
	v_cvt_pk_bf16_f32 v2, v18, v19
	v_cvt_pk_bf16_f32 v3, v20, v21
	global_store_dwordx4 v[16:17], v[0:3], off offset:256 sc1
	s_cbranch_vccz .LBB0_1281
	s_waitcnt vmcnt(0)
	s_cmpk_gt_u32 s53, 0xff
	s_cbranch_scc1 .LBB0_1292
	s_barrier

; #define PG8_STAGE(bufoff, gbase, voff) do { _Pragma("unroll") for (int _i = 0; _i < 2; ++_i) \
;         __builtin_amdgcn_global_load_lds((const unsigned*)((const char*)(gbase) + (voff)[_i]), (LAS unsigned*)(lds + (bufoff) + ldsw + _i * 8192), 16, 0, 0); } while (0)
; #define PG8_LDA(dst, b, h) do { _Pragma("unroll") for (int m = 0; m < 4; ++m) _Pragma("unroll") for (int k = 0; k < 2; ++k) dst[m][k] = *(const LAS bf16x8*)(lds + PG8_SA(b, h) + aoff + m * 2048 + k * 1024); } while (0)
; #define PG8_LDB(dst, b, h) do { _Pragma("unroll") for (int n = 0; n < 2; ++n) _Pragma("unroll") for (int k = 0; k < 2; ++k) dst[n][k] = *(const LAS bf16x8*)(lds + PG8_SB(b, h) + boff + n * 2048 + k * 1024); } while (0)
; #define PG8_MMA(ai, bj, At, Bt) do { __builtin_amdgcn_s_setprio(1); _Pragma("unroll") for (int m = 0; m < 4; ++m) _Pragma("unroll") for (int n = 0; n < 2; ++n) _Pragma("unroll") for (int k = 0; k < 2; ++k) \
;         acc[ai][bj][m][n] = __builtin_amdgcn_mfma_f32_16x16x32_bf16(Bt[n][k], At[m][k], acc[ai][bj][m][n], 0, 0, 0); __builtin_amdgcn_s_setprio(0); } while (0)
; #define PG8_WAIT_L(n) asm volatile("s_waitcnt lgkmcnt(" #n ")" ::: "memory")
; #define PG8_BAR __builtin_amdgcn_s_barrier()
; #define PG8_SCHED __builtin_amdgcn_sched_barrier(0)
;     ...
;             PG8_LDB(B0, 0, 0); PG8_SCHED; PG8_LDA(At, 0, 0); PG8_STAGE(PG8_SA(1, 1), a1 + hA, voffA);
;             PG8_WAIT_L(8); PG8_BAR; PG8_WAIT_L(0); PG8_MMA(0, 0, At, B0); PG8_BAR; PG8_SCHED;
;             PG8_LDB(B1, 0, 1); PG8_STAGE(PG8_SB(0, 0), b2, voffB);
;             PG8_BAR; PG8_WAIT_L(0); PG8_MMA(0, 1, At, B1); PG8_BAR;
;             PG8_LDA(At, 0, 1); PG8_STAGE(PG8_SA(0, 0), a2, voffA);
;             PG8_BAR; PG8_WAIT_L(0); PG8_MMA(1, 0, At, B0); PG8_BAR; PG8_SCHED;
.LBB0_2099:
	ds_read_b128 v[156:159], v151
	ds_read_b128 v[160:163], v151 offset:1024
	ds_read_b128 v[170:173], v151 offset:2048
	ds_read_b128 v[174:177], v151 offset:3072
	s_add_u32 s38, s36, 0xfffc0080
	s_addc_u32 s39, s37, -1
	s_cmp_eq_u32 s71, 12
	s_cselect_b32 s41, s25, s39
	s_cselect_b32 s40, s44, s38
	s_cselect_b32 s39, s35, s70
	s_cselect_b32 s38, s45, s69
	v_lshl_add_u64 v[146:147], s[36:37], 0, v[138:139]
	s_add_i32 m0, s53, 0xc000
	ds_read_b128 v[178:181], v152
	ds_read_b128 v[182:185], v152 offset:1024
	ds_read_b128 v[186:189], v152 offset:2048
	ds_read_b128 v[190:193], v152 offset:3072
	ds_read_b128 v[194:197], v152 offset:4096
	ds_read_b128 v[198:201], v152 offset:5120
	ds_read_b128 v[202:205], v152 offset:6144
	ds_read_b128 v[206:209], v152 offset:7168
	global_load_lds_dwordx4 v[146:147], off
	v_lshl_add_u64 v[146:147], s[36:37], 0, v[136:137]
	s_add_i32 m0, s53, 0xe000
	s_nop 0
	global_load_lds_dwordx4 v[146:147], off
	s_waitcnt lgkmcnt(8)
	s_barrier
	s_waitcnt lgkmcnt(0)
	s_setprio 1
	s_waitcnt lgkmcnt(0)
	v_mfma_f32_16x16x32_bf16 v[124:127], v[156:159], v[178:181], v[124:127]
	v_mfma_f32_16x16x32_bf16 v[120:123], v[170:173], v[178:181], v[120:123]
	v_mfma_f32_16x16x32_bf16 v[108:111], v[156:159], v[186:189], v[108:111]
	v_mfma_f32_16x16x32_bf16 v[104:107], v[170:173], v[186:189], v[104:107]
	v_mfma_f32_16x16x32_bf16 v[92:95], v[156:159], v[194:197], v[92:95]
	v_mfma_f32_16x16x32_bf16 v[88:91], v[170:173], v[194:197], v[88:91]
	v_mfma_f32_16x16x32_bf16 v[76:79], v[156:159], v[202:205], v[76:79]
	v_mfma_f32_16x16x32_bf16 v[72:75], v[170:173], v[202:205], v[72:75]
	v_mfma_f32_16x16x32_bf16 v[124:127], v[160:163], v[182:185], v[124:127]
	v_mfma_f32_16x16x32_bf16 v[120:123], v[174:177], v[182:185], v[120:123]
	v_mfma_f32_16x16x32_bf16 v[108:111], v[160:163], v[190:193], v[108:111]
	v_mfma_f32_16x16x32_bf16 v[104:107], v[174:177], v[190:193], v[104:107]
	v_mfma_f32_16x16x32_bf16 v[92:95], v[160:163], v[198:201], v[92:95]
	v_mfma_f32_16x16x32_bf16 v[88:91], v[174:177], v[198:201], v[88:91]
	v_mfma_f32_16x16x32_bf16 v[76:79], v[160:163], v[206:209], v[76:79]
	v_mfma_f32_16x16x32_bf16 v[72:75], v[174:177], v[206:209], v[72:75]
	s_setprio 0
	s_barrier
	s_add_i32 s72, s61, s52
	v_lshl_add_u64 v[146:147], s[38:39], 0, v[130:131]
	s_mov_b32 m0, s72
	ds_read_b128 v[210:213], v153
	ds_read_b128 v[214:217], v153 offset:1024
	ds_read_b128 v[218:221], v153 offset:2048
	ds_read_b128 v[222:225], v153 offset:3072
	global_load_lds_dwordx4 v[146:147], off
	v_lshl_add_u64 v[164:165], s[38:39], 0, v[134:135]
	s_add_i32 m0, s72, 0x2000
	s_nop 0
	global_load_lds_dwordx4 v[164:165], off
	s_barrier
	s_waitcnt lgkmcnt(0)
	s_setprio 1
	s_waitcnt lgkmcnt(0)
	v_mfma_f32_16x16x32_bf16 v[116:119], v[210:213], v[178:181], v[116:119]
	v_mfma_f32_16x16x32_bf16 v[112:115], v[218:221], v[178:181], v[112:115]
	v_mfma_f32_16x16x32_bf16 v[100:103], v[210:213], v[186:189], v[100:103]
	v_mfma_f32_16x16x32_bf16 v[96:99], v[218:221], v[186:189], v[96:99]
	v_mfma_f32_16x16x32_bf16 v[84:87], v[210:213], v[194:197], v[84:87]
	v_mfma_f32_16x16x32_bf16 v[80:83], v[218:221], v[194:197], v[80:83]
	v_mfma_f32_16x16x32_bf16 v[68:71], v[210:213], v[202:205], v[68:71]
	v_mfma_f32_16x16x32_bf16 v[64:67], v[218:221], v[202:205], v[64:67]
	v_mfma_f32_16x16x32_bf16 v[116:119], v[214:217], v[182:185], v[116:119]
	v_mfma_f32_16x16x32_bf16 v[112:115], v[222:225], v[182:185], v[112:115]
	v_mfma_f32_16x16x32_bf16 v[100:103], v[214:217], v[190:193], v[100:103]
	v_mfma_f32_16x16x32_bf16 v[96:99], v[222:225], v[190:193], v[96:99]
	v_mfma_f32_16x16x32_bf16 v[84:87], v[214:217], v[198:201], v[84:87]
	v_mfma_f32_16x16x32_bf16 v[80:83], v[222:225], v[198:201], v[80:83]
	v_mfma_f32_16x16x32_bf16 v[68:71], v[214:217], v[206:209], v[68:71]
	v_mfma_f32_16x16x32_bf16 v[64:67], v[222:225], v[206:209], v[64:67]
	s_setprio 0
	s_mov_b32 m0, s53
	v_lshl_add_u64 v[226:227], s[40:41], 0, v[128:129]
	s_barrier
	ds_read_b128 v[178:181], v152 offset:16384
	ds_read_b128 v[182:185], v152 offset:17408
	ds_read_b128 v[186:189], v152 offset:18432
	ds_read_b128 v[190:193], v152 offset:19456
	ds_read_b128 v[194:197], v152 offset:20480
	ds_read_b128 v[198:201], v152 offset:21504
	ds_read_b128 v[202:205], v152 offset:22528
	ds_read_b128 v[206:209], v152 offset:23552
	global_load_lds_dwordx4 v[226:227], off
	v_lshl_add_u64 v[228:229], s[40:41], 0, v[132:133]
	s_mov_b32 m0, s54
	s_nop 0
	global_load_lds_dwordx4 v[228:229], off
	s_barrier
	s_waitcnt lgkmcnt(0)
	s_setprio 1
	s_waitcnt lgkmcnt(0)
	v_mfma_f32_16x16x32_bf16 v[60:63], v[156:159], v[178:181], v[60:63]
	v_mfma_f32_16x16x32_bf16 v[56:59], v[170:173], v[178:181], v[56:59]
	v_mfma_f32_16x16x32_bf16 v[44:47], v[156:159], v[186:189], v[44:47]
	v_mfma_f32_16x16x32_bf16 v[40:43], v[170:173], v[186:189], v[40:43]
	v_mfma_f32_16x16x32_bf16 v[28:31], v[156:159], v[194:197], v[28:31]
	v_mfma_f32_16x16x32_bf16 v[24:27], v[170:173], v[194:197], v[24:27]
	v_mfma_f32_16x16x32_bf16 v[12:15], v[156:159], v[202:205], v[12:15]
	v_mfma_f32_16x16x32_bf16 v[8:11], v[170:173], v[202:205], v[8:11]
	v_mfma_f32_16x16x32_bf16 v[60:63], v[160:163], v[182:185], v[60:63]
	v_mfma_f32_16x16x32_bf16 v[56:59], v[174:177], v[182:185], v[56:59]
	v_mfma_f32_16x16x32_bf16 v[44:47], v[160:163], v[190:193], v[44:47]
	v_mfma_f32_16x16x32_bf16 v[40:43], v[174:177], v[190:193], v[40:43]
	v_mfma_f32_16x16x32_bf16 v[28:31], v[160:163], v[198:201], v[28:31]
	v_mfma_f32_16x16x32_bf16 v[24:27], v[174:177], v[198:201], v[24:27]
	v_mfma_f32_16x16x32_bf16 v[12:15], v[160:163], v[206:209], v[12:15]
	v_mfma_f32_16x16x32_bf16 v[8:11], v[174:177], v[206:209], v[8:11]
	s_setprio 0
	s_barrier
; #define PG8_STAGE(bufoff, gbase, voff) do { _Pragma("unroll") for (int _i = 0; _i < 2; ++_i) \
;         __builtin_amdgcn_global_load_lds((const unsigned*)((const char*)(gbase) + (voff)[_i]), (LAS unsigned*)(lds + (bufoff) + ldsw + _i * 8192), 16, 0, 0); } while (0)
; #define PG8_LDA(dst, b, h) do { _Pragma("unroll") for (int m = 0; m < 4; ++m) _Pragma("unroll") for (int k = 0; k < 2; ++k) dst[m][k] = *(const LAS bf16x8*)(lds + PG8_SA(b, h) + aoff + m * 2048 + k * 1024); } while (0)
; #define PG8_LDB(dst, b, h) do { _Pragma("unroll") for (int n = 0; n < 2; ++n) _Pragma("unroll") for (int k = 0; k < 2; ++k) dst[n][k] = *(const LAS bf16x8*)(lds + PG8_SB(b, h) + boff + n * 2048 + k * 1024); } while (0)
; #define PG8_MMA(ai, bj, At, Bt) do { __builtin_amdgcn_s_setprio(1); _Pragma("unroll") for (int m = 0; m < 4; ++m) _Pragma("unroll") for (int n = 0; n < 2; ++n) _Pragma("unroll") for (int k = 0; k < 2; ++k) \
;         acc[ai][bj][m][n] = __builtin_amdgcn_mfma_f32_16x16x32_bf16(Bt[n][k], At[m][k], acc[ai][bj][m][n], 0, 0, 0); __builtin_amdgcn_s_setprio(0); } while (0)
; #define PG8_WAIT_V(n) asm volatile("s_waitcnt vmcnt(" #n ")" ::: "memory")
; #define PG8_WAIT_L(n) asm volatile("s_waitcnt lgkmcnt(" #n ")" ::: "memory")
; #define PG8_BAR __builtin_amdgcn_s_barrier()
; #define PG8_SCHED __builtin_amdgcn_sched_barrier(0)
;     ...
;             PG8_STAGE(PG8_SB(0, 1), b2 + hB, voffB);
;             PG8_WAIT_V(6); PG8_BAR; PG8_MMA(1, 1, At, B1); PG8_BAR;
;             PG8_LDB(B0, 1, 0); PG8_SCHED; PG8_LDA(At, 1, 0); PG8_STAGE(PG8_SA(0, 1), a2 + hA, voffA);
;             PG8_WAIT_L(8); PG8_BAR; PG8_WAIT_L(0); PG8_MMA(0, 0, At, B0); PG8_BAR; PG8_SCHED;
;             PG8_LDB(B1, 1, 1); PG8_STAGE(PG8_SB(1, 0), b3, voffB);
;             PG8_BAR; PG8_WAIT_L(0); PG8_MMA(0, 1, At, B1); PG8_BAR;
;             PG8_LDA(At, 1, 1); PG8_STAGE(PG8_SA(1, 0), a3, voffA);
;             PG8_BAR; PG8_WAIT_L(0); PG8_MMA(1, 0, At, B0); PG8_BAR; PG8_SCHED;
	s_add_u32 s72, s38, 0x40000
	s_addc_u32 s73, s39, 0
	s_add_i32 s74, s62, s52
	v_lshl_add_u64 v[156:157], s[72:73], 0, v[130:131]
	s_mov_b32 m0, s74
	s_nop 0
	global_load_lds_dwordx4 v[156:157], off
	v_lshl_add_u64 v[156:157], s[72:73], 0, v[134:135]
	s_add_i32 m0, s74, 0x2000
	s_nop 0
	global_load_lds_dwordx4 v[156:157], off
	s_waitcnt vmcnt(6)
	s_barrier
	s_setprio 1
	v_mfma_f32_16x16x32_bf16 v[52:55], v[210:213], v[178:181], v[52:55]
	v_mfma_f32_16x16x32_bf16 v[48:51], v[218:221], v[178:181], v[48:51]
	v_mfma_f32_16x16x32_bf16 v[36:39], v[210:213], v[186:189], v[36:39]
	v_mfma_f32_16x16x32_bf16 v[32:35], v[218:221], v[186:189], v[32:35]
	v_mfma_f32_16x16x32_bf16 v[20:23], v[210:213], v[194:197], v[20:23]
	v_mfma_f32_16x16x32_bf16 v[16:19], v[218:221], v[194:197], v[16:19]
	v_mfma_f32_16x16x32_bf16 v[4:7], v[210:213], v[202:205], v[4:7]
	v_mfma_f32_16x16x32_bf16 v[0:3], v[218:221], v[202:205], v[0:3]
	v_mfma_f32_16x16x32_bf16 v[52:55], v[214:217], v[182:185], v[52:55]
	v_mfma_f32_16x16x32_bf16 v[48:51], v[222:225], v[182:185], v[48:51]
	v_mfma_f32_16x16x32_bf16 v[36:39], v[214:217], v[190:193], v[36:39]
	v_mfma_f32_16x16x32_bf16 v[32:35], v[222:225], v[190:193], v[32:35]
	v_mfma_f32_16x16x32_bf16 v[20:23], v[214:217], v[198:201], v[20:23]
	v_mfma_f32_16x16x32_bf16 v[16:19], v[222:225], v[198:201], v[16:19]
	v_mfma_f32_16x16x32_bf16 v[4:7], v[214:217], v[206:209], v[4:7]
	v_mfma_f32_16x16x32_bf16 v[0:3], v[222:225], v[206:209], v[0:3]
	s_setprio 0
	s_add_i32 s72, 0, 0x18000
	v_add_u32_e32 v155, s72, v149
	s_barrier
	ds_read_b128 v[156:159], v155
	ds_read_b128 v[160:163], v155 offset:1024
	ds_read_b128 v[170:173], v155 offset:2048
	ds_read_b128 v[174:177], v155 offset:3072
	s_add_u32 s40, s40, 0x40000
	s_addc_u32 s41, s41, 0
	s_mov_b32 m0, s55
	v_lshl_add_u64 v[210:211], s[40:41], 0, v[128:129]
	ds_read_b128 v[178:181], v152 offset:32768
	ds_read_b128 v[182:185], v152 offset:33792
	ds_read_b128 v[186:189], v152 offset:34816
	ds_read_b128 v[190:193], v152 offset:35840
	ds_read_b128 v[194:197], v152 offset:36864
	ds_read_b128 v[198:201], v152 offset:37888
	ds_read_b128 v[202:205], v152 offset:38912
	ds_read_b128 v[206:209], v152 offset:39936
	global_load_lds_dwordx4 v[210:211], off
	v_lshl_add_u64 v[210:211], s[40:41], 0, v[132:133]
	s_mov_b32 m0, s56
	s_nop 0
	global_load_lds_dwordx4 v[210:211], off
	s_waitcnt lgkmcnt(8)
	s_barrier
	s_waitcnt lgkmcnt(0)
	s_setprio 1
	s_waitcnt lgkmcnt(0)
	v_mfma_f32_16x16x32_bf16 v[124:127], v[156:159], v[178:181], v[124:127]
	v_mfma_f32_16x16x32_bf16 v[120:123], v[170:173], v[178:181], v[120:123]
	v_mfma_f32_16x16x32_bf16 v[108:111], v[156:159], v[186:189], v[108:111]
	v_mfma_f32_16x16x32_bf16 v[104:107], v[170:173], v[186:189], v[104:107]
	v_mfma_f32_16x16x32_bf16 v[92:95], v[156:159], v[194:197], v[92:95]
	v_mfma_f32_16x16x32_bf16 v[88:91], v[170:173], v[194:197], v[88:91]
	v_mfma_f32_16x16x32_bf16 v[76:79], v[156:159], v[202:205], v[76:79]
	v_mfma_f32_16x16x32_bf16 v[72:75], v[170:173], v[202:205], v[72:75]
	v_mfma_f32_16x16x32_bf16 v[124:127], v[160:163], v[182:185], v[124:127]
	v_mfma_f32_16x16x32_bf16 v[120:123], v[174:177], v[182:185], v[120:123]
	v_mfma_f32_16x16x32_bf16 v[108:111], v[160:163], v[190:193], v[108:111]
	v_mfma_f32_16x16x32_bf16 v[104:107], v[174:177], v[190:193], v[104:107]
	v_mfma_f32_16x16x32_bf16 v[92:95], v[160:163], v[198:201], v[92:95]
	v_mfma_f32_16x16x32_bf16 v[88:91], v[174:177], v[198:201], v[88:91]
	v_mfma_f32_16x16x32_bf16 v[76:79], v[160:163], v[206:209], v[76:79]
	v_mfma_f32_16x16x32_bf16 v[72:75], v[174:177], v[206:209], v[72:75]
	s_setprio 0
	s_barrier
	s_add_i32 s40, 0, 0x1c000
	s_add_i32 s41, s72, s52
	v_add_u32_e32 v155, s40, v149
	v_lshl_add_u64 v[146:147], v[146:147], 0, s[26:27]
	s_mov_b32 m0, s41
	ds_read_b128 v[210:213], v155
	ds_read_b128 v[214:217], v155 offset:1024
	ds_read_b128 v[218:221], v155 offset:2048
	ds_read_b128 v[222:225], v155 offset:3072
	global_load_lds_dwordx4 v[146:147], off
	v_lshl_add_u64 v[146:147], v[164:165], 0, s[26:27]
	s_add_i32 m0, s41, 0x2000
	s_nop 0
	global_load_lds_dwordx4 v[146:147], off
	s_barrier
	s_waitcnt lgkmcnt(0)
	s_setprio 1
	s_waitcnt lgkmcnt(0)
	v_mfma_f32_16x16x32_bf16 v[116:119], v[210:213], v[178:181], v[116:119]
	v_mfma_f32_16x16x32_bf16 v[112:115], v[218:221], v[178:181], v[112:115]
	v_mfma_f32_16x16x32_bf16 v[100:103], v[210:213], v[186:189], v[100:103]
	v_mfma_f32_16x16x32_bf16 v[96:99], v[218:221], v[186:189], v[96:99]
	v_mfma_f32_16x16x32_bf16 v[84:87], v[210:213], v[194:197], v[84:87]
	v_mfma_f32_16x16x32_bf16 v[80:83], v[218:221], v[194:197], v[80:83]
	v_mfma_f32_16x16x32_bf16 v[68:71], v[210:213], v[202:205], v[68:71]
	v_mfma_f32_16x16x32_bf16 v[64:67], v[218:221], v[202:205], v[64:67]
	v_mfma_f32_16x16x32_bf16 v[116:119], v[214:217], v[182:185], v[116:119]
	v_mfma_f32_16x16x32_bf16 v[112:115], v[222:225], v[182:185], v[112:115]
	v_mfma_f32_16x16x32_bf16 v[100:103], v[214:217], v[190:193], v[100:103]
	v_mfma_f32_16x16x32_bf16 v[96:99], v[222:225], v[190:193], v[96:99]
	v_mfma_f32_16x16x32_bf16 v[84:87], v[214:217], v[198:201], v[84:87]
	v_mfma_f32_16x16x32_bf16 v[80:83], v[222:225], v[198:201], v[80:83]
	v_mfma_f32_16x16x32_bf16 v[68:71], v[214:217], v[206:209], v[68:71]
	v_mfma_f32_16x16x32_bf16 v[64:67], v[222:225], v[206:209], v[64:67]
	s_setprio 0
	s_mov_b32 m0, s58
	v_lshl_add_u64 v[146:147], v[226:227], 0, s[26:27]
	s_barrier
	ds_read_b128 v[178:181], v152 offset:49152
	ds_read_b128 v[182:185], v152 offset:50176
	ds_read_b128 v[186:189], v152 offset:51200
	ds_read_b128 v[190:193], v152 offset:52224
	ds_read_b128 v[194:197], v152 offset:53248
	ds_read_b128 v[198:201], v152 offset:54272
	ds_read_b128 v[202:205], v152 offset:55296
	ds_read_b128 v[206:209], v152 offset:56320
	global_load_lds_dwordx4 v[146:147], off
	v_lshl_add_u64 v[146:147], v[228:229], 0, s[26:27]
	s_mov_b32 m0, s59
	s_nop 0
	global_load_lds_dwordx4 v[146:147], off
	s_barrier
; #define PG8_STAGE(bufoff, gbase, voff) do { _Pragma("unroll") for (int _i = 0; _i < 2; ++_i) \
;         __builtin_amdgcn_global_load_lds((const unsigned*)((const char*)(gbase) + (voff)[_i]), (LAS unsigned*)(lds + (bufoff) + ldsw + _i * 8192), 16, 0, 0); } while (0)
; #define PG8_MMA(ai, bj, At, Bt) do { __builtin_amdgcn_s_setprio(1); _Pragma("unroll") for (int m = 0; m < 4; ++m) _Pragma("unroll") for (int n = 0; n < 2; ++n) _Pragma("unroll") for (int k = 0; k < 2; ++k) \
;         acc[ai][bj][m][n] = __builtin_amdgcn_mfma_f32_16x16x32_bf16(Bt[n][k], At[m][k], acc[ai][bj][m][n], 0, 0, 0); __builtin_amdgcn_s_setprio(0); } while (0)
; #define PG8_WAIT_V(n) asm volatile("s_waitcnt vmcnt(" #n ")" ::: "memory")
; #define PG8_WAIT_L(n) asm volatile("s_waitcnt lgkmcnt(" #n ")" ::: "memory")
; #define PG8_BAR __builtin_amdgcn_s_barrier()
; #define PG8_SCHED __builtin_amdgcn_sched_barrier(0)
;     ...
;             PG8_BAR; PG8_WAIT_L(0); PG8_MMA(1, 0, At, B0); PG8_BAR; PG8_SCHED;
;             PG8_STAGE(PG8_SB(1, 1), b3 + hB, voffB);
;             PG8_WAIT_V(6); PG8_BAR; PG8_MMA(1, 1, At, B1); PG8_BAR;
;         }
; __device__ __forceinline__ float row_rstd(const float* ssq, int row) {
;     const f32x4* p = (const f32x4*)(ssq + (size_t)row * 16);
;     const f32x4 a = p[0], b = p[1], c = p[2], d = p[3];
;     const float s = ((a[0] + a[1]) + (a[2] + a[3])) + ((b[0] + b[1]) + (b[2] + b[3])) + ((c[0] + c[1]) + (c[2] + c[3])) + ((d[0] + d[1]) + (d[2] + d[3]));
	s_waitcnt lgkmcnt(0)
	s_setprio 1
	s_waitcnt lgkmcnt(0)
	v_mfma_f32_16x16x32_bf16 v[60:63], v[156:159], v[178:181], v[60:63]
	v_mfma_f32_16x16x32_bf16 v[56:59], v[170:173], v[178:181], v[56:59]
	v_mfma_f32_16x16x32_bf16 v[44:47], v[156:159], v[186:189], v[44:47]
	v_mfma_f32_16x16x32_bf16 v[40:43], v[170:173], v[186:189], v[40:43]
	v_mfma_f32_16x16x32_bf16 v[28:31], v[156:159], v[194:197], v[28:31]
	v_mfma_f32_16x16x32_bf16 v[24:27], v[170:173], v[194:197], v[24:27]
	v_mfma_f32_16x16x32_bf16 v[12:15], v[156:159], v[202:205], v[12:15]
	v_mfma_f32_16x16x32_bf16 v[8:11], v[170:173], v[202:205], v[8:11]
	v_mfma_f32_16x16x32_bf16 v[60:63], v[160:163], v[182:185], v[60:63]
	v_mfma_f32_16x16x32_bf16 v[56:59], v[174:177], v[182:185], v[56:59]
	v_mfma_f32_16x16x32_bf16 v[44:47], v[160:163], v[190:193], v[44:47]
	v_mfma_f32_16x16x32_bf16 v[40:43], v[174:177], v[190:193], v[40:43]
	v_mfma_f32_16x16x32_bf16 v[28:31], v[160:163], v[198:201], v[28:31]
	v_mfma_f32_16x16x32_bf16 v[24:27], v[174:177], v[198:201], v[24:27]
	v_mfma_f32_16x16x32_bf16 v[12:15], v[160:163], v[206:209], v[12:15]
	v_mfma_f32_16x16x32_bf16 v[8:11], v[174:177], v[206:209], v[8:11]
	s_setprio 0
	s_barrier
	s_add_u32 s38, s38, 0x40080
	s_addc_u32 s39, s39, 0
	s_add_i32 s40, s40, s52
	v_lshl_add_u64 v[146:147], s[38:39], 0, v[130:131]
	s_mov_b32 m0, s40
	s_nop 0
	global_load_lds_dwordx4 v[146:147], off
	v_lshl_add_u64 v[146:147], s[38:39], 0, v[134:135]
	s_add_i32 m0, s40, 0x2000
	s_nop 0
	global_load_lds_dwordx4 v[146:147], off
	s_waitcnt vmcnt(6)
	s_barrier
	s_setprio 1
	v_mfma_f32_16x16x32_bf16 v[52:55], v[210:213], v[178:181], v[52:55]
	v_mfma_f32_16x16x32_bf16 v[48:51], v[218:221], v[178:181], v[48:51]
	v_mfma_f32_16x16x32_bf16 v[36:39], v[210:213], v[186:189], v[36:39]
	v_mfma_f32_16x16x32_bf16 v[32:35], v[218:221], v[186:189], v[32:35]
	v_mfma_f32_16x16x32_bf16 v[20:23], v[210:213], v[194:197], v[20:23]
	v_mfma_f32_16x16x32_bf16 v[16:19], v[218:221], v[194:197], v[16:19]
	v_mfma_f32_16x16x32_bf16 v[4:7], v[210:213], v[202:205], v[4:7]
	v_mfma_f32_16x16x32_bf16 v[0:3], v[218:221], v[202:205], v[0:3]
	v_mfma_f32_16x16x32_bf16 v[52:55], v[214:217], v[182:185], v[52:55]
	v_mfma_f32_16x16x32_bf16 v[48:51], v[222:225], v[182:185], v[48:51]
	v_mfma_f32_16x16x32_bf16 v[36:39], v[214:217], v[190:193], v[36:39]
	v_mfma_f32_16x16x32_bf16 v[32:35], v[222:225], v[190:193], v[32:35]
	v_mfma_f32_16x16x32_bf16 v[20:23], v[214:217], v[198:201], v[20:23]
	v_mfma_f32_16x16x32_bf16 v[16:19], v[222:225], v[198:201], v[16:19]
	v_mfma_f32_16x16x32_bf16 v[4:7], v[214:217], v[206:209], v[4:7]
	v_mfma_f32_16x16x32_bf16 v[0:3], v[222:225], v[206:209], v[0:3]
	s_setprio 0
	s_add_i32 s71, s71, 2
	s_add_u32 s69, s69, 0x100
	s_addc_u32 s70, s70, 0
	s_add_u32 s36, s36, 0x100
	s_addc_u32 s37, s37, 0
	s_cmp_gt_u32 s71, 13
	s_barrier
	s_cbranch_scc0 .LBB0_2099
	v_lshl_add_u32 v146, s68, 8, v148
	v_ashrrev_i32_e32 v147, 31, v146
	v_lshlrev_b64 v[156:157], 6, v[146:147]
	v_lshl_add_u64 v[164:165], s[22:23], 0, v[156:157]
	v_subrev_u32_e32 v180, s22, v164
	v_add_u32_e32 v181, 0x0, v180
	global_load_dwordx4 v[182:185], v181, s[22:23]
	v_add_u32_e32 v181, 0x10, v180
	global_load_dwordx4 v[186:189], v181, s[22:23]
	v_add_u32_e32 v181, 0x20, v180
	global_load_dwordx4 v[190:193], v181, s[22:23]
	v_add_u32_e32 v181, 0x30, v180
	global_load_dwordx4 v[194:197], v181, s[22:23]
	v_add_u32_e32 v181, 0x400, v180
	global_load_dwordx4 v[198:201], v181, s[22:23]
	v_add_u32_e32 v181, 0x410, v180
	global_load_dwordx4 v[202:205], v181, s[22:23]
	v_add_u32_e32 v181, 0x420, v180
	global_load_dwordx4 v[206:209], v181, s[22:23]
	v_add_u32_e32 v181, 0x430, v180
	global_load_dwordx4 v[210:213], v181, s[22:23]
	v_add_u32_e32 v181, 0x800, v180
	global_load_dwordx4 v[214:217], v181, s[22:23]
	v_add_u32_e32 v181, 0x810, v180
	global_load_dwordx4 v[218:221], v181, s[22:23]
	v_add_u32_e32 v181, 0x820, v180
	global_load_dwordx4 v[222:225], v181, s[22:23]
	v_add_u32_e32 v181, 0x830, v180
	global_load_dwordx4 v[232:235], v181, s[22:23]
	v_add_u32_e32 v181, 0xc00, v180
	global_load_dwordx4 v[236:239], v181, s[22:23]
	v_add_u32_e32 v181, 0xc10, v180
	global_load_dwordx4 v[240:243], v181, s[22:23]
	v_add_u32_e32 v181, 0xc20, v180
	global_load_dwordx4 v[244:247], v181, s[22:23]
	v_add_u32_e32 v181, 0xc30, v180
	global_load_dwordx4 v[248:251], v181, s[22:23]
	v_or_b32_e32 v164, 16, v146
	v_lshl_or_b32 v147, s33, 9, v150
	v_ashrrev_i32_e32 v165, 31, v164
	v_lshl_add_u32 v155, v146, 13, v147
	s_waitcnt vmcnt(12)
; __device__ __forceinline__ u32x4 pack8(const f32x4 v0, const f32x4 v1) { u32x4 w; w.x = pk2(v0[0], v0[1]); w.y = pk2(v0[2], v0[3]); w.z = pk2(v1[0], v1[1]); w.w = pk2(v1[2], v1[3]); return w; }
; __device__ __forceinline__ float row_rstd(const float* ssq, int row) {
;     const f32x4* p = (const f32x4*)(ssq + (size_t)row * 16);
;     const f32x4 a = p[0], b = p[1], c = p[2], d = p[3];
;     const float s = ((a[0] + a[1]) + (a[2] + a[3])) + ((b[0] + b[1]) + (b[2] + b[3])) + ((c[0] + c[1]) + (c[2] + c[3])) + ((d[0] + d[1]) + (d[2] + d[3]));
;     return rsqrtf(s * (1.0f / 1024.0f) + 1e-6f);
;     __device__ __forceinline__ void operator()(const f32x4 (&acc)[2][2][4][2], const Unit& u, int wr, int wc, int fr, int fq) const {
;     ...
;             for (int m = 0; m < 4; ++m) {
;                 const int row = row0 + ai * 128 + m * 16; const float rs = row_rstd(ssq, row);
; #pragma unroll
;                 for (int bj = 0; bj < 2; ++bj) { f32x4 v0 = acc[ai][bj][m][0] * rs, v1 = acc[ai][bj][m][1] * rs;
; #pragma unroll
;                     for (int j = 0; j < 4; ++j) { const float a = fmaxf(v0[j], 0.f), b = fmaxf(v1[j], 0.f); v0[j] = a * a; v1[j] = b * b; }
;                     __builtin_amdgcn_raw_buffer_store_b128(pack8(v0, v1), rsrc, (unsigned)(((size_t)row * DFF + col0 + bj * 128) * 2), 0, 16  ); }
;             }
	v_mov_b32_e32 v178, v183
	v_mov_b32_e32 v179, v184
	v_mov_b32_e32 v157, v185
	v_mov_b32_e32 v158, v187
	v_mov_b32_e32 v159, v188
	v_mov_b32_e32 v161, v189
	v_mov_b32_e32 v156, v182
	v_pk_add_f32 v[156:157], v[178:179], v[156:157]
	v_mov_b32_e32 v160, v186
	v_pk_add_f32 v[158:159], v[158:159], v[160:161]
	v_pk_add_f32 v[156:157], v[156:157], v[156:157] op_sel:[0,1] op_sel_hi:[1,0]
	v_pk_add_f32 v[158:159], v[158:159], v[158:159] op_sel:[0,1] op_sel_hi:[1,0]
	v_add_f32_e32 v162, v190, v191
	v_add_f32_e32 v170, v192, v193
	v_mov_b32_e32 v163, v196
	v_mov_b32_e32 v171, v197
	v_mov_b32_e32 v157, v194
	v_mov_b32_e32 v159, v195
	v_pk_add_f32 v[160:161], v[162:163], v[170:171]
	v_pk_add_f32 v[156:157], v[156:157], v[158:159]
	s_nop 0
	v_pk_add_f32 v[156:157], v[156:157], v[160:161]
	s_nop 0
	v_add_f32_e32 v156, v156, v157
	v_fmamk_f32 v156, v156, 0x3a800000, v154
	v_mul_f32_e32 v157, 0x4b800000, v156
	v_cmp_gt_f32_e32 vcc, s63, v156
	s_nop 1
	v_cndmask_b32_e32 v156, v156, v157, vcc
	v_rsq_f32_e32 v158, v156
	v_lshlrev_b64 v[156:157], 6, v[164:165]
	v_lshl_add_u64 v[156:157], s[22:23], 0, v[156:157]
	v_mul_f32_e32 v159, 0x45800000, v158
	v_cndmask_b32_e32 v158, v158, v159, vcc
	v_pk_mul_f32 v[126:127], v[126:127], v[158:159] op_sel_hi:[1,0]
	v_pk_mul_f32 v[124:125], v[124:125], v[158:159] op_sel_hi:[1,0]
	v_pk_mul_f32 v[122:123], v[122:123], v[158:159] op_sel_hi:[1,0]
	v_pk_mul_f32 v[120:121], v[120:121], v[158:159] op_sel_hi:[1,0]
	v_pk_mul_f32 v[114:115], v[114:115], v[158:159] op_sel_hi:[1,0]
	v_pk_mul_f32 v[112:113], v[112:113], v[158:159] op_sel_hi:[1,0]
	v_pk_mul_f32 v[118:119], v[118:119], v[158:159] op_sel_hi:[1,0]
	v_pk_mul_f32 v[116:117], v[116:117], v[158:159] op_sel_hi:[1,0]
	v_max_f32_e32 v124, 0, v124
	v_max_f32_e32 v120, 0, v120
	v_max_f32_e32 v125, 0, v125
	v_max_f32_e32 v121, 0, v121
	v_max_f32_e32 v126, 0, v126
	v_max_f32_e32 v122, 0, v122
	v_max_f32_e32 v127, 0, v127
	v_max_f32_e32 v123, 0, v123
	v_max_f32_e32 v112, 0, v112
	v_max_f32_e32 v113, 0, v113
	v_max_f32_e32 v114, 0, v114
	v_max_f32_e32 v115, 0, v115
	v_max_f32_e32 v116, 0, v116
	v_max_f32_e32 v117, 0, v117
	v_max_f32_e32 v118, 0, v118
	v_max_f32_e32 v119, 0, v119
	v_pk_mul_f32 v[124:125], v[124:125], v[124:125]
	v_pk_mul_f32 v[120:121], v[120:121], v[120:121]
	v_pk_mul_f32 v[126:127], v[126:127], v[126:127]
	v_pk_mul_f32 v[122:123], v[122:123], v[122:123]
	v_pk_mul_f32 v[158:159], v[112:113], v[112:113]
	v_pk_mul_f32 v[160:161], v[114:115], v[114:115]
	v_cvt_pk_bf16_f32 v112, v124, v125
	v_cvt_pk_bf16_f32 v113, v126, v127
	v_cvt_pk_bf16_f32 v114, v120, v121
	v_cvt_pk_bf16_f32 v115, v122, v123
	v_pk_mul_f32 v[116:117], v[116:117], v[116:117]
	v_pk_mul_f32 v[118:119], v[118:119], v[118:119]
	buffer_store_dwordx4 v[112:115], v155, s[12:15], 0 offen sc1
	s_nop 1
	v_cvt_pk_bf16_f32 v112, v116, v117
	v_cvt_pk_bf16_f32 v113, v118, v119
	v_cvt_pk_bf16_f32 v114, v158, v159
	v_cvt_pk_bf16_f32 v115, v160, v161
	buffer_store_dwordx4 v[112:115], v155, s[12:15], 0 offen offset:256 sc1
	s_nop 0
	v_or_b32_e32 v156, 32, v146
	v_ashrrev_i32_e32 v157, 31, v156
	v_lshl_add_u32 v155, v164, 13, v147
	v_add_u32_e32 v181, 0x2000, v180
	global_load_dwordx4 v[182:185], v181, s[22:23]
	v_add_u32_e32 v181, 0x2010, v180
	global_load_dwordx4 v[186:189], v181, s[22:23]
	v_add_u32_e32 v181, 0x2020, v180
	global_load_dwordx4 v[190:193], v181, s[22:23]
	v_add_u32_e32 v181, 0x2030, v180
	global_load_dwordx4 v[194:197], v181, s[22:23]
	s_waitcnt vmcnt(14)
	v_mov_b32_e32 v158, v199
	v_mov_b32_e32 v159, v200
	v_mov_b32_e32 v113, v201
	v_mov_b32_e32 v114, v203
	v_mov_b32_e32 v115, v204
	v_mov_b32_e32 v117, v205
	v_mov_b32_e32 v112, v198
	v_pk_add_f32 v[112:113], v[158:159], v[112:113]
	v_mov_b32_e32 v116, v202
	v_pk_add_f32 v[114:115], v[114:115], v[116:117]
	v_pk_add_f32 v[112:113], v[112:113], v[112:113] op_sel:[0,1] op_sel_hi:[1,0]
	v_pk_add_f32 v[114:115], v[114:115], v[114:115] op_sel:[0,1] op_sel_hi:[1,0]
	v_add_f32_e32 v118, v206, v207
	v_add_f32_e32 v120, v208, v209
	v_mov_b32_e32 v119, v212
	v_mov_b32_e32 v121, v213
	v_mov_b32_e32 v113, v210
	v_mov_b32_e32 v115, v211
	v_pk_add_f32 v[116:117], v[118:119], v[120:121]
	v_pk_add_f32 v[112:113], v[112:113], v[114:115]
	s_nop 0
	v_pk_add_f32 v[112:113], v[112:113], v[116:117]
	s_nop 0
	v_add_f32_e32 v112, v112, v113
	v_fmamk_f32 v112, v112, 0x3a800000, v154
	v_mul_f32_e32 v113, 0x4b800000, v112
	v_cmp_gt_f32_e32 vcc, s63, v112
	s_nop 1
	v_cndmask_b32_e32 v112, v112, v113, vcc
	v_rsq_f32_e32 v114, v112
	v_lshlrev_b64 v[112:113], 6, v[156:157]
	v_lshl_add_u64 v[112:113], s[22:23], 0, v[112:113]
	v_mul_f32_e32 v115, 0x45800000, v114
	v_cndmask_b32_e32 v114, v114, v115, vcc
	v_pk_mul_f32 v[110:111], v[110:111], v[114:115] op_sel_hi:[1,0]
	v_pk_mul_f32 v[108:109], v[108:109], v[114:115] op_sel_hi:[1,0]
	v_pk_mul_f32 v[106:107], v[106:107], v[114:115] op_sel_hi:[1,0]
	v_pk_mul_f32 v[104:105], v[104:105], v[114:115] op_sel_hi:[1,0]
	v_pk_mul_f32 v[98:99], v[98:99], v[114:115] op_sel_hi:[1,0]
	v_pk_mul_f32 v[96:97], v[96:97], v[114:115] op_sel_hi:[1,0]
	v_pk_mul_f32 v[102:103], v[102:103], v[114:115] op_sel_hi:[1,0]
	v_pk_mul_f32 v[100:101], v[100:101], v[114:115] op_sel_hi:[1,0]
	v_max_f32_e32 v108, 0, v108
	v_max_f32_e32 v104, 0, v104
	v_max_f32_e32 v109, 0, v109
	v_max_f32_e32 v105, 0, v105
	v_max_f32_e32 v110, 0, v110
	v_max_f32_e32 v106, 0, v106
	v_max_f32_e32 v111, 0, v111
	v_max_f32_e32 v107, 0, v107
	v_max_f32_e32 v96, 0, v96
	v_max_f32_e32 v97, 0, v97
	v_max_f32_e32 v98, 0, v98
	v_max_f32_e32 v99, 0, v99
	v_max_f32_e32 v100, 0, v100
	v_max_f32_e32 v101, 0, v101
	v_max_f32_e32 v102, 0, v102
	v_max_f32_e32 v103, 0, v103
	v_pk_mul_f32 v[108:109], v[108:109], v[108:109]
	v_pk_mul_f32 v[104:105], v[104:105], v[104:105]
	v_pk_mul_f32 v[110:111], v[110:111], v[110:111]
	v_pk_mul_f32 v[106:107], v[106:107], v[106:107]
	v_pk_mul_f32 v[114:115], v[96:97], v[96:97]
	v_pk_mul_f32 v[116:117], v[98:99], v[98:99]
	v_cvt_pk_bf16_f32 v96, v108, v109
	v_cvt_pk_bf16_f32 v97, v110, v111
	v_cvt_pk_bf16_f32 v98, v104, v105
	v_cvt_pk_bf16_f32 v99, v106, v107
	v_pk_mul_f32 v[100:101], v[100:101], v[100:101]
	v_pk_mul_f32 v[102:103], v[102:103], v[102:103]
	buffer_store_dwordx4 v[96:99], v155, s[12:15], 0 offen sc1
	s_nop 1
	v_cvt_pk_bf16_f32 v96, v100, v101
	v_cvt_pk_bf16_f32 v97, v102, v103
	v_cvt_pk_bf16_f32 v98, v114, v115
	v_cvt_pk_bf16_f32 v99, v116, v117
	buffer_store_dwordx4 v[96:99], v155, s[12:15], 0 offen offset:256 sc1
	s_nop 0
	v_or_b32_e32 v112, 48, v146
	v_ashrrev_i32_e32 v113, 31, v112
	v_lshl_add_u32 v116, v156, 13, v147
	v_add_u32_e32 v181, 0x2400, v180
	global_load_dwordx4 v[198:201], v181, s[22:23]
	v_add_u32_e32 v181, 0x2410, v180
	global_load_dwordx4 v[202:205], v181, s[22:23]
	v_add_u32_e32 v181, 0x2420, v180
	global_load_dwordx4 v[206:209], v181, s[22:23]
	v_add_u32_e32 v181, 0x2430, v180
	global_load_dwordx4 v[210:213], v181, s[22:23]
	s_waitcnt vmcnt(16)
; __device__ __forceinline__ u32x4 pack8(const f32x4 v0, const f32x4 v1) { u32x4 w; w.x = pk2(v0[0], v0[1]); w.y = pk2(v0[2], v0[3]); w.z = pk2(v1[0], v1[1]); w.w = pk2(v1[2], v1[3]); return w; }
; __device__ __forceinline__ float row_rstd(const float* ssq, int row) {
;     const f32x4* p = (const f32x4*)(ssq + (size_t)row * 16);
;     const f32x4 a = p[0], b = p[1], c = p[2], d = p[3];
;     const float s = ((a[0] + a[1]) + (a[2] + a[3])) + ((b[0] + b[1]) + (b[2] + b[3])) + ((c[0] + c[1]) + (c[2] + c[3])) + ((d[0] + d[1]) + (d[2] + d[3]));
;     return rsqrtf(s * (1.0f / 1024.0f) + 1e-6f);
;     __device__ __forceinline__ void operator()(const f32x4 (&acc)[2][2][4][2], const Unit& u, int wr, int wc, int fr, int fq) const {
;     ...
;             for (int m = 0; m < 4; ++m) {
;                 const int row = row0 + ai * 128 + m * 16; const float rs = row_rstd(ssq, row);
; #pragma unroll
;                 for (int bj = 0; bj < 2; ++bj) { f32x4 v0 = acc[ai][bj][m][0] * rs, v1 = acc[ai][bj][m][1] * rs;
; #pragma unroll
;                     for (int j = 0; j < 4; ++j) { const float a = fmaxf(v0[j], 0.f), b = fmaxf(v1[j], 0.f); v0[j] = a * a; v1[j] = b * b; }
;                     __builtin_amdgcn_raw_buffer_store_b128(pack8(v0, v1), rsrc, (unsigned)(((size_t)row * DFF + col0 + bj * 128) * 2), 0, 16  ); }
;             }
	v_mov_b32_e32 v114, v215
	v_mov_b32_e32 v115, v216
	v_mov_b32_e32 v97, v217
	v_mov_b32_e32 v98, v219
	v_mov_b32_e32 v99, v220
	v_mov_b32_e32 v101, v221
	v_mov_b32_e32 v96, v214
	v_pk_add_f32 v[96:97], v[114:115], v[96:97]
	v_mov_b32_e32 v100, v218
	v_pk_add_f32 v[98:99], v[98:99], v[100:101]
	v_pk_add_f32 v[96:97], v[96:97], v[96:97] op_sel:[0,1] op_sel_hi:[1,0]
	v_pk_add_f32 v[98:99], v[98:99], v[98:99] op_sel:[0,1] op_sel_hi:[1,0]
	v_add_f32_e32 v102, v222, v223
	v_add_f32_e32 v104, v224, v225
	v_mov_b32_e32 v103, v234
	v_mov_b32_e32 v105, v235
	v_mov_b32_e32 v97, v232
	v_mov_b32_e32 v99, v233
	v_pk_add_f32 v[100:101], v[102:103], v[104:105]
	v_pk_add_f32 v[96:97], v[96:97], v[98:99]
	s_nop 0
	v_pk_add_f32 v[96:97], v[96:97], v[100:101]
	s_nop 0
	v_add_f32_e32 v96, v96, v97
	v_fmamk_f32 v96, v96, 0x3a800000, v154
	v_mul_f32_e32 v97, 0x4b800000, v96
	v_cmp_gt_f32_e32 vcc, s63, v96
	s_nop 1
	v_cndmask_b32_e32 v96, v96, v97, vcc
	v_rsq_f32_e32 v98, v96
	v_lshlrev_b64 v[96:97], 6, v[112:113]
	v_lshl_add_u64 v[96:97], s[22:23], 0, v[96:97]
	v_mul_f32_e32 v99, 0x45800000, v98
	v_cndmask_b32_e32 v98, v98, v99, vcc
	v_pk_mul_f32 v[94:95], v[94:95], v[98:99] op_sel_hi:[1,0]
	v_pk_mul_f32 v[92:93], v[92:93], v[98:99] op_sel_hi:[1,0]
	v_pk_mul_f32 v[90:91], v[90:91], v[98:99] op_sel_hi:[1,0]
	v_pk_mul_f32 v[88:89], v[88:89], v[98:99] op_sel_hi:[1,0]
	v_pk_mul_f32 v[82:83], v[82:83], v[98:99] op_sel_hi:[1,0]
	v_pk_mul_f32 v[80:81], v[80:81], v[98:99] op_sel_hi:[1,0]
	v_pk_mul_f32 v[86:87], v[86:87], v[98:99] op_sel_hi:[1,0]
	v_pk_mul_f32 v[84:85], v[84:85], v[98:99] op_sel_hi:[1,0]
	v_max_f32_e32 v92, 0, v92
	v_max_f32_e32 v88, 0, v88
	v_max_f32_e32 v93, 0, v93
	v_max_f32_e32 v89, 0, v89
	v_max_f32_e32 v94, 0, v94
	v_max_f32_e32 v90, 0, v90
	v_max_f32_e32 v95, 0, v95
	v_max_f32_e32 v91, 0, v91
	v_max_f32_e32 v80, 0, v80
	v_max_f32_e32 v81, 0, v81
	v_max_f32_e32 v82, 0, v82
	v_max_f32_e32 v83, 0, v83
	v_max_f32_e32 v84, 0, v84
	v_max_f32_e32 v85, 0, v85
	v_max_f32_e32 v86, 0, v86
	v_max_f32_e32 v87, 0, v87
	v_pk_mul_f32 v[92:93], v[92:93], v[92:93]
	v_pk_mul_f32 v[88:89], v[88:89], v[88:89]
	v_pk_mul_f32 v[94:95], v[94:95], v[94:95]
	v_pk_mul_f32 v[90:91], v[90:91], v[90:91]
	v_pk_mul_f32 v[98:99], v[80:81], v[80:81]
	v_pk_mul_f32 v[100:101], v[82:83], v[82:83]
	v_cvt_pk_bf16_f32 v80, v92, v93
	v_cvt_pk_bf16_f32 v81, v94, v95
	v_cvt_pk_bf16_f32 v82, v88, v89
	v_cvt_pk_bf16_f32 v83, v90, v91
	v_pk_mul_f32 v[84:85], v[84:85], v[84:85]
	v_pk_mul_f32 v[86:87], v[86:87], v[86:87]
	buffer_store_dwordx4 v[80:83], v116, s[12:15], 0 offen sc1
	s_nop 1
	v_cvt_pk_bf16_f32 v80, v84, v85
	v_cvt_pk_bf16_f32 v81, v86, v87
	v_cvt_pk_bf16_f32 v82, v98, v99
	v_cvt_pk_bf16_f32 v83, v100, v101
	buffer_store_dwordx4 v[80:83], v116, s[12:15], 0 offen offset:256 sc1
	s_nop 0
	v_add_u32_e32 v96, 0x80, v146
	v_ashrrev_i32_e32 v97, 31, v96
	v_lshl_add_u32 v100, v112, 13, v147
	v_add_u32_e32 v181, 0x2800, v180
	global_load_dwordx4 v[214:217], v181, s[22:23]
	v_add_u32_e32 v181, 0x2810, v180
	global_load_dwordx4 v[218:221], v181, s[22:23]
	v_add_u32_e32 v181, 0x2820, v180
	global_load_dwordx4 v[222:225], v181, s[22:23]
	v_add_u32_e32 v181, 0x2830, v180
	global_load_dwordx4 v[232:235], v181, s[22:23]
	s_waitcnt vmcnt(18)
	v_mov_b32_e32 v98, v237
	v_mov_b32_e32 v99, v238
	v_mov_b32_e32 v81, v239
	v_mov_b32_e32 v82, v241
	v_mov_b32_e32 v83, v242
	v_mov_b32_e32 v85, v243
	v_mov_b32_e32 v80, v236
	v_pk_add_f32 v[80:81], v[98:99], v[80:81]
	v_mov_b32_e32 v84, v240
	v_pk_add_f32 v[82:83], v[82:83], v[84:85]
	v_pk_add_f32 v[80:81], v[80:81], v[80:81] op_sel:[0,1] op_sel_hi:[1,0]
	v_pk_add_f32 v[82:83], v[82:83], v[82:83] op_sel:[0,1] op_sel_hi:[1,0]
	v_add_f32_e32 v86, v244, v245
	v_add_f32_e32 v88, v246, v247
	v_mov_b32_e32 v87, v250
	v_mov_b32_e32 v89, v251
	v_mov_b32_e32 v81, v248
	v_mov_b32_e32 v83, v249
	v_pk_add_f32 v[84:85], v[86:87], v[88:89]
	v_pk_add_f32 v[80:81], v[80:81], v[82:83]
	s_nop 0
	v_pk_add_f32 v[80:81], v[80:81], v[84:85]
	s_nop 0
	v_add_f32_e32 v80, v80, v81
	v_fmamk_f32 v80, v80, 0x3a800000, v154
	v_mul_f32_e32 v81, 0x4b800000, v80
	v_cmp_gt_f32_e32 vcc, s63, v80
	s_nop 1
	v_cndmask_b32_e32 v80, v80, v81, vcc
	v_rsq_f32_e32 v82, v80
	v_lshlrev_b64 v[80:81], 6, v[96:97]
	v_lshl_add_u64 v[80:81], s[22:23], 0, v[80:81]
	v_mul_f32_e32 v83, 0x45800000, v82
	v_cndmask_b32_e32 v82, v82, v83, vcc
	v_pk_mul_f32 v[78:79], v[78:79], v[82:83] op_sel_hi:[1,0]
	v_pk_mul_f32 v[76:77], v[76:77], v[82:83] op_sel_hi:[1,0]
	v_pk_mul_f32 v[74:75], v[74:75], v[82:83] op_sel_hi:[1,0]
	v_pk_mul_f32 v[72:73], v[72:73], v[82:83] op_sel_hi:[1,0]
	v_pk_mul_f32 v[66:67], v[66:67], v[82:83] op_sel_hi:[1,0]
	v_pk_mul_f32 v[64:65], v[64:65], v[82:83] op_sel_hi:[1,0]
	v_pk_mul_f32 v[70:71], v[70:71], v[82:83] op_sel_hi:[1,0]
	v_pk_mul_f32 v[68:69], v[68:69], v[82:83] op_sel_hi:[1,0]
	v_max_f32_e32 v76, 0, v76
	v_max_f32_e32 v72, 0, v72
	v_max_f32_e32 v77, 0, v77
	v_max_f32_e32 v73, 0, v73
	v_max_f32_e32 v78, 0, v78
	v_max_f32_e32 v74, 0, v74
	v_max_f32_e32 v79, 0, v79
	v_max_f32_e32 v75, 0, v75
	v_max_f32_e32 v64, 0, v64
	v_max_f32_e32 v65, 0, v65
	v_max_f32_e32 v66, 0, v66
	v_max_f32_e32 v67, 0, v67
	v_max_f32_e32 v68, 0, v68
	v_max_f32_e32 v69, 0, v69
	v_max_f32_e32 v70, 0, v70
	v_max_f32_e32 v71, 0, v71
	v_pk_mul_f32 v[76:77], v[76:77], v[76:77]
	v_pk_mul_f32 v[72:73], v[72:73], v[72:73]
	v_pk_mul_f32 v[78:79], v[78:79], v[78:79]
	v_pk_mul_f32 v[74:75], v[74:75], v[74:75]
	v_pk_mul_f32 v[82:83], v[64:65], v[64:65]
	v_pk_mul_f32 v[84:85], v[66:67], v[66:67]
	v_cvt_pk_bf16_f32 v64, v76, v77
	v_cvt_pk_bf16_f32 v65, v78, v79
	v_cvt_pk_bf16_f32 v66, v72, v73
	v_cvt_pk_bf16_f32 v67, v74, v75
	v_pk_mul_f32 v[68:69], v[68:69], v[68:69]
	v_pk_mul_f32 v[70:71], v[70:71], v[70:71]
	buffer_store_dwordx4 v[64:67], v100, s[12:15], 0 offen sc1
	s_nop 1
	v_cvt_pk_bf16_f32 v64, v68, v69
	v_cvt_pk_bf16_f32 v65, v70, v71
	v_cvt_pk_bf16_f32 v66, v82, v83
	v_cvt_pk_bf16_f32 v67, v84, v85
	buffer_store_dwordx4 v[64:67], v100, s[12:15], 0 offen offset:256 sc1
	s_nop 0
	v_add_u32_e32 v80, 0x90, v146
	v_ashrrev_i32_e32 v81, 31, v80
	v_lshl_add_u32 v84, v96, 13, v147
	v_add_u32_e32 v181, 0x2c00, v180
	global_load_dwordx4 v[236:239], v181, s[22:23]
	v_add_u32_e32 v181, 0x2c10, v180
	global_load_dwordx4 v[240:243], v181, s[22:23]
	v_add_u32_e32 v181, 0x2c20, v180
	global_load_dwordx4 v[244:247], v181, s[22:23]
	v_add_u32_e32 v181, 0x2c30, v180
	global_load_dwordx4 v[248:251], v181, s[22:23]
	s_waitcnt vmcnt(18)
; __device__ __forceinline__ u32x4 pack8(const f32x4 v0, const f32x4 v1) { u32x4 w; w.x = pk2(v0[0], v0[1]); w.y = pk2(v0[2], v0[3]); w.z = pk2(v1[0], v1[1]); w.w = pk2(v1[2], v1[3]); return w; }
; __device__ __forceinline__ float row_rstd(const float* ssq, int row) {
;     const f32x4* p = (const f32x4*)(ssq + (size_t)row * 16);
;     const f32x4 a = p[0], b = p[1], c = p[2], d = p[3];
;     const float s = ((a[0] + a[1]) + (a[2] + a[3])) + ((b[0] + b[1]) + (b[2] + b[3])) + ((c[0] + c[1]) + (c[2] + c[3])) + ((d[0] + d[1]) + (d[2] + d[3]));
;     return rsqrtf(s * (1.0f / 1024.0f) + 1e-6f);
;     __device__ __forceinline__ void operator()(const f32x4 (&acc)[2][2][4][2], const Unit& u, int wr, int wc, int fr, int fq) const {
;     ...
;             for (int m = 0; m < 4; ++m) {
;                 const int row = row0 + ai * 128 + m * 16; const float rs = row_rstd(ssq, row);
; #pragma unroll
;                 for (int bj = 0; bj < 2; ++bj) { f32x4 v0 = acc[ai][bj][m][0] * rs, v1 = acc[ai][bj][m][1] * rs;
; #pragma unroll
;                     for (int j = 0; j < 4; ++j) { const float a = fmaxf(v0[j], 0.f), b = fmaxf(v1[j], 0.f); v0[j] = a * a; v1[j] = b * b; }
;                     __builtin_amdgcn_raw_buffer_store_b128(pack8(v0, v1), rsrc, (unsigned)(((size_t)row * DFF + col0 + bj * 128) * 2), 0, 16  ); }
;             }
	v_mov_b32_e32 v82, v183
	v_mov_b32_e32 v83, v184
	v_mov_b32_e32 v65, v185
	v_mov_b32_e32 v66, v187
	v_mov_b32_e32 v67, v188
	v_mov_b32_e32 v69, v189
	v_mov_b32_e32 v64, v182
	v_pk_add_f32 v[64:65], v[82:83], v[64:65]
	v_mov_b32_e32 v68, v186
	v_pk_add_f32 v[66:67], v[66:67], v[68:69]
	v_pk_add_f32 v[64:65], v[64:65], v[64:65] op_sel:[0,1] op_sel_hi:[1,0]
	v_pk_add_f32 v[66:67], v[66:67], v[66:67] op_sel:[0,1] op_sel_hi:[1,0]
	v_add_f32_e32 v70, v190, v191
	v_add_f32_e32 v72, v192, v193
	v_mov_b32_e32 v71, v196
	v_mov_b32_e32 v73, v197
	v_mov_b32_e32 v65, v194
	v_mov_b32_e32 v67, v195
	v_pk_add_f32 v[68:69], v[70:71], v[72:73]
	v_pk_add_f32 v[64:65], v[64:65], v[66:67]
	s_nop 0
	v_pk_add_f32 v[64:65], v[64:65], v[68:69]
	s_nop 0
	v_add_f32_e32 v64, v64, v65
	v_fmamk_f32 v64, v64, 0x3a800000, v154
	v_mul_f32_e32 v65, 0x4b800000, v64
	v_cmp_gt_f32_e32 vcc, s63, v64
	s_nop 1
	v_cndmask_b32_e32 v64, v64, v65, vcc
	v_rsq_f32_e32 v66, v64
	v_lshlrev_b64 v[64:65], 6, v[80:81]
	v_lshl_add_u64 v[64:65], s[22:23], 0, v[64:65]
	v_mul_f32_e32 v67, 0x45800000, v66
	v_cndmask_b32_e32 v66, v66, v67, vcc
	v_pk_mul_f32 v[62:63], v[62:63], v[66:67] op_sel_hi:[1,0]
	v_pk_mul_f32 v[60:61], v[60:61], v[66:67] op_sel_hi:[1,0]
	v_pk_mul_f32 v[58:59], v[58:59], v[66:67] op_sel_hi:[1,0]
	v_pk_mul_f32 v[56:57], v[56:57], v[66:67] op_sel_hi:[1,0]
	v_pk_mul_f32 v[50:51], v[50:51], v[66:67] op_sel_hi:[1,0]
	v_pk_mul_f32 v[48:49], v[48:49], v[66:67] op_sel_hi:[1,0]
	v_pk_mul_f32 v[54:55], v[54:55], v[66:67] op_sel_hi:[1,0]
	v_pk_mul_f32 v[52:53], v[52:53], v[66:67] op_sel_hi:[1,0]
	v_max_f32_e32 v60, 0, v60
	v_max_f32_e32 v56, 0, v56
	v_max_f32_e32 v61, 0, v61
	v_max_f32_e32 v57, 0, v57
	v_max_f32_e32 v62, 0, v62
	v_max_f32_e32 v58, 0, v58
	v_max_f32_e32 v63, 0, v63
	v_max_f32_e32 v59, 0, v59
	v_max_f32_e32 v48, 0, v48
	v_max_f32_e32 v49, 0, v49
	v_max_f32_e32 v50, 0, v50
	v_max_f32_e32 v51, 0, v51
	v_max_f32_e32 v52, 0, v52
	v_max_f32_e32 v53, 0, v53
	v_max_f32_e32 v54, 0, v54
	v_max_f32_e32 v55, 0, v55
	v_pk_mul_f32 v[60:61], v[60:61], v[60:61]
	v_pk_mul_f32 v[56:57], v[56:57], v[56:57]
	v_pk_mul_f32 v[62:63], v[62:63], v[62:63]
	v_pk_mul_f32 v[58:59], v[58:59], v[58:59]
	v_pk_mul_f32 v[66:67], v[48:49], v[48:49]
	v_pk_mul_f32 v[68:69], v[50:51], v[50:51]
	v_cvt_pk_bf16_f32 v48, v60, v61
	v_cvt_pk_bf16_f32 v49, v62, v63
	v_cvt_pk_bf16_f32 v50, v56, v57
	v_cvt_pk_bf16_f32 v51, v58, v59
	v_pk_mul_f32 v[52:53], v[52:53], v[52:53]
	v_pk_mul_f32 v[54:55], v[54:55], v[54:55]
	buffer_store_dwordx4 v[48:51], v84, s[12:15], 0 offen sc1
	s_nop 1
	v_cvt_pk_bf16_f32 v48, v52, v53
	v_cvt_pk_bf16_f32 v49, v54, v55
	v_cvt_pk_bf16_f32 v50, v66, v67
	v_cvt_pk_bf16_f32 v51, v68, v69
	buffer_store_dwordx4 v[48:51], v84, s[12:15], 0 offen offset:256 sc1
	s_nop 0
	v_add_u32_e32 v64, 0xa0, v146
	v_ashrrev_i32_e32 v65, 31, v64
	v_lshl_add_u32 v68, v80, 13, v147
	s_waitcnt vmcnt(14)
	v_mov_b32_e32 v66, v199
	v_mov_b32_e32 v67, v200
	v_mov_b32_e32 v49, v201
	v_mov_b32_e32 v50, v203
	v_mov_b32_e32 v51, v204
	v_mov_b32_e32 v53, v205
	v_mov_b32_e32 v48, v198
	v_pk_add_f32 v[48:49], v[66:67], v[48:49]
	v_mov_b32_e32 v52, v202
	v_pk_add_f32 v[50:51], v[50:51], v[52:53]
	v_pk_add_f32 v[48:49], v[48:49], v[48:49] op_sel:[0,1] op_sel_hi:[1,0]
	v_pk_add_f32 v[50:51], v[50:51], v[50:51] op_sel:[0,1] op_sel_hi:[1,0]
	v_add_f32_e32 v54, v206, v207
	v_add_f32_e32 v56, v208, v209
	v_mov_b32_e32 v55, v212
	v_mov_b32_e32 v57, v213
	v_mov_b32_e32 v49, v210
	v_mov_b32_e32 v51, v211
	v_pk_add_f32 v[52:53], v[54:55], v[56:57]
	v_pk_add_f32 v[48:49], v[48:49], v[50:51]
	s_nop 0
	v_pk_add_f32 v[48:49], v[48:49], v[52:53]
	s_nop 0
	v_add_f32_e32 v48, v48, v49
	v_fmamk_f32 v48, v48, 0x3a800000, v154
	v_mul_f32_e32 v49, 0x4b800000, v48
	v_cmp_gt_f32_e32 vcc, s63, v48
	s_nop 1
	v_cndmask_b32_e32 v48, v48, v49, vcc
	v_rsq_f32_e32 v50, v48
	v_lshlrev_b64 v[48:49], 6, v[64:65]
	v_lshl_add_u64 v[48:49], s[22:23], 0, v[48:49]
	v_mul_f32_e32 v51, 0x45800000, v50
	v_cndmask_b32_e32 v50, v50, v51, vcc
	v_pk_mul_f32 v[46:47], v[46:47], v[50:51] op_sel_hi:[1,0]
	v_pk_mul_f32 v[44:45], v[44:45], v[50:51] op_sel_hi:[1,0]
	v_pk_mul_f32 v[42:43], v[42:43], v[50:51] op_sel_hi:[1,0]
	v_pk_mul_f32 v[40:41], v[40:41], v[50:51] op_sel_hi:[1,0]
	v_pk_mul_f32 v[34:35], v[34:35], v[50:51] op_sel_hi:[1,0]
	v_pk_mul_f32 v[32:33], v[32:33], v[50:51] op_sel_hi:[1,0]
	v_pk_mul_f32 v[38:39], v[38:39], v[50:51] op_sel_hi:[1,0]
	v_pk_mul_f32 v[36:37], v[36:37], v[50:51] op_sel_hi:[1,0]
	v_max_f32_e32 v44, 0, v44
	v_max_f32_e32 v40, 0, v40
	v_max_f32_e32 v45, 0, v45
	v_max_f32_e32 v41, 0, v41
	v_max_f32_e32 v46, 0, v46
	v_max_f32_e32 v42, 0, v42
	v_max_f32_e32 v47, 0, v47
	v_max_f32_e32 v43, 0, v43
	v_max_f32_e32 v32, 0, v32
	v_max_f32_e32 v33, 0, v33
	v_max_f32_e32 v34, 0, v34
	v_max_f32_e32 v35, 0, v35
	v_max_f32_e32 v36, 0, v36
	v_max_f32_e32 v37, 0, v37
	v_max_f32_e32 v38, 0, v38
	v_max_f32_e32 v39, 0, v39
	v_pk_mul_f32 v[44:45], v[44:45], v[44:45]
	v_pk_mul_f32 v[40:41], v[40:41], v[40:41]
	v_pk_mul_f32 v[46:47], v[46:47], v[46:47]
	v_pk_mul_f32 v[42:43], v[42:43], v[42:43]
	v_pk_mul_f32 v[50:51], v[32:33], v[32:33]
	v_pk_mul_f32 v[52:53], v[34:35], v[34:35]
	v_cvt_pk_bf16_f32 v32, v44, v45
	v_cvt_pk_bf16_f32 v33, v46, v47
	v_cvt_pk_bf16_f32 v34, v40, v41
	v_cvt_pk_bf16_f32 v35, v42, v43
	v_pk_mul_f32 v[36:37], v[36:37], v[36:37]
	v_pk_mul_f32 v[38:39], v[38:39], v[38:39]
	buffer_store_dwordx4 v[32:35], v68, s[12:15], 0 offen sc1
	s_nop 1
	v_cvt_pk_bf16_f32 v32, v36, v37
	v_cvt_pk_bf16_f32 v33, v38, v39
	v_cvt_pk_bf16_f32 v34, v50, v51
	v_cvt_pk_bf16_f32 v35, v52, v53
	buffer_store_dwordx4 v[32:35], v68, s[12:15], 0 offen offset:256 sc1
	s_nop 0
	v_add_u32_e32 v48, 0xb0, v146
	v_ashrrev_i32_e32 v49, 31, v48
	v_lshl_add_u32 v52, v64, 13, v147
	s_waitcnt vmcnt(10)
; __device__ __forceinline__ u32x4 pack8(const f32x4 v0, const f32x4 v1) { u32x4 w; w.x = pk2(v0[0], v0[1]); w.y = pk2(v0[2], v0[3]); w.z = pk2(v1[0], v1[1]); w.w = pk2(v1[2], v1[3]); return w; }
; __device__ __forceinline__ float row_rstd(const float* ssq, int row) {
;     const f32x4* p = (const f32x4*)(ssq + (size_t)row * 16);
;     const f32x4 a = p[0], b = p[1], c = p[2], d = p[3];
;     const float s = ((a[0] + a[1]) + (a[2] + a[3])) + ((b[0] + b[1]) + (b[2] + b[3])) + ((c[0] + c[1]) + (c[2] + c[3])) + ((d[0] + d[1]) + (d[2] + d[3]));
;     return rsqrtf(s * (1.0f / 1024.0f) + 1e-6f);
;     __device__ __forceinline__ void operator()(const f32x4 (&acc)[2][2][4][2], const Unit& u, int wr, int wc, int fr, int fq) const {
;     ...
;             for (int m = 0; m < 4; ++m) {
;                 const int row = row0 + ai * 128 + m * 16; const float rs = row_rstd(ssq, row);
; #pragma unroll
;                 for (int bj = 0; bj < 2; ++bj) { f32x4 v0 = acc[ai][bj][m][0] * rs, v1 = acc[ai][bj][m][1] * rs;
; #pragma unroll
;                     for (int j = 0; j < 4; ++j) { const float a = fmaxf(v0[j], 0.f), b = fmaxf(v1[j], 0.f); v0[j] = a * a; v1[j] = b * b; }
;                     __builtin_amdgcn_raw_buffer_store_b128(pack8(v0, v1), rsrc, (unsigned)(((size_t)row * DFF + col0 + bj * 128) * 2), 0, 16  ); }
;             }
;         asm volatile("s_waitcnt vmcnt(0)" ::: "memory");
;         if (fr == 0 && fq == 0) (void)__hip_atomic_fetch_add(ready + 64 * (pm_off + u.pm), 1u, __ATOMIC_RELAXED, __HIP_MEMORY_SCOPE_AGENT);
	v_mov_b32_e32 v50, v215
	v_mov_b32_e32 v51, v216
	v_mov_b32_e32 v33, v217
	v_mov_b32_e32 v34, v219
	v_mov_b32_e32 v35, v220
	v_mov_b32_e32 v37, v221
	v_mov_b32_e32 v32, v214
	v_pk_add_f32 v[32:33], v[50:51], v[32:33]
	v_mov_b32_e32 v36, v218
	v_pk_add_f32 v[34:35], v[34:35], v[36:37]
	v_pk_add_f32 v[32:33], v[32:33], v[32:33] op_sel:[0,1] op_sel_hi:[1,0]
	v_pk_add_f32 v[34:35], v[34:35], v[34:35] op_sel:[0,1] op_sel_hi:[1,0]
	v_add_f32_e32 v38, v222, v223
	v_add_f32_e32 v40, v224, v225
	v_mov_b32_e32 v39, v234
	v_mov_b32_e32 v41, v235
	v_mov_b32_e32 v33, v232
	v_mov_b32_e32 v35, v233
	v_pk_add_f32 v[36:37], v[38:39], v[40:41]
	v_pk_add_f32 v[32:33], v[32:33], v[34:35]
	s_nop 0
	v_pk_add_f32 v[32:33], v[32:33], v[36:37]
	s_nop 0
	v_add_f32_e32 v32, v32, v33
	v_fmamk_f32 v32, v32, 0x3a800000, v154
	v_mul_f32_e32 v33, 0x4b800000, v32
	v_cmp_gt_f32_e32 vcc, s63, v32
	s_nop 1
	v_cndmask_b32_e32 v32, v32, v33, vcc
	v_rsq_f32_e32 v34, v32
	v_lshlrev_b64 v[32:33], 6, v[48:49]
	v_lshl_add_u64 v[32:33], s[22:23], 0, v[32:33]
	v_mul_f32_e32 v35, 0x45800000, v34
	v_cndmask_b32_e32 v34, v34, v35, vcc
	v_pk_mul_f32 v[30:31], v[30:31], v[34:35] op_sel_hi:[1,0]
	v_pk_mul_f32 v[28:29], v[28:29], v[34:35] op_sel_hi:[1,0]
	v_pk_mul_f32 v[26:27], v[26:27], v[34:35] op_sel_hi:[1,0]
	v_pk_mul_f32 v[24:25], v[24:25], v[34:35] op_sel_hi:[1,0]
	v_pk_mul_f32 v[18:19], v[18:19], v[34:35] op_sel_hi:[1,0]
	v_pk_mul_f32 v[16:17], v[16:17], v[34:35] op_sel_hi:[1,0]
	v_pk_mul_f32 v[22:23], v[22:23], v[34:35] op_sel_hi:[1,0]
	v_pk_mul_f32 v[20:21], v[20:21], v[34:35] op_sel_hi:[1,0]
	v_max_f32_e32 v28, 0, v28
	v_max_f32_e32 v24, 0, v24
	v_max_f32_e32 v29, 0, v29
	v_max_f32_e32 v25, 0, v25
	v_max_f32_e32 v30, 0, v30
	v_max_f32_e32 v26, 0, v26
	v_max_f32_e32 v31, 0, v31
	v_max_f32_e32 v27, 0, v27
	v_max_f32_e32 v16, 0, v16
	v_max_f32_e32 v17, 0, v17
	v_max_f32_e32 v18, 0, v18
	v_max_f32_e32 v19, 0, v19
	v_max_f32_e32 v20, 0, v20
	v_max_f32_e32 v21, 0, v21
	v_max_f32_e32 v22, 0, v22
	v_max_f32_e32 v23, 0, v23
	v_pk_mul_f32 v[28:29], v[28:29], v[28:29]
	v_pk_mul_f32 v[24:25], v[24:25], v[24:25]
	v_pk_mul_f32 v[30:31], v[30:31], v[30:31]
	v_pk_mul_f32 v[26:27], v[26:27], v[26:27]
	v_pk_mul_f32 v[34:35], v[16:17], v[16:17]
	v_pk_mul_f32 v[36:37], v[18:19], v[18:19]
	v_cvt_pk_bf16_f32 v16, v28, v29
	v_cvt_pk_bf16_f32 v17, v30, v31
	v_cvt_pk_bf16_f32 v18, v24, v25
	v_cvt_pk_bf16_f32 v19, v26, v27
	v_pk_mul_f32 v[20:21], v[20:21], v[20:21]
	v_pk_mul_f32 v[22:23], v[22:23], v[22:23]
	buffer_store_dwordx4 v[16:19], v52, s[12:15], 0 offen sc1
	s_nop 1
	v_cvt_pk_bf16_f32 v16, v20, v21
	v_cvt_pk_bf16_f32 v17, v22, v23
	v_cvt_pk_bf16_f32 v18, v34, v35
	v_cvt_pk_bf16_f32 v19, v36, v37
	buffer_store_dwordx4 v[16:19], v52, s[12:15], 0 offen offset:256 sc1
	s_nop 0
	s_waitcnt vmcnt(6)
	v_mov_b32_e32 v32, v237
	v_mov_b32_e32 v33, v238
	v_mov_b32_e32 v17, v239
	v_mov_b32_e32 v18, v241
	v_mov_b32_e32 v19, v242
	v_mov_b32_e32 v21, v243
	v_mov_b32_e32 v16, v236
	v_pk_add_f32 v[16:17], v[32:33], v[16:17]
	v_mov_b32_e32 v20, v240
	v_pk_add_f32 v[18:19], v[18:19], v[20:21]
	v_pk_add_f32 v[16:17], v[16:17], v[16:17] op_sel:[0,1] op_sel_hi:[1,0]
	v_pk_add_f32 v[18:19], v[18:19], v[18:19] op_sel:[0,1] op_sel_hi:[1,0]
	v_add_f32_e32 v22, v244, v245
	v_add_f32_e32 v24, v246, v247
	v_mov_b32_e32 v23, v250
	v_mov_b32_e32 v25, v251
	v_mov_b32_e32 v17, v248
	v_mov_b32_e32 v19, v249
	v_pk_add_f32 v[20:21], v[22:23], v[24:25]
	v_pk_add_f32 v[16:17], v[16:17], v[18:19]
	s_nop 0
	v_pk_add_f32 v[16:17], v[16:17], v[20:21]
	s_nop 0
	v_add_f32_e32 v16, v16, v17
	v_fmamk_f32 v16, v16, 0x3a800000, v154
	v_mul_f32_e32 v17, 0x4b800000, v16
	v_cmp_gt_f32_e32 vcc, s63, v16
	s_nop 1
	v_cndmask_b32_e32 v16, v16, v17, vcc
	v_rsq_f32_e32 v16, v16
	v_lshl_add_u32 v17, v48, 13, v147
	v_mul_f32_e32 v18, 0x45800000, v16
	v_cndmask_b32_e32 v16, v16, v18, vcc
	v_pk_mul_f32 v[14:15], v[14:15], v[16:17] op_sel_hi:[1,0]
	v_pk_mul_f32 v[12:13], v[12:13], v[16:17] op_sel_hi:[1,0]
	v_pk_mul_f32 v[10:11], v[10:11], v[16:17] op_sel_hi:[1,0]
	v_pk_mul_f32 v[8:9], v[8:9], v[16:17] op_sel_hi:[1,0]
	v_pk_mul_f32 v[2:3], v[2:3], v[16:17] op_sel_hi:[1,0]
	v_pk_mul_f32 v[0:1], v[0:1], v[16:17] op_sel_hi:[1,0]
	v_pk_mul_f32 v[6:7], v[6:7], v[16:17] op_sel_hi:[1,0]
	v_pk_mul_f32 v[4:5], v[4:5], v[16:17] op_sel_hi:[1,0]
	v_max_f32_e32 v12, 0, v12
	v_max_f32_e32 v8, 0, v8
	v_max_f32_e32 v13, 0, v13
	v_max_f32_e32 v9, 0, v9
	v_max_f32_e32 v14, 0, v14
	v_max_f32_e32 v10, 0, v10
	v_max_f32_e32 v15, 0, v15
	v_max_f32_e32 v11, 0, v11
	v_max_f32_e32 v0, 0, v0
	v_max_f32_e32 v1, 0, v1
	v_max_f32_e32 v2, 0, v2
	v_max_f32_e32 v3, 0, v3
	v_max_f32_e32 v4, 0, v4
	v_max_f32_e32 v5, 0, v5
	v_max_f32_e32 v6, 0, v6
	v_max_f32_e32 v7, 0, v7
	v_pk_mul_f32 v[12:13], v[12:13], v[12:13]
	v_pk_mul_f32 v[8:9], v[8:9], v[8:9]
	v_pk_mul_f32 v[14:15], v[14:15], v[14:15]
	v_pk_mul_f32 v[10:11], v[10:11], v[10:11]
	v_mul_f32_e32 v16, v0, v0
	v_mul_f32_e32 v18, v1, v1
	v_mul_f32_e32 v19, v2, v2
	v_mul_f32_e32 v20, v3, v3
	v_cvt_pk_bf16_f32 v0, v12, v13
	v_cvt_pk_bf16_f32 v1, v14, v15
	v_cvt_pk_bf16_f32 v2, v8, v9
	v_cvt_pk_bf16_f32 v3, v10, v11
	v_pk_mul_f32 v[4:5], v[4:5], v[4:5]
	v_pk_mul_f32 v[6:7], v[6:7], v[6:7]
	buffer_store_dwordx4 v[0:3], v17, s[12:15], 0 offen sc1
	s_nop 1
	v_cvt_pk_bf16_f32 v0, v4, v5
	v_cvt_pk_bf16_f32 v1, v6, v7
	v_cvt_pk_bf16_f32 v2, v16, v18
	v_cvt_pk_bf16_f32 v3, v19, v20
	buffer_store_dwordx4 v[0:3], v17, s[12:15], 0 offen offset:256 sc1
	s_waitcnt vmcnt(0)
	s_and_saveexec_b64 s[36:37], s[6:7]
	s_cbranch_execz .LBB0_2091
	s_mov_b64 s[38:39], exec
	v_mbcnt_lo_u32_b32 v0, s38, 0
	v_mbcnt_hi_u32_b32 v0, s39, v0
	v_cmp_eq_u32_e32 vcc, 0, v0
	s_and_b64 s[40:41], exec, vcc
	s_mov_b64 exec, s[40:41]
	s_cbranch_execz .LBB0_2091
	s_lshl_b32 s40, s68, 6
	s_ashr_i32 s41, s40, 31
	s_lshl_b64 s[40:41], s[40:41], 2
	s_add_u32 s40, s66, s40
	s_addc_u32 s41, s67, s41
	s_bcnt1_i32_b64 s25, s[38:39]
	v_mov_b32_e32 v0, s25
	global_atomic_add v131, v0, s[40:41]
	s_branch .LBB0_2091

; #define PG8_STAGE(bufoff, gbase, voff) do { _Pragma("unroll") for (int _i = 0; _i < 2; ++_i) \
;         __builtin_amdgcn_global_load_lds((const unsigned*)((const char*)(gbase) + (voff)[_i]), (LAS unsigned*)(lds + (bufoff) + ldsw + _i * 8192), 16, 0, 0); } while (0)
; #define PG8_LDA(dst, b, h) do { _Pragma("unroll") for (int m = 0; m < 4; ++m) _Pragma("unroll") for (int k = 0; k < 2; ++k) dst[m][k] = *(const LAS bf16x8*)(lds + PG8_SA(b, h) + aoff + m * 2048 + k * 1024); } while (0)
; #define PG8_LDB(dst, b, h) do { _Pragma("unroll") for (int n = 0; n < 2; ++n) _Pragma("unroll") for (int k = 0; k < 2; ++k) dst[n][k] = *(const LAS bf16x8*)(lds + PG8_SB(b, h) + boff + n * 2048 + k * 1024); } while (0)
; #define PG8_MMA(ai, bj, At, Bt) do { __builtin_amdgcn_s_setprio(1); _Pragma("unroll") for (int m = 0; m < 4; ++m) _Pragma("unroll") for (int n = 0; n < 2; ++n) _Pragma("unroll") for (int k = 0; k < 2; ++k) \
;         acc[ai][bj][m][n] = __builtin_amdgcn_mfma_f32_16x16x32_bf16(Bt[n][k], At[m][k], acc[ai][bj][m][n], 0, 0, 0); __builtin_amdgcn_s_setprio(0); } while (0)
; #define PG8_WAIT_L(n) asm volatile("s_waitcnt lgkmcnt(" #n ")" ::: "memory")
; #define PG8_BAR __builtin_amdgcn_s_barrier()
; #define PG8_SCHED __builtin_amdgcn_sched_barrier(0)
;     ...
;             PG8_LDB(B0, 0, 0); PG8_SCHED; PG8_LDA(At, 0, 0); PG8_STAGE(PG8_SA(1, 1), a1 + hA, voffA);
;             PG8_WAIT_L(8); PG8_BAR; PG8_WAIT_L(0); PG8_MMA(0, 0, At, B0); PG8_BAR; PG8_SCHED;
;             PG8_LDB(B1, 0, 1); PG8_STAGE(PG8_SB(0, 0), b2, voffB);
;             PG8_BAR; PG8_WAIT_L(0); PG8_MMA(0, 1, At, B1); PG8_BAR;
;             PG8_LDA(At, 0, 1); PG8_STAGE(PG8_SA(0, 0), a2, voffA);
;             PG8_BAR; PG8_WAIT_L(0); PG8_MMA(1, 0, At, B0); PG8_BAR; PG8_SCHED;
.LBB0_2122:
	ds_read_b128 v[150:153], v143
	ds_read_b128 v[154:157], v143 offset:1024
	ds_read_b128 v[158:161], v143 offset:2048
	ds_read_b128 v[162:165], v143 offset:3072
	s_add_u32 s36, s34, 0xfffc0080
	s_addc_u32 s37, s35, -1
	s_cmp_eq_u32 s71, 12
	s_cselect_b32 s39, s21, s37
	s_cselect_b32 s38, s44, s36
	s_cselect_b32 s37, s29, s70
	s_cselect_b32 s36, s45, s69
	v_lshl_add_u64 v[202:203], s[34:35], 0, v[138:139]
	s_add_i32 m0, s53, 0xc000
	ds_read_b128 v[170:173], v146
	ds_read_b128 v[174:177], v146 offset:1024
	ds_read_b128 v[178:181], v146 offset:2048
	ds_read_b128 v[182:185], v146 offset:3072
	ds_read_b128 v[186:189], v146 offset:4096
	ds_read_b128 v[190:193], v146 offset:5120
	ds_read_b128 v[194:197], v146 offset:6144
	ds_read_b128 v[198:201], v146 offset:7168
	global_load_lds_dwordx4 v[202:203], off
	v_lshl_add_u64 v[202:203], s[34:35], 0, v[136:137]
	s_add_i32 m0, s53, 0xe000
	s_nop 0
	global_load_lds_dwordx4 v[202:203], off
	s_waitcnt lgkmcnt(8)
	s_barrier
	s_waitcnt lgkmcnt(0)
	s_setprio 1
	s_waitcnt lgkmcnt(0)
	v_mfma_f32_16x16x32_bf16 v[124:127], v[150:153], v[170:173], v[124:127]
	v_mfma_f32_16x16x32_bf16 v[120:123], v[158:161], v[170:173], v[120:123]
	v_mfma_f32_16x16x32_bf16 v[108:111], v[150:153], v[178:181], v[108:111]
	v_mfma_f32_16x16x32_bf16 v[104:107], v[158:161], v[178:181], v[104:107]
	v_mfma_f32_16x16x32_bf16 v[92:95], v[150:153], v[186:189], v[92:95]
	v_mfma_f32_16x16x32_bf16 v[88:91], v[158:161], v[186:189], v[88:91]
	v_mfma_f32_16x16x32_bf16 v[76:79], v[150:153], v[194:197], v[76:79]
	v_mfma_f32_16x16x32_bf16 v[72:75], v[158:161], v[194:197], v[72:75]
	v_mfma_f32_16x16x32_bf16 v[124:127], v[154:157], v[174:177], v[124:127]
	v_mfma_f32_16x16x32_bf16 v[120:123], v[162:165], v[174:177], v[120:123]
	v_mfma_f32_16x16x32_bf16 v[108:111], v[154:157], v[182:185], v[108:111]
	v_mfma_f32_16x16x32_bf16 v[104:107], v[162:165], v[182:185], v[104:107]
	v_mfma_f32_16x16x32_bf16 v[92:95], v[154:157], v[190:193], v[92:95]
	v_mfma_f32_16x16x32_bf16 v[88:91], v[162:165], v[190:193], v[88:91]
	v_mfma_f32_16x16x32_bf16 v[76:79], v[154:157], v[198:201], v[76:79]
	v_mfma_f32_16x16x32_bf16 v[72:75], v[162:165], v[198:201], v[72:75]
	s_setprio 0
	s_barrier
	s_add_i32 s72, s61, s52
	v_lshl_add_u64 v[218:219], s[36:37], 0, v[130:131]
	s_mov_b32 m0, s72
	ds_read_b128 v[202:205], v147
	ds_read_b128 v[206:209], v147 offset:1024
	ds_read_b128 v[210:213], v147 offset:2048
	ds_read_b128 v[214:217], v147 offset:3072
	global_load_lds_dwordx4 v[218:219], off
	v_lshl_add_u64 v[220:221], s[36:37], 0, v[134:135]
	s_add_i32 m0, s72, 0x2000
	s_nop 0
	global_load_lds_dwordx4 v[220:221], off
	s_barrier
	s_waitcnt lgkmcnt(0)
	s_setprio 1
	s_waitcnt lgkmcnt(0)
	v_mfma_f32_16x16x32_bf16 v[116:119], v[202:205], v[170:173], v[116:119]
	v_mfma_f32_16x16x32_bf16 v[112:115], v[210:213], v[170:173], v[112:115]
	v_mfma_f32_16x16x32_bf16 v[100:103], v[202:205], v[178:181], v[100:103]
	v_mfma_f32_16x16x32_bf16 v[96:99], v[210:213], v[178:181], v[96:99]
	v_mfma_f32_16x16x32_bf16 v[84:87], v[202:205], v[186:189], v[84:87]
	v_mfma_f32_16x16x32_bf16 v[80:83], v[210:213], v[186:189], v[80:83]
	v_mfma_f32_16x16x32_bf16 v[68:71], v[202:205], v[194:197], v[68:71]
	v_mfma_f32_16x16x32_bf16 v[64:67], v[210:213], v[194:197], v[64:67]
	v_mfma_f32_16x16x32_bf16 v[116:119], v[206:209], v[174:177], v[116:119]
	v_mfma_f32_16x16x32_bf16 v[112:115], v[214:217], v[174:177], v[112:115]
	v_mfma_f32_16x16x32_bf16 v[100:103], v[206:209], v[182:185], v[100:103]
	v_mfma_f32_16x16x32_bf16 v[96:99], v[214:217], v[182:185], v[96:99]
	v_mfma_f32_16x16x32_bf16 v[84:87], v[206:209], v[190:193], v[84:87]
	v_mfma_f32_16x16x32_bf16 v[80:83], v[214:217], v[190:193], v[80:83]
	v_mfma_f32_16x16x32_bf16 v[68:71], v[206:209], v[198:201], v[68:71]
	v_mfma_f32_16x16x32_bf16 v[64:67], v[214:217], v[198:201], v[64:67]
	s_setprio 0
	s_mov_b32 m0, s53
	v_lshl_add_u64 v[222:223], s[38:39], 0, v[128:129]
	s_barrier
	ds_read_b128 v[170:173], v146 offset:16384
	ds_read_b128 v[174:177], v146 offset:17408
	ds_read_b128 v[178:181], v146 offset:18432
	ds_read_b128 v[182:185], v146 offset:19456
	ds_read_b128 v[186:189], v146 offset:20480
	ds_read_b128 v[190:193], v146 offset:21504
	ds_read_b128 v[194:197], v146 offset:22528
	ds_read_b128 v[198:201], v146 offset:23552
	global_load_lds_dwordx4 v[222:223], off
	v_lshl_add_u64 v[224:225], s[38:39], 0, v[132:133]
	s_mov_b32 m0, s54
	s_nop 0
	global_load_lds_dwordx4 v[224:225], off
	s_barrier
	s_waitcnt lgkmcnt(0)
	s_setprio 1
	s_waitcnt lgkmcnt(0)
	v_mfma_f32_16x16x32_bf16 v[60:63], v[150:153], v[170:173], v[60:63]
	v_mfma_f32_16x16x32_bf16 v[56:59], v[158:161], v[170:173], v[56:59]
	v_mfma_f32_16x16x32_bf16 v[44:47], v[150:153], v[178:181], v[44:47]
	v_mfma_f32_16x16x32_bf16 v[40:43], v[158:161], v[178:181], v[40:43]
	v_mfma_f32_16x16x32_bf16 v[28:31], v[150:153], v[186:189], v[28:31]
	v_mfma_f32_16x16x32_bf16 v[24:27], v[158:161], v[186:189], v[24:27]
	v_mfma_f32_16x16x32_bf16 v[12:15], v[150:153], v[194:197], v[12:15]
	v_mfma_f32_16x16x32_bf16 v[8:11], v[158:161], v[194:197], v[8:11]
	v_mfma_f32_16x16x32_bf16 v[60:63], v[154:157], v[174:177], v[60:63]
	v_mfma_f32_16x16x32_bf16 v[56:59], v[162:165], v[174:177], v[56:59]
	v_mfma_f32_16x16x32_bf16 v[44:47], v[154:157], v[182:185], v[44:47]
	v_mfma_f32_16x16x32_bf16 v[40:43], v[162:165], v[182:185], v[40:43]
	v_mfma_f32_16x16x32_bf16 v[28:31], v[154:157], v[190:193], v[28:31]
	v_mfma_f32_16x16x32_bf16 v[24:27], v[162:165], v[190:193], v[24:27]
	v_mfma_f32_16x16x32_bf16 v[12:15], v[154:157], v[198:201], v[12:15]
	v_mfma_f32_16x16x32_bf16 v[8:11], v[162:165], v[198:201], v[8:11]
	s_setprio 0
	s_barrier
; #define PG8_STAGE(bufoff, gbase, voff) do { _Pragma("unroll") for (int _i = 0; _i < 2; ++_i) \
;         __builtin_amdgcn_global_load_lds((const unsigned*)((const char*)(gbase) + (voff)[_i]), (LAS unsigned*)(lds + (bufoff) + ldsw + _i * 8192), 16, 0, 0); } while (0)
; #define PG8_LDA(dst, b, h) do { _Pragma("unroll") for (int m = 0; m < 4; ++m) _Pragma("unroll") for (int k = 0; k < 2; ++k) dst[m][k] = *(const LAS bf16x8*)(lds + PG8_SA(b, h) + aoff + m * 2048 + k * 1024); } while (0)
; #define PG8_LDB(dst, b, h) do { _Pragma("unroll") for (int n = 0; n < 2; ++n) _Pragma("unroll") for (int k = 0; k < 2; ++k) dst[n][k] = *(const LAS bf16x8*)(lds + PG8_SB(b, h) + boff + n * 2048 + k * 1024); } while (0)
; #define PG8_MMA(ai, bj, At, Bt) do { __builtin_amdgcn_s_setprio(1); _Pragma("unroll") for (int m = 0; m < 4; ++m) _Pragma("unroll") for (int n = 0; n < 2; ++n) _Pragma("unroll") for (int k = 0; k < 2; ++k) \
;         acc[ai][bj][m][n] = __builtin_amdgcn_mfma_f32_16x16x32_bf16(Bt[n][k], At[m][k], acc[ai][bj][m][n], 0, 0, 0); __builtin_amdgcn_s_setprio(0); } while (0)
; #define PG8_WAIT_V(n) asm volatile("s_waitcnt vmcnt(" #n ")" ::: "memory")
; #define PG8_WAIT_L(n) asm volatile("s_waitcnt lgkmcnt(" #n ")" ::: "memory")
; #define PG8_BAR __builtin_amdgcn_s_barrier()
; #define PG8_SCHED __builtin_amdgcn_sched_barrier(0)
;     ...
;             PG8_STAGE(PG8_SB(0, 1), b2 + hB, voffB);
;             PG8_WAIT_V(6); PG8_BAR; PG8_MMA(1, 1, At, B1); PG8_BAR;
;             PG8_LDB(B0, 1, 0); PG8_SCHED; PG8_LDA(At, 1, 0); PG8_STAGE(PG8_SA(0, 1), a2 + hA, voffA);
;             PG8_WAIT_L(8); PG8_BAR; PG8_WAIT_L(0); PG8_MMA(0, 0, At, B0); PG8_BAR; PG8_SCHED;
;             PG8_LDB(B1, 1, 1); PG8_STAGE(PG8_SB(1, 0), b3, voffB);
;             PG8_BAR; PG8_WAIT_L(0); PG8_MMA(0, 1, At, B1); PG8_BAR;
;             PG8_LDA(At, 1, 1); PG8_STAGE(PG8_SA(1, 0), a3, voffA);
;             PG8_BAR; PG8_WAIT_L(0); PG8_MMA(1, 0, At, B0); PG8_BAR; PG8_SCHED;
	s_add_u32 s72, s36, 0x40000
	s_addc_u32 s73, s37, 0
	s_add_i32 s74, s62, s52
	v_lshl_add_u64 v[150:151], s[72:73], 0, v[130:131]
	s_mov_b32 m0, s74
	s_nop 0
	global_load_lds_dwordx4 v[150:151], off
	v_lshl_add_u64 v[150:151], s[72:73], 0, v[134:135]
	s_add_i32 m0, s74, 0x2000
	s_nop 0
	global_load_lds_dwordx4 v[150:151], off
	s_waitcnt vmcnt(6)
	s_barrier
	s_setprio 1
	v_mfma_f32_16x16x32_bf16 v[52:55], v[202:205], v[170:173], v[52:55]
	v_mfma_f32_16x16x32_bf16 v[48:51], v[210:213], v[170:173], v[48:51]
	v_mfma_f32_16x16x32_bf16 v[36:39], v[202:205], v[178:181], v[36:39]
	v_mfma_f32_16x16x32_bf16 v[32:35], v[210:213], v[178:181], v[32:35]
	v_mfma_f32_16x16x32_bf16 v[20:23], v[202:205], v[186:189], v[20:23]
	v_mfma_f32_16x16x32_bf16 v[16:19], v[210:213], v[186:189], v[16:19]
	v_mfma_f32_16x16x32_bf16 v[4:7], v[202:205], v[194:197], v[4:7]
	v_mfma_f32_16x16x32_bf16 v[0:3], v[210:213], v[194:197], v[0:3]
	v_mfma_f32_16x16x32_bf16 v[52:55], v[206:209], v[174:177], v[52:55]
	v_mfma_f32_16x16x32_bf16 v[48:51], v[214:217], v[174:177], v[48:51]
	v_mfma_f32_16x16x32_bf16 v[36:39], v[206:209], v[182:185], v[36:39]
	v_mfma_f32_16x16x32_bf16 v[32:35], v[214:217], v[182:185], v[32:35]
	v_mfma_f32_16x16x32_bf16 v[20:23], v[206:209], v[190:193], v[20:23]
	v_mfma_f32_16x16x32_bf16 v[16:19], v[214:217], v[190:193], v[16:19]
	v_mfma_f32_16x16x32_bf16 v[4:7], v[206:209], v[198:201], v[4:7]
	v_mfma_f32_16x16x32_bf16 v[0:3], v[214:217], v[198:201], v[0:3]
	s_setprio 0
	s_add_i32 s72, 0, 0x18000
	v_add_u32_e32 v149, s72, v141
	s_barrier
	ds_read_b128 v[150:153], v149
	ds_read_b128 v[154:157], v149 offset:1024
	ds_read_b128 v[158:161], v149 offset:2048
	ds_read_b128 v[162:165], v149 offset:3072
	s_add_u32 s38, s38, 0x40000
	s_addc_u32 s39, s39, 0
	s_mov_b32 m0, s55
	v_lshl_add_u64 v[202:203], s[38:39], 0, v[128:129]
	ds_read_b128 v[170:173], v146 offset:32768
	ds_read_b128 v[174:177], v146 offset:33792
	ds_read_b128 v[178:181], v146 offset:34816
	ds_read_b128 v[182:185], v146 offset:35840
	ds_read_b128 v[186:189], v146 offset:36864
	ds_read_b128 v[190:193], v146 offset:37888
	ds_read_b128 v[194:197], v146 offset:38912
	ds_read_b128 v[198:201], v146 offset:39936
	global_load_lds_dwordx4 v[202:203], off
	v_lshl_add_u64 v[202:203], s[38:39], 0, v[132:133]
	s_mov_b32 m0, s56
	s_nop 0
	global_load_lds_dwordx4 v[202:203], off
	s_waitcnt lgkmcnt(8)
	s_barrier
	s_waitcnt lgkmcnt(0)
	s_setprio 1
	s_waitcnt lgkmcnt(0)
	v_mfma_f32_16x16x32_bf16 v[124:127], v[150:153], v[170:173], v[124:127]
	v_mfma_f32_16x16x32_bf16 v[120:123], v[158:161], v[170:173], v[120:123]
	v_mfma_f32_16x16x32_bf16 v[108:111], v[150:153], v[178:181], v[108:111]
	v_mfma_f32_16x16x32_bf16 v[104:107], v[158:161], v[178:181], v[104:107]
	v_mfma_f32_16x16x32_bf16 v[92:95], v[150:153], v[186:189], v[92:95]
	v_mfma_f32_16x16x32_bf16 v[88:91], v[158:161], v[186:189], v[88:91]
	v_mfma_f32_16x16x32_bf16 v[76:79], v[150:153], v[194:197], v[76:79]
	v_mfma_f32_16x16x32_bf16 v[72:75], v[158:161], v[194:197], v[72:75]
	v_mfma_f32_16x16x32_bf16 v[124:127], v[154:157], v[174:177], v[124:127]
	v_mfma_f32_16x16x32_bf16 v[120:123], v[162:165], v[174:177], v[120:123]
	v_mfma_f32_16x16x32_bf16 v[108:111], v[154:157], v[182:185], v[108:111]
	v_mfma_f32_16x16x32_bf16 v[104:107], v[162:165], v[182:185], v[104:107]
	v_mfma_f32_16x16x32_bf16 v[92:95], v[154:157], v[190:193], v[92:95]
	v_mfma_f32_16x16x32_bf16 v[88:91], v[162:165], v[190:193], v[88:91]
	v_mfma_f32_16x16x32_bf16 v[76:79], v[154:157], v[198:201], v[76:79]
	v_mfma_f32_16x16x32_bf16 v[72:75], v[162:165], v[198:201], v[72:75]
	s_setprio 0
	s_barrier
	s_add_i32 s38, 0, 0x1c000
	s_add_i32 s39, s72, s52
	v_add_u32_e32 v149, s38, v141
	v_lshl_add_u64 v[218:219], v[218:219], 0, s[22:23]
	s_mov_b32 m0, s39
	ds_read_b128 v[202:205], v149
	ds_read_b128 v[206:209], v149 offset:1024
	ds_read_b128 v[210:213], v149 offset:2048
	ds_read_b128 v[214:217], v149 offset:3072
	global_load_lds_dwordx4 v[218:219], off
	v_lshl_add_u64 v[218:219], v[220:221], 0, s[22:23]
	s_add_i32 m0, s39, 0x2000
	s_nop 0
	global_load_lds_dwordx4 v[218:219], off
	s_barrier
	s_waitcnt lgkmcnt(0)
	s_setprio 1
	s_waitcnt lgkmcnt(0)
	v_mfma_f32_16x16x32_bf16 v[116:119], v[202:205], v[170:173], v[116:119]
	v_mfma_f32_16x16x32_bf16 v[112:115], v[210:213], v[170:173], v[112:115]
	v_mfma_f32_16x16x32_bf16 v[100:103], v[202:205], v[178:181], v[100:103]
	v_mfma_f32_16x16x32_bf16 v[96:99], v[210:213], v[178:181], v[96:99]
	v_mfma_f32_16x16x32_bf16 v[84:87], v[202:205], v[186:189], v[84:87]
	v_mfma_f32_16x16x32_bf16 v[80:83], v[210:213], v[186:189], v[80:83]
	v_mfma_f32_16x16x32_bf16 v[68:71], v[202:205], v[194:197], v[68:71]
	v_mfma_f32_16x16x32_bf16 v[64:67], v[210:213], v[194:197], v[64:67]
	v_mfma_f32_16x16x32_bf16 v[116:119], v[206:209], v[174:177], v[116:119]
	v_mfma_f32_16x16x32_bf16 v[112:115], v[214:217], v[174:177], v[112:115]
	v_mfma_f32_16x16x32_bf16 v[100:103], v[206:209], v[182:185], v[100:103]
	v_mfma_f32_16x16x32_bf16 v[96:99], v[214:217], v[182:185], v[96:99]
	v_mfma_f32_16x16x32_bf16 v[84:87], v[206:209], v[190:193], v[84:87]
	v_mfma_f32_16x16x32_bf16 v[80:83], v[214:217], v[190:193], v[80:83]
	v_mfma_f32_16x16x32_bf16 v[68:71], v[206:209], v[198:201], v[68:71]
	v_mfma_f32_16x16x32_bf16 v[64:67], v[214:217], v[198:201], v[64:67]
	s_setprio 0
	s_mov_b32 m0, s58
	v_lshl_add_u64 v[218:219], v[222:223], 0, s[22:23]
	s_barrier
	ds_read_b128 v[170:173], v146 offset:49152
	ds_read_b128 v[174:177], v146 offset:50176
	ds_read_b128 v[178:181], v146 offset:51200
	ds_read_b128 v[182:185], v146 offset:52224
	ds_read_b128 v[186:189], v146 offset:53248
	ds_read_b128 v[190:193], v146 offset:54272
	ds_read_b128 v[194:197], v146 offset:55296
	ds_read_b128 v[198:201], v146 offset:56320
	global_load_lds_dwordx4 v[218:219], off
	v_lshl_add_u64 v[218:219], v[224:225], 0, s[22:23]
	s_mov_b32 m0, s59
	s_nop 0
	global_load_lds_dwordx4 v[218:219], off
	s_barrier
; #define PG8_STAGE(bufoff, gbase, voff) do { _Pragma("unroll") for (int _i = 0; _i < 2; ++_i) \
;         __builtin_amdgcn_global_load_lds((const unsigned*)((const char*)(gbase) + (voff)[_i]), (LAS unsigned*)(lds + (bufoff) + ldsw + _i * 8192), 16, 0, 0); } while (0)
; #define PG8_MMA(ai, bj, At, Bt) do { __builtin_amdgcn_s_setprio(1); _Pragma("unroll") for (int m = 0; m < 4; ++m) _Pragma("unroll") for (int n = 0; n < 2; ++n) _Pragma("unroll") for (int k = 0; k < 2; ++k) \
;         acc[ai][bj][m][n] = __builtin_amdgcn_mfma_f32_16x16x32_bf16(Bt[n][k], At[m][k], acc[ai][bj][m][n], 0, 0, 0); __builtin_amdgcn_s_setprio(0); } while (0)
; #define PG8_WAIT_V(n) asm volatile("s_waitcnt vmcnt(" #n ")" ::: "memory")
; #define PG8_WAIT_L(n) asm volatile("s_waitcnt lgkmcnt(" #n ")" ::: "memory")
; #define PG8_BAR __builtin_amdgcn_s_barrier()
; #define PG8_SCHED __builtin_amdgcn_sched_barrier(0)
;     ...
;             PG8_BAR; PG8_WAIT_L(0); PG8_MMA(1, 0, At, B0); PG8_BAR; PG8_SCHED;
;             PG8_STAGE(PG8_SB(1, 1), b3 + hB, voffB);
;             PG8_WAIT_V(6); PG8_BAR; PG8_MMA(1, 1, At, B1); PG8_BAR;
;         }
; __device__ __forceinline__ float row_rstd(const float* ssq, int row) {
;     const f32x4* p = (const f32x4*)(ssq + (size_t)row * 16);
;     const f32x4 a = p[0], b = p[1], c = p[2], d = p[3];
;     const float s = ((a[0] + a[1]) + (a[2] + a[3])) + ((b[0] + b[1]) + (b[2] + b[3])) + ((c[0] + c[1]) + (c[2] + c[3])) + ((d[0] + d[1]) + (d[2] + d[3]));
	s_waitcnt lgkmcnt(0)
	s_setprio 1
	s_waitcnt lgkmcnt(0)
	v_mfma_f32_16x16x32_bf16 v[60:63], v[150:153], v[170:173], v[60:63]
	v_mfma_f32_16x16x32_bf16 v[56:59], v[158:161], v[170:173], v[56:59]
	v_mfma_f32_16x16x32_bf16 v[44:47], v[150:153], v[178:181], v[44:47]
	v_mfma_f32_16x16x32_bf16 v[40:43], v[158:161], v[178:181], v[40:43]
	v_mfma_f32_16x16x32_bf16 v[28:31], v[150:153], v[186:189], v[28:31]
	v_mfma_f32_16x16x32_bf16 v[24:27], v[158:161], v[186:189], v[24:27]
	v_mfma_f32_16x16x32_bf16 v[12:15], v[150:153], v[194:197], v[12:15]
	v_mfma_f32_16x16x32_bf16 v[8:11], v[158:161], v[194:197], v[8:11]
	v_mfma_f32_16x16x32_bf16 v[60:63], v[154:157], v[174:177], v[60:63]
	v_mfma_f32_16x16x32_bf16 v[56:59], v[162:165], v[174:177], v[56:59]
	v_mfma_f32_16x16x32_bf16 v[44:47], v[154:157], v[182:185], v[44:47]
	v_mfma_f32_16x16x32_bf16 v[40:43], v[162:165], v[182:185], v[40:43]
	v_mfma_f32_16x16x32_bf16 v[28:31], v[154:157], v[190:193], v[28:31]
	v_mfma_f32_16x16x32_bf16 v[24:27], v[162:165], v[190:193], v[24:27]
	v_mfma_f32_16x16x32_bf16 v[12:15], v[154:157], v[198:201], v[12:15]
	v_mfma_f32_16x16x32_bf16 v[8:11], v[162:165], v[198:201], v[8:11]
	s_setprio 0
	s_barrier
	s_add_u32 s36, s36, 0x40080
	s_addc_u32 s37, s37, 0
	s_add_i32 s38, s38, s52
	v_lshl_add_u64 v[150:151], s[36:37], 0, v[130:131]
	s_mov_b32 m0, s38
	s_nop 0
	global_load_lds_dwordx4 v[150:151], off
	v_lshl_add_u64 v[150:151], s[36:37], 0, v[134:135]
	s_add_i32 m0, s38, 0x2000
	s_nop 0
	global_load_lds_dwordx4 v[150:151], off
	s_waitcnt vmcnt(6)
	s_barrier
	s_setprio 1
	v_mfma_f32_16x16x32_bf16 v[52:55], v[202:205], v[170:173], v[52:55]
	v_mfma_f32_16x16x32_bf16 v[48:51], v[210:213], v[170:173], v[48:51]
	v_mfma_f32_16x16x32_bf16 v[36:39], v[202:205], v[178:181], v[36:39]
	v_mfma_f32_16x16x32_bf16 v[32:35], v[210:213], v[178:181], v[32:35]
	v_mfma_f32_16x16x32_bf16 v[20:23], v[202:205], v[186:189], v[20:23]
	v_mfma_f32_16x16x32_bf16 v[16:19], v[210:213], v[186:189], v[16:19]
	v_mfma_f32_16x16x32_bf16 v[4:7], v[202:205], v[194:197], v[4:7]
	v_mfma_f32_16x16x32_bf16 v[0:3], v[210:213], v[194:197], v[0:3]
	v_mfma_f32_16x16x32_bf16 v[52:55], v[206:209], v[174:177], v[52:55]
	v_mfma_f32_16x16x32_bf16 v[48:51], v[214:217], v[174:177], v[48:51]
	v_mfma_f32_16x16x32_bf16 v[36:39], v[206:209], v[182:185], v[36:39]
	v_mfma_f32_16x16x32_bf16 v[32:35], v[214:217], v[182:185], v[32:35]
	v_mfma_f32_16x16x32_bf16 v[20:23], v[206:209], v[190:193], v[20:23]
	v_mfma_f32_16x16x32_bf16 v[16:19], v[214:217], v[190:193], v[16:19]
	v_mfma_f32_16x16x32_bf16 v[4:7], v[206:209], v[198:201], v[4:7]
	v_mfma_f32_16x16x32_bf16 v[0:3], v[214:217], v[198:201], v[0:3]
	s_setprio 0
	s_add_i32 s71, s71, 2
	s_add_u32 s69, s69, 0x100
	s_addc_u32 s70, s70, 0
	s_add_u32 s34, s34, 0x100
	s_addc_u32 s35, s35, 0
	s_cmp_gt_u32 s71, 13
	s_barrier
	s_cbranch_scc0 .LBB0_2122
	v_lshl_add_u32 v150, s68, 8, v140
	v_add_u32_e32 v164, 0x4000, v150
	v_ashrrev_i32_e32 v165, 31, v164
	v_lshlrev_b64 v[152:153], 6, v[164:165]
	v_lshl_add_u64 v[170:171], s[14:15], 0, v[152:153]
	v_subrev_u32_e32 v176, s14, v170
	v_add_u32_e32 v177, 0x0, v176
	global_load_dwordx4 v[178:181], v177, s[14:15]
	v_add_u32_e32 v177, 0x10, v176
	global_load_dwordx4 v[182:185], v177, s[14:15]
	v_add_u32_e32 v177, 0x20, v176
	global_load_dwordx4 v[186:189], v177, s[14:15]
	v_add_u32_e32 v177, 0x30, v176
	global_load_dwordx4 v[190:193], v177, s[14:15]
	v_add_u32_e32 v177, 0x400, v176
	global_load_dwordx4 v[194:197], v177, s[14:15]
	v_add_u32_e32 v177, 0x410, v176
	global_load_dwordx4 v[198:201], v177, s[14:15]
	v_add_u32_e32 v177, 0x420, v176
	global_load_dwordx4 v[202:205], v177, s[14:15]
	v_add_u32_e32 v177, 0x430, v176
	global_load_dwordx4 v[206:209], v177, s[14:15]
	v_add_u32_e32 v177, 0x800, v176
	global_load_dwordx4 v[210:213], v177, s[14:15]
	v_add_u32_e32 v177, 0x810, v176
	global_load_dwordx4 v[214:217], v177, s[14:15]
	v_add_u32_e32 v177, 0x820, v176
	global_load_dwordx4 v[232:235], v177, s[14:15]
	v_add_u32_e32 v177, 0x830, v176
	global_load_dwordx4 v[236:239], v177, s[14:15]
	v_add_u32_e32 v177, 0xc00, v176
	global_load_dwordx4 v[240:243], v177, s[14:15]
	v_add_u32_e32 v177, 0xc10, v176
	global_load_dwordx4 v[244:247], v177, s[14:15]
	v_add_u32_e32 v177, 0xc20, v176
	global_load_dwordx4 v[248:251], v177, s[14:15]
	v_add_u32_e32 v177, 0xc30, v176
	global_load_dwordx4 v[252:255], v177, s[14:15]
	s_nop 0
	v_lshl_or_b32 v149, s33, 9, v142
	v_lshl_add_u32 v151, v164, 13, v149
	v_add_u32_e32 v174, 0x4010, v150
	v_ashrrev_i32_e32 v175, 31, v174
	s_waitcnt vmcnt(12)
; __device__ __forceinline__ u32x4 pack8(const f32x4 v0, const f32x4 v1) { u32x4 w; w.x = pk2(v0[0], v0[1]); w.y = pk2(v0[2], v0[3]); w.z = pk2(v1[0], v1[1]); w.w = pk2(v1[2], v1[3]); return w; }
; __device__ __forceinline__ float row_rstd(const float* ssq, int row) {
;     const f32x4* p = (const f32x4*)(ssq + (size_t)row * 16);
;     const f32x4 a = p[0], b = p[1], c = p[2], d = p[3];
;     const float s = ((a[0] + a[1]) + (a[2] + a[3])) + ((b[0] + b[1]) + (b[2] + b[3])) + ((c[0] + c[1]) + (c[2] + c[3])) + ((d[0] + d[1]) + (d[2] + d[3]));
;     return rsqrtf(s * (1.0f / 1024.0f) + 1e-6f);
;     __device__ __forceinline__ void operator()(const f32x4 (&acc)[2][2][4][2], const Unit& u, int wr, int wc, int fr, int fq) const {
;     ...
;             for (int m = 0; m < 4; ++m) {
;                 const int row = row0 + ai * 128 + m * 16; const float rs = row_rstd(ssq, row);
; #pragma unroll
;                 for (int bj = 0; bj < 2; ++bj) { f32x4 v0 = acc[ai][bj][m][0] * rs, v1 = acc[ai][bj][m][1] * rs;
; #pragma unroll
;                     for (int j = 0; j < 4; ++j) { const float a = fmaxf(v0[j], 0.f), b = fmaxf(v1[j], 0.f); v0[j] = a * a; v1[j] = b * b; }
;                     __builtin_amdgcn_raw_buffer_store_b128(pack8(v0, v1), rsrc, (unsigned)(((size_t)row * DFF + col0 + bj * 128) * 2), 0, 16  ); }
;             }
	v_mov_b32_e32 v164, v179
	v_mov_b32_e32 v165, v180
	v_mov_b32_e32 v153, v181
	v_mov_b32_e32 v154, v183
	v_mov_b32_e32 v155, v184
	v_mov_b32_e32 v157, v185
	v_mov_b32_e32 v152, v178
	v_pk_add_f32 v[152:153], v[164:165], v[152:153]
	v_mov_b32_e32 v156, v182
	v_pk_add_f32 v[154:155], v[154:155], v[156:157]
	v_pk_add_f32 v[152:153], v[152:153], v[152:153] op_sel:[0,1] op_sel_hi:[1,0]
	v_pk_add_f32 v[154:155], v[154:155], v[154:155] op_sel:[0,1] op_sel_hi:[1,0]
	v_add_f32_e32 v158, v186, v187
	v_add_f32_e32 v160, v188, v189
	v_mov_b32_e32 v159, v192
	v_mov_b32_e32 v161, v193
	v_mov_b32_e32 v153, v190
	v_mov_b32_e32 v155, v191
	v_pk_add_f32 v[156:157], v[158:159], v[160:161]
	v_pk_add_f32 v[152:153], v[152:153], v[154:155]
	s_nop 0
	v_pk_add_f32 v[152:153], v[152:153], v[156:157]
	s_nop 0
	v_add_f32_e32 v152, v152, v153
	v_fmamk_f32 v152, v152, 0x3a800000, v148
	v_mul_f32_e32 v153, 0x4b800000, v152
	v_cmp_gt_f32_e32 vcc, s63, v152
	s_nop 1
	v_cndmask_b32_e32 v152, v152, v153, vcc
	v_rsq_f32_e32 v154, v152
	v_lshlrev_b64 v[152:153], 6, v[174:175]
	v_lshl_add_u64 v[152:153], s[14:15], 0, v[152:153]
	v_mul_f32_e32 v155, 0x45800000, v154
	v_cndmask_b32_e32 v154, v154, v155, vcc
	v_pk_mul_f32 v[126:127], v[126:127], v[154:155] op_sel_hi:[1,0]
	v_pk_mul_f32 v[124:125], v[124:125], v[154:155] op_sel_hi:[1,0]
	v_pk_mul_f32 v[122:123], v[122:123], v[154:155] op_sel_hi:[1,0]
	v_pk_mul_f32 v[120:121], v[120:121], v[154:155] op_sel_hi:[1,0]
	v_pk_mul_f32 v[114:115], v[114:115], v[154:155] op_sel_hi:[1,0]
	v_pk_mul_f32 v[112:113], v[112:113], v[154:155] op_sel_hi:[1,0]
	v_pk_mul_f32 v[118:119], v[118:119], v[154:155] op_sel_hi:[1,0]
	v_pk_mul_f32 v[116:117], v[116:117], v[154:155] op_sel_hi:[1,0]
	v_max_f32_e32 v124, 0, v124
	v_max_f32_e32 v120, 0, v120
	v_max_f32_e32 v125, 0, v125
	v_max_f32_e32 v121, 0, v121
	v_max_f32_e32 v126, 0, v126
	v_max_f32_e32 v122, 0, v122
	v_max_f32_e32 v127, 0, v127
	v_max_f32_e32 v123, 0, v123
	v_max_f32_e32 v112, 0, v112
	v_max_f32_e32 v113, 0, v113
	v_max_f32_e32 v114, 0, v114
	v_max_f32_e32 v115, 0, v115
	v_max_f32_e32 v116, 0, v116
	v_max_f32_e32 v117, 0, v117
	v_max_f32_e32 v118, 0, v118
	v_max_f32_e32 v119, 0, v119
	v_pk_mul_f32 v[124:125], v[124:125], v[124:125]
	v_pk_mul_f32 v[120:121], v[120:121], v[120:121]
	v_pk_mul_f32 v[126:127], v[126:127], v[126:127]
	v_pk_mul_f32 v[122:123], v[122:123], v[122:123]
	v_pk_mul_f32 v[154:155], v[112:113], v[112:113]
	v_pk_mul_f32 v[156:157], v[114:115], v[114:115]
	v_cvt_pk_bf16_f32 v112, v124, v125
	v_cvt_pk_bf16_f32 v113, v126, v127
	v_cvt_pk_bf16_f32 v114, v120, v121
	v_cvt_pk_bf16_f32 v115, v122, v123
	v_pk_mul_f32 v[116:117], v[116:117], v[116:117]
	v_pk_mul_f32 v[118:119], v[118:119], v[118:119]
	buffer_store_dwordx4 v[112:115], v151, s[8:11], 0 offen sc1
	s_nop 1
	v_cvt_pk_bf16_f32 v112, v116, v117
	v_cvt_pk_bf16_f32 v113, v118, v119
	v_cvt_pk_bf16_f32 v114, v154, v155
	v_cvt_pk_bf16_f32 v115, v156, v157
	buffer_store_dwordx4 v[112:115], v151, s[8:11], 0 offen offset:256 sc1
	s_nop 0
	v_add_u32_e32 v152, 0x4020, v150
	v_ashrrev_i32_e32 v153, 31, v152
	v_lshl_add_u32 v151, v174, 13, v149
	v_add_u32_e32 v177, 0x2000, v176
	global_load_dwordx4 v[178:181], v177, s[14:15]
	v_add_u32_e32 v177, 0x2010, v176
	global_load_dwordx4 v[182:185], v177, s[14:15]
	v_add_u32_e32 v177, 0x2020, v176
	global_load_dwordx4 v[186:189], v177, s[14:15]
	v_add_u32_e32 v177, 0x2030, v176
	global_load_dwordx4 v[190:193], v177, s[14:15]
	s_waitcnt vmcnt(14)
	v_mov_b32_e32 v154, v195
	v_mov_b32_e32 v155, v196
	v_mov_b32_e32 v113, v197
	v_mov_b32_e32 v114, v199
	v_mov_b32_e32 v115, v200
	v_mov_b32_e32 v117, v201
	v_mov_b32_e32 v112, v194
	v_pk_add_f32 v[112:113], v[154:155], v[112:113]
	v_mov_b32_e32 v116, v198
	v_pk_add_f32 v[114:115], v[114:115], v[116:117]
	v_pk_add_f32 v[112:113], v[112:113], v[112:113] op_sel:[0,1] op_sel_hi:[1,0]
	v_pk_add_f32 v[114:115], v[114:115], v[114:115] op_sel:[0,1] op_sel_hi:[1,0]
	v_add_f32_e32 v118, v202, v203
	v_add_f32_e32 v120, v204, v205
	v_mov_b32_e32 v119, v208
	v_mov_b32_e32 v121, v209
	v_mov_b32_e32 v113, v206
	v_mov_b32_e32 v115, v207
	v_pk_add_f32 v[116:117], v[118:119], v[120:121]
	v_pk_add_f32 v[112:113], v[112:113], v[114:115]
	s_nop 0
	v_pk_add_f32 v[112:113], v[112:113], v[116:117]
	s_nop 0
	v_add_f32_e32 v112, v112, v113
	v_fmamk_f32 v112, v112, 0x3a800000, v148
	v_mul_f32_e32 v113, 0x4b800000, v112
	v_cmp_gt_f32_e32 vcc, s63, v112
	s_nop 1
	v_cndmask_b32_e32 v112, v112, v113, vcc
	v_rsq_f32_e32 v114, v112
	v_lshlrev_b64 v[112:113], 6, v[152:153]
	v_lshl_add_u64 v[112:113], s[14:15], 0, v[112:113]
	v_mul_f32_e32 v115, 0x45800000, v114
	v_cndmask_b32_e32 v114, v114, v115, vcc
	v_pk_mul_f32 v[110:111], v[110:111], v[114:115] op_sel_hi:[1,0]
	v_pk_mul_f32 v[108:109], v[108:109], v[114:115] op_sel_hi:[1,0]
	v_pk_mul_f32 v[106:107], v[106:107], v[114:115] op_sel_hi:[1,0]
	v_pk_mul_f32 v[104:105], v[104:105], v[114:115] op_sel_hi:[1,0]
	v_pk_mul_f32 v[98:99], v[98:99], v[114:115] op_sel_hi:[1,0]
	v_pk_mul_f32 v[96:97], v[96:97], v[114:115] op_sel_hi:[1,0]
	v_pk_mul_f32 v[102:103], v[102:103], v[114:115] op_sel_hi:[1,0]
	v_pk_mul_f32 v[100:101], v[100:101], v[114:115] op_sel_hi:[1,0]
	v_max_f32_e32 v108, 0, v108
	v_max_f32_e32 v104, 0, v104
	v_max_f32_e32 v109, 0, v109
	v_max_f32_e32 v105, 0, v105
	v_max_f32_e32 v110, 0, v110
	v_max_f32_e32 v106, 0, v106
	v_max_f32_e32 v111, 0, v111
	v_max_f32_e32 v107, 0, v107
	v_max_f32_e32 v96, 0, v96
	v_max_f32_e32 v97, 0, v97
	v_max_f32_e32 v98, 0, v98
	v_max_f32_e32 v99, 0, v99
	v_max_f32_e32 v100, 0, v100
	v_max_f32_e32 v101, 0, v101
	v_max_f32_e32 v102, 0, v102
	v_max_f32_e32 v103, 0, v103
	v_pk_mul_f32 v[108:109], v[108:109], v[108:109]
	v_pk_mul_f32 v[104:105], v[104:105], v[104:105]
	v_pk_mul_f32 v[110:111], v[110:111], v[110:111]
	v_pk_mul_f32 v[106:107], v[106:107], v[106:107]
	v_pk_mul_f32 v[114:115], v[96:97], v[96:97]
	v_pk_mul_f32 v[116:117], v[98:99], v[98:99]
	v_cvt_pk_bf16_f32 v96, v108, v109
	v_cvt_pk_bf16_f32 v97, v110, v111
	v_cvt_pk_bf16_f32 v98, v104, v105
	v_cvt_pk_bf16_f32 v99, v106, v107
	v_pk_mul_f32 v[100:101], v[100:101], v[100:101]
	v_pk_mul_f32 v[102:103], v[102:103], v[102:103]
	buffer_store_dwordx4 v[96:99], v151, s[8:11], 0 offen sc1
	s_nop 1
	v_cvt_pk_bf16_f32 v96, v100, v101
	v_cvt_pk_bf16_f32 v97, v102, v103
	v_cvt_pk_bf16_f32 v98, v114, v115
	v_cvt_pk_bf16_f32 v99, v116, v117
	buffer_store_dwordx4 v[96:99], v151, s[8:11], 0 offen offset:256 sc1
	s_nop 0
	v_add_u32_e32 v112, 0x4030, v150
	v_ashrrev_i32_e32 v113, 31, v112
	v_lshl_add_u32 v116, v152, 13, v149
	v_add_u32_e32 v177, 0x2400, v176
	global_load_dwordx4 v[194:197], v177, s[14:15]
	v_add_u32_e32 v177, 0x2410, v176
	global_load_dwordx4 v[198:201], v177, s[14:15]
	v_add_u32_e32 v177, 0x2420, v176
	global_load_dwordx4 v[202:205], v177, s[14:15]
	v_add_u32_e32 v177, 0x2430, v176
	global_load_dwordx4 v[206:209], v177, s[14:15]
	s_waitcnt vmcnt(16)
; __device__ __forceinline__ u32x4 pack8(const f32x4 v0, const f32x4 v1) { u32x4 w; w.x = pk2(v0[0], v0[1]); w.y = pk2(v0[2], v0[3]); w.z = pk2(v1[0], v1[1]); w.w = pk2(v1[2], v1[3]); return w; }
; __device__ __forceinline__ float row_rstd(const float* ssq, int row) {
;     const f32x4* p = (const f32x4*)(ssq + (size_t)row * 16);
;     const f32x4 a = p[0], b = p[1], c = p[2], d = p[3];
;     const float s = ((a[0] + a[1]) + (a[2] + a[3])) + ((b[0] + b[1]) + (b[2] + b[3])) + ((c[0] + c[1]) + (c[2] + c[3])) + ((d[0] + d[1]) + (d[2] + d[3]));
;     return rsqrtf(s * (1.0f / 1024.0f) + 1e-6f);
;     __device__ __forceinline__ void operator()(const f32x4 (&acc)[2][2][4][2], const Unit& u, int wr, int wc, int fr, int fq) const {
;     ...
;             for (int m = 0; m < 4; ++m) {
;                 const int row = row0 + ai * 128 + m * 16; const float rs = row_rstd(ssq, row);
; #pragma unroll
;                 for (int bj = 0; bj < 2; ++bj) { f32x4 v0 = acc[ai][bj][m][0] * rs, v1 = acc[ai][bj][m][1] * rs;
; #pragma unroll
;                     for (int j = 0; j < 4; ++j) { const float a = fmaxf(v0[j], 0.f), b = fmaxf(v1[j], 0.f); v0[j] = a * a; v1[j] = b * b; }
;                     __builtin_amdgcn_raw_buffer_store_b128(pack8(v0, v1), rsrc, (unsigned)(((size_t)row * DFF + col0 + bj * 128) * 2), 0, 16  ); }
;             }
	v_mov_b32_e32 v114, v211
	v_mov_b32_e32 v115, v212
	v_mov_b32_e32 v97, v213
	v_mov_b32_e32 v98, v215
	v_mov_b32_e32 v99, v216
	v_mov_b32_e32 v101, v217
	v_mov_b32_e32 v96, v210
	v_pk_add_f32 v[96:97], v[114:115], v[96:97]
	v_mov_b32_e32 v100, v214
	v_pk_add_f32 v[98:99], v[98:99], v[100:101]
	v_pk_add_f32 v[96:97], v[96:97], v[96:97] op_sel:[0,1] op_sel_hi:[1,0]
	v_pk_add_f32 v[98:99], v[98:99], v[98:99] op_sel:[0,1] op_sel_hi:[1,0]
	v_add_f32_e32 v102, v232, v233
	v_add_f32_e32 v104, v234, v235
	v_mov_b32_e32 v103, v238
	v_mov_b32_e32 v105, v239
	v_mov_b32_e32 v97, v236
	v_mov_b32_e32 v99, v237
	v_pk_add_f32 v[100:101], v[102:103], v[104:105]
	v_pk_add_f32 v[96:97], v[96:97], v[98:99]
	s_nop 0
	v_pk_add_f32 v[96:97], v[96:97], v[100:101]
	s_nop 0
	v_add_f32_e32 v96, v96, v97
	v_fmamk_f32 v96, v96, 0x3a800000, v148
	v_mul_f32_e32 v97, 0x4b800000, v96
	v_cmp_gt_f32_e32 vcc, s63, v96
	s_nop 1
	v_cndmask_b32_e32 v96, v96, v97, vcc
	v_rsq_f32_e32 v98, v96
	v_lshlrev_b64 v[96:97], 6, v[112:113]
	v_lshl_add_u64 v[96:97], s[14:15], 0, v[96:97]
	v_mul_f32_e32 v99, 0x45800000, v98
	v_cndmask_b32_e32 v98, v98, v99, vcc
	v_pk_mul_f32 v[94:95], v[94:95], v[98:99] op_sel_hi:[1,0]
	v_pk_mul_f32 v[92:93], v[92:93], v[98:99] op_sel_hi:[1,0]
	v_pk_mul_f32 v[90:91], v[90:91], v[98:99] op_sel_hi:[1,0]
	v_pk_mul_f32 v[88:89], v[88:89], v[98:99] op_sel_hi:[1,0]
	v_pk_mul_f32 v[82:83], v[82:83], v[98:99] op_sel_hi:[1,0]
	v_pk_mul_f32 v[80:81], v[80:81], v[98:99] op_sel_hi:[1,0]
	v_pk_mul_f32 v[86:87], v[86:87], v[98:99] op_sel_hi:[1,0]
	v_pk_mul_f32 v[84:85], v[84:85], v[98:99] op_sel_hi:[1,0]
	v_max_f32_e32 v92, 0, v92
	v_max_f32_e32 v88, 0, v88
	v_max_f32_e32 v93, 0, v93
	v_max_f32_e32 v89, 0, v89
	v_max_f32_e32 v94, 0, v94
	v_max_f32_e32 v90, 0, v90
	v_max_f32_e32 v95, 0, v95
	v_max_f32_e32 v91, 0, v91
	v_max_f32_e32 v80, 0, v80
	v_max_f32_e32 v81, 0, v81
	v_max_f32_e32 v82, 0, v82
	v_max_f32_e32 v83, 0, v83
	v_max_f32_e32 v84, 0, v84
	v_max_f32_e32 v85, 0, v85
	v_max_f32_e32 v86, 0, v86
	v_max_f32_e32 v87, 0, v87
	v_pk_mul_f32 v[92:93], v[92:93], v[92:93]
	v_pk_mul_f32 v[88:89], v[88:89], v[88:89]
	v_pk_mul_f32 v[94:95], v[94:95], v[94:95]
	v_pk_mul_f32 v[90:91], v[90:91], v[90:91]
	v_pk_mul_f32 v[98:99], v[80:81], v[80:81]
	v_pk_mul_f32 v[100:101], v[82:83], v[82:83]
	v_cvt_pk_bf16_f32 v80, v92, v93
	v_cvt_pk_bf16_f32 v81, v94, v95
	v_cvt_pk_bf16_f32 v82, v88, v89
	v_cvt_pk_bf16_f32 v83, v90, v91
	v_pk_mul_f32 v[84:85], v[84:85], v[84:85]
	v_pk_mul_f32 v[86:87], v[86:87], v[86:87]
	buffer_store_dwordx4 v[80:83], v116, s[8:11], 0 offen sc1
	s_nop 1
	v_cvt_pk_bf16_f32 v80, v84, v85
	v_cvt_pk_bf16_f32 v81, v86, v87
	v_cvt_pk_bf16_f32 v82, v98, v99
	v_cvt_pk_bf16_f32 v83, v100, v101
	buffer_store_dwordx4 v[80:83], v116, s[8:11], 0 offen offset:256 sc1
	s_nop 0
	v_add_u32_e32 v96, 0x4080, v150
	v_ashrrev_i32_e32 v97, 31, v96
	v_lshl_add_u32 v100, v112, 13, v149
	v_add_u32_e32 v177, 0x2800, v176
	global_load_dwordx4 v[210:213], v177, s[14:15]
	v_add_u32_e32 v177, 0x2810, v176
	global_load_dwordx4 v[214:217], v177, s[14:15]
	v_add_u32_e32 v177, 0x2820, v176
	global_load_dwordx4 v[232:235], v177, s[14:15]
	v_add_u32_e32 v177, 0x2830, v176
	global_load_dwordx4 v[236:239], v177, s[14:15]
	s_waitcnt vmcnt(18)
	v_mov_b32_e32 v98, v241
	v_mov_b32_e32 v99, v242
	v_mov_b32_e32 v81, v243
	v_mov_b32_e32 v82, v245
	v_mov_b32_e32 v83, v246
	v_mov_b32_e32 v85, v247
	v_mov_b32_e32 v80, v240
	v_pk_add_f32 v[80:81], v[98:99], v[80:81]
	v_mov_b32_e32 v84, v244
	v_pk_add_f32 v[82:83], v[82:83], v[84:85]
	v_pk_add_f32 v[80:81], v[80:81], v[80:81] op_sel:[0,1] op_sel_hi:[1,0]
	v_pk_add_f32 v[82:83], v[82:83], v[82:83] op_sel:[0,1] op_sel_hi:[1,0]
	v_add_f32_e32 v86, v248, v249
	v_add_f32_e32 v88, v250, v251
	v_mov_b32_e32 v87, v254
	v_mov_b32_e32 v89, v255
	v_mov_b32_e32 v81, v252
	v_mov_b32_e32 v83, v253
	v_pk_add_f32 v[84:85], v[86:87], v[88:89]
	v_pk_add_f32 v[80:81], v[80:81], v[82:83]
	s_nop 0
	v_pk_add_f32 v[80:81], v[80:81], v[84:85]
	s_nop 0
	v_add_f32_e32 v80, v80, v81
	v_fmamk_f32 v80, v80, 0x3a800000, v148
	v_mul_f32_e32 v81, 0x4b800000, v80
	v_cmp_gt_f32_e32 vcc, s63, v80
	s_nop 1
	v_cndmask_b32_e32 v80, v80, v81, vcc
	v_rsq_f32_e32 v82, v80
	v_lshlrev_b64 v[80:81], 6, v[96:97]
	v_lshl_add_u64 v[80:81], s[14:15], 0, v[80:81]
	v_mul_f32_e32 v83, 0x45800000, v82
	v_cndmask_b32_e32 v82, v82, v83, vcc
	v_pk_mul_f32 v[78:79], v[78:79], v[82:83] op_sel_hi:[1,0]
	v_pk_mul_f32 v[76:77], v[76:77], v[82:83] op_sel_hi:[1,0]
	v_pk_mul_f32 v[74:75], v[74:75], v[82:83] op_sel_hi:[1,0]
	v_pk_mul_f32 v[72:73], v[72:73], v[82:83] op_sel_hi:[1,0]
	v_pk_mul_f32 v[66:67], v[66:67], v[82:83] op_sel_hi:[1,0]
	v_pk_mul_f32 v[64:65], v[64:65], v[82:83] op_sel_hi:[1,0]
	v_pk_mul_f32 v[70:71], v[70:71], v[82:83] op_sel_hi:[1,0]
	v_pk_mul_f32 v[68:69], v[68:69], v[82:83] op_sel_hi:[1,0]
	v_max_f32_e32 v76, 0, v76
	v_max_f32_e32 v72, 0, v72
	v_max_f32_e32 v77, 0, v77
	v_max_f32_e32 v73, 0, v73
	v_max_f32_e32 v78, 0, v78
	v_max_f32_e32 v74, 0, v74
	v_max_f32_e32 v79, 0, v79
	v_max_f32_e32 v75, 0, v75
	v_max_f32_e32 v64, 0, v64
	v_max_f32_e32 v65, 0, v65
	v_max_f32_e32 v66, 0, v66
	v_max_f32_e32 v67, 0, v67
	v_max_f32_e32 v68, 0, v68
	v_max_f32_e32 v69, 0, v69
	v_max_f32_e32 v70, 0, v70
	v_max_f32_e32 v71, 0, v71
	v_pk_mul_f32 v[76:77], v[76:77], v[76:77]
	v_pk_mul_f32 v[72:73], v[72:73], v[72:73]
	v_pk_mul_f32 v[78:79], v[78:79], v[78:79]
	v_pk_mul_f32 v[74:75], v[74:75], v[74:75]
	v_pk_mul_f32 v[82:83], v[64:65], v[64:65]
	v_pk_mul_f32 v[84:85], v[66:67], v[66:67]
	v_cvt_pk_bf16_f32 v64, v76, v77
	v_cvt_pk_bf16_f32 v65, v78, v79
	v_cvt_pk_bf16_f32 v66, v72, v73
	v_cvt_pk_bf16_f32 v67, v74, v75
	v_pk_mul_f32 v[68:69], v[68:69], v[68:69]
	v_pk_mul_f32 v[70:71], v[70:71], v[70:71]
	buffer_store_dwordx4 v[64:67], v100, s[8:11], 0 offen sc1
	s_nop 1
	v_cvt_pk_bf16_f32 v64, v68, v69
	v_cvt_pk_bf16_f32 v65, v70, v71
	v_cvt_pk_bf16_f32 v66, v82, v83
	v_cvt_pk_bf16_f32 v67, v84, v85
	buffer_store_dwordx4 v[64:67], v100, s[8:11], 0 offen offset:256 sc1
	s_nop 0
	v_add_u32_e32 v80, 0x4090, v150
	v_ashrrev_i32_e32 v81, 31, v80
	v_lshl_add_u32 v84, v96, 13, v149
	v_add_u32_e32 v177, 0x2c00, v176
	global_load_dwordx4 v[240:243], v177, s[14:15]
	v_add_u32_e32 v177, 0x2c10, v176
	global_load_dwordx4 v[244:247], v177, s[14:15]
	v_add_u32_e32 v177, 0x2c20, v176
	global_load_dwordx4 v[248:251], v177, s[14:15]
	v_add_u32_e32 v177, 0x2c30, v176
	global_load_dwordx4 v[252:255], v177, s[14:15]
	s_waitcnt vmcnt(18)
; __device__ __forceinline__ u32x4 pack8(const f32x4 v0, const f32x4 v1) { u32x4 w; w.x = pk2(v0[0], v0[1]); w.y = pk2(v0[2], v0[3]); w.z = pk2(v1[0], v1[1]); w.w = pk2(v1[2], v1[3]); return w; }
; __device__ __forceinline__ float row_rstd(const float* ssq, int row) {
;     const f32x4* p = (const f32x4*)(ssq + (size_t)row * 16);
;     const f32x4 a = p[0], b = p[1], c = p[2], d = p[3];
;     const float s = ((a[0] + a[1]) + (a[2] + a[3])) + ((b[0] + b[1]) + (b[2] + b[3])) + ((c[0] + c[1]) + (c[2] + c[3])) + ((d[0] + d[1]) + (d[2] + d[3]));
;     return rsqrtf(s * (1.0f / 1024.0f) + 1e-6f);
;     __device__ __forceinline__ void operator()(const f32x4 (&acc)[2][2][4][2], const Unit& u, int wr, int wc, int fr, int fq) const {
;     ...
;             for (int m = 0; m < 4; ++m) {
;                 const int row = row0 + ai * 128 + m * 16; const float rs = row_rstd(ssq, row);
; #pragma unroll
;                 for (int bj = 0; bj < 2; ++bj) { f32x4 v0 = acc[ai][bj][m][0] * rs, v1 = acc[ai][bj][m][1] * rs;
; #pragma unroll
;                     for (int j = 0; j < 4; ++j) { const float a = fmaxf(v0[j], 0.f), b = fmaxf(v1[j], 0.f); v0[j] = a * a; v1[j] = b * b; }
;                     __builtin_amdgcn_raw_buffer_store_b128(pack8(v0, v1), rsrc, (unsigned)(((size_t)row * DFF + col0 + bj * 128) * 2), 0, 16  ); }
;             }
	v_mov_b32_e32 v82, v179
	v_mov_b32_e32 v83, v180
	v_mov_b32_e32 v65, v181
	v_mov_b32_e32 v66, v183
	v_mov_b32_e32 v67, v184
	v_mov_b32_e32 v69, v185
	v_mov_b32_e32 v64, v178
	v_pk_add_f32 v[64:65], v[82:83], v[64:65]
	v_mov_b32_e32 v68, v182
	v_pk_add_f32 v[66:67], v[66:67], v[68:69]
	v_pk_add_f32 v[64:65], v[64:65], v[64:65] op_sel:[0,1] op_sel_hi:[1,0]
	v_pk_add_f32 v[66:67], v[66:67], v[66:67] op_sel:[0,1] op_sel_hi:[1,0]
	v_add_f32_e32 v70, v186, v187
	v_add_f32_e32 v72, v188, v189
	v_mov_b32_e32 v71, v192
	v_mov_b32_e32 v73, v193
	v_mov_b32_e32 v65, v190
	v_mov_b32_e32 v67, v191
	v_pk_add_f32 v[68:69], v[70:71], v[72:73]
	v_pk_add_f32 v[64:65], v[64:65], v[66:67]
	s_nop 0
	v_pk_add_f32 v[64:65], v[64:65], v[68:69]
	s_nop 0
	v_add_f32_e32 v64, v64, v65
	v_fmamk_f32 v64, v64, 0x3a800000, v148
	v_mul_f32_e32 v65, 0x4b800000, v64
	v_cmp_gt_f32_e32 vcc, s63, v64
	s_nop 1
	v_cndmask_b32_e32 v64, v64, v65, vcc
	v_rsq_f32_e32 v66, v64
	v_lshlrev_b64 v[64:65], 6, v[80:81]
	v_lshl_add_u64 v[64:65], s[14:15], 0, v[64:65]
	v_mul_f32_e32 v67, 0x45800000, v66
	v_cndmask_b32_e32 v66, v66, v67, vcc
	v_pk_mul_f32 v[62:63], v[62:63], v[66:67] op_sel_hi:[1,0]
	v_pk_mul_f32 v[60:61], v[60:61], v[66:67] op_sel_hi:[1,0]
	v_pk_mul_f32 v[58:59], v[58:59], v[66:67] op_sel_hi:[1,0]
	v_pk_mul_f32 v[56:57], v[56:57], v[66:67] op_sel_hi:[1,0]
	v_pk_mul_f32 v[50:51], v[50:51], v[66:67] op_sel_hi:[1,0]
	v_pk_mul_f32 v[48:49], v[48:49], v[66:67] op_sel_hi:[1,0]
	v_pk_mul_f32 v[54:55], v[54:55], v[66:67] op_sel_hi:[1,0]
	v_pk_mul_f32 v[52:53], v[52:53], v[66:67] op_sel_hi:[1,0]
	v_max_f32_e32 v60, 0, v60
	v_max_f32_e32 v56, 0, v56
	v_max_f32_e32 v61, 0, v61
	v_max_f32_e32 v57, 0, v57
	v_max_f32_e32 v62, 0, v62
	v_max_f32_e32 v58, 0, v58
	v_max_f32_e32 v63, 0, v63
	v_max_f32_e32 v59, 0, v59
	v_max_f32_e32 v48, 0, v48
	v_max_f32_e32 v49, 0, v49
	v_max_f32_e32 v50, 0, v50
	v_max_f32_e32 v51, 0, v51
	v_max_f32_e32 v52, 0, v52
	v_max_f32_e32 v53, 0, v53
	v_max_f32_e32 v54, 0, v54
	v_max_f32_e32 v55, 0, v55
	v_pk_mul_f32 v[60:61], v[60:61], v[60:61]
	v_pk_mul_f32 v[56:57], v[56:57], v[56:57]
	v_pk_mul_f32 v[62:63], v[62:63], v[62:63]
	v_pk_mul_f32 v[58:59], v[58:59], v[58:59]
	v_pk_mul_f32 v[66:67], v[48:49], v[48:49]
	v_pk_mul_f32 v[68:69], v[50:51], v[50:51]
	v_cvt_pk_bf16_f32 v48, v60, v61
	v_cvt_pk_bf16_f32 v49, v62, v63
	v_cvt_pk_bf16_f32 v50, v56, v57
	v_cvt_pk_bf16_f32 v51, v58, v59
	v_pk_mul_f32 v[52:53], v[52:53], v[52:53]
	v_pk_mul_f32 v[54:55], v[54:55], v[54:55]
	buffer_store_dwordx4 v[48:51], v84, s[8:11], 0 offen sc1
	s_nop 1
	v_cvt_pk_bf16_f32 v48, v52, v53
	v_cvt_pk_bf16_f32 v49, v54, v55
	v_cvt_pk_bf16_f32 v50, v66, v67
	v_cvt_pk_bf16_f32 v51, v68, v69
	buffer_store_dwordx4 v[48:51], v84, s[8:11], 0 offen offset:256 sc1
	s_nop 0
	v_add_u32_e32 v64, 0x40a0, v150
	v_ashrrev_i32_e32 v65, 31, v64
	v_lshl_add_u32 v68, v80, 13, v149
	s_waitcnt vmcnt(14)
	v_mov_b32_e32 v66, v195
	v_mov_b32_e32 v67, v196
	v_mov_b32_e32 v49, v197
	v_mov_b32_e32 v50, v199
	v_mov_b32_e32 v51, v200
	v_mov_b32_e32 v53, v201
	v_mov_b32_e32 v48, v194
	v_pk_add_f32 v[48:49], v[66:67], v[48:49]
	v_mov_b32_e32 v52, v198
	v_pk_add_f32 v[50:51], v[50:51], v[52:53]
	v_pk_add_f32 v[48:49], v[48:49], v[48:49] op_sel:[0,1] op_sel_hi:[1,0]
	v_pk_add_f32 v[50:51], v[50:51], v[50:51] op_sel:[0,1] op_sel_hi:[1,0]
	v_add_f32_e32 v54, v202, v203
	v_add_f32_e32 v56, v204, v205
	v_mov_b32_e32 v55, v208
	v_mov_b32_e32 v57, v209
	v_mov_b32_e32 v49, v206
	v_mov_b32_e32 v51, v207
	v_pk_add_f32 v[52:53], v[54:55], v[56:57]
	v_pk_add_f32 v[48:49], v[48:49], v[50:51]
	s_nop 0
	v_pk_add_f32 v[48:49], v[48:49], v[52:53]
	s_nop 0
	v_add_f32_e32 v48, v48, v49
	v_fmamk_f32 v48, v48, 0x3a800000, v148
	v_mul_f32_e32 v49, 0x4b800000, v48
	v_cmp_gt_f32_e32 vcc, s63, v48
	s_nop 1
	v_cndmask_b32_e32 v48, v48, v49, vcc
	v_rsq_f32_e32 v50, v48
	v_lshlrev_b64 v[48:49], 6, v[64:65]
	v_lshl_add_u64 v[48:49], s[14:15], 0, v[48:49]
	v_mul_f32_e32 v51, 0x45800000, v50
	v_cndmask_b32_e32 v50, v50, v51, vcc
	v_pk_mul_f32 v[46:47], v[46:47], v[50:51] op_sel_hi:[1,0]
	v_pk_mul_f32 v[44:45], v[44:45], v[50:51] op_sel_hi:[1,0]
	v_pk_mul_f32 v[42:43], v[42:43], v[50:51] op_sel_hi:[1,0]
	v_pk_mul_f32 v[40:41], v[40:41], v[50:51] op_sel_hi:[1,0]
	v_pk_mul_f32 v[34:35], v[34:35], v[50:51] op_sel_hi:[1,0]
	v_pk_mul_f32 v[32:33], v[32:33], v[50:51] op_sel_hi:[1,0]
	v_pk_mul_f32 v[38:39], v[38:39], v[50:51] op_sel_hi:[1,0]
	v_pk_mul_f32 v[36:37], v[36:37], v[50:51] op_sel_hi:[1,0]
	v_max_f32_e32 v44, 0, v44
	v_max_f32_e32 v40, 0, v40
	v_max_f32_e32 v45, 0, v45
	v_max_f32_e32 v41, 0, v41
	v_max_f32_e32 v46, 0, v46
	v_max_f32_e32 v42, 0, v42
	v_max_f32_e32 v47, 0, v47
	v_max_f32_e32 v43, 0, v43
	v_max_f32_e32 v32, 0, v32
	v_max_f32_e32 v33, 0, v33
	v_max_f32_e32 v34, 0, v34
	v_max_f32_e32 v35, 0, v35
	v_max_f32_e32 v36, 0, v36
	v_max_f32_e32 v37, 0, v37
	v_max_f32_e32 v38, 0, v38
	v_max_f32_e32 v39, 0, v39
	v_pk_mul_f32 v[44:45], v[44:45], v[44:45]
	v_pk_mul_f32 v[40:41], v[40:41], v[40:41]
	v_pk_mul_f32 v[46:47], v[46:47], v[46:47]
	v_pk_mul_f32 v[42:43], v[42:43], v[42:43]
	v_pk_mul_f32 v[50:51], v[32:33], v[32:33]
	v_pk_mul_f32 v[52:53], v[34:35], v[34:35]
	v_cvt_pk_bf16_f32 v32, v44, v45
	v_cvt_pk_bf16_f32 v33, v46, v47
	v_cvt_pk_bf16_f32 v34, v40, v41
	v_cvt_pk_bf16_f32 v35, v42, v43
	v_pk_mul_f32 v[36:37], v[36:37], v[36:37]
	v_pk_mul_f32 v[38:39], v[38:39], v[38:39]
	buffer_store_dwordx4 v[32:35], v68, s[8:11], 0 offen sc1
	s_nop 1
	v_cvt_pk_bf16_f32 v32, v36, v37
	v_cvt_pk_bf16_f32 v33, v38, v39
	v_cvt_pk_bf16_f32 v34, v50, v51
	v_cvt_pk_bf16_f32 v35, v52, v53
	buffer_store_dwordx4 v[32:35], v68, s[8:11], 0 offen offset:256 sc1
	s_nop 0
	v_add_u32_e32 v48, 0x40b0, v150
	v_ashrrev_i32_e32 v49, 31, v48
	v_lshl_add_u32 v52, v64, 13, v149
	s_waitcnt vmcnt(10)
; __device__ __forceinline__ u32x4 pack8(const f32x4 v0, const f32x4 v1) { u32x4 w; w.x = pk2(v0[0], v0[1]); w.y = pk2(v0[2], v0[3]); w.z = pk2(v1[0], v1[1]); w.w = pk2(v1[2], v1[3]); return w; }
; __device__ __forceinline__ float row_rstd(const float* ssq, int row) {
;     const f32x4* p = (const f32x4*)(ssq + (size_t)row * 16);
;     const f32x4 a = p[0], b = p[1], c = p[2], d = p[3];
;     const float s = ((a[0] + a[1]) + (a[2] + a[3])) + ((b[0] + b[1]) + (b[2] + b[3])) + ((c[0] + c[1]) + (c[2] + c[3])) + ((d[0] + d[1]) + (d[2] + d[3]));
;     return rsqrtf(s * (1.0f / 1024.0f) + 1e-6f);
;     __device__ __forceinline__ void operator()(const f32x4 (&acc)[2][2][4][2], const Unit& u, int wr, int wc, int fr, int fq) const {
;     ...
;             for (int m = 0; m < 4; ++m) {
;                 const int row = row0 + ai * 128 + m * 16; const float rs = row_rstd(ssq, row);
; #pragma unroll
;                 for (int bj = 0; bj < 2; ++bj) { f32x4 v0 = acc[ai][bj][m][0] * rs, v1 = acc[ai][bj][m][1] * rs;
; #pragma unroll
;                     for (int j = 0; j < 4; ++j) { const float a = fmaxf(v0[j], 0.f), b = fmaxf(v1[j], 0.f); v0[j] = a * a; v1[j] = b * b; }
;                     __builtin_amdgcn_raw_buffer_store_b128(pack8(v0, v1), rsrc, (unsigned)(((size_t)row * DFF + col0 + bj * 128) * 2), 0, 16  ); }
;             }
;         asm volatile("s_waitcnt vmcnt(0)" ::: "memory");
;         if (fr == 0 && fq == 0) (void)__hip_atomic_fetch_add(ready + 64 * (pm_off + u.pm), 1u, __ATOMIC_RELAXED, __HIP_MEMORY_SCOPE_AGENT);
	v_mov_b32_e32 v50, v211
	v_mov_b32_e32 v51, v212
	v_mov_b32_e32 v33, v213
	v_mov_b32_e32 v34, v215
	v_mov_b32_e32 v35, v216
	v_mov_b32_e32 v37, v217
	v_mov_b32_e32 v32, v210
	v_pk_add_f32 v[32:33], v[50:51], v[32:33]
	v_mov_b32_e32 v36, v214
	v_pk_add_f32 v[34:35], v[34:35], v[36:37]
	v_pk_add_f32 v[32:33], v[32:33], v[32:33] op_sel:[0,1] op_sel_hi:[1,0]
	v_pk_add_f32 v[34:35], v[34:35], v[34:35] op_sel:[0,1] op_sel_hi:[1,0]
	v_add_f32_e32 v38, v232, v233
	v_add_f32_e32 v40, v234, v235
	v_mov_b32_e32 v39, v238
	v_mov_b32_e32 v41, v239
	v_mov_b32_e32 v33, v236
	v_mov_b32_e32 v35, v237
	v_pk_add_f32 v[36:37], v[38:39], v[40:41]
	v_pk_add_f32 v[32:33], v[32:33], v[34:35]
	s_nop 0
	v_pk_add_f32 v[32:33], v[32:33], v[36:37]
	s_nop 0
	v_add_f32_e32 v32, v32, v33
	v_fmamk_f32 v32, v32, 0x3a800000, v148
	v_mul_f32_e32 v33, 0x4b800000, v32
	v_cmp_gt_f32_e32 vcc, s63, v32
	s_nop 1
	v_cndmask_b32_e32 v32, v32, v33, vcc
	v_rsq_f32_e32 v34, v32
	v_lshlrev_b64 v[32:33], 6, v[48:49]
	v_lshl_add_u64 v[32:33], s[14:15], 0, v[32:33]
	v_mul_f32_e32 v35, 0x45800000, v34
	v_cndmask_b32_e32 v34, v34, v35, vcc
	v_pk_mul_f32 v[30:31], v[30:31], v[34:35] op_sel_hi:[1,0]
	v_pk_mul_f32 v[28:29], v[28:29], v[34:35] op_sel_hi:[1,0]
	v_pk_mul_f32 v[26:27], v[26:27], v[34:35] op_sel_hi:[1,0]
	v_pk_mul_f32 v[24:25], v[24:25], v[34:35] op_sel_hi:[1,0]
	v_pk_mul_f32 v[18:19], v[18:19], v[34:35] op_sel_hi:[1,0]
	v_pk_mul_f32 v[16:17], v[16:17], v[34:35] op_sel_hi:[1,0]
	v_pk_mul_f32 v[22:23], v[22:23], v[34:35] op_sel_hi:[1,0]
	v_pk_mul_f32 v[20:21], v[20:21], v[34:35] op_sel_hi:[1,0]
	v_max_f32_e32 v28, 0, v28
	v_max_f32_e32 v24, 0, v24
	v_max_f32_e32 v29, 0, v29
	v_max_f32_e32 v25, 0, v25
	v_max_f32_e32 v30, 0, v30
	v_max_f32_e32 v26, 0, v26
	v_max_f32_e32 v31, 0, v31
	v_max_f32_e32 v27, 0, v27
	v_max_f32_e32 v16, 0, v16
	v_max_f32_e32 v17, 0, v17
	v_max_f32_e32 v18, 0, v18
	v_max_f32_e32 v19, 0, v19
	v_max_f32_e32 v20, 0, v20
	v_max_f32_e32 v21, 0, v21
	v_max_f32_e32 v22, 0, v22
	v_max_f32_e32 v23, 0, v23
	v_pk_mul_f32 v[28:29], v[28:29], v[28:29]
	v_pk_mul_f32 v[24:25], v[24:25], v[24:25]
	v_pk_mul_f32 v[30:31], v[30:31], v[30:31]
	v_pk_mul_f32 v[26:27], v[26:27], v[26:27]
	v_pk_mul_f32 v[34:35], v[16:17], v[16:17]
	v_pk_mul_f32 v[36:37], v[18:19], v[18:19]
	v_cvt_pk_bf16_f32 v16, v28, v29
	v_cvt_pk_bf16_f32 v17, v30, v31
	v_cvt_pk_bf16_f32 v18, v24, v25
	v_cvt_pk_bf16_f32 v19, v26, v27
	v_pk_mul_f32 v[20:21], v[20:21], v[20:21]
	v_pk_mul_f32 v[22:23], v[22:23], v[22:23]
	buffer_store_dwordx4 v[16:19], v52, s[8:11], 0 offen sc1
	s_nop 1
	v_cvt_pk_bf16_f32 v16, v20, v21
	v_cvt_pk_bf16_f32 v17, v22, v23
	v_cvt_pk_bf16_f32 v18, v34, v35
	v_cvt_pk_bf16_f32 v19, v36, v37
	buffer_store_dwordx4 v[16:19], v52, s[8:11], 0 offen offset:256 sc1
	s_nop 0
	s_waitcnt vmcnt(6)
	v_mov_b32_e32 v32, v241
	v_mov_b32_e32 v33, v242
	v_mov_b32_e32 v17, v243
	v_mov_b32_e32 v18, v245
	v_mov_b32_e32 v19, v246
	v_mov_b32_e32 v21, v247
	v_mov_b32_e32 v16, v240
	v_pk_add_f32 v[16:17], v[32:33], v[16:17]
	v_mov_b32_e32 v20, v244
	v_pk_add_f32 v[18:19], v[18:19], v[20:21]
	v_pk_add_f32 v[16:17], v[16:17], v[16:17] op_sel:[0,1] op_sel_hi:[1,0]
	v_pk_add_f32 v[18:19], v[18:19], v[18:19] op_sel:[0,1] op_sel_hi:[1,0]
	v_add_f32_e32 v22, v248, v249
	v_add_f32_e32 v24, v250, v251
	v_mov_b32_e32 v23, v254
	v_mov_b32_e32 v25, v255
	v_mov_b32_e32 v17, v252
	v_mov_b32_e32 v19, v253
	v_pk_add_f32 v[20:21], v[22:23], v[24:25]
	v_pk_add_f32 v[16:17], v[16:17], v[18:19]
	s_nop 0
	v_pk_add_f32 v[16:17], v[16:17], v[20:21]
	s_nop 0
	v_add_f32_e32 v16, v16, v17
	v_fmamk_f32 v16, v16, 0x3a800000, v148
	v_mul_f32_e32 v17, 0x4b800000, v16
	v_cmp_gt_f32_e32 vcc, s63, v16
	s_nop 1
	v_cndmask_b32_e32 v16, v16, v17, vcc
	v_rsq_f32_e32 v16, v16
	v_lshl_add_u32 v17, v48, 13, v149
	v_mul_f32_e32 v18, 0x45800000, v16
	v_cndmask_b32_e32 v16, v16, v18, vcc
	v_pk_mul_f32 v[14:15], v[14:15], v[16:17] op_sel_hi:[1,0]
	v_pk_mul_f32 v[12:13], v[12:13], v[16:17] op_sel_hi:[1,0]
	v_pk_mul_f32 v[10:11], v[10:11], v[16:17] op_sel_hi:[1,0]
	v_pk_mul_f32 v[8:9], v[8:9], v[16:17] op_sel_hi:[1,0]
	v_pk_mul_f32 v[2:3], v[2:3], v[16:17] op_sel_hi:[1,0]
	v_pk_mul_f32 v[0:1], v[0:1], v[16:17] op_sel_hi:[1,0]
	v_pk_mul_f32 v[6:7], v[6:7], v[16:17] op_sel_hi:[1,0]
	v_pk_mul_f32 v[4:5], v[4:5], v[16:17] op_sel_hi:[1,0]
	v_max_f32_e32 v12, 0, v12
	v_max_f32_e32 v8, 0, v8
	v_max_f32_e32 v13, 0, v13
	v_max_f32_e32 v9, 0, v9
	v_max_f32_e32 v14, 0, v14
	v_max_f32_e32 v10, 0, v10
	v_max_f32_e32 v15, 0, v15
	v_max_f32_e32 v11, 0, v11
	v_max_f32_e32 v0, 0, v0
	v_max_f32_e32 v1, 0, v1
	v_max_f32_e32 v2, 0, v2
	v_max_f32_e32 v3, 0, v3
	v_max_f32_e32 v4, 0, v4
	v_max_f32_e32 v5, 0, v5
	v_max_f32_e32 v6, 0, v6
	v_max_f32_e32 v7, 0, v7
	v_pk_mul_f32 v[12:13], v[12:13], v[12:13]
	v_pk_mul_f32 v[8:9], v[8:9], v[8:9]
	v_pk_mul_f32 v[14:15], v[14:15], v[14:15]
	v_pk_mul_f32 v[10:11], v[10:11], v[10:11]
	v_mul_f32_e32 v16, v0, v0
	v_mul_f32_e32 v18, v1, v1
	v_mul_f32_e32 v19, v2, v2
	v_mul_f32_e32 v20, v3, v3
	v_cvt_pk_bf16_f32 v0, v12, v13
	v_cvt_pk_bf16_f32 v1, v14, v15
	v_cvt_pk_bf16_f32 v2, v8, v9
	v_cvt_pk_bf16_f32 v3, v10, v11
	v_pk_mul_f32 v[4:5], v[4:5], v[4:5]
	v_pk_mul_f32 v[6:7], v[6:7], v[6:7]
	buffer_store_dwordx4 v[0:3], v17, s[8:11], 0 offen sc1
	s_nop 1
	v_cvt_pk_bf16_f32 v0, v4, v5
	v_cvt_pk_bf16_f32 v1, v6, v7
	v_cvt_pk_bf16_f32 v2, v16, v18
	v_cvt_pk_bf16_f32 v3, v19, v20
	buffer_store_dwordx4 v[0:3], v17, s[8:11], 0 offen offset:256 sc1
	s_waitcnt vmcnt(0)
	s_and_saveexec_b64 s[34:35], s[6:7]
	s_cbranch_execz .LBB0_2114
	s_mov_b64 s[36:37], exec
	v_mbcnt_lo_u32_b32 v0, s36, 0
	v_mbcnt_hi_u32_b32 v0, s37, v0
	v_cmp_eq_u32_e32 vcc, 0, v0
	s_and_b64 s[38:39], exec, vcc
	s_mov_b64 exec, s[38:39]
	s_cbranch_execz .LBB0_2114
	s_lshl_b32 s21, s68, 6
	s_add_i32 s38, s21, 0x1000
	s_ashr_i32 s39, s38, 31
	s_lshl_b64 s[38:39], s[38:39], 2
	s_add_u32 s38, s66, s38
	s_addc_u32 s39, s67, s39
	s_bcnt1_i32_b64 s21, s[36:37]
	v_mov_b32_e32 v0, s21
	global_atomic_add v131, v0, s[38:39]
	s_branch .LBB0_2114
